# p0 weight conversion loops: per-row gain loads issued early and together (were load + vmcnt(0) ladders), vmcnt waits recomputed
# speedup vs baseline: 1.0155x; 1.0016x over previous
.LBB0_30:
	v_or_b32_e32 v26, s26, v110
	v_mad_i64_i32 v[6:7], s[56:57], v26, s59, v[24:25]
	global_load_dwordx4 v[6:9], v[6:7], off
	v_cndmask_b32_e64 v5, 0, 1, s[48:49]
	v_cmp_ne_u32_e32 vcc, 1, v5
	v_ashrrev_i32_e32 v27, 31, v26
	v_or_b32_e32 v5, 4, v26
	v_or_b32_e32 v23, 8, v26
	v_or_b32_e32 v32, 12, v26
	v_or_b32_e32 v33, 16, v26
	v_or_b32_e32 v36, 20, v26
	v_or_b32_e32 v37, 24, v26
	v_or_b32_e32 v66, 28, v26
	v_or_b32_e32 v67, 32, v26
	v_or_b32_e32 v70, 36, v26
	v_or_b32_e32 v71, 40, v26
	v_or_b32_e32 v74, 44, v26
	v_or_b32_e32 v75, 48, v26
	v_or_b32_e32 v111, 52, v26
	v_or_b32_e32 v114, 56, v26
	v_or_b32_e32 v115, 60, v26
	v_mad_i64_i32 v[28:29], s[56:57], v5, s59, v[24:25]
	v_mad_i64_i32 v[30:31], s[56:57], v23, s59, v[24:25]
	v_mad_i64_i32 v[34:35], s[56:57], v32, s59, v[24:25]
	v_mad_i64_i32 v[64:65], s[56:57], v33, s59, v[24:25]
	v_mad_i64_i32 v[68:69], s[56:57], v36, s59, v[24:25]
	v_mad_i64_i32 v[72:73], s[56:57], v37, s59, v[24:25]
	v_mad_i64_i32 v[112:113], s[56:57], v66, s59, v[24:25]
	v_lshl_add_u64 v[148:149], v[26:27], 2, s[38:39]
	global_load_dword v166, v[148:149], off
	global_load_dword v168, v[148:149], off offset:16
	global_load_dword v170, v[148:149], off offset:32
	global_load_dword v172, v[148:149], off offset:48
	global_load_dword v174, v[148:149], off offset:64
	global_load_dword v176, v[148:149], off offset:80
	global_load_dword v178, v[148:149], off offset:96
	global_load_dword v180, v[148:149], off offset:112
	global_load_dword v182, v[148:149], off offset:128
	global_load_dword v184, v[148:149], off offset:144
	global_load_dword v186, v[148:149], off offset:160
	global_load_dword v188, v[148:149], off offset:176
	global_load_dword v190, v[148:149], off offset:192
	global_load_dword v192, v[148:149], off offset:208
	global_load_dword v194, v[148:149], off offset:224
	v_mad_i64_i32 v[116:117], s[56:57], v67, s59, v[24:25]
	v_mad_i64_i32 v[120:121], s[56:57], v70, s59, v[24:25]
	v_mad_i64_i32 v[124:125], s[56:57], v71, s59, v[24:25]
	v_mad_i64_i32 v[128:129], s[56:57], v74, s59, v[24:25]
	v_mad_i64_i32 v[132:133], s[56:57], v75, s59, v[24:25]
	v_mad_i64_i32 v[136:137], s[56:57], v111, s59, v[24:25]
	v_mad_i64_i32 v[140:141], s[56:57], v114, s59, v[24:25]
	v_mad_i64_i32 v[144:145], s[56:57], v115, s59, v[24:25]
	s_nop 0
	global_load_dwordx4 v[26:29], v[28:29], off
	s_nop 0
	s_nop 0
	global_load_dwordx4 v[30:33], v[30:31], off
	s_nop 0
	global_load_dwordx4 v[34:37], v[34:35], off
	s_nop 0
	s_nop 0
	global_load_dwordx4 v[64:67], v[64:65], off
	s_nop 0
	global_load_dwordx4 v[68:71], v[68:69], off
	s_nop 0
	s_nop 0
	global_load_dwordx4 v[72:75], v[72:73], off
	s_nop 0
	global_load_dwordx4 v[112:115], v[112:113], off
	s_nop 0
	s_nop 0
	global_load_dwordx4 v[116:119], v[116:117], off
	s_nop 0
	global_load_dwordx4 v[120:123], v[120:121], off
	s_nop 0
	s_nop 0
	global_load_dwordx4 v[124:127], v[124:125], off
	s_nop 0
	global_load_dwordx4 v[128:131], v[128:129], off
	s_nop 0
	s_nop 0
	global_load_dwordx4 v[132:135], v[132:133], off
	s_nop 0
	global_load_dwordx4 v[136:139], v[136:137], off
	s_nop 0
	s_nop 0
	global_load_dwordx4 v[140:143], v[140:141], off
	s_nop 0
	global_load_dwordx4 v[144:147], v[144:145], off
	s_nop 0
	global_load_dword v148, v[148:149], off offset:240
	s_mov_b32 s26, 64
	s_mov_b64 s[48:49], 0
	s_and_b64 vcc, exec, vcc
	s_waitcnt vmcnt(30)
	v_mul_f32_e32 v6, v6, v166
	v_mul_f32_e32 v7, v7, v166
	v_mul_f32_e32 v8, v8, v166
	v_mul_f32_e32 v5, v9, v166
	s_waitcnt vmcnt(15)
	v_mul_f32_e32 v9, v26, v168
	v_mul_f32_e32 v26, v27, v168
	v_mul_f32_e32 v27, v28, v168
	v_mul_f32_e32 v23, v29, v168
	s_waitcnt vmcnt(14)
	v_mul_f32_e32 v28, v30, v170
	v_mul_f32_e32 v29, v31, v170
	v_mul_f32_e32 v30, v32, v170
	v_mul_f32_e32 v31, v33, v170
	s_waitcnt vmcnt(13)
	v_mul_f32_e32 v32, v34, v172
	v_mul_f32_e32 v33, v35, v172
	v_mul_f32_e32 v34, v36, v172
	v_mul_f32_e32 v35, v37, v172
	v_max3_f32 v4, v4, |v6|, |v9|
	v_max3_f32 v3, v3, |v7|, |v26|
	v_max3_f32 v2, v2, |v8|, |v27|
	v_max3_f32 v0, v0, |v5|, |v23|
	s_waitcnt vmcnt(12)
	v_mul_f32_e32 v36, v64, v174
	v_mul_f32_e32 v37, v65, v174
	v_mul_f32_e32 v64, v66, v174
	v_mul_f32_e32 v65, v67, v174
	s_waitcnt vmcnt(11)
	v_mul_f32_e32 v66, v68, v176
	v_mul_f32_e32 v67, v69, v176
	v_mul_f32_e32 v68, v70, v176
	v_mul_f32_e32 v69, v71, v176
	v_max3_f32 v4, v4, |v28|, |v32|
	v_max3_f32 v3, v3, |v29|, |v33|
	v_max3_f32 v2, v2, |v30|, |v34|
	v_max3_f32 v0, v0, |v31|, |v35|
	s_waitcnt vmcnt(10)
	v_mul_f32_e32 v70, v72, v178
	v_mul_f32_e32 v71, v73, v178
	v_mul_f32_e32 v72, v74, v178
	v_mul_f32_e32 v73, v75, v178
	s_waitcnt vmcnt(9)
	v_mul_f32_e32 v74, v112, v180
	v_mul_f32_e32 v75, v113, v180
	v_mul_f32_e32 v111, v114, v180
	v_mul_f32_e32 v112, v115, v180
	v_max3_f32 v4, v4, |v36|, |v66|
	v_max3_f32 v3, v3, |v37|, |v67|
	v_max3_f32 v2, v2, |v64|, |v68|
	v_max3_f32 v0, v0, |v65|, |v69|
	s_waitcnt vmcnt(8)
	v_mul_f32_e32 v113, v116, v182
	v_mul_f32_e32 v114, v117, v182
	v_mul_f32_e32 v115, v118, v182
	v_mul_f32_e32 v116, v119, v182
	s_waitcnt vmcnt(7)
	v_mul_f32_e32 v117, v120, v184
	v_mul_f32_e32 v118, v121, v184
	v_mul_f32_e32 v119, v122, v184
	v_mul_f32_e32 v120, v123, v184
	v_max3_f32 v4, v4, |v70|, |v74|
	v_max3_f32 v3, v3, |v71|, |v75|
	v_max3_f32 v2, v2, |v72|, |v111|
	v_max3_f32 v0, v0, |v73|, |v112|
	s_waitcnt vmcnt(6)
	v_mul_f32_e32 v121, v124, v186
	v_mul_f32_e32 v122, v125, v186
	v_mul_f32_e32 v123, v126, v186
	v_mul_f32_e32 v124, v127, v186
	s_waitcnt vmcnt(5)
	v_mul_f32_e32 v125, v128, v188
	v_mul_f32_e32 v126, v129, v188
	v_mul_f32_e32 v127, v130, v188
	v_mul_f32_e32 v128, v131, v188
	v_max3_f32 v4, v4, |v113|, |v117|
	v_max3_f32 v3, v3, |v114|, |v118|
	v_max3_f32 v2, v2, |v115|, |v119|
	v_max3_f32 v0, v0, |v116|, |v120|
	s_waitcnt vmcnt(4)
	v_mul_f32_e32 v129, v132, v190
	v_mul_f32_e32 v130, v133, v190
	v_mul_f32_e32 v131, v134, v190
	v_mul_f32_e32 v132, v135, v190
	s_waitcnt vmcnt(3)
	v_mul_f32_e32 v133, v136, v192
	v_mul_f32_e32 v134, v137, v192
	v_mul_f32_e32 v135, v138, v192
	v_mul_f32_e32 v136, v139, v192
	v_max3_f32 v4, v4, |v121|, |v125|
	v_max3_f32 v3, v3, |v122|, |v126|
	v_max3_f32 v2, v2, |v123|, |v127|
	v_max3_f32 v0, v0, |v124|, |v128|
	s_waitcnt vmcnt(2)
	v_mul_f32_e32 v137, v140, v194
	v_mul_f32_e32 v138, v141, v194
	v_mul_f32_e32 v139, v142, v194
	v_mul_f32_e32 v140, v143, v194
	s_waitcnt vmcnt(0)
	v_mul_f32_e32 v141, v144, v148
	v_mul_f32_e32 v142, v145, v148
	v_mul_f32_e32 v143, v146, v148
	v_mul_f32_e32 v144, v147, v148
	v_max3_f32 v4, v4, |v129|, |v133|
	v_max3_f32 v3, v3, |v130|, |v134|
	v_max3_f32 v2, v2, |v131|, |v135|
	v_max3_f32 v0, v0, |v132|, |v136|
	v_max3_f32 v4, v4, |v137|, |v141|
	v_max3_f32 v3, v3, |v138|, |v142|
	v_max3_f32 v2, v2, |v139|, |v143|
	v_max3_f32 v0, v0, |v140|, |v144|
	s_cbranch_vccz .LBB0_30
	v_and_b32_e32 v6, 64, v88
	v_xor_b32_e32 v5, 16, v88
	v_add_u32_e32 v6, 64, v6
	v_cmp_lt_i32_e32 vcc, v5, v6
	s_nop 1
	v_cndmask_b32_e32 v5, v88, v5, vcc
	v_lshlrev_b32_e32 v7, 2, v5
	ds_bpermute_b32 v8, v7, v4
	v_xor_b32_e32 v5, 32, v88
	v_cmp_lt_i32_e32 vcc, v5, v6
	ds_bpermute_b32 v6, v7, v3
	ds_bpermute_b32 v23, v7, v0
	v_cndmask_b32_e32 v5, v88, v5, vcc
	v_lshlrev_b32_e32 v9, 2, v5
	s_waitcnt lgkmcnt(2)
	v_max_f32_e32 v5, v8, v8
	ds_bpermute_b32 v8, v7, v2
	v_max_f32_e32 v4, v4, v4
	s_waitcnt lgkmcnt(2)
	v_max_f32_e32 v6, v6, v6
	v_max_f32_e32 v3, v3, v3
	v_max_f32_e32 v2, v2, v2
	s_waitcnt lgkmcnt(0)
	v_max_f32_e32 v7, v8, v8
	v_max_f32_e32 v8, v23, v23
	v_max_f32_e32 v0, v0, v0
	v_max_f32_e32 v4, v4, v5
	v_max_f32_e32 v3, v3, v6
	v_max_f32_e32 v2, v2, v7
	v_max_f32_e32 v0, v0, v8
	ds_bpermute_b32 v5, v9, v4
	ds_bpermute_b32 v6, v9, v3
	ds_bpermute_b32 v7, v9, v2
	ds_bpermute_b32 v8, v9, v0
	s_and_saveexec_b64 s[48:49], s[2:3]
	s_cbranch_execz .LBB0_33
	s_waitcnt lgkmcnt(0)
	v_max_f32_e32 v8, v8, v8
	v_max_f32_e32 v0, v0, v0
	v_max_f32_e32 v9, v0, v8
	v_max_f32_e32 v0, v7, v7
	v_max_f32_e32 v2, v2, v2
	v_max_f32_e32 v8, v2, v0
	v_max_f32_e32 v0, v6, v6
	v_max_f32_e32 v2, v3, v3
	v_max_f32_e32 v7, v2, v0
	v_max_f32_e32 v0, v5, v5
	v_max_f32_e32 v2, v4, v4
	v_max_f32_e32 v6, v2, v0
	v_add_u32_e32 v0, s6, v60
	ds_write_b128 v0, v[6:9]

.LBB0_36:
	s_or_b32 vcc_lo, s7, s31
	v_or_b32_e32 v70, vcc_lo, v62
	v_ashrrev_i32_e32 v71, 31, v70
	v_lshl_add_u64 v[132:133], v[70:71], 2, s[38:39]
	v_mad_i64_i32 v[2:3], s[56:57], v70, s59, v[24:25]
	global_load_dword v132, v[132:133], off
	v_add_u32_e32 v23, v77, v78
	global_load_dwordx4 v[72:75], v[2:3], off nt
	s_ashr_i32 vcc_hi, vcc_lo, 31
	v_or_b32_e32 v2, 4, v70
	v_mad_i64_i32 v[2:3], s[56:57], v2, s59, v[24:25]
	global_load_dwordx4 v[112:115], v[2:3], off nt
	v_add_u32_e32 v71, 0x410, v23
	v_or_b32_e32 v2, 8, v70
	v_mad_i64_i32 v[2:3], s[56:57], v2, s59, v[24:25]
	global_load_dwordx4 v[116:119], v[2:3], off nt
	v_or_b32_e32 v2, 12, v70
	v_mad_i64_i32 v[2:3], s[56:57], v2, s59, v[24:25]
	global_load_dwordx4 v[120:123], v[2:3], off nt
	v_or_b32_e32 v2, 16, v70
	v_mad_i64_i32 v[2:3], s[56:57], v2, s59, v[24:25]
	global_load_dwordx4 v[124:127], v[2:3], off nt
	v_or_b32_e32 v2, 20, v70
	v_mad_i64_i32 v[2:3], s[56:57], v2, s59, v[24:25]
	global_load_dwordx4 v[128:131], v[2:3], off nt
	v_or_b32_e32 v2, 24, v70
	v_mad_i64_i32 v[2:3], s[56:57], v2, s59, v[24:25]
	global_load_dwordx4 v[6:9], v[2:3], off nt
	v_or_b32_e32 v2, 28, v70
	v_mad_i64_i32 v[2:3], s[56:57], v2, s59, v[24:25]
	global_load_dwordx4 v[2:5], v[2:3], off nt
	s_mov_b32 s7, 64
	s_waitcnt vmcnt(8)
	v_pk_mul_f32 v[134:135], v[26:27], v[132:133] op_sel_hi:[1,0]
	s_waitcnt vmcnt(7)
	v_pk_mul_f32 v[72:73], v[72:73], v[134:135]
	ds_write2_b32 v23, v72, v73 offset1:1
	v_pk_mul_f32 v[72:73], v[28:29], v[132:133] op_sel_hi:[1,0]
	s_nop 0
	v_pk_mul_f32 v[72:73], v[74:75], v[72:73]
	ds_write2_b32 v23, v72, v73 offset0:2 offset1:3
	v_lshl_add_u64 v[72:73], vcc, 0, v[62:63]
	v_lshl_add_u64 v[72:73], v[72:73], 2, s[38:39]
	global_load_dword v140, v[72:73], off offset:32
	global_load_dword v142, v[72:73], off offset:48
	global_load_dword v144, v[72:73], off offset:64
	global_load_dword v146, v[72:73], off offset:80
	global_load_dword v148, v[72:73], off offset:96
	global_load_dword v150, v[72:73], off offset:112
	global_load_dword v152, v[72:73], off offset:128
	global_load_dword v154, v[72:73], off offset:144
	global_load_dword v156, v[72:73], off offset:160
	global_load_dword v158, v[72:73], off offset:176
	global_load_dword v160, v[72:73], off offset:192
	global_load_dword v162, v[72:73], off offset:208
	global_load_dword v164, v[72:73], off offset:224
	global_load_dword v166, v[72:73], off offset:240
	global_load_dword v74, v[72:73], off offset:16
	s_waitcnt vmcnt(0)
	v_pk_mul_f32 v[132:133], v[26:27], v[74:75] op_sel_hi:[1,0]
	s_nop 0
	v_pk_mul_f32 v[112:113], v[112:113], v[132:133]
	v_pk_mul_f32 v[74:75], v[28:29], v[74:75] op_sel_hi:[1,0]
	ds_write2_b32 v71, v112, v113 offset1:1
	v_pk_mul_f32 v[74:75], v[114:115], v[74:75]
	v_add_u32_e32 v71, 0x418, v23
	ds_write2_b32 v71, v74, v75 offset1:1
	v_add_u32_e32 v71, 0x820, v23
	v_pk_mul_f32 v[112:113], v[26:27], v[140:141] op_sel_hi:[1,0]
	s_nop 0
	v_pk_mul_f32 v[112:113], v[116:117], v[112:113]
	v_pk_mul_f32 v[74:75], v[28:29], v[140:141] op_sel_hi:[1,0]
	ds_write2_b32 v71, v112, v113 offset1:1
	v_pk_mul_f32 v[74:75], v[118:119], v[74:75]
	v_add_u32_e32 v71, 0x828, v23
	ds_write2_b32 v71, v74, v75 offset1:1
	v_add_u32_e32 v71, 0xc30, v23
	v_pk_mul_f32 v[112:113], v[26:27], v[142:143] op_sel_hi:[1,0]
	s_nop 0
	v_pk_mul_f32 v[112:113], v[120:121], v[112:113]
	v_pk_mul_f32 v[74:75], v[28:29], v[142:143] op_sel_hi:[1,0]
	ds_write2_b32 v71, v112, v113 offset1:1
	v_pk_mul_f32 v[74:75], v[122:123], v[74:75]
	v_add_u32_e32 v71, 0xc38, v23
	ds_write2_b32 v71, v74, v75 offset1:1
	v_add_u32_e32 v71, 0x1040, v23
	v_pk_mul_f32 v[112:113], v[26:27], v[144:145] op_sel_hi:[1,0]
	s_nop 0
	v_pk_mul_f32 v[112:113], v[124:125], v[112:113]
	v_pk_mul_f32 v[74:75], v[28:29], v[144:145] op_sel_hi:[1,0]
	ds_write2_b32 v71, v112, v113 offset1:1
	v_pk_mul_f32 v[74:75], v[126:127], v[74:75]
	v_add_u32_e32 v71, 0x1048, v23
	ds_write2_b32 v71, v74, v75 offset1:1
	v_add_u32_e32 v23, 0x1450, v23
	v_pk_mul_f32 v[112:113], v[26:27], v[146:147] op_sel_hi:[1,0]
	s_nop 0
	v_pk_mul_f32 v[112:113], v[128:129], v[112:113]
	v_pk_mul_f32 v[74:75], v[28:29], v[146:147] op_sel_hi:[1,0]
	ds_write2_b32 v23, v112, v113 offset1:1
	v_pk_mul_f32 v[74:75], v[130:131], v[74:75]
	v_add_u32_e32 v23, v77, v79
	ds_write2_b32 v23, v74, v75 offset0:2 offset1:3
	v_add_u32_e32 v71, 0x410, v23
	v_pk_mul_f32 v[112:113], v[26:27], v[148:149] op_sel_hi:[1,0]
	s_nop 0
	v_pk_mul_f32 v[6:7], v[6:7], v[112:113]
	ds_write2_b32 v71, v6, v7 offset1:1
	v_pk_mul_f32 v[6:7], v[28:29], v[148:149] op_sel_hi:[1,0]
	v_or_b32_e32 v71, 40, v70
	v_pk_mul_f32 v[6:7], v[8:9], v[6:7]
	v_add_u32_e32 v8, 0x418, v23
	ds_write2_b32 v8, v6, v7 offset1:1
	v_mad_i64_i32 v[74:75], s[56:57], v71, s59, v[24:25]
	v_or_b32_e32 v71, 44, v70
	global_load_dwordx4 v[112:115], v[74:75], off nt
	v_mad_i64_i32 v[74:75], s[56:57], v71, s59, v[24:25]
	v_or_b32_e32 v71, 48, v70
	global_load_dwordx4 v[116:119], v[74:75], off nt
	v_mad_i64_i32 v[74:75], s[56:57], v71, s59, v[24:25]
	v_or_b32_e32 v71, 52, v70
	global_load_dwordx4 v[120:123], v[74:75], off nt
	v_mad_i64_i32 v[74:75], s[56:57], v71, s59, v[24:25]
	v_or_b32_e32 v71, 56, v70
	global_load_dwordx4 v[124:127], v[74:75], off nt
	v_mad_i64_i32 v[74:75], s[56:57], v71, s59, v[24:25]
	global_load_dwordx4 v[128:131], v[74:75], off nt
	v_pk_mul_f32 v[8:9], v[26:27], v[150:151] op_sel_hi:[1,0]
	s_nop 0
	v_pk_mul_f32 v[2:3], v[2:3], v[8:9]
	v_add_u32_e32 v7, 0x820, v23
	ds_write2_b32 v7, v2, v3 offset1:1
	v_pk_mul_f32 v[2:3], v[28:29], v[150:151] op_sel_hi:[1,0]
	v_or_b32_e32 v6, 36, v70
	v_pk_mul_f32 v[2:3], v[4:5], v[2:3]
	v_add_u32_e32 v4, 0x828, v23
	ds_write2_b32 v4, v2, v3 offset1:1
	v_or_b32_e32 v2, 32, v70
	v_or_b32_e32 v70, 60, v70
	v_mad_i64_i32 v[2:3], s[56:57], v2, s59, v[24:25]
	v_mad_i64_i32 v[6:7], s[56:57], v6, s59, v[24:25]
	v_mad_i64_i32 v[70:71], s[56:57], v70, s59, v[24:25]
	global_load_dwordx4 v[2:5], v[2:3], off nt
	s_nop 0
	global_load_dwordx4 v[6:9], v[6:7], off nt
	s_nop 0
	global_load_dwordx4 v[132:135], v[70:71], off nt
	s_nop 0
	v_pk_mul_f32 v[74:75], v[26:27], v[152:153] op_sel_hi:[1,0]
	s_nop 0
	s_waitcnt vmcnt(2)
	v_pk_mul_f32 v[2:3], v[2:3], v[74:75]
	v_add_u32_e32 v71, 0xc30, v23
	ds_write2_b32 v71, v2, v3 offset1:1
	v_pk_mul_f32 v[2:3], v[28:29], v[152:153] op_sel_hi:[1,0]
	s_nop 0
	v_pk_mul_f32 v[2:3], v[4:5], v[2:3]
	v_add_u32_e32 v4, 0xc38, v23
	ds_write2_b32 v4, v2, v3 offset1:1
	v_pk_mul_f32 v[4:5], v[26:27], v[154:155] op_sel_hi:[1,0]
	s_nop 0
	s_waitcnt vmcnt(1)
	v_pk_mul_f32 v[4:5], v[6:7], v[4:5]
	v_add_u32_e32 v3, 0x1040, v23
	ds_write2_b32 v3, v4, v5 offset1:1
	v_pk_mul_f32 v[2:3], v[28:29], v[154:155] op_sel_hi:[1,0]
	v_add_u32_e32 v4, 0x1048, v23
	v_pk_mul_f32 v[2:3], v[8:9], v[2:3]
	ds_write2_b32 v4, v2, v3 offset1:1
	v_pk_mul_f32 v[4:5], v[26:27], v[156:157] op_sel_hi:[1,0]
	s_nop 0
	v_pk_mul_f32 v[4:5], v[112:113], v[4:5]
	v_add_u32_e32 v3, 0x1450, v23
	ds_write2_b32 v3, v4, v5 offset1:1
	v_pk_mul_f32 v[2:3], v[28:29], v[156:157] op_sel_hi:[1,0]
	v_add_u32_e32 v4, 0x1458, v23
	v_pk_mul_f32 v[2:3], v[114:115], v[2:3]
	ds_write2_b32 v4, v2, v3 offset1:1
	v_pk_mul_f32 v[4:5], v[26:27], v[158:159] op_sel_hi:[1,0]
	s_nop 0
	v_pk_mul_f32 v[4:5], v[116:117], v[4:5]
	v_add_u32_e32 v3, 0x1860, v23
	ds_write2_b32 v3, v4, v5 offset1:1
	v_pk_mul_f32 v[2:3], v[28:29], v[158:159] op_sel_hi:[1,0]
	v_add_u32_e32 v4, 0x1868, v23
	v_pk_mul_f32 v[2:3], v[118:119], v[2:3]
	ds_write2_b32 v4, v2, v3 offset1:1
	v_pk_mul_f32 v[4:5], v[26:27], v[160:161] op_sel_hi:[1,0]
	s_nop 0
	v_pk_mul_f32 v[4:5], v[120:121], v[4:5]
	v_add_u32_e32 v3, 0x1c70, v23
	ds_write2_b32 v3, v4, v5 offset1:1
	v_pk_mul_f32 v[2:3], v[28:29], v[160:161] op_sel_hi:[1,0]
	v_add_u32_e32 v4, 0x1c78, v23
	v_pk_mul_f32 v[2:3], v[122:123], v[2:3]
	ds_write2_b32 v4, v2, v3 offset1:1
	v_pk_mul_f32 v[4:5], v[26:27], v[162:163] op_sel_hi:[1,0]
	s_nop 0
	v_pk_mul_f32 v[4:5], v[124:125], v[4:5]
	v_add_u32_e32 v3, 0x2080, v23
	ds_write2_b32 v3, v4, v5 offset1:1
	v_pk_mul_f32 v[2:3], v[28:29], v[162:163] op_sel_hi:[1,0]
	v_add_u32_e32 v4, 0x2088, v23
	v_pk_mul_f32 v[2:3], v[126:127], v[2:3]
	ds_write2_b32 v4, v2, v3 offset1:1
	v_pk_mul_f32 v[4:5], v[26:27], v[164:165] op_sel_hi:[1,0]
	s_nop 0
	v_pk_mul_f32 v[4:5], v[128:129], v[4:5]
	v_add_u32_e32 v3, 0x2490, v23
	ds_write2_b32 v3, v4, v5 offset1:1
	v_pk_mul_f32 v[2:3], v[28:29], v[164:165] op_sel_hi:[1,0]
	v_add_u32_e32 v4, 0x2498, v23
	v_pk_mul_f32 v[2:3], v[130:131], v[2:3]
	ds_write2_b32 v4, v2, v3 offset1:1
	v_pk_mul_f32 v[4:5], v[26:27], v[166:167] op_sel_hi:[1,0]
	s_nop 0
	s_waitcnt vmcnt(0)
	v_pk_mul_f32 v[4:5], v[132:133], v[4:5]
	v_add_u32_e32 v3, 0x28a0, v23
	ds_write2_b32 v3, v4, v5 offset1:1
	v_pk_mul_f32 v[2:3], v[28:29], v[166:167] op_sel_hi:[1,0]
	v_add_u32_e32 v4, 0x28a8, v23
	v_pk_mul_f32 v[2:3], v[134:135], v[2:3]
	ds_write2_b32 v4, v2, v3 offset1:1
	s_waitcnt lgkmcnt(0)
	ds_read2_b32 v[8:9], v13 offset0:130 offset1:138
	ds_read2_b32 v[70:71], v13 offset0:195 offset1:203
	ds_read2_b32 v[4:5], v13 offset1:8
	ds_read2_b32 v[6:7], v13 offset0:65 offset1:73
	v_lshl_add_u64 v[2:3], v[14:15], 0, vcc
	s_waitcnt lgkmcnt(3)
	v_med3_f32 v8, v8, s61, v89
	s_waitcnt lgkmcnt(2)
	v_med3_f32 v23, v70, s61, v89
	v_add_f32_e32 v8, 0x4b400000, v8
	v_add_f32_e32 v23, 0x4b400000, v23
	v_perm_b32 v8, v23, v8, s0
	v_add_u32_e32 v23, 0x400, v13
	ds_read2_b32 v[74:75], v23 offset0:4 offset1:12
	ds_read2_b32 v[112:113], v23 offset0:69 offset1:77
	ds_read2_b32 v[114:115], v23 offset0:134 offset1:142
	ds_read2_b32 v[116:117], v23 offset0:199 offset1:207
	s_waitcnt lgkmcnt(5)
	v_med3_f32 v4, v4, s61, v89
	s_waitcnt lgkmcnt(4)
	v_med3_f32 v6, v6, s61, v89
	v_add_f32_e32 v4, 0x4b400000, v4
	v_add_f32_e32 v6, 0x4b400000, v6
	v_perm_b32 v4, v6, v4, s0
	v_perm_b32 v72, v8, v4, s1
	s_waitcnt lgkmcnt(3)
	v_med3_f32 v4, v74, s61, v89
	s_waitcnt lgkmcnt(2)
	v_med3_f32 v6, v112, s61, v89
	s_waitcnt lgkmcnt(1)
	v_med3_f32 v8, v114, s61, v89
	s_waitcnt lgkmcnt(0)
	v_med3_f32 v70, v116, s61, v89
	v_add_f32_e32 v4, 0x4b400000, v4
	v_add_f32_e32 v6, 0x4b400000, v6
	v_add_f32_e32 v8, 0x4b400000, v8
	v_add_f32_e32 v70, 0x4b400000, v70
	v_perm_b32 v8, v70, v8, s0
	v_perm_b32 v4, v6, v4, s0
	v_perm_b32 v73, v8, v4, s1
	v_med3_f32 v4, v5, s61, v89
	v_med3_f32 v5, v7, s61, v89
	v_med3_f32 v6, v9, s61, v89
	v_med3_f32 v7, v71, s61, v89
	v_add_f32_e32 v4, 0x4b400000, v4
	v_add_f32_e32 v5, 0x4b400000, v5
	v_add_f32_e32 v6, 0x4b400000, v6
	v_add_f32_e32 v7, 0x4b400000, v7
	v_perm_b32 v6, v7, v6, s0
	v_perm_b32 v4, v5, v4, s0
	v_perm_b32 v4, v6, v4, s1
	v_med3_f32 v5, v75, s61, v89
	v_med3_f32 v6, v113, s61, v89
	v_med3_f32 v7, v115, s61, v89
	v_med3_f32 v8, v117, s61, v89
	v_add_f32_e32 v5, 0x4b400000, v5
	v_add_f32_e32 v6, 0x4b400000, v6
	v_add_f32_e32 v7, 0x4b400000, v7
	v_add_f32_e32 v8, 0x4b400000, v8
	v_perm_b32 v7, v8, v7, s0
	v_perm_b32 v5, v6, v5, s0
	v_perm_b32 v5, v7, v5, s1
	v_lshl_add_u64 v[6:7], v[2:3], 0, v[30:31]
	global_store_dwordx2 v[6:7], v[4:5], off
	ds_read2_b32 v[4:5], v13 offset0:16 offset1:24
	ds_read2_b32 v[6:7], v13 offset0:81 offset1:89
	ds_read2_b32 v[8:9], v13 offset0:146 offset1:154
	ds_read2_b32 v[70:71], v13 offset0:211 offset1:219
	ds_read2_b32 v[74:75], v23 offset0:20 offset1:28
	ds_read2_b32 v[112:113], v23 offset0:85 offset1:93
	ds_read2_b32 v[114:115], v23 offset0:150 offset1:158
	ds_read2_b32 v[116:117], v23 offset0:215 offset1:223
	s_waitcnt lgkmcnt(7)
	v_med3_f32 v4, v4, s61, v89
	s_waitcnt lgkmcnt(6)
	v_med3_f32 v6, v6, s61, v89
	s_waitcnt lgkmcnt(5)
	v_med3_f32 v8, v8, s61, v89
	s_waitcnt lgkmcnt(4)
	v_med3_f32 v70, v70, s61, v89
	v_add_f32_e32 v4, 0x4b400000, v4
	v_add_f32_e32 v6, 0x4b400000, v6
	v_add_f32_e32 v8, 0x4b400000, v8
	v_add_f32_e32 v70, 0x4b400000, v70
	v_lshl_add_u64 v[118:119], v[2:3], 0, v[0:1]
	v_perm_b32 v8, v70, v8, s0
	v_perm_b32 v4, v6, v4, s0
	global_store_dwordx2 v[118:119], v[72:73], off
	v_perm_b32 v72, v8, v4, s1
	s_waitcnt lgkmcnt(3)
	v_med3_f32 v4, v74, s61, v89
	s_waitcnt lgkmcnt(2)
	v_med3_f32 v6, v112, s61, v89
	s_waitcnt lgkmcnt(1)
	v_med3_f32 v8, v114, s61, v89
	s_waitcnt lgkmcnt(0)
	v_med3_f32 v70, v116, s61, v89
	v_add_f32_e32 v4, 0x4b400000, v4
	v_add_f32_e32 v6, 0x4b400000, v6
	v_add_f32_e32 v8, 0x4b400000, v8
	v_add_f32_e32 v70, 0x4b400000, v70
	v_perm_b32 v8, v70, v8, s0
	v_perm_b32 v4, v6, v4, s0
	v_perm_b32 v73, v8, v4, s1
	v_med3_f32 v4, v5, s61, v89
	v_med3_f32 v5, v7, s61, v89
	v_med3_f32 v6, v9, s61, v89
	v_med3_f32 v7, v71, s61, v89
	v_add_f32_e32 v4, 0x4b400000, v4
	v_add_f32_e32 v5, 0x4b400000, v5
	v_add_f32_e32 v6, 0x4b400000, v6
	v_add_f32_e32 v7, 0x4b400000, v7
	v_perm_b32 v6, v7, v6, s0
	v_perm_b32 v4, v5, v4, s0
	v_perm_b32 v4, v6, v4, s1
	v_med3_f32 v5, v75, s61, v89
	v_med3_f32 v6, v113, s61, v89
	v_med3_f32 v7, v115, s61, v89
	v_med3_f32 v8, v117, s61, v89
	v_add_f32_e32 v5, 0x4b400000, v5
	v_add_f32_e32 v6, 0x4b400000, v6
	v_add_f32_e32 v7, 0x4b400000, v7
	v_add_f32_e32 v8, 0x4b400000, v8
	v_perm_b32 v7, v8, v7, s0
	v_perm_b32 v5, v6, v5, s0
	v_perm_b32 v5, v7, v5, s1
	v_lshl_add_u64 v[6:7], v[2:3], 0, v[34:35]
	global_store_dwordx2 v[6:7], v[4:5], off
	ds_read2_b32 v[4:5], v13 offset0:32 offset1:40
	ds_read2_b32 v[6:7], v13 offset0:97 offset1:105
	ds_read2_b32 v[8:9], v13 offset0:162 offset1:170
	ds_read2_b32 v[70:71], v13 offset0:227 offset1:235
	ds_read2_b32 v[74:75], v23 offset0:36 offset1:44
	ds_read2_b32 v[112:113], v23 offset0:101 offset1:109
	ds_read2_b32 v[114:115], v23 offset0:166 offset1:174
	ds_read2_b32 v[116:117], v23 offset0:231 offset1:239
	s_waitcnt lgkmcnt(7)
	v_med3_f32 v4, v4, s61, v89
	s_waitcnt lgkmcnt(6)
	v_med3_f32 v6, v6, s61, v89
	s_waitcnt lgkmcnt(5)
	v_med3_f32 v8, v8, s61, v89
	s_waitcnt lgkmcnt(4)
	v_med3_f32 v70, v70, s61, v89
	v_add_f32_e32 v4, 0x4b400000, v4
	v_add_f32_e32 v6, 0x4b400000, v6
	v_add_f32_e32 v8, 0x4b400000, v8
	v_add_f32_e32 v70, 0x4b400000, v70
	v_lshl_add_u64 v[118:119], v[2:3], 0, v[32:33]
	v_perm_b32 v8, v70, v8, s0
	v_perm_b32 v4, v6, v4, s0
	global_store_dwordx2 v[118:119], v[72:73], off
	v_perm_b32 v72, v8, v4, s1
	s_waitcnt lgkmcnt(3)
	v_med3_f32 v4, v74, s61, v89
	s_waitcnt lgkmcnt(2)
	v_med3_f32 v6, v112, s61, v89
	s_waitcnt lgkmcnt(1)
	v_med3_f32 v8, v114, s61, v89
	s_waitcnt lgkmcnt(0)
	v_med3_f32 v70, v116, s61, v89
	v_add_f32_e32 v4, 0x4b400000, v4
	v_add_f32_e32 v6, 0x4b400000, v6
	v_add_f32_e32 v8, 0x4b400000, v8
	v_add_f32_e32 v70, 0x4b400000, v70
	v_perm_b32 v8, v70, v8, s0
	v_perm_b32 v4, v6, v4, s0
	v_perm_b32 v73, v8, v4, s1
	v_med3_f32 v4, v5, s61, v89
	v_med3_f32 v5, v7, s61, v89
	v_med3_f32 v6, v9, s61, v89
	v_med3_f32 v7, v71, s61, v89
	v_add_f32_e32 v4, 0x4b400000, v4
	v_add_f32_e32 v5, 0x4b400000, v5
	v_add_f32_e32 v6, 0x4b400000, v6
	v_add_f32_e32 v7, 0x4b400000, v7
	v_perm_b32 v6, v7, v6, s0
	v_perm_b32 v4, v5, v4, s0
	v_perm_b32 v4, v6, v4, s1
	v_med3_f32 v5, v75, s61, v89
	v_med3_f32 v6, v113, s61, v89
	v_med3_f32 v7, v115, s61, v89
	v_med3_f32 v8, v117, s61, v89
	v_add_f32_e32 v5, 0x4b400000, v5
	v_add_f32_e32 v6, 0x4b400000, v6
	v_add_f32_e32 v7, 0x4b400000, v7
	v_add_f32_e32 v8, 0x4b400000, v8
	v_perm_b32 v7, v8, v7, s0
	v_perm_b32 v5, v6, v5, s0
	v_perm_b32 v5, v7, v5, s1
	v_lshl_add_u64 v[6:7], v[2:3], 0, v[64:65]
	global_store_dwordx2 v[6:7], v[4:5], off
	ds_read2_b32 v[4:5], v13 offset0:48 offset1:56
	ds_read2_b32 v[6:7], v13 offset0:113 offset1:121
	ds_read2_b32 v[8:9], v13 offset0:178 offset1:186
	ds_read2_b32 v[70:71], v13 offset0:243 offset1:251
	ds_read2_b32 v[74:75], v23 offset0:52 offset1:60
	ds_read2_b32 v[112:113], v23 offset0:117 offset1:125
	ds_read2_b32 v[114:115], v23 offset0:182 offset1:190
	ds_read2_b32 v[116:117], v23 offset0:247 offset1:255
	s_waitcnt lgkmcnt(7)
	v_med3_f32 v4, v4, s61, v89
	s_waitcnt lgkmcnt(6)
	v_med3_f32 v6, v6, s61, v89
	s_waitcnt lgkmcnt(5)
	v_med3_f32 v8, v8, s61, v89
	s_waitcnt lgkmcnt(4)
	v_med3_f32 v70, v70, s61, v89
	v_add_f32_e32 v4, 0x4b400000, v4
	v_add_f32_e32 v6, 0x4b400000, v6
	v_add_f32_e32 v8, 0x4b400000, v8
	v_add_f32_e32 v70, 0x4b400000, v70
	v_lshl_add_u64 v[118:119], v[2:3], 0, v[36:37]
	v_perm_b32 v8, v70, v8, s0
	v_perm_b32 v4, v6, v4, s0
	global_store_dwordx2 v[118:119], v[72:73], off
	v_perm_b32 v72, v8, v4, s1
	s_waitcnt lgkmcnt(3)
	v_med3_f32 v4, v74, s61, v89
	s_waitcnt lgkmcnt(2)
	v_med3_f32 v6, v112, s61, v89
	s_waitcnt lgkmcnt(1)
	v_med3_f32 v8, v114, s61, v89
	s_waitcnt lgkmcnt(0)
	v_med3_f32 v23, v116, s61, v89
	v_add_f32_e32 v4, 0x4b400000, v4
	v_add_f32_e32 v6, 0x4b400000, v6
	v_add_f32_e32 v8, 0x4b400000, v8
	v_add_f32_e32 v23, 0x4b400000, v23
	v_perm_b32 v8, v23, v8, s0
	v_perm_b32 v4, v6, v4, s0
	v_perm_b32 v73, v8, v4, s1
	v_med3_f32 v4, v5, s61, v89
	v_med3_f32 v5, v7, s61, v89
	v_med3_f32 v6, v9, s61, v89
	v_med3_f32 v7, v71, s61, v89
	v_add_f32_e32 v4, 0x4b400000, v4
	v_add_f32_e32 v5, 0x4b400000, v5
	v_add_f32_e32 v6, 0x4b400000, v6
	v_add_f32_e32 v7, 0x4b400000, v7
	v_perm_b32 v6, v7, v6, s0
	v_perm_b32 v4, v5, v4, s0
	v_perm_b32 v4, v6, v4, s1
	v_med3_f32 v5, v75, s61, v89
	v_med3_f32 v6, v113, s61, v89
	v_med3_f32 v7, v115, s61, v89
	v_med3_f32 v8, v117, s61, v89
	v_add_f32_e32 v5, 0x4b400000, v5
	v_add_f32_e32 v6, 0x4b400000, v6
	v_add_f32_e32 v7, 0x4b400000, v7
	v_add_f32_e32 v8, 0x4b400000, v8
	v_perm_b32 v7, v8, v7, s0
	v_perm_b32 v5, v6, v5, s0
	v_lshl_add_u64 v[118:119], v[2:3], 0, v[66:67]
	v_perm_b32 v5, v7, v5, s1
	v_lshl_add_u64 v[2:3], v[2:3], 0, v[68:69]
	global_store_dwordx2 v[118:119], v[72:73], off
	global_store_dwordx2 v[2:3], v[4:5], off
	s_waitcnt lgkmcnt(0)
	s_and_b64 vcc, exec, s[48:49]
	s_mov_b64 s[48:49], 0
	s_cbranch_vccnz .LBB0_36
	s_barrier

.LBB0_40:
	v_or_b32_e32 v26, s7, v110
	v_mad_i64_i32 v[6:7], s[56:57], v26, s22, v[24:25]
	global_load_dwordx4 v[6:9], v[6:7], off
	v_cndmask_b32_e64 v5, 0, 1, s[48:49]
	v_cmp_ne_u32_e32 vcc, 1, v5
	v_ashrrev_i32_e32 v27, 31, v26
	v_or_b32_e32 v5, 4, v26
	v_or_b32_e32 v23, 8, v26
	v_or_b32_e32 v32, 12, v26
	v_or_b32_e32 v33, 16, v26
	v_or_b32_e32 v36, 20, v26
	v_or_b32_e32 v37, 24, v26
	v_or_b32_e32 v66, 28, v26
	v_or_b32_e32 v67, 32, v26
	v_or_b32_e32 v70, 36, v26
	v_or_b32_e32 v71, 40, v26
	v_or_b32_e32 v74, 44, v26
	v_or_b32_e32 v75, 48, v26
	v_or_b32_e32 v111, 52, v26
	v_or_b32_e32 v114, 56, v26
	v_or_b32_e32 v115, 60, v26
	v_mad_i64_i32 v[28:29], s[56:57], v5, s22, v[24:25]
	v_mad_i64_i32 v[30:31], s[56:57], v23, s22, v[24:25]
	v_mad_i64_i32 v[34:35], s[56:57], v32, s22, v[24:25]
	v_mad_i64_i32 v[64:65], s[56:57], v33, s22, v[24:25]
	v_mad_i64_i32 v[68:69], s[56:57], v36, s22, v[24:25]
	v_mad_i64_i32 v[72:73], s[56:57], v37, s22, v[24:25]
	v_mad_i64_i32 v[112:113], s[56:57], v66, s22, v[24:25]
	v_lshl_add_u64 v[148:149], v[26:27], 2, s[10:11]
	global_load_dword v166, v[148:149], off
	global_load_dword v168, v[148:149], off offset:16
	global_load_dword v170, v[148:149], off offset:32
	global_load_dword v172, v[148:149], off offset:48
	global_load_dword v174, v[148:149], off offset:64
	global_load_dword v176, v[148:149], off offset:80
	global_load_dword v178, v[148:149], off offset:96
	global_load_dword v180, v[148:149], off offset:112
	global_load_dword v182, v[148:149], off offset:128
	global_load_dword v184, v[148:149], off offset:144
	global_load_dword v186, v[148:149], off offset:160
	global_load_dword v188, v[148:149], off offset:176
	global_load_dword v190, v[148:149], off offset:192
	global_load_dword v192, v[148:149], off offset:208
	global_load_dword v194, v[148:149], off offset:224
	v_mad_i64_i32 v[116:117], s[56:57], v67, s22, v[24:25]
	v_mad_i64_i32 v[120:121], s[56:57], v70, s22, v[24:25]
	v_mad_i64_i32 v[124:125], s[56:57], v71, s22, v[24:25]
	v_mad_i64_i32 v[128:129], s[56:57], v74, s22, v[24:25]
	v_mad_i64_i32 v[132:133], s[56:57], v75, s22, v[24:25]
	v_mad_i64_i32 v[136:137], s[56:57], v111, s22, v[24:25]
	v_mad_i64_i32 v[140:141], s[56:57], v114, s22, v[24:25]
	v_mad_i64_i32 v[144:145], s[56:57], v115, s22, v[24:25]
	s_nop 0
	global_load_dwordx4 v[26:29], v[28:29], off
	s_nop 0
	s_nop 0
	global_load_dwordx4 v[30:33], v[30:31], off
	s_nop 0
	global_load_dwordx4 v[34:37], v[34:35], off
	s_nop 0
	s_nop 0
	global_load_dwordx4 v[64:67], v[64:65], off
	s_nop 0
	global_load_dwordx4 v[68:71], v[68:69], off
	s_nop 0
	s_nop 0
	global_load_dwordx4 v[72:75], v[72:73], off
	s_nop 0
	global_load_dwordx4 v[112:115], v[112:113], off
	s_nop 0
	s_nop 0
	global_load_dwordx4 v[116:119], v[116:117], off
	s_nop 0
	global_load_dwordx4 v[120:123], v[120:121], off
	s_nop 0
	s_nop 0
	global_load_dwordx4 v[124:127], v[124:125], off
	s_nop 0
	global_load_dwordx4 v[128:131], v[128:129], off
	s_nop 0
	s_nop 0
	global_load_dwordx4 v[132:135], v[132:133], off
	s_nop 0
	global_load_dwordx4 v[136:139], v[136:137], off
	s_nop 0
	s_nop 0
	global_load_dwordx4 v[140:143], v[140:141], off
	s_nop 0
	global_load_dwordx4 v[144:147], v[144:145], off
	s_nop 0
	global_load_dword v148, v[148:149], off offset:240
	s_mov_b32 s7, 64
	s_mov_b64 s[48:49], 0
	s_and_b64 vcc, exec, vcc
	s_waitcnt vmcnt(30)
	v_mul_f32_e32 v6, v6, v166
	v_mul_f32_e32 v7, v7, v166
	v_mul_f32_e32 v8, v8, v166
	v_mul_f32_e32 v5, v9, v166
	s_waitcnt vmcnt(15)
	v_mul_f32_e32 v9, v26, v168
	v_mul_f32_e32 v26, v27, v168
	v_mul_f32_e32 v27, v28, v168
	v_mul_f32_e32 v23, v29, v168
	s_waitcnt vmcnt(14)
	v_mul_f32_e32 v28, v30, v170
	v_mul_f32_e32 v29, v31, v170
	v_mul_f32_e32 v30, v32, v170
	v_mul_f32_e32 v31, v33, v170
	s_waitcnt vmcnt(13)
	v_mul_f32_e32 v32, v34, v172
	v_mul_f32_e32 v33, v35, v172
	v_mul_f32_e32 v34, v36, v172
	v_mul_f32_e32 v35, v37, v172
	v_max3_f32 v4, v4, |v6|, |v9|
	v_max3_f32 v3, v3, |v7|, |v26|
	v_max3_f32 v2, v2, |v8|, |v27|
	v_max3_f32 v0, v0, |v5|, |v23|
	s_waitcnt vmcnt(12)
	v_mul_f32_e32 v36, v64, v174
	v_mul_f32_e32 v37, v65, v174
	v_mul_f32_e32 v64, v66, v174
	v_mul_f32_e32 v65, v67, v174
	s_waitcnt vmcnt(11)
	v_mul_f32_e32 v66, v68, v176
	v_mul_f32_e32 v67, v69, v176
	v_mul_f32_e32 v68, v70, v176
	v_mul_f32_e32 v69, v71, v176
	v_max3_f32 v4, v4, |v28|, |v32|
	v_max3_f32 v3, v3, |v29|, |v33|
	v_max3_f32 v2, v2, |v30|, |v34|
	v_max3_f32 v0, v0, |v31|, |v35|
	s_waitcnt vmcnt(10)
	v_mul_f32_e32 v70, v72, v178
	v_mul_f32_e32 v71, v73, v178
	v_mul_f32_e32 v72, v74, v178
	v_mul_f32_e32 v73, v75, v178
	s_waitcnt vmcnt(9)
	v_mul_f32_e32 v74, v112, v180
	v_mul_f32_e32 v75, v113, v180
	v_mul_f32_e32 v111, v114, v180
	v_mul_f32_e32 v112, v115, v180
	v_max3_f32 v4, v4, |v36|, |v66|
	v_max3_f32 v3, v3, |v37|, |v67|
	v_max3_f32 v2, v2, |v64|, |v68|
	v_max3_f32 v0, v0, |v65|, |v69|
	s_waitcnt vmcnt(8)
	v_mul_f32_e32 v113, v116, v182
	v_mul_f32_e32 v114, v117, v182
	v_mul_f32_e32 v115, v118, v182
	v_mul_f32_e32 v116, v119, v182
	s_waitcnt vmcnt(7)
	v_mul_f32_e32 v117, v120, v184
	v_mul_f32_e32 v118, v121, v184
	v_mul_f32_e32 v119, v122, v184
	v_mul_f32_e32 v120, v123, v184
	v_max3_f32 v4, v4, |v70|, |v74|
	v_max3_f32 v3, v3, |v71|, |v75|
	v_max3_f32 v2, v2, |v72|, |v111|
	v_max3_f32 v0, v0, |v73|, |v112|
	s_waitcnt vmcnt(6)
	v_mul_f32_e32 v121, v124, v186
	v_mul_f32_e32 v122, v125, v186
	v_mul_f32_e32 v123, v126, v186
	v_mul_f32_e32 v124, v127, v186
	s_waitcnt vmcnt(5)
	v_mul_f32_e32 v125, v128, v188
	v_mul_f32_e32 v126, v129, v188
	v_mul_f32_e32 v127, v130, v188
	v_mul_f32_e32 v128, v131, v188
	v_max3_f32 v4, v4, |v113|, |v117|
	v_max3_f32 v3, v3, |v114|, |v118|
	v_max3_f32 v2, v2, |v115|, |v119|
	v_max3_f32 v0, v0, |v116|, |v120|
	s_waitcnt vmcnt(4)
	v_mul_f32_e32 v129, v132, v190
	v_mul_f32_e32 v130, v133, v190
	v_mul_f32_e32 v131, v134, v190
	v_mul_f32_e32 v132, v135, v190
	s_waitcnt vmcnt(3)
	v_mul_f32_e32 v133, v136, v192
	v_mul_f32_e32 v134, v137, v192
	v_mul_f32_e32 v135, v138, v192
	v_mul_f32_e32 v136, v139, v192
	v_max3_f32 v4, v4, |v121|, |v125|
	v_max3_f32 v3, v3, |v122|, |v126|
	v_max3_f32 v2, v2, |v123|, |v127|
	v_max3_f32 v0, v0, |v124|, |v128|
	s_waitcnt vmcnt(2)
	v_mul_f32_e32 v137, v140, v194
	v_mul_f32_e32 v138, v141, v194
	v_mul_f32_e32 v139, v142, v194
	v_mul_f32_e32 v140, v143, v194
	s_waitcnt vmcnt(0)
	v_mul_f32_e32 v141, v144, v148
	v_mul_f32_e32 v142, v145, v148
	v_mul_f32_e32 v143, v146, v148
	v_mul_f32_e32 v144, v147, v148
	v_max3_f32 v4, v4, |v129|, |v133|
	v_max3_f32 v3, v3, |v130|, |v134|
	v_max3_f32 v2, v2, |v131|, |v135|
	v_max3_f32 v0, v0, |v132|, |v136|
	v_max3_f32 v4, v4, |v137|, |v141|
	v_max3_f32 v3, v3, |v138|, |v142|
	v_max3_f32 v2, v2, |v139|, |v143|
	v_max3_f32 v0, v0, |v140|, |v144|
	s_cbranch_vccz .LBB0_40
	v_and_b32_e32 v6, 64, v88
	v_xor_b32_e32 v5, 16, v88
	v_add_u32_e32 v6, 64, v6
	v_cmp_lt_i32_e32 vcc, v5, v6
	s_nop 1
	v_cndmask_b32_e32 v5, v88, v5, vcc
	v_lshlrev_b32_e32 v7, 2, v5
	ds_bpermute_b32 v8, v7, v4
	v_xor_b32_e32 v5, 32, v88
	v_cmp_lt_i32_e32 vcc, v5, v6
	ds_bpermute_b32 v6, v7, v3
	ds_bpermute_b32 v23, v7, v0
	v_cndmask_b32_e32 v5, v88, v5, vcc
	v_lshlrev_b32_e32 v9, 2, v5
	s_waitcnt lgkmcnt(2)
	v_max_f32_e32 v5, v8, v8
	ds_bpermute_b32 v8, v7, v2
	v_max_f32_e32 v4, v4, v4
	s_waitcnt lgkmcnt(2)
	v_max_f32_e32 v6, v6, v6
	v_max_f32_e32 v3, v3, v3
	v_max_f32_e32 v2, v2, v2
	s_waitcnt lgkmcnt(0)
	v_max_f32_e32 v7, v8, v8
	v_max_f32_e32 v8, v23, v23
	v_max_f32_e32 v0, v0, v0
	v_max_f32_e32 v4, v4, v5
	v_max_f32_e32 v3, v3, v6
	v_max_f32_e32 v2, v2, v7
	v_max_f32_e32 v0, v0, v8
	ds_bpermute_b32 v5, v9, v4
	ds_bpermute_b32 v6, v9, v3
	ds_bpermute_b32 v7, v9, v2
	ds_bpermute_b32 v8, v9, v0
	s_and_saveexec_b64 s[48:49], s[2:3]
	s_cbranch_execz .LBB0_43
	s_waitcnt lgkmcnt(0)
	v_max_f32_e32 v8, v8, v8
	v_max_f32_e32 v0, v0, v0
	v_max_f32_e32 v9, v0, v8
	v_max_f32_e32 v0, v7, v7
	v_max_f32_e32 v2, v2, v2
	v_max_f32_e32 v8, v2, v0
	v_max_f32_e32 v0, v6, v6
	v_max_f32_e32 v2, v3, v3
	v_max_f32_e32 v7, v2, v0
	v_max_f32_e32 v0, v5, v5
	v_max_f32_e32 v2, v4, v4
	v_max_f32_e32 v6, v2, v0
	v_add_u32_e32 v0, s6, v60
	ds_write_b128 v0, v[6:9]

.LBB0_46:
	s_or_b32 vcc_lo, s7, s31
	v_or_b32_e32 v72, vcc_lo, v62
	v_mad_i64_i32 v[2:3], s[56:57], v72, s22, v[24:25]
	v_or_b32_e32 v0, 4, v72
	global_load_dwordx4 v[112:115], v[2:3], off nt
	v_mad_i64_i32 v[2:3], s[56:57], v0, s22, v[24:25]
	v_or_b32_e32 v0, 8, v72
	global_load_dwordx4 v[116:119], v[2:3], off nt
	v_mad_i64_i32 v[2:3], s[56:57], v0, s22, v[24:25]
	v_or_b32_e32 v0, 12, v72
	global_load_dwordx4 v[120:123], v[2:3], off nt
	v_mad_i64_i32 v[2:3], s[56:57], v0, s22, v[24:25]
	v_or_b32_e32 v0, 16, v72
	global_load_dwordx4 v[124:127], v[2:3], off nt
	v_mad_i64_i32 v[2:3], s[56:57], v0, s22, v[24:25]
	v_or_b32_e32 v0, 20, v72
	v_ashrrev_i32_e32 v73, 31, v72
	global_load_dwordx4 v[128:131], v[2:3], off nt
	v_mad_i64_i32 v[2:3], s[56:57], v0, s22, v[24:25]
	v_or_b32_e32 v0, 24, v72
	global_load_dwordx4 v[132:135], v[2:3], off nt
	v_mad_i64_i32 v[2:3], s[56:57], v0, s22, v[24:25]
	v_or_b32_e32 v0, 28, v72
	v_lshl_add_u64 v[74:75], v[72:73], 2, s[10:11]
	global_load_dwordx4 v[6:9], v[2:3], off nt
	v_mad_i64_i32 v[2:3], s[56:57], v0, s22, v[24:25]
	global_load_dword v0, v[74:75], off
	v_add_u32_e32 v23, v77, v78
	s_ashr_i32 vcc_hi, vcc_lo, 31
	v_add_u32_e32 v73, 0x410, v23
	global_load_dwordx4 v[2:5], v[2:3], off nt
	s_mov_b32 s7, 64
	s_waitcnt vmcnt(1)
	v_pk_mul_f32 v[74:75], v[26:27], v[0:1] op_sel_hi:[1,0]
	s_nop 0
	v_pk_mul_f32 v[74:75], v[112:113], v[74:75]
	ds_write2_b32 v23, v74, v75 offset1:1
	v_pk_mul_f32 v[74:75], v[28:29], v[0:1] op_sel_hi:[1,0]
	s_nop 0
	v_pk_mul_f32 v[74:75], v[114:115], v[74:75]
	ds_write2_b32 v23, v74, v75 offset0:2 offset1:3
	v_lshl_add_u64 v[74:75], vcc, 0, v[62:63]
	v_lshl_add_u64 v[74:75], v[74:75], 2, s[10:11]
	global_load_dword v140, v[74:75], off offset:32
	global_load_dword v142, v[74:75], off offset:48
	global_load_dword v144, v[74:75], off offset:64
	global_load_dword v146, v[74:75], off offset:80
	global_load_dword v148, v[74:75], off offset:96
	global_load_dword v150, v[74:75], off offset:112
	global_load_dword v152, v[74:75], off offset:128
	global_load_dword v154, v[74:75], off offset:144
	global_load_dword v156, v[74:75], off offset:160
	global_load_dword v158, v[74:75], off offset:176
	global_load_dword v160, v[74:75], off offset:192
	global_load_dword v162, v[74:75], off offset:208
	global_load_dword v164, v[74:75], off offset:224
	global_load_dword v166, v[74:75], off offset:240
	global_load_dword v0, v[74:75], off offset:16
	s_waitcnt vmcnt(0)
	v_pk_mul_f32 v[112:113], v[26:27], v[0:1] op_sel_hi:[1,0]
	s_nop 0
	v_pk_mul_f32 v[112:113], v[116:117], v[112:113]
	ds_write2_b32 v73, v112, v113 offset1:1
	v_pk_mul_f32 v[112:113], v[28:29], v[0:1] op_sel_hi:[1,0]
	v_add_u32_e32 v0, 0x418, v23
	v_pk_mul_f32 v[112:113], v[118:119], v[112:113]
	ds_write2_b32 v0, v112, v113 offset1:1
	v_add_u32_e32 v73, 0x820, v23
	v_pk_mul_f32 v[112:113], v[26:27], v[140:141] op_sel_hi:[1,0]
	s_nop 0
	v_pk_mul_f32 v[112:113], v[120:121], v[112:113]
	ds_write2_b32 v73, v112, v113 offset1:1
	v_pk_mul_f32 v[112:113], v[28:29], v[140:141] op_sel_hi:[1,0]
	v_add_u32_e32 v0, 0x828, v23
	v_pk_mul_f32 v[112:113], v[122:123], v[112:113]
	ds_write2_b32 v0, v112, v113 offset1:1
	v_add_u32_e32 v73, 0xc30, v23
	v_pk_mul_f32 v[112:113], v[26:27], v[142:143] op_sel_hi:[1,0]
	s_nop 0
	v_pk_mul_f32 v[112:113], v[124:125], v[112:113]
	ds_write2_b32 v73, v112, v113 offset1:1
	v_pk_mul_f32 v[112:113], v[28:29], v[142:143] op_sel_hi:[1,0]
	v_add_u32_e32 v0, 0xc38, v23
	v_pk_mul_f32 v[112:113], v[126:127], v[112:113]
	ds_write2_b32 v0, v112, v113 offset1:1
	v_add_u32_e32 v73, 0x1040, v23
	v_pk_mul_f32 v[112:113], v[26:27], v[144:145] op_sel_hi:[1,0]
	s_nop 0
	v_pk_mul_f32 v[112:113], v[128:129], v[112:113]
	ds_write2_b32 v73, v112, v113 offset1:1
	v_pk_mul_f32 v[112:113], v[28:29], v[144:145] op_sel_hi:[1,0]
	v_add_u32_e32 v0, 0x1048, v23
	v_pk_mul_f32 v[112:113], v[130:131], v[112:113]
	ds_write2_b32 v0, v112, v113 offset1:1
	v_add_u32_e32 v23, 0x1450, v23
	v_pk_mul_f32 v[112:113], v[26:27], v[146:147] op_sel_hi:[1,0]
	s_nop 0
	v_pk_mul_f32 v[112:113], v[132:133], v[112:113]
	ds_write2_b32 v23, v112, v113 offset1:1
	v_pk_mul_f32 v[112:113], v[28:29], v[146:147] op_sel_hi:[1,0]
	v_pk_mul_f32 v[112:113], v[134:135], v[112:113]
	v_add_u32_e32 v23, v77, v79
	ds_write2_b32 v23, v112, v113 offset0:2 offset1:3
	v_add_u32_e32 v73, 0x410, v23
	v_pk_mul_f32 v[112:113], v[26:27], v[148:149] op_sel_hi:[1,0]
	s_nop 0
	v_pk_mul_f32 v[6:7], v[6:7], v[112:113]
	ds_write2_b32 v73, v6, v7 offset1:1
	v_pk_mul_f32 v[6:7], v[28:29], v[148:149] op_sel_hi:[1,0]
	v_add_u32_e32 v0, 0x418, v23
	v_pk_mul_f32 v[6:7], v[8:9], v[6:7]
	ds_write2_b32 v0, v6, v7 offset1:1
	v_pk_mul_f32 v[6:7], v[26:27], v[150:151] op_sel_hi:[1,0]
	s_nop 0
	v_pk_mul_f32 v[2:3], v[2:3], v[6:7]
	v_add_u32_e32 v6, 0x820, v23
	ds_write2_b32 v6, v2, v3 offset1:1
	v_pk_mul_f32 v[2:3], v[28:29], v[150:151] op_sel_hi:[1,0]
	v_add_u32_e32 v0, 0x828, v23
	v_pk_mul_f32 v[2:3], v[4:5], v[2:3]
	ds_write2_b32 v0, v2, v3 offset1:1
	v_or_b32_e32 v0, 32, v72
	v_mad_i64_i32 v[2:3], s[56:57], v0, s22, v[24:25]
	v_or_b32_e32 v0, 36, v72
	v_mad_i64_i32 v[6:7], s[56:57], v0, s22, v[24:25]
	v_or_b32_e32 v0, 40, v72
	v_mad_i64_i32 v[112:113], s[56:57], v0, s22, v[24:25]
	v_or_b32_e32 v0, 44, v72
	v_mad_i64_i32 v[116:117], s[56:57], v0, s22, v[24:25]
	v_or_b32_e32 v0, 48, v72
	v_mad_i64_i32 v[120:121], s[56:57], v0, s22, v[24:25]
	v_or_b32_e32 v0, 52, v72
	v_mad_i64_i32 v[124:125], s[56:57], v0, s22, v[24:25]
	v_or_b32_e32 v0, 56, v72
	v_mad_i64_i32 v[128:129], s[56:57], v0, s22, v[24:25]
	v_or_b32_e32 v0, 60, v72
	v_mad_i64_i32 v[72:73], s[56:57], v0, s22, v[24:25]
	global_load_dwordx4 v[2:5], v[2:3], off nt
	s_nop 0
	global_load_dwordx4 v[6:9], v[6:7], off nt
	s_nop 0
	global_load_dwordx4 v[112:115], v[112:113], off nt
	s_nop 0
	global_load_dwordx4 v[116:119], v[116:117], off nt
	s_nop 0
	global_load_dwordx4 v[120:123], v[120:121], off nt
	s_nop 0
	global_load_dwordx4 v[124:127], v[124:125], off nt
	s_nop 0
	global_load_dwordx4 v[128:131], v[128:129], off nt
	s_nop 0
	global_load_dwordx4 v[132:135], v[72:73], off nt
	v_pk_mul_f32 v[72:73], v[26:27], v[152:153] op_sel_hi:[1,0]
	s_nop 0
	s_waitcnt vmcnt(7)
	v_pk_mul_f32 v[2:3], v[2:3], v[72:73]
	v_add_u32_e32 v72, 0xc30, v23
	ds_write2_b32 v72, v2, v3 offset1:1
	v_pk_mul_f32 v[2:3], v[28:29], v[152:153] op_sel_hi:[1,0]
	v_add_u32_e32 v0, 0xc38, v23
	v_pk_mul_f32 v[2:3], v[4:5], v[2:3]
	ds_write2_b32 v0, v2, v3 offset1:1
	v_add_u32_e32 v4, 0x1040, v23
	v_pk_mul_f32 v[2:3], v[26:27], v[154:155] op_sel_hi:[1,0]
	s_nop 0
	s_waitcnt vmcnt(6)
	v_pk_mul_f32 v[2:3], v[6:7], v[2:3]
	ds_write2_b32 v4, v2, v3 offset1:1
	v_pk_mul_f32 v[2:3], v[28:29], v[154:155] op_sel_hi:[1,0]
	v_add_u32_e32 v0, 0x1048, v23
	v_pk_mul_f32 v[2:3], v[8:9], v[2:3]
	ds_write2_b32 v0, v2, v3 offset1:1
	v_add_u32_e32 v4, 0x1450, v23
	v_pk_mul_f32 v[2:3], v[26:27], v[156:157] op_sel_hi:[1,0]
	s_nop 0
	s_waitcnt vmcnt(5)
	v_pk_mul_f32 v[2:3], v[112:113], v[2:3]
	ds_write2_b32 v4, v2, v3 offset1:1
	v_pk_mul_f32 v[2:3], v[28:29], v[156:157] op_sel_hi:[1,0]
	v_add_u32_e32 v0, 0x1458, v23
	v_pk_mul_f32 v[2:3], v[114:115], v[2:3]
	ds_write2_b32 v0, v2, v3 offset1:1
	v_add_u32_e32 v4, 0x1860, v23
	v_pk_mul_f32 v[2:3], v[26:27], v[158:159] op_sel_hi:[1,0]
	s_nop 0
	s_waitcnt vmcnt(4)
	v_pk_mul_f32 v[2:3], v[116:117], v[2:3]
	ds_write2_b32 v4, v2, v3 offset1:1
	v_pk_mul_f32 v[2:3], v[28:29], v[158:159] op_sel_hi:[1,0]
	v_add_u32_e32 v0, 0x1868, v23
	v_pk_mul_f32 v[2:3], v[118:119], v[2:3]
	ds_write2_b32 v0, v2, v3 offset1:1
	v_add_u32_e32 v4, 0x1c70, v23
	v_pk_mul_f32 v[2:3], v[26:27], v[160:161] op_sel_hi:[1,0]
	s_nop 0
	s_waitcnt vmcnt(3)
	v_pk_mul_f32 v[2:3], v[120:121], v[2:3]
	ds_write2_b32 v4, v2, v3 offset1:1
	v_pk_mul_f32 v[2:3], v[28:29], v[160:161] op_sel_hi:[1,0]
	v_add_u32_e32 v0, 0x1c78, v23
	v_pk_mul_f32 v[2:3], v[122:123], v[2:3]
	ds_write2_b32 v0, v2, v3 offset1:1
	v_add_u32_e32 v4, 0x2080, v23
	v_pk_mul_f32 v[2:3], v[26:27], v[162:163] op_sel_hi:[1,0]
	s_nop 0
	s_waitcnt vmcnt(2)
	v_pk_mul_f32 v[2:3], v[124:125], v[2:3]
	ds_write2_b32 v4, v2, v3 offset1:1
	v_pk_mul_f32 v[2:3], v[28:29], v[162:163] op_sel_hi:[1,0]
	v_add_u32_e32 v0, 0x2088, v23
	v_pk_mul_f32 v[2:3], v[126:127], v[2:3]
	ds_write2_b32 v0, v2, v3 offset1:1
	v_add_u32_e32 v4, 0x2490, v23
	v_pk_mul_f32 v[2:3], v[26:27], v[164:165] op_sel_hi:[1,0]
	s_nop 0
	s_waitcnt vmcnt(1)
	v_pk_mul_f32 v[2:3], v[128:129], v[2:3]
	ds_write2_b32 v4, v2, v3 offset1:1
	v_pk_mul_f32 v[2:3], v[28:29], v[164:165] op_sel_hi:[1,0]
	v_add_u32_e32 v0, 0x2498, v23
	v_pk_mul_f32 v[2:3], v[130:131], v[2:3]
	ds_write2_b32 v0, v2, v3 offset1:1
	v_add_u32_e32 v4, 0x28a0, v23
	v_pk_mul_f32 v[2:3], v[26:27], v[166:167] op_sel_hi:[1,0]
	s_nop 0
	s_waitcnt vmcnt(0)
	v_pk_mul_f32 v[2:3], v[132:133], v[2:3]
	ds_write2_b32 v4, v2, v3 offset1:1
	v_pk_mul_f32 v[2:3], v[28:29], v[166:167] op_sel_hi:[1,0]
	v_add_u32_e32 v0, 0x28a8, v23
	v_pk_mul_f32 v[2:3], v[134:135], v[2:3]
	ds_write2_b32 v0, v2, v3 offset1:1
	s_waitcnt lgkmcnt(0)
	ds_read2_b32 v[4:5], v13 offset1:8
	ds_read2_b32 v[6:7], v13 offset0:65 offset1:73
	ds_read2_b32 v[8:9], v13 offset0:130 offset1:138
	ds_read2_b32 v[72:73], v13 offset0:195 offset1:203
	v_lshl_add_u64 v[2:3], v[16:17], 0, vcc
	s_waitcnt lgkmcnt(3)
	v_med3_f32 v0, v4, s61, v89
	s_waitcnt lgkmcnt(2)
	v_med3_f32 v4, v6, s61, v89
	s_waitcnt lgkmcnt(1)
	v_med3_f32 v6, v8, s61, v89
	s_waitcnt lgkmcnt(0)
	v_med3_f32 v8, v72, s61, v89
	v_add_f32_e32 v0, 0x4b400000, v0
	v_add_f32_e32 v4, 0x4b400000, v4
	v_add_f32_e32 v6, 0x4b400000, v6
	v_add_f32_e32 v8, 0x4b400000, v8
	v_perm_b32 v6, v8, v6, s0
	v_perm_b32 v0, v4, v0, s0
	v_perm_b32 v74, v6, v0, s1
	v_add_u32_e32 v0, 0x400, v13
	ds_read2_b32 v[112:113], v0 offset0:4 offset1:12
	ds_read2_b32 v[114:115], v0 offset0:69 offset1:77
	ds_read2_b32 v[116:117], v0 offset0:134 offset1:142
	ds_read2_b32 v[118:119], v0 offset0:199 offset1:207
	v_lshl_add_u64 v[120:121], v[2:3], 0, v[30:31]
	s_waitcnt lgkmcnt(3)
	v_med3_f32 v4, v112, s61, v89
	s_waitcnt lgkmcnt(2)
	v_med3_f32 v6, v114, s61, v89
	s_waitcnt lgkmcnt(1)
	v_med3_f32 v8, v116, s61, v89
	s_waitcnt lgkmcnt(0)
	v_med3_f32 v23, v118, s61, v89
	v_add_f32_e32 v4, 0x4b400000, v4
	v_add_f32_e32 v6, 0x4b400000, v6
	v_add_f32_e32 v8, 0x4b400000, v8
	v_add_f32_e32 v23, 0x4b400000, v23
	v_perm_b32 v8, v23, v8, s0
	v_perm_b32 v4, v6, v4, s0
	v_perm_b32 v75, v8, v4, s1
	v_med3_f32 v4, v5, s61, v89
	v_med3_f32 v5, v7, s61, v89
	v_med3_f32 v6, v9, s61, v89
	v_med3_f32 v7, v73, s61, v89
	v_add_f32_e32 v4, 0x4b400000, v4
	v_add_f32_e32 v5, 0x4b400000, v5
	v_add_f32_e32 v6, 0x4b400000, v6
	v_add_f32_e32 v7, 0x4b400000, v7
	v_perm_b32 v6, v7, v6, s0
	v_perm_b32 v4, v5, v4, s0
	v_perm_b32 v4, v6, v4, s1
	v_med3_f32 v5, v113, s61, v89
	v_med3_f32 v6, v115, s61, v89
	v_med3_f32 v7, v117, s61, v89
	v_med3_f32 v8, v119, s61, v89
	v_add_f32_e32 v5, 0x4b400000, v5
	v_add_f32_e32 v6, 0x4b400000, v6
	v_add_f32_e32 v7, 0x4b400000, v7
	v_add_f32_e32 v8, 0x4b400000, v8
	v_perm_b32 v7, v8, v7, s0
	v_perm_b32 v5, v6, v5, s0
	v_perm_b32 v5, v7, v5, s1
	v_lshl_add_u64 v[6:7], v[2:3], 0, v[32:33]
	global_store_dwordx2 v[6:7], v[4:5], off
	ds_read2_b32 v[4:5], v13 offset0:16 offset1:24
	ds_read2_b32 v[6:7], v13 offset0:81 offset1:89
	ds_read2_b32 v[8:9], v13 offset0:146 offset1:154
	ds_read2_b32 v[72:73], v13 offset0:211 offset1:219
	ds_read2_b32 v[112:113], v0 offset0:20 offset1:28
	ds_read2_b32 v[114:115], v0 offset0:85 offset1:93
	ds_read2_b32 v[116:117], v0 offset0:150 offset1:158
	ds_read2_b32 v[118:119], v0 offset0:215 offset1:223
	s_waitcnt lgkmcnt(7)
	v_med3_f32 v4, v4, s61, v89
	s_waitcnt lgkmcnt(6)
	v_med3_f32 v6, v6, s61, v89
	s_waitcnt lgkmcnt(5)
	v_med3_f32 v8, v8, s61, v89
	s_waitcnt lgkmcnt(4)
	v_med3_f32 v23, v72, s61, v89
	v_add_f32_e32 v4, 0x4b400000, v4
	v_add_f32_e32 v6, 0x4b400000, v6
	v_add_f32_e32 v8, 0x4b400000, v8
	v_add_f32_e32 v23, 0x4b400000, v23
	v_perm_b32 v8, v23, v8, s0
	v_perm_b32 v4, v6, v4, s0
	global_store_dwordx2 v[120:121], v[74:75], off
	v_perm_b32 v74, v8, v4, s1
	s_waitcnt lgkmcnt(3)
	v_med3_f32 v4, v112, s61, v89
	s_waitcnt lgkmcnt(2)
	v_med3_f32 v6, v114, s61, v89
	s_waitcnt lgkmcnt(1)
	v_med3_f32 v8, v116, s61, v89
	s_waitcnt lgkmcnt(0)
	v_med3_f32 v23, v118, s61, v89
	v_add_f32_e32 v4, 0x4b400000, v4
	v_add_f32_e32 v6, 0x4b400000, v6
	v_add_f32_e32 v8, 0x4b400000, v8
	v_add_f32_e32 v23, 0x4b400000, v23
	v_perm_b32 v8, v23, v8, s0
	v_perm_b32 v4, v6, v4, s0
	v_perm_b32 v75, v8, v4, s1
	v_med3_f32 v4, v5, s61, v89
	v_med3_f32 v5, v7, s61, v89
	v_med3_f32 v6, v9, s61, v89
	v_med3_f32 v7, v73, s61, v89
	v_add_f32_e32 v4, 0x4b400000, v4
	v_add_f32_e32 v5, 0x4b400000, v5
	v_add_f32_e32 v6, 0x4b400000, v6
	v_add_f32_e32 v7, 0x4b400000, v7
	v_perm_b32 v6, v7, v6, s0
	v_perm_b32 v4, v5, v4, s0
	v_perm_b32 v4, v6, v4, s1
	v_med3_f32 v5, v113, s61, v89
	v_med3_f32 v6, v115, s61, v89
	v_med3_f32 v7, v117, s61, v89
	v_med3_f32 v8, v119, s61, v89
	v_add_f32_e32 v5, 0x4b400000, v5
	v_add_f32_e32 v6, 0x4b400000, v6
	v_add_f32_e32 v7, 0x4b400000, v7
	v_add_f32_e32 v8, 0x4b400000, v8
	v_perm_b32 v7, v8, v7, s0
	v_perm_b32 v5, v6, v5, s0
	v_perm_b32 v5, v7, v5, s1
	v_lshl_add_u64 v[6:7], v[2:3], 0, v[36:37]
	global_store_dwordx2 v[6:7], v[4:5], off
	ds_read2_b32 v[4:5], v13 offset0:32 offset1:40
	ds_read2_b32 v[6:7], v13 offset0:97 offset1:105
	ds_read2_b32 v[8:9], v13 offset0:162 offset1:170
	ds_read2_b32 v[72:73], v13 offset0:227 offset1:235
	ds_read2_b32 v[112:113], v0 offset0:36 offset1:44
	ds_read2_b32 v[114:115], v0 offset0:101 offset1:109
	ds_read2_b32 v[116:117], v0 offset0:166 offset1:174
	ds_read2_b32 v[118:119], v0 offset0:231 offset1:239
	s_waitcnt lgkmcnt(7)
	v_med3_f32 v4, v4, s61, v89
	s_waitcnt lgkmcnt(6)
	v_med3_f32 v6, v6, s61, v89
	s_waitcnt lgkmcnt(5)
	v_med3_f32 v8, v8, s61, v89
	s_waitcnt lgkmcnt(4)
	v_med3_f32 v23, v72, s61, v89
	v_add_f32_e32 v4, 0x4b400000, v4
	v_add_f32_e32 v6, 0x4b400000, v6
	v_add_f32_e32 v8, 0x4b400000, v8
	v_add_f32_e32 v23, 0x4b400000, v23
	v_lshl_add_u64 v[120:121], v[2:3], 0, v[34:35]
	v_perm_b32 v8, v23, v8, s0
	v_perm_b32 v4, v6, v4, s0
	global_store_dwordx2 v[120:121], v[74:75], off
	v_perm_b32 v74, v8, v4, s1
	s_waitcnt lgkmcnt(3)
	v_med3_f32 v4, v112, s61, v89
	s_waitcnt lgkmcnt(2)
	v_med3_f32 v6, v114, s61, v89
	s_waitcnt lgkmcnt(1)
	v_med3_f32 v8, v116, s61, v89
	s_waitcnt lgkmcnt(0)
	v_med3_f32 v23, v118, s61, v89
	v_add_f32_e32 v4, 0x4b400000, v4
	v_add_f32_e32 v6, 0x4b400000, v6
	v_add_f32_e32 v8, 0x4b400000, v8
	v_add_f32_e32 v23, 0x4b400000, v23
	v_perm_b32 v8, v23, v8, s0
	v_perm_b32 v4, v6, v4, s0
	v_perm_b32 v75, v8, v4, s1
	v_med3_f32 v4, v5, s61, v89
	v_med3_f32 v5, v7, s61, v89
	v_med3_f32 v6, v9, s61, v89
	v_med3_f32 v7, v73, s61, v89
	v_add_f32_e32 v4, 0x4b400000, v4
	v_add_f32_e32 v5, 0x4b400000, v5
	v_add_f32_e32 v6, 0x4b400000, v6
	v_add_f32_e32 v7, 0x4b400000, v7
	v_perm_b32 v6, v7, v6, s0
	v_perm_b32 v4, v5, v4, s0
	v_perm_b32 v4, v6, v4, s1
	v_med3_f32 v5, v113, s61, v89
	v_med3_f32 v6, v115, s61, v89
	v_med3_f32 v7, v117, s61, v89
	v_med3_f32 v8, v119, s61, v89
	v_add_f32_e32 v5, 0x4b400000, v5
	v_add_f32_e32 v6, 0x4b400000, v6
	v_add_f32_e32 v7, 0x4b400000, v7
	v_add_f32_e32 v8, 0x4b400000, v8
	v_perm_b32 v7, v8, v7, s0
	v_perm_b32 v5, v6, v5, s0
	v_perm_b32 v5, v7, v5, s1
	v_lshl_add_u64 v[6:7], v[2:3], 0, v[66:67]
	global_store_dwordx2 v[6:7], v[4:5], off
	ds_read2_b32 v[4:5], v13 offset0:48 offset1:56
	ds_read2_b32 v[6:7], v13 offset0:113 offset1:121
	ds_read2_b32 v[8:9], v13 offset0:178 offset1:186
	ds_read2_b32 v[72:73], v13 offset0:243 offset1:251
	ds_read2_b32 v[112:113], v0 offset0:52 offset1:60
	ds_read2_b32 v[114:115], v0 offset0:117 offset1:125
	ds_read2_b32 v[116:117], v0 offset0:182 offset1:190
	ds_read2_b32 v[118:119], v0 offset0:247 offset1:255
	s_waitcnt lgkmcnt(7)
	v_med3_f32 v4, v4, s61, v89
	s_waitcnt lgkmcnt(6)
	v_med3_f32 v6, v6, s61, v89
	s_waitcnt lgkmcnt(5)
	v_med3_f32 v8, v8, s61, v89
	s_waitcnt lgkmcnt(4)
	v_med3_f32 v23, v72, s61, v89
	v_add_f32_e32 v4, 0x4b400000, v4
	v_add_f32_e32 v6, 0x4b400000, v6
	v_add_f32_e32 v8, 0x4b400000, v8
	v_add_f32_e32 v23, 0x4b400000, v23
	v_lshl_add_u64 v[120:121], v[2:3], 0, v[64:65]
	v_perm_b32 v8, v23, v8, s0
	v_perm_b32 v4, v6, v4, s0
	global_store_dwordx2 v[120:121], v[74:75], off
	v_perm_b32 v74, v8, v4, s1
	s_waitcnt lgkmcnt(3)
	v_med3_f32 v4, v112, s61, v89
	s_waitcnt lgkmcnt(2)
	v_med3_f32 v6, v114, s61, v89
	s_waitcnt lgkmcnt(1)
	v_med3_f32 v8, v116, s61, v89
	s_waitcnt lgkmcnt(0)
	v_med3_f32 v0, v118, s61, v89
	v_add_f32_e32 v4, 0x4b400000, v4
	v_add_f32_e32 v6, 0x4b400000, v6
	v_add_f32_e32 v8, 0x4b400000, v8
	v_add_f32_e32 v0, 0x4b400000, v0
	v_perm_b32 v0, v0, v8, s0
	v_perm_b32 v4, v6, v4, s0
	v_perm_b32 v75, v0, v4, s1
	v_med3_f32 v0, v5, s61, v89
	v_med3_f32 v4, v7, s61, v89
	v_med3_f32 v5, v9, s61, v89
	v_med3_f32 v6, v73, s61, v89
	v_add_f32_e32 v0, 0x4b400000, v0
	v_add_f32_e32 v4, 0x4b400000, v4
	v_add_f32_e32 v5, 0x4b400000, v5
	v_add_f32_e32 v6, 0x4b400000, v6
	v_perm_b32 v5, v6, v5, s0
	v_perm_b32 v0, v4, v0, s0
	v_perm_b32 v4, v5, v0, s1
	v_med3_f32 v0, v113, s61, v89
	v_med3_f32 v5, v115, s61, v89
	v_med3_f32 v6, v117, s61, v89
	v_med3_f32 v7, v119, s61, v89
	v_add_f32_e32 v0, 0x4b400000, v0
	v_add_f32_e32 v5, 0x4b400000, v5
	v_add_f32_e32 v6, 0x4b400000, v6
	v_add_f32_e32 v7, 0x4b400000, v7
	v_perm_b32 v6, v7, v6, s0
	v_perm_b32 v0, v5, v0, s0
	v_lshl_add_u64 v[120:121], v[2:3], 0, v[68:69]
	v_perm_b32 v5, v6, v0, s1
	v_lshl_add_u64 v[2:3], v[2:3], 0, v[70:71]
	global_store_dwordx2 v[120:121], v[74:75], off
	global_store_dwordx2 v[2:3], v[4:5], off
	s_waitcnt lgkmcnt(0)
	s_and_b64 vcc, exec, s[48:49]
	s_mov_b64 s[48:49], 0
	s_cbranch_vccnz .LBB0_46
	s_barrier

.LBB0_64:
	v_or_b32_e32 v2, s9, v110
	v_mad_i64_i32 v[8:9], s[56:57], v2, s22, v[24:25]
	global_load_dwordx4 v[26:29], v[8:9], off
	v_cndmask_b32_e64 v3, 0, 1, s[48:49]
	v_cmp_ne_u32_e32 vcc, 1, v3
	v_ashrrev_i32_e32 v3, 31, v2
	v_or_b32_e32 v7, 4, v2
	v_or_b32_e32 v23, 8, v2
	v_or_b32_e32 v30, 12, v2
	v_or_b32_e32 v31, 16, v2
	v_or_b32_e32 v32, 20, v2
	v_or_b32_e32 v33, 24, v2
	v_or_b32_e32 v36, 28, v2
	v_or_b32_e32 v37, 32, v2
	v_or_b32_e32 v66, 36, v2
	v_or_b32_e32 v67, 40, v2
	v_or_b32_e32 v70, 44, v2
	v_or_b32_e32 v71, 48, v2
	v_or_b32_e32 v74, 52, v2
	v_or_b32_e32 v75, 56, v2
	v_or_b32_e32 v111, 60, v2
	v_mad_i64_i32 v[8:9], s[56:57], v7, s22, v[24:25]
	v_mad_i64_i32 v[34:35], s[56:57], v23, s22, v[24:25]
	v_mad_i64_i32 v[64:65], s[56:57], v30, s22, v[24:25]
	v_mad_i64_i32 v[68:69], s[56:57], v31, s22, v[24:25]
	v_mad_i64_i32 v[72:73], s[56:57], v32, s22, v[24:25]
	v_mad_i64_i32 v[112:113], s[56:57], v33, s22, v[24:25]
	v_mad_i64_i32 v[116:117], s[56:57], v36, s22, v[24:25]
	v_lshl_add_u64 v[2:3], v[2:3], 2, s[10:11]
	global_load_dword v166, v[2:3], off
	global_load_dword v168, v[2:3], off offset:16
	global_load_dword v170, v[2:3], off offset:32
	global_load_dword v172, v[2:3], off offset:48
	global_load_dword v174, v[2:3], off offset:64
	global_load_dword v176, v[2:3], off offset:80
	global_load_dword v178, v[2:3], off offset:96
	global_load_dword v180, v[2:3], off offset:112
	global_load_dword v182, v[2:3], off offset:128
	global_load_dword v184, v[2:3], off offset:144
	global_load_dword v186, v[2:3], off offset:160
	global_load_dword v188, v[2:3], off offset:176
	global_load_dword v190, v[2:3], off offset:192
	global_load_dword v192, v[2:3], off offset:208
	global_load_dword v194, v[2:3], off offset:224
	v_mad_i64_i32 v[120:121], s[56:57], v37, s22, v[24:25]
	v_mad_i64_i32 v[124:125], s[56:57], v66, s22, v[24:25]
	v_mad_i64_i32 v[128:129], s[56:57], v67, s22, v[24:25]
	v_mad_i64_i32 v[132:133], s[56:57], v70, s22, v[24:25]
	v_mad_i64_i32 v[136:137], s[56:57], v71, s22, v[24:25]
	v_mad_i64_i32 v[140:141], s[56:57], v74, s22, v[24:25]
	v_mad_i64_i32 v[144:145], s[56:57], v75, s22, v[24:25]
	v_mad_i64_i32 v[148:149], s[56:57], v111, s22, v[24:25]
	global_load_dwordx4 v[30:33], v[8:9], off
	s_nop 0
	s_nop 0
	global_load_dwordx4 v[34:37], v[34:35], off
	s_nop 0
	global_load_dwordx4 v[64:67], v[64:65], off
	s_nop 0
	s_nop 0
	global_load_dwordx4 v[68:71], v[68:69], off
	s_nop 0
	global_load_dwordx4 v[72:75], v[72:73], off
	s_nop 0
	s_nop 0
	global_load_dwordx4 v[112:115], v[112:113], off
	s_nop 0
	global_load_dwordx4 v[116:119], v[116:117], off
	s_nop 0
	s_nop 0
	global_load_dwordx4 v[120:123], v[120:121], off
	s_nop 0
	global_load_dwordx4 v[124:127], v[124:125], off
	s_nop 0
	s_nop 0
	global_load_dwordx4 v[128:131], v[128:129], off
	s_nop 0
	global_load_dwordx4 v[132:135], v[132:133], off
	s_nop 0
	s_nop 0
	global_load_dwordx4 v[136:139], v[136:137], off
	s_nop 0
	global_load_dwordx4 v[140:143], v[140:141], off
	s_nop 0
	s_nop 0
	global_load_dwordx4 v[144:147], v[144:145], off
	s_nop 0
	global_load_dwordx4 v[148:151], v[148:149], off
	s_nop 0
	global_load_dword v2, v[2:3], off offset:240
	s_mov_b32 s9, 64
	s_mov_b64 s[48:49], 0
	s_and_b64 vcc, exec, vcc
	s_waitcnt vmcnt(30)
	v_mul_f32_e32 v3, v26, v166
	v_mul_f32_e32 v26, v27, v166
	v_mul_f32_e32 v27, v28, v166
	v_mul_f32_e32 v7, v29, v166
	s_waitcnt vmcnt(15)
	v_mul_f32_e32 v28, v30, v168
	v_mul_f32_e32 v29, v31, v168
	v_mul_f32_e32 v30, v32, v168
	v_mul_f32_e32 v8, v33, v168
	s_waitcnt vmcnt(14)
	v_mul_f32_e32 v31, v34, v170
	v_mul_f32_e32 v32, v35, v170
	v_mul_f32_e32 v33, v36, v170
	v_mul_f32_e32 v9, v37, v170
	s_waitcnt vmcnt(13)
	v_mul_f32_e32 v34, v64, v172
	v_mul_f32_e32 v35, v65, v172
	v_mul_f32_e32 v36, v66, v172
	v_mul_f32_e32 v23, v67, v172
	v_max3_f32 v3, v6, |v3|, |v28|
	v_max3_f32 v5, v5, |v26|, |v29|
	v_max3_f32 v4, v4, |v27|, |v30|
	v_max3_f32 v0, v0, |v7|, |v8|
	s_waitcnt vmcnt(12)
	v_mul_f32_e32 v37, v68, v174
	v_mul_f32_e32 v64, v69, v174
	v_mul_f32_e32 v65, v70, v174
	v_mul_f32_e32 v66, v71, v174
	s_waitcnt vmcnt(11)
	v_mul_f32_e32 v67, v72, v176
	v_mul_f32_e32 v68, v73, v176
	v_mul_f32_e32 v69, v74, v176
	v_mul_f32_e32 v70, v75, v176
	v_max3_f32 v3, v3, |v31|, |v34|
	v_max3_f32 v5, v5, |v32|, |v35|
	v_max3_f32 v4, v4, |v33|, |v36|
	v_max3_f32 v0, v0, |v9|, |v23|
	s_waitcnt vmcnt(10)
	v_mul_f32_e32 v71, v112, v178
	v_mul_f32_e32 v72, v113, v178
	v_mul_f32_e32 v73, v114, v178
	v_mul_f32_e32 v74, v115, v178
	s_waitcnt vmcnt(9)
	v_mul_f32_e32 v75, v116, v180
	v_mul_f32_e32 v111, v117, v180
	v_mul_f32_e32 v112, v118, v180
	v_mul_f32_e32 v113, v119, v180
	v_max3_f32 v3, v3, |v37|, |v67|
	v_max3_f32 v5, v5, |v64|, |v68|
	v_max3_f32 v4, v4, |v65|, |v69|
	v_max3_f32 v0, v0, |v66|, |v70|
	s_waitcnt vmcnt(8)
	v_mul_f32_e32 v114, v120, v182
	v_mul_f32_e32 v115, v121, v182
	v_mul_f32_e32 v116, v122, v182
	v_mul_f32_e32 v117, v123, v182
	s_waitcnt vmcnt(7)
	v_mul_f32_e32 v118, v124, v184
	v_mul_f32_e32 v119, v125, v184
	v_mul_f32_e32 v120, v126, v184
	v_mul_f32_e32 v121, v127, v184
	v_max3_f32 v3, v3, |v71|, |v75|
	v_max3_f32 v5, v5, |v72|, |v111|
	v_max3_f32 v4, v4, |v73|, |v112|
	v_max3_f32 v0, v0, |v74|, |v113|
	s_waitcnt vmcnt(6)
	v_mul_f32_e32 v122, v128, v186
	v_mul_f32_e32 v123, v129, v186
	v_mul_f32_e32 v124, v130, v186
	v_mul_f32_e32 v125, v131, v186
	s_waitcnt vmcnt(5)
	v_mul_f32_e32 v126, v132, v188
	v_mul_f32_e32 v127, v133, v188
	v_mul_f32_e32 v128, v134, v188
	v_mul_f32_e32 v129, v135, v188
	v_max3_f32 v3, v3, |v114|, |v118|
	v_max3_f32 v5, v5, |v115|, |v119|
	v_max3_f32 v4, v4, |v116|, |v120|
	v_max3_f32 v0, v0, |v117|, |v121|
	s_waitcnt vmcnt(4)
	v_mul_f32_e32 v130, v136, v190
	v_mul_f32_e32 v131, v137, v190
	v_mul_f32_e32 v132, v138, v190
	v_mul_f32_e32 v133, v139, v190
	s_waitcnt vmcnt(3)
	v_mul_f32_e32 v134, v140, v192
	v_mul_f32_e32 v135, v141, v192
	v_mul_f32_e32 v136, v142, v192
	v_mul_f32_e32 v137, v143, v192
	v_max3_f32 v3, v3, |v122|, |v126|
	v_max3_f32 v5, v5, |v123|, |v127|
	v_max3_f32 v4, v4, |v124|, |v128|
	v_max3_f32 v0, v0, |v125|, |v129|
	s_waitcnt vmcnt(2)
	v_mul_f32_e32 v138, v144, v194
	v_mul_f32_e32 v139, v145, v194
	v_mul_f32_e32 v140, v146, v194
	v_mul_f32_e32 v141, v147, v194
	s_waitcnt vmcnt(0)
	v_mul_f32_e32 v142, v148, v2
	v_mul_f32_e32 v143, v149, v2
	v_mul_f32_e32 v144, v150, v2
	v_mul_f32_e32 v2, v151, v2
	v_max3_f32 v3, v3, |v130|, |v134|
	v_max3_f32 v5, v5, |v131|, |v135|
	v_max3_f32 v4, v4, |v132|, |v136|
	v_max3_f32 v0, v0, |v133|, |v137|
	v_max3_f32 v6, v3, |v138|, |v142|
	v_max3_f32 v5, v5, |v139|, |v143|
	v_max3_f32 v4, v4, |v140|, |v144|
	v_max3_f32 v0, v0, |v141|, |v2|
	s_cbranch_vccz .LBB0_64
	v_and_b32_e32 v3, 64, v88
	v_xor_b32_e32 v2, 16, v88
	v_add_u32_e32 v3, 64, v3
	v_cmp_lt_i32_e32 vcc, v2, v3
	s_nop 1
	v_cndmask_b32_e32 v2, v88, v2, vcc
	v_lshlrev_b32_e32 v7, 2, v2
	ds_bpermute_b32 v8, v7, v6
	ds_bpermute_b32 v23, v7, v5
	v_xor_b32_e32 v2, 32, v88
	v_cmp_lt_i32_e32 vcc, v2, v3
	v_max_f32_e32 v3, v6, v6
	v_max_f32_e32 v5, v5, v5
	v_cndmask_b32_e32 v2, v88, v2, vcc
	v_lshlrev_b32_e32 v9, 2, v2
	s_waitcnt lgkmcnt(1)
	v_max_f32_e32 v2, v8, v8
	s_waitcnt lgkmcnt(0)
	v_max_f32_e32 v6, v23, v23
	ds_bpermute_b32 v8, v7, v4
	ds_bpermute_b32 v23, v7, v0
	v_max_f32_e32 v4, v4, v4
	v_max_f32_e32 v0, v0, v0
	v_max_f32_e32 v2, v3, v2
	s_waitcnt lgkmcnt(1)
	v_max_f32_e32 v7, v8, v8
	s_waitcnt lgkmcnt(0)
	v_max_f32_e32 v8, v23, v23
	v_max_f32_e32 v5, v5, v6
	v_max_f32_e32 v4, v4, v7
	v_max_f32_e32 v0, v0, v8
	ds_bpermute_b32 v3, v9, v2
	ds_bpermute_b32 v6, v9, v5
	ds_bpermute_b32 v7, v9, v4
	ds_bpermute_b32 v8, v9, v0
	s_and_saveexec_b64 s[48:49], s[2:3]
	s_cbranch_execz .LBB0_67
	s_waitcnt lgkmcnt(0)
	v_max_f32_e32 v8, v8, v8
	v_max_f32_e32 v0, v0, v0
	v_max_f32_e32 v9, v0, v8
	v_max_f32_e32 v0, v7, v7
	v_max_f32_e32 v4, v4, v4
	v_max_f32_e32 v8, v4, v0
	v_max_f32_e32 v0, v6, v6
	v_max_f32_e32 v4, v5, v5
	v_max_f32_e32 v7, v4, v0
	v_max_f32_e32 v0, v3, v3
	v_max_f32_e32 v2, v2, v2
	v_max_f32_e32 v6, v2, v0
	v_add_u32_e32 v0, s6, v60
	ds_write_b128 v0, v[6:9]

.LBB0_70:
	s_or_b32 vcc_lo, s7, s31
	v_or_b32_e32 v72, vcc_lo, v62
	v_mad_i64_i32 v[2:3], s[56:57], v72, s22, v[24:25]
	v_or_b32_e32 v0, 4, v72
	global_load_dwordx4 v[112:115], v[2:3], off nt
	v_mad_i64_i32 v[2:3], s[56:57], v0, s22, v[24:25]
	v_or_b32_e32 v0, 8, v72
	global_load_dwordx4 v[116:119], v[2:3], off nt
	v_mad_i64_i32 v[2:3], s[56:57], v0, s22, v[24:25]
	v_or_b32_e32 v0, 12, v72
	global_load_dwordx4 v[120:123], v[2:3], off nt
	v_mad_i64_i32 v[2:3], s[56:57], v0, s22, v[24:25]
	v_or_b32_e32 v0, 16, v72
	global_load_dwordx4 v[124:127], v[2:3], off nt
	v_mad_i64_i32 v[2:3], s[56:57], v0, s22, v[24:25]
	v_or_b32_e32 v0, 20, v72
	v_ashrrev_i32_e32 v73, 31, v72
	global_load_dwordx4 v[128:131], v[2:3], off nt
	v_mad_i64_i32 v[2:3], s[56:57], v0, s22, v[24:25]
	v_or_b32_e32 v0, 24, v72
	global_load_dwordx4 v[132:135], v[2:3], off nt
	v_mad_i64_i32 v[2:3], s[56:57], v0, s22, v[24:25]
	v_or_b32_e32 v0, 28, v72
	v_lshl_add_u64 v[74:75], v[72:73], 2, s[10:11]
	global_load_dwordx4 v[6:9], v[2:3], off nt
	v_mad_i64_i32 v[2:3], s[56:57], v0, s22, v[24:25]
	global_load_dword v0, v[74:75], off
	v_add_u32_e32 v23, v77, v78
	s_ashr_i32 vcc_hi, vcc_lo, 31
	v_add_u32_e32 v73, 0x410, v23
	global_load_dwordx4 v[2:5], v[2:3], off nt
	s_mov_b32 s7, 64
	s_waitcnt vmcnt(1)
	v_pk_mul_f32 v[74:75], v[26:27], v[0:1] op_sel_hi:[1,0]
	s_nop 0
	v_pk_mul_f32 v[74:75], v[112:113], v[74:75]
	ds_write2_b32 v23, v74, v75 offset1:1
	v_pk_mul_f32 v[74:75], v[28:29], v[0:1] op_sel_hi:[1,0]
	s_nop 0
	v_pk_mul_f32 v[74:75], v[114:115], v[74:75]
	ds_write2_b32 v23, v74, v75 offset0:2 offset1:3
	v_lshl_add_u64 v[74:75], vcc, 0, v[62:63]
	v_lshl_add_u64 v[74:75], v[74:75], 2, s[10:11]
	global_load_dword v140, v[74:75], off offset:32
	global_load_dword v142, v[74:75], off offset:48
	global_load_dword v144, v[74:75], off offset:64
	global_load_dword v146, v[74:75], off offset:80
	global_load_dword v148, v[74:75], off offset:96
	global_load_dword v150, v[74:75], off offset:112
	global_load_dword v152, v[74:75], off offset:128
	global_load_dword v154, v[74:75], off offset:144
	global_load_dword v156, v[74:75], off offset:160
	global_load_dword v158, v[74:75], off offset:176
	global_load_dword v160, v[74:75], off offset:192
	global_load_dword v162, v[74:75], off offset:208
	global_load_dword v164, v[74:75], off offset:224
	global_load_dword v166, v[74:75], off offset:240
	global_load_dword v0, v[74:75], off offset:16
	s_waitcnt vmcnt(0)
	v_pk_mul_f32 v[112:113], v[26:27], v[0:1] op_sel_hi:[1,0]
	s_nop 0
	v_pk_mul_f32 v[112:113], v[116:117], v[112:113]
	ds_write2_b32 v73, v112, v113 offset1:1
	v_pk_mul_f32 v[112:113], v[28:29], v[0:1] op_sel_hi:[1,0]
	v_add_u32_e32 v0, 0x418, v23
	v_pk_mul_f32 v[112:113], v[118:119], v[112:113]
	ds_write2_b32 v0, v112, v113 offset1:1
	v_add_u32_e32 v73, 0x820, v23
	v_pk_mul_f32 v[112:113], v[26:27], v[140:141] op_sel_hi:[1,0]
	s_nop 0
	v_pk_mul_f32 v[112:113], v[120:121], v[112:113]
	ds_write2_b32 v73, v112, v113 offset1:1
	v_pk_mul_f32 v[112:113], v[28:29], v[140:141] op_sel_hi:[1,0]
	v_add_u32_e32 v0, 0x828, v23
	v_pk_mul_f32 v[112:113], v[122:123], v[112:113]
	ds_write2_b32 v0, v112, v113 offset1:1
	v_add_u32_e32 v73, 0xc30, v23
	v_pk_mul_f32 v[112:113], v[26:27], v[142:143] op_sel_hi:[1,0]
	s_nop 0
	v_pk_mul_f32 v[112:113], v[124:125], v[112:113]
	ds_write2_b32 v73, v112, v113 offset1:1
	v_pk_mul_f32 v[112:113], v[28:29], v[142:143] op_sel_hi:[1,0]
	v_add_u32_e32 v0, 0xc38, v23
	v_pk_mul_f32 v[112:113], v[126:127], v[112:113]
	ds_write2_b32 v0, v112, v113 offset1:1
	v_add_u32_e32 v73, 0x1040, v23
	v_pk_mul_f32 v[112:113], v[26:27], v[144:145] op_sel_hi:[1,0]
	s_nop 0
	v_pk_mul_f32 v[112:113], v[128:129], v[112:113]
	ds_write2_b32 v73, v112, v113 offset1:1
	v_pk_mul_f32 v[112:113], v[28:29], v[144:145] op_sel_hi:[1,0]
	v_add_u32_e32 v0, 0x1048, v23
	v_pk_mul_f32 v[112:113], v[130:131], v[112:113]
	ds_write2_b32 v0, v112, v113 offset1:1
	v_add_u32_e32 v23, 0x1450, v23
	v_pk_mul_f32 v[112:113], v[26:27], v[146:147] op_sel_hi:[1,0]
	s_nop 0
	v_pk_mul_f32 v[112:113], v[132:133], v[112:113]
	ds_write2_b32 v23, v112, v113 offset1:1
	v_pk_mul_f32 v[112:113], v[28:29], v[146:147] op_sel_hi:[1,0]
	v_pk_mul_f32 v[112:113], v[134:135], v[112:113]
	v_add_u32_e32 v23, v77, v79
	ds_write2_b32 v23, v112, v113 offset0:2 offset1:3
	v_add_u32_e32 v73, 0x410, v23
	v_pk_mul_f32 v[112:113], v[26:27], v[148:149] op_sel_hi:[1,0]
	s_nop 0
	v_pk_mul_f32 v[6:7], v[6:7], v[112:113]
	ds_write2_b32 v73, v6, v7 offset1:1
	v_pk_mul_f32 v[6:7], v[28:29], v[148:149] op_sel_hi:[1,0]
	v_add_u32_e32 v0, 0x418, v23
	v_pk_mul_f32 v[6:7], v[8:9], v[6:7]
	ds_write2_b32 v0, v6, v7 offset1:1
	v_pk_mul_f32 v[6:7], v[26:27], v[150:151] op_sel_hi:[1,0]
	s_nop 0
	v_pk_mul_f32 v[2:3], v[2:3], v[6:7]
	v_add_u32_e32 v6, 0x820, v23
	ds_write2_b32 v6, v2, v3 offset1:1
	v_pk_mul_f32 v[2:3], v[28:29], v[150:151] op_sel_hi:[1,0]
	v_add_u32_e32 v0, 0x828, v23
	v_pk_mul_f32 v[2:3], v[4:5], v[2:3]
	ds_write2_b32 v0, v2, v3 offset1:1
	v_or_b32_e32 v0, 32, v72
	v_mad_i64_i32 v[2:3], s[56:57], v0, s22, v[24:25]
	v_or_b32_e32 v0, 36, v72
	v_mad_i64_i32 v[6:7], s[56:57], v0, s22, v[24:25]
	v_or_b32_e32 v0, 40, v72
	v_mad_i64_i32 v[112:113], s[56:57], v0, s22, v[24:25]
	v_or_b32_e32 v0, 44, v72
	v_mad_i64_i32 v[116:117], s[56:57], v0, s22, v[24:25]
	v_or_b32_e32 v0, 48, v72
	v_mad_i64_i32 v[120:121], s[56:57], v0, s22, v[24:25]
	v_or_b32_e32 v0, 52, v72
	v_mad_i64_i32 v[124:125], s[56:57], v0, s22, v[24:25]
	v_or_b32_e32 v0, 56, v72
	v_mad_i64_i32 v[128:129], s[56:57], v0, s22, v[24:25]
	v_or_b32_e32 v0, 60, v72
	v_mad_i64_i32 v[72:73], s[56:57], v0, s22, v[24:25]
	global_load_dwordx4 v[2:5], v[2:3], off nt
	s_nop 0
	global_load_dwordx4 v[6:9], v[6:7], off nt
	s_nop 0
	global_load_dwordx4 v[112:115], v[112:113], off nt
	s_nop 0
	global_load_dwordx4 v[116:119], v[116:117], off nt
	s_nop 0
	global_load_dwordx4 v[120:123], v[120:121], off nt
	s_nop 0
	global_load_dwordx4 v[124:127], v[124:125], off nt
	s_nop 0
	global_load_dwordx4 v[128:131], v[128:129], off nt
	s_nop 0
	global_load_dwordx4 v[132:135], v[72:73], off nt
	v_pk_mul_f32 v[72:73], v[26:27], v[152:153] op_sel_hi:[1,0]
	s_nop 0
	s_waitcnt vmcnt(7)
	v_pk_mul_f32 v[2:3], v[2:3], v[72:73]
	v_add_u32_e32 v72, 0xc30, v23
	ds_write2_b32 v72, v2, v3 offset1:1
	v_pk_mul_f32 v[2:3], v[28:29], v[152:153] op_sel_hi:[1,0]
	v_add_u32_e32 v0, 0xc38, v23
	v_pk_mul_f32 v[2:3], v[4:5], v[2:3]
	ds_write2_b32 v0, v2, v3 offset1:1
	v_add_u32_e32 v4, 0x1040, v23
	v_pk_mul_f32 v[2:3], v[26:27], v[154:155] op_sel_hi:[1,0]
	s_nop 0
	s_waitcnt vmcnt(6)
	v_pk_mul_f32 v[2:3], v[6:7], v[2:3]
	ds_write2_b32 v4, v2, v3 offset1:1
	v_pk_mul_f32 v[2:3], v[28:29], v[154:155] op_sel_hi:[1,0]
	v_add_u32_e32 v0, 0x1048, v23
	v_pk_mul_f32 v[2:3], v[8:9], v[2:3]
	ds_write2_b32 v0, v2, v3 offset1:1
	v_add_u32_e32 v4, 0x1450, v23
	v_pk_mul_f32 v[2:3], v[26:27], v[156:157] op_sel_hi:[1,0]
	s_nop 0
	s_waitcnt vmcnt(5)
	v_pk_mul_f32 v[2:3], v[112:113], v[2:3]
	ds_write2_b32 v4, v2, v3 offset1:1
	v_pk_mul_f32 v[2:3], v[28:29], v[156:157] op_sel_hi:[1,0]
	v_add_u32_e32 v0, 0x1458, v23
	v_pk_mul_f32 v[2:3], v[114:115], v[2:3]
	ds_write2_b32 v0, v2, v3 offset1:1
	v_add_u32_e32 v4, 0x1860, v23
	v_pk_mul_f32 v[2:3], v[26:27], v[158:159] op_sel_hi:[1,0]
	s_nop 0
	s_waitcnt vmcnt(4)
	v_pk_mul_f32 v[2:3], v[116:117], v[2:3]
	ds_write2_b32 v4, v2, v3 offset1:1
	v_pk_mul_f32 v[2:3], v[28:29], v[158:159] op_sel_hi:[1,0]
	v_add_u32_e32 v0, 0x1868, v23
	v_pk_mul_f32 v[2:3], v[118:119], v[2:3]
	ds_write2_b32 v0, v2, v3 offset1:1
	v_add_u32_e32 v4, 0x1c70, v23
	v_pk_mul_f32 v[2:3], v[26:27], v[160:161] op_sel_hi:[1,0]
	s_nop 0
	s_waitcnt vmcnt(3)
	v_pk_mul_f32 v[2:3], v[120:121], v[2:3]
	ds_write2_b32 v4, v2, v3 offset1:1
	v_pk_mul_f32 v[2:3], v[28:29], v[160:161] op_sel_hi:[1,0]
	v_add_u32_e32 v0, 0x1c78, v23
	v_pk_mul_f32 v[2:3], v[122:123], v[2:3]
	ds_write2_b32 v0, v2, v3 offset1:1
	v_add_u32_e32 v4, 0x2080, v23
	v_pk_mul_f32 v[2:3], v[26:27], v[162:163] op_sel_hi:[1,0]
	s_nop 0
	s_waitcnt vmcnt(2)
	v_pk_mul_f32 v[2:3], v[124:125], v[2:3]
	ds_write2_b32 v4, v2, v3 offset1:1
	v_pk_mul_f32 v[2:3], v[28:29], v[162:163] op_sel_hi:[1,0]
	v_add_u32_e32 v0, 0x2088, v23
	v_pk_mul_f32 v[2:3], v[126:127], v[2:3]
	ds_write2_b32 v0, v2, v3 offset1:1
	v_add_u32_e32 v4, 0x2490, v23
	v_pk_mul_f32 v[2:3], v[26:27], v[164:165] op_sel_hi:[1,0]
	s_nop 0
	s_waitcnt vmcnt(1)
	v_pk_mul_f32 v[2:3], v[128:129], v[2:3]
	ds_write2_b32 v4, v2, v3 offset1:1
	v_pk_mul_f32 v[2:3], v[28:29], v[164:165] op_sel_hi:[1,0]
	v_add_u32_e32 v0, 0x2498, v23
	v_pk_mul_f32 v[2:3], v[130:131], v[2:3]
	ds_write2_b32 v0, v2, v3 offset1:1
	v_add_u32_e32 v4, 0x28a0, v23
	v_pk_mul_f32 v[2:3], v[26:27], v[166:167] op_sel_hi:[1,0]
	s_nop 0
	s_waitcnt vmcnt(0)
	v_pk_mul_f32 v[2:3], v[132:133], v[2:3]
	ds_write2_b32 v4, v2, v3 offset1:1
	v_pk_mul_f32 v[2:3], v[28:29], v[166:167] op_sel_hi:[1,0]
	v_add_u32_e32 v0, 0x28a8, v23
	v_pk_mul_f32 v[2:3], v[134:135], v[2:3]
	ds_write2_b32 v0, v2, v3 offset1:1
	s_waitcnt lgkmcnt(0)
	ds_read2_b32 v[4:5], v13 offset1:8
	ds_read2_b32 v[6:7], v13 offset0:65 offset1:73
	ds_read2_b32 v[8:9], v13 offset0:130 offset1:138
	ds_read2_b32 v[72:73], v13 offset0:195 offset1:203
	v_lshl_add_u64 v[2:3], v[20:21], 0, vcc
	s_waitcnt lgkmcnt(3)
	v_med3_f32 v0, v4, s61, v89
	s_waitcnt lgkmcnt(2)
	v_med3_f32 v4, v6, s61, v89
	s_waitcnt lgkmcnt(1)
	v_med3_f32 v6, v8, s61, v89
	s_waitcnt lgkmcnt(0)
	v_med3_f32 v8, v72, s61, v89
	v_add_f32_e32 v0, 0x4b400000, v0
	v_add_f32_e32 v4, 0x4b400000, v4
	v_add_f32_e32 v6, 0x4b400000, v6
	v_add_f32_e32 v8, 0x4b400000, v8
	v_perm_b32 v6, v8, v6, s0
	v_perm_b32 v0, v4, v0, s0
	v_perm_b32 v74, v6, v0, s1
	v_add_u32_e32 v0, 0x400, v13
	ds_read2_b32 v[112:113], v0 offset0:4 offset1:12
	ds_read2_b32 v[114:115], v0 offset0:69 offset1:77
	ds_read2_b32 v[116:117], v0 offset0:134 offset1:142
	ds_read2_b32 v[118:119], v0 offset0:199 offset1:207
	v_lshl_add_u64 v[120:121], v[2:3], 0, v[30:31]
	s_waitcnt lgkmcnt(3)
	v_med3_f32 v4, v112, s61, v89
	s_waitcnt lgkmcnt(2)
	v_med3_f32 v6, v114, s61, v89
	s_waitcnt lgkmcnt(1)
	v_med3_f32 v8, v116, s61, v89
	s_waitcnt lgkmcnt(0)
	v_med3_f32 v23, v118, s61, v89
	v_add_f32_e32 v4, 0x4b400000, v4
	v_add_f32_e32 v6, 0x4b400000, v6
	v_add_f32_e32 v8, 0x4b400000, v8
	v_add_f32_e32 v23, 0x4b400000, v23
	v_perm_b32 v8, v23, v8, s0
	v_perm_b32 v4, v6, v4, s0
	v_perm_b32 v75, v8, v4, s1
	v_med3_f32 v4, v5, s61, v89
	v_med3_f32 v5, v7, s61, v89
	v_med3_f32 v6, v9, s61, v89
	v_med3_f32 v7, v73, s61, v89
	v_add_f32_e32 v4, 0x4b400000, v4
	v_add_f32_e32 v5, 0x4b400000, v5
	v_add_f32_e32 v6, 0x4b400000, v6
	v_add_f32_e32 v7, 0x4b400000, v7
	v_perm_b32 v6, v7, v6, s0
	v_perm_b32 v4, v5, v4, s0
	v_perm_b32 v4, v6, v4, s1
	v_med3_f32 v5, v113, s61, v89
	v_med3_f32 v6, v115, s61, v89
	v_med3_f32 v7, v117, s61, v89
	v_med3_f32 v8, v119, s61, v89
	v_add_f32_e32 v5, 0x4b400000, v5
	v_add_f32_e32 v6, 0x4b400000, v6
	v_add_f32_e32 v7, 0x4b400000, v7
	v_add_f32_e32 v8, 0x4b400000, v8
	v_perm_b32 v7, v8, v7, s0
	v_perm_b32 v5, v6, v5, s0
	v_perm_b32 v5, v7, v5, s1
	v_lshl_add_u64 v[6:7], v[2:3], 0, v[32:33]
	global_store_dwordx2 v[6:7], v[4:5], off
	ds_read2_b32 v[4:5], v13 offset0:16 offset1:24
	ds_read2_b32 v[6:7], v13 offset0:81 offset1:89
	ds_read2_b32 v[8:9], v13 offset0:146 offset1:154
	ds_read2_b32 v[72:73], v13 offset0:211 offset1:219
	ds_read2_b32 v[112:113], v0 offset0:20 offset1:28
	ds_read2_b32 v[114:115], v0 offset0:85 offset1:93
	ds_read2_b32 v[116:117], v0 offset0:150 offset1:158
	ds_read2_b32 v[118:119], v0 offset0:215 offset1:223
	s_waitcnt lgkmcnt(7)
	v_med3_f32 v4, v4, s61, v89
	s_waitcnt lgkmcnt(6)
	v_med3_f32 v6, v6, s61, v89
	s_waitcnt lgkmcnt(5)
	v_med3_f32 v8, v8, s61, v89
	s_waitcnt lgkmcnt(4)
	v_med3_f32 v23, v72, s61, v89
	v_add_f32_e32 v4, 0x4b400000, v4
	v_add_f32_e32 v6, 0x4b400000, v6
	v_add_f32_e32 v8, 0x4b400000, v8
	v_add_f32_e32 v23, 0x4b400000, v23
	v_perm_b32 v8, v23, v8, s0
	v_perm_b32 v4, v6, v4, s0
	global_store_dwordx2 v[120:121], v[74:75], off
	v_perm_b32 v74, v8, v4, s1
	s_waitcnt lgkmcnt(3)
	v_med3_f32 v4, v112, s61, v89
	s_waitcnt lgkmcnt(2)
	v_med3_f32 v6, v114, s61, v89
	s_waitcnt lgkmcnt(1)
	v_med3_f32 v8, v116, s61, v89
	s_waitcnt lgkmcnt(0)
	v_med3_f32 v23, v118, s61, v89
	v_add_f32_e32 v4, 0x4b400000, v4
	v_add_f32_e32 v6, 0x4b400000, v6
	v_add_f32_e32 v8, 0x4b400000, v8
	v_add_f32_e32 v23, 0x4b400000, v23
	v_perm_b32 v8, v23, v8, s0
	v_perm_b32 v4, v6, v4, s0
	v_perm_b32 v75, v8, v4, s1
	v_med3_f32 v4, v5, s61, v89
	v_med3_f32 v5, v7, s61, v89
	v_med3_f32 v6, v9, s61, v89
	v_med3_f32 v7, v73, s61, v89
	v_add_f32_e32 v4, 0x4b400000, v4
	v_add_f32_e32 v5, 0x4b400000, v5
	v_add_f32_e32 v6, 0x4b400000, v6
	v_add_f32_e32 v7, 0x4b400000, v7
	v_perm_b32 v6, v7, v6, s0
	v_perm_b32 v4, v5, v4, s0
	v_perm_b32 v4, v6, v4, s1
	v_med3_f32 v5, v113, s61, v89
	v_med3_f32 v6, v115, s61, v89
	v_med3_f32 v7, v117, s61, v89
	v_med3_f32 v8, v119, s61, v89
	v_add_f32_e32 v5, 0x4b400000, v5
	v_add_f32_e32 v6, 0x4b400000, v6
	v_add_f32_e32 v7, 0x4b400000, v7
	v_add_f32_e32 v8, 0x4b400000, v8
	v_perm_b32 v7, v8, v7, s0
	v_perm_b32 v5, v6, v5, s0
	v_perm_b32 v5, v7, v5, s1
	v_lshl_add_u64 v[6:7], v[2:3], 0, v[36:37]
	global_store_dwordx2 v[6:7], v[4:5], off
	ds_read2_b32 v[4:5], v13 offset0:32 offset1:40
	ds_read2_b32 v[6:7], v13 offset0:97 offset1:105
	ds_read2_b32 v[8:9], v13 offset0:162 offset1:170
	ds_read2_b32 v[72:73], v13 offset0:227 offset1:235
	ds_read2_b32 v[112:113], v0 offset0:36 offset1:44
	ds_read2_b32 v[114:115], v0 offset0:101 offset1:109
	ds_read2_b32 v[116:117], v0 offset0:166 offset1:174
	ds_read2_b32 v[118:119], v0 offset0:231 offset1:239
	s_waitcnt lgkmcnt(7)
	v_med3_f32 v4, v4, s61, v89
	s_waitcnt lgkmcnt(6)
	v_med3_f32 v6, v6, s61, v89
	s_waitcnt lgkmcnt(5)
	v_med3_f32 v8, v8, s61, v89
	s_waitcnt lgkmcnt(4)
	v_med3_f32 v23, v72, s61, v89
	v_add_f32_e32 v4, 0x4b400000, v4
	v_add_f32_e32 v6, 0x4b400000, v6
	v_add_f32_e32 v8, 0x4b400000, v8
	v_add_f32_e32 v23, 0x4b400000, v23
	v_lshl_add_u64 v[120:121], v[2:3], 0, v[34:35]
	v_perm_b32 v8, v23, v8, s0
	v_perm_b32 v4, v6, v4, s0
	global_store_dwordx2 v[120:121], v[74:75], off
	v_perm_b32 v74, v8, v4, s1
	s_waitcnt lgkmcnt(3)
	v_med3_f32 v4, v112, s61, v89
	s_waitcnt lgkmcnt(2)
	v_med3_f32 v6, v114, s61, v89
	s_waitcnt lgkmcnt(1)
	v_med3_f32 v8, v116, s61, v89
	s_waitcnt lgkmcnt(0)
	v_med3_f32 v23, v118, s61, v89
	v_add_f32_e32 v4, 0x4b400000, v4
	v_add_f32_e32 v6, 0x4b400000, v6
	v_add_f32_e32 v8, 0x4b400000, v8
	v_add_f32_e32 v23, 0x4b400000, v23
	v_perm_b32 v8, v23, v8, s0
	v_perm_b32 v4, v6, v4, s0
	v_perm_b32 v75, v8, v4, s1
	v_med3_f32 v4, v5, s61, v89
	v_med3_f32 v5, v7, s61, v89
	v_med3_f32 v6, v9, s61, v89
	v_med3_f32 v7, v73, s61, v89
	v_add_f32_e32 v4, 0x4b400000, v4
	v_add_f32_e32 v5, 0x4b400000, v5
	v_add_f32_e32 v6, 0x4b400000, v6
	v_add_f32_e32 v7, 0x4b400000, v7
	v_perm_b32 v6, v7, v6, s0
	v_perm_b32 v4, v5, v4, s0
	v_perm_b32 v4, v6, v4, s1
	v_med3_f32 v5, v113, s61, v89
	v_med3_f32 v6, v115, s61, v89
	v_med3_f32 v7, v117, s61, v89
	v_med3_f32 v8, v119, s61, v89
	v_add_f32_e32 v5, 0x4b400000, v5
	v_add_f32_e32 v6, 0x4b400000, v6
	v_add_f32_e32 v7, 0x4b400000, v7
	v_add_f32_e32 v8, 0x4b400000, v8
	v_perm_b32 v7, v8, v7, s0
	v_perm_b32 v5, v6, v5, s0
	v_perm_b32 v5, v7, v5, s1
	v_lshl_add_u64 v[6:7], v[2:3], 0, v[66:67]
	global_store_dwordx2 v[6:7], v[4:5], off
	ds_read2_b32 v[4:5], v13 offset0:48 offset1:56
	ds_read2_b32 v[6:7], v13 offset0:113 offset1:121
	ds_read2_b32 v[8:9], v13 offset0:178 offset1:186
	ds_read2_b32 v[72:73], v13 offset0:243 offset1:251
	ds_read2_b32 v[112:113], v0 offset0:52 offset1:60
	ds_read2_b32 v[114:115], v0 offset0:117 offset1:125
	ds_read2_b32 v[116:117], v0 offset0:182 offset1:190
	ds_read2_b32 v[118:119], v0 offset0:247 offset1:255
	s_waitcnt lgkmcnt(7)
	v_med3_f32 v4, v4, s61, v89
	s_waitcnt lgkmcnt(6)
	v_med3_f32 v6, v6, s61, v89
	s_waitcnt lgkmcnt(5)
	v_med3_f32 v8, v8, s61, v89
	s_waitcnt lgkmcnt(4)
	v_med3_f32 v23, v72, s61, v89
	v_add_f32_e32 v4, 0x4b400000, v4
	v_add_f32_e32 v6, 0x4b400000, v6
	v_add_f32_e32 v8, 0x4b400000, v8
	v_add_f32_e32 v23, 0x4b400000, v23
	v_lshl_add_u64 v[120:121], v[2:3], 0, v[64:65]
	v_perm_b32 v8, v23, v8, s0
	v_perm_b32 v4, v6, v4, s0
	global_store_dwordx2 v[120:121], v[74:75], off
	v_perm_b32 v74, v8, v4, s1
	s_waitcnt lgkmcnt(3)
	v_med3_f32 v4, v112, s61, v89
	s_waitcnt lgkmcnt(2)
	v_med3_f32 v6, v114, s61, v89
	s_waitcnt lgkmcnt(1)
	v_med3_f32 v8, v116, s61, v89
	s_waitcnt lgkmcnt(0)
	v_med3_f32 v0, v118, s61, v89
	v_add_f32_e32 v4, 0x4b400000, v4
	v_add_f32_e32 v6, 0x4b400000, v6
	v_add_f32_e32 v8, 0x4b400000, v8
	v_add_f32_e32 v0, 0x4b400000, v0
	v_perm_b32 v0, v0, v8, s0
	v_perm_b32 v4, v6, v4, s0
	v_perm_b32 v75, v0, v4, s1
	v_med3_f32 v0, v5, s61, v89
	v_med3_f32 v4, v7, s61, v89
	v_med3_f32 v5, v9, s61, v89
	v_med3_f32 v6, v73, s61, v89
	v_add_f32_e32 v0, 0x4b400000, v0
	v_add_f32_e32 v4, 0x4b400000, v4
	v_add_f32_e32 v5, 0x4b400000, v5
	v_add_f32_e32 v6, 0x4b400000, v6
	v_perm_b32 v5, v6, v5, s0
	v_perm_b32 v0, v4, v0, s0
	v_perm_b32 v4, v5, v0, s1
	v_med3_f32 v0, v113, s61, v89
	v_med3_f32 v5, v115, s61, v89
	v_med3_f32 v6, v117, s61, v89
	v_med3_f32 v7, v119, s61, v89
	v_add_f32_e32 v0, 0x4b400000, v0
	v_add_f32_e32 v5, 0x4b400000, v5
	v_add_f32_e32 v6, 0x4b400000, v6
	v_add_f32_e32 v7, 0x4b400000, v7
	v_perm_b32 v6, v7, v6, s0
	v_perm_b32 v0, v5, v0, s0
	v_lshl_add_u64 v[120:121], v[2:3], 0, v[68:69]
	v_perm_b32 v5, v6, v0, s1
	v_lshl_add_u64 v[2:3], v[2:3], 0, v[70:71]
	global_store_dwordx2 v[120:121], v[74:75], off
	global_store_dwordx2 v[2:3], v[4:5], off
	s_waitcnt lgkmcnt(0)
	s_and_b64 vcc, exec, s[48:49]
	s_mov_b64 s[48:49], 0
	s_cbranch_vccnz .LBB0_70
	s_barrier
	s_branch .LBB0_26

.LBB0_1800:
	v_or_b32_e32 v110, s2, v86
	v_ashrrev_i32_e32 v111, 31, v110
	v_lshl_add_u64 v[112:113], v[110:111], 2, s[16:17]
	global_load_dword v114, v[112:113], off
	v_or_b32_e32 v110, s2, v86
	v_or_b32_e32 v112, 4, v110
	v_ashrrev_i32_e32 v113, 31, v112
	v_lshl_add_u64 v[110:111], v[112:113], 2, s[16:17]
	global_load_dword v116, v[110:111], off
	v_or_b32_e32 v110, s2, v86
	v_or_b32_e32 v112, 8, v110
	v_ashrrev_i32_e32 v113, 31, v112
	v_lshl_add_u64 v[110:111], v[112:113], 2, s[16:17]
	global_load_dword v118, v[110:111], off
	v_or_b32_e32 v110, s2, v86
	v_or_b32_e32 v112, 12, v110
	v_ashrrev_i32_e32 v113, 31, v112
	v_lshl_add_u64 v[110:111], v[112:113], 2, s[16:17]
	global_load_dword v120, v[110:111], off
	v_or_b32_e32 v110, s2, v86
	v_or_b32_e32 v112, 16, v110
	v_ashrrev_i32_e32 v113, 31, v112
	v_lshl_add_u64 v[110:111], v[112:113], 2, s[16:17]
	global_load_dword v122, v[110:111], off
	v_or_b32_e32 v110, s2, v86
	v_or_b32_e32 v112, 20, v110
	v_ashrrev_i32_e32 v113, 31, v112
	v_lshl_add_u64 v[110:111], v[112:113], 2, s[16:17]
	global_load_dword v124, v[110:111], off
	v_or_b32_e32 v110, s2, v86
	v_or_b32_e32 v112, 24, v110
	v_ashrrev_i32_e32 v113, 31, v112
	v_lshl_add_u64 v[110:111], v[112:113], 2, s[16:17]
	global_load_dword v126, v[110:111], off
	v_or_b32_e32 v110, s2, v86
	v_or_b32_e32 v112, 28, v110
	v_ashrrev_i32_e32 v113, 31, v112
	v_lshl_add_u64 v[110:111], v[112:113], 2, s[16:17]
	global_load_dword v128, v[110:111], off
	v_or_b32_e32 v110, s2, v86
	v_or_b32_e32 v112, 32, v110
	v_ashrrev_i32_e32 v113, 31, v112
	v_lshl_add_u64 v[112:113], v[112:113], 2, s[16:17]
	global_load_dword v130, v[112:113], off
	v_or_b32_e32 v110, s2, v86
	v_or_b32_e32 v112, 36, v110
	v_ashrrev_i32_e32 v113, 31, v112
	v_lshl_add_u64 v[110:111], v[112:113], 2, s[16:17]
	global_load_dword v132, v[110:111], off
	v_or_b32_e32 v110, s2, v86
	v_or_b32_e32 v112, 40, v110
	v_ashrrev_i32_e32 v113, 31, v112
	v_lshl_add_u64 v[110:111], v[112:113], 2, s[16:17]
	global_load_dword v134, v[110:111], off
	v_or_b32_e32 v110, s2, v86
	v_or_b32_e32 v112, 44, v110
	v_ashrrev_i32_e32 v113, 31, v112
	v_lshl_add_u64 v[110:111], v[112:113], 2, s[16:17]
	global_load_dword v136, v[110:111], off
	v_or_b32_e32 v110, s2, v86
	v_or_b32_e32 v112, 48, v110
	v_ashrrev_i32_e32 v113, 31, v112
	v_lshl_add_u64 v[110:111], v[112:113], 2, s[16:17]
	global_load_dword v138, v[110:111], off
	v_or_b32_e32 v110, s2, v86
	v_or_b32_e32 v112, 52, v110
	v_ashrrev_i32_e32 v113, 31, v112
	v_lshl_add_u64 v[110:111], v[112:113], 2, s[16:17]
	global_load_dword v140, v[110:111], off
	v_or_b32_e32 v110, s2, v86
	v_or_b32_e32 v112, 56, v110
	v_ashrrev_i32_e32 v113, 31, v112
	v_lshl_add_u64 v[110:111], v[112:113], 2, s[16:17]
	global_load_dword v142, v[110:111], off
	v_or_b32_e32 v110, s2, v86
	v_or_b32_e32 v110, 60, v110
	v_ashrrev_i32_e32 v111, 31, v110
	v_lshl_add_u64 v[112:113], v[110:111], 2, s[16:17]
	global_load_dword v144, v[112:113], off
	v_or_b32_e32 v92, s2, v86
	v_cndmask_b32_e64 v4, 0, 1, s[14:15]
	v_cmp_ne_u32_e32 vcc, 1, v4
	v_mad_i64_i32 v[4:5], s[2:3], v92, s50, v[22:23]
	global_load_dwordx4 v[4:7], v[4:5], off
	v_or_b32_e32 v94, 4, v92
	v_mad_i64_i32 v[24:25], s[2:3], v94, s50, v[22:23]
	global_load_dwordx4 v[24:27], v[24:25], off
	v_or_b32_e32 v96, 8, v92
	v_mad_i64_i32 v[28:29], s[2:3], v96, s50, v[22:23]
	global_load_dwordx4 v[28:31], v[28:29], off
	v_or_b32_e32 v98, 12, v92
	v_mad_i64_i32 v[32:33], s[2:3], v98, s50, v[22:23]
	global_load_dwordx4 v[32:35], v[32:33], off
	v_or_b32_e32 v100, 16, v92
	v_mad_i64_i32 v[38:39], s[2:3], v100, s50, v[22:23]
	global_load_dwordx4 v[38:41], v[38:39], off
	v_or_b32_e32 v102, 20, v92
	v_mad_i64_i32 v[42:43], s[2:3], v102, s50, v[22:23]
	global_load_dwordx4 v[42:45], v[42:43], off
	v_or_b32_e32 v104, 24, v92
	v_mad_i64_i32 v[46:47], s[2:3], v104, s50, v[22:23]
	global_load_dwordx4 v[46:49], v[46:47], off
	v_or_b32_e32 v106, 28, v92
	v_mad_i64_i32 v[88:89], s[2:3], v106, s50, v[22:23]
	global_load_dwordx4 v[88:91], v[88:89], off
	s_mov_b64 s[14:15], 0
	s_and_b64 vcc, exec, vcc
	s_waitcnt vmcnt(7)
	v_mul_f32_e32 v36, v4, v114
	v_mul_f32_e32 v87, v5, v114
	v_mul_f32_e32 v6, v6, v114
	v_mul_f32_e32 v7, v7, v114
	v_or_b32_e32 v94, 40, v92
	s_waitcnt vmcnt(6)
	v_mul_f32_e32 v5, v24, v116
	v_max3_f32 v3, v3, |v36|, |v5|
	v_mul_f32_e32 v5, v25, v116
	v_max3_f32 v2, v2, |v87|, |v5|
	v_mul_f32_e32 v5, v26, v116
	v_max3_f32 v5, v1, |v6|, |v5|
	v_mul_f32_e32 v1, v27, v116
	v_max3_f32 v4, v0, |v7|, |v1|
	v_or_b32_e32 v96, 44, v92
	s_waitcnt vmcnt(5)
	v_mul_f32_e32 v6, v28, v118
	v_mul_f32_e32 v7, v29, v118
	v_mul_f32_e32 v21, v30, v118
	v_mul_f32_e32 v24, v31, v118
	v_or_b32_e32 v98, 48, v92
	v_mad_i64_i32 v[28:29], s[2:3], v96, s50, v[22:23]
	global_load_dwordx4 v[28:31], v[28:29], off
	s_waitcnt vmcnt(5)
	v_mul_f32_e32 v1, v32, v120
	v_max3_f32 v3, v3, |v6|, |v1|
	v_mul_f32_e32 v1, v33, v120
	v_max3_f32 v2, v2, |v7|, |v1|
	v_mul_f32_e32 v1, v34, v120
	v_mul_f32_e32 v0, v35, v120
	v_max3_f32 v5, v5, |v21|, |v1|
	v_max3_f32 v4, v4, |v24|, |v0|
	v_mad_i64_i32 v[32:33], s[2:3], v98, s50, v[22:23]
	global_load_dwordx4 v[32:35], v[32:33], off
	v_or_b32_e32 v100, 52, v92
	s_waitcnt vmcnt(5)
	v_mul_f32_e32 v6, v38, v122
	v_mul_f32_e32 v7, v39, v122
	v_mul_f32_e32 v21, v40, v122
	v_mul_f32_e32 v24, v41, v122
	v_mad_i64_i32 v[38:39], s[2:3], v100, s50, v[22:23]
	global_load_dwordx4 v[38:41], v[38:39], off
	v_or_b32_e32 v102, 56, v92
	s_waitcnt vmcnt(5)
	v_mul_f32_e32 v1, v42, v124
	v_max3_f32 v3, v3, |v6|, |v1|
	v_mul_f32_e32 v1, v43, v124
	v_max3_f32 v2, v2, |v7|, |v1|
	v_mul_f32_e32 v1, v44, v124
	v_mul_f32_e32 v0, v45, v124
	v_max3_f32 v5, v5, |v21|, |v1|
	v_max3_f32 v4, v4, |v24|, |v0|
	v_mad_i64_i32 v[42:43], s[2:3], v102, s50, v[22:23]
	global_load_dwordx4 v[42:45], v[42:43], off
	s_waitcnt vmcnt(5)
	v_mul_f32_e32 v6, v46, v126
	v_mul_f32_e32 v7, v47, v126
	v_mul_f32_e32 v21, v48, v126
	v_mul_f32_e32 v24, v49, v126
	s_waitcnt vmcnt(4)
	v_mul_f32_e32 v1, v88, v128
	v_max3_f32 v36, v3, |v6|, |v1|
	v_mul_f32_e32 v1, v89, v128
	v_or_b32_e32 v88, 32, v92
	v_max3_f32 v87, v2, |v7|, |v1|
	v_mul_f32_e32 v1, v90, v128
	v_mul_f32_e32 v0, v91, v128
	v_max3_f32 v21, v5, |v21|, |v1|
	v_max3_f32 v104, v4, |v24|, |v0|
	v_mad_i64_i32 v[0:1], s[2:3], v88, s50, v[22:23]
	global_load_dwordx4 v[0:3], v[0:1], off
	v_or_b32_e32 v90, 36, v92
	v_mad_i64_i32 v[4:5], s[2:3], v90, s50, v[22:23]
	global_load_dwordx4 v[4:7], v[4:5], off
	v_mad_i64_i32 v[24:25], s[2:3], v94, s50, v[22:23]
	global_load_dwordx4 v[24:27], v[24:25], off
	v_or_b32_e32 v92, 60, v92
	v_mad_i64_i32 v[46:47], s[2:3], v92, s50, v[22:23]
	global_load_dwordx4 v[46:49], v[46:47], off
	s_mov_b32 s2, 64
	s_waitcnt vmcnt(3)
	v_mul_f32_e32 v89, v0, v130
	v_mul_f32_e32 v105, v1, v130
	v_mul_f32_e32 v2, v2, v130
	v_mul_f32_e32 v3, v3, v130
	s_waitcnt vmcnt(2)
	v_mul_f32_e32 v1, v4, v132
	v_max3_f32 v4, v36, |v89|, |v1|
	v_mul_f32_e32 v1, v5, v132
	v_max3_f32 v5, v87, |v105|, |v1|
	v_mul_f32_e32 v1, v6, v132
	v_mul_f32_e32 v0, v7, v132
	v_max3_f32 v2, v21, |v2|, |v1|
	v_max3_f32 v3, v104, |v3|, |v0|
	s_waitcnt vmcnt(1)
	v_mul_f32_e32 v6, v24, v134
	v_mul_f32_e32 v7, v25, v134
	v_mul_f32_e32 v21, v26, v134
	v_mul_f32_e32 v24, v27, v134
	v_mul_f32_e32 v1, v28, v136
	v_max3_f32 v4, v4, |v6|, |v1|
	v_mul_f32_e32 v1, v29, v136
	v_max3_f32 v5, v5, |v7|, |v1|
	v_mul_f32_e32 v1, v30, v136
	v_mul_f32_e32 v0, v31, v136
	v_max3_f32 v2, v2, |v21|, |v1|
	v_max3_f32 v3, v3, |v24|, |v0|
	v_mul_f32_e32 v6, v32, v138
	v_mul_f32_e32 v7, v33, v138
	v_mul_f32_e32 v21, v34, v138
	v_mul_f32_e32 v24, v35, v138
	v_mul_f32_e32 v1, v38, v140
	v_max3_f32 v4, v4, |v6|, |v1|
	v_mul_f32_e32 v1, v39, v140
	v_max3_f32 v5, v5, |v7|, |v1|
	v_mul_f32_e32 v1, v40, v140
	v_mul_f32_e32 v0, v41, v140
	v_max3_f32 v6, v2, |v21|, |v1|
	v_max3_f32 v7, v3, |v24|, |v0|
	v_mul_f32_e32 v2, v42, v142
	v_mul_f32_e32 v21, v43, v142
	v_mul_f32_e32 v24, v44, v142
	v_mul_f32_e32 v25, v45, v142
	s_waitcnt vmcnt(0)
	v_mul_f32_e32 v1, v46, v144
	v_max3_f32 v3, v4, |v2|, |v1|
	v_mul_f32_e32 v1, v47, v144
	v_max3_f32 v2, v5, |v21|, |v1|
	v_mul_f32_e32 v1, v48, v144
	v_mul_f32_e32 v0, v49, v144
	v_max3_f32 v1, v6, |v24|, |v1|
	v_max3_f32 v0, v7, |v25|, |v0|
	s_cbranch_vccz .LBB0_1800
	v_and_b32_e32 v5, 64, v57
	v_xor_b32_e32 v4, 16, v57
	v_add_u32_e32 v5, 64, v5
	v_cmp_lt_i32_e32 vcc, v4, v5
	s_nop 1
	v_cndmask_b32_e32 v4, v57, v4, vcc
	v_lshlrev_b32_e32 v6, 2, v4
	ds_bpermute_b32 v7, v6, v3
	v_xor_b32_e32 v4, 32, v57
	v_cmp_lt_i32_e32 vcc, v4, v5
	ds_bpermute_b32 v5, v6, v2
	ds_bpermute_b32 v24, v6, v0
	v_cndmask_b32_e32 v4, v57, v4, vcc
	v_lshlrev_b32_e32 v21, 2, v4
	s_waitcnt lgkmcnt(2)
	v_max_f32_e32 v4, v7, v7
	ds_bpermute_b32 v7, v6, v1
	v_max_f32_e32 v3, v3, v3
	s_waitcnt lgkmcnt(2)
	v_max_f32_e32 v5, v5, v5
	v_max_f32_e32 v2, v2, v2
	v_max_f32_e32 v1, v1, v1
	s_waitcnt lgkmcnt(0)
	v_max_f32_e32 v6, v7, v7
	v_max_f32_e32 v7, v24, v24
	v_max_f32_e32 v0, v0, v0
	v_max_f32_e32 v3, v3, v4
	v_max_f32_e32 v2, v2, v5
	v_max_f32_e32 v1, v1, v6
	v_max_f32_e32 v0, v0, v7
	ds_bpermute_b32 v4, v21, v3
	ds_bpermute_b32 v5, v21, v2
	ds_bpermute_b32 v6, v21, v1
	ds_bpermute_b32 v7, v21, v0
	s_and_saveexec_b64 s[14:15], s[4:5]
	s_cbranch_execz .LBB0_1803
	s_waitcnt lgkmcnt(0)
	v_max_f32_e32 v7, v7, v7
	v_max_f32_e32 v0, v0, v0
	v_max_f32_e32 v7, v0, v7
	v_max_f32_e32 v0, v6, v6
	v_max_f32_e32 v1, v1, v1
	v_max_f32_e32 v6, v1, v0
	v_max_f32_e32 v0, v5, v5
	v_max_f32_e32 v1, v2, v2
	v_max_f32_e32 v5, v1, v0
	v_max_f32_e32 v0, v4, v4
	v_max_f32_e32 v1, v3, v3
	v_max_f32_e32 v4, v1, v0
	v_add_u32_e32 v0, s90, v52
	ds_write_b128 v0, v[4:7]

.LBB0_1806:
	s_or_b32 s34, s0, s89
	v_or_b32_e32 v112, s34, v62
	v_ashrrev_i32_e32 v113, 31, v112
	v_lshl_add_u64 v[114:115], v[112:113], 2, s[16:17]
	global_load_dword v116, v[114:115], off
	v_or_b32_e32 v112, s34, v11
	v_ashrrev_i32_e32 v113, 31, v112
	v_lshl_add_u64 v[112:113], v[112:113], 2, s[16:17]
	global_load_dword v118, v[112:113], off
	v_or_b32_e32 v112, s34, v71
	v_ashrrev_i32_e32 v113, 31, v112
	v_lshl_add_u64 v[112:113], v[112:113], 2, s[16:17]
	global_load_dword v120, v[112:113], off
	v_or_b32_e32 v112, s34, v72
	v_ashrrev_i32_e32 v113, 31, v112
	v_lshl_add_u64 v[112:113], v[112:113], 2, s[16:17]
	global_load_dword v122, v[112:113], off
	v_or_b32_e32 v112, s34, v73
	v_ashrrev_i32_e32 v113, 31, v112
	v_lshl_add_u64 v[112:113], v[112:113], 2, s[16:17]
	global_load_dword v124, v[112:113], off
	v_or_b32_e32 v112, s34, v74
	v_ashrrev_i32_e32 v113, 31, v112
	v_lshl_add_u64 v[112:113], v[112:113], 2, s[16:17]
	global_load_dword v126, v[112:113], off
	v_or_b32_e32 v112, s34, v76
	v_ashrrev_i32_e32 v113, 31, v112
	v_lshl_add_u64 v[112:113], v[112:113], 2, s[16:17]
	global_load_dword v128, v[112:113], off
	v_or_b32_e32 v112, s34, v77
	v_ashrrev_i32_e32 v113, 31, v112
	v_lshl_add_u64 v[112:113], v[112:113], 2, s[16:17]
	global_load_dword v130, v[112:113], off
	v_or_b32_e32 v112, s34, v78
	v_ashrrev_i32_e32 v113, 31, v112
	v_lshl_add_u64 v[112:113], v[112:113], 2, s[16:17]
	global_load_dword v132, v[112:113], off
	v_or_b32_e32 v112, s34, v79
	v_ashrrev_i32_e32 v113, 31, v112
	v_lshl_add_u64 v[112:113], v[112:113], 2, s[16:17]
	global_load_dword v134, v[112:113], off
	v_or_b32_e32 v112, s34, v80
	v_ashrrev_i32_e32 v113, 31, v112
	v_lshl_add_u64 v[112:113], v[112:113], 2, s[16:17]
	global_load_dword v136, v[112:113], off
	v_or_b32_e32 v112, s34, v81
	v_ashrrev_i32_e32 v113, 31, v112
	v_lshl_add_u64 v[112:113], v[112:113], 2, s[16:17]
	global_load_dword v138, v[112:113], off
	v_or_b32_e32 v112, s34, v82
	v_ashrrev_i32_e32 v113, 31, v112
	v_lshl_add_u64 v[112:113], v[112:113], 2, s[16:17]
	global_load_dword v140, v[112:113], off
	v_or_b32_e32 v112, s34, v83
	v_ashrrev_i32_e32 v113, 31, v112
	v_lshl_add_u64 v[112:113], v[112:113], 2, s[16:17]
	global_load_dword v142, v[112:113], off
	v_or_b32_e32 v112, s34, v84
	v_ashrrev_i32_e32 v113, 31, v112
	v_lshl_add_u64 v[112:113], v[112:113], 2, s[16:17]
	global_load_dword v144, v[112:113], off
	v_or_b32_e32 v112, s34, v85
	v_ashrrev_i32_e32 v113, 31, v112
	v_lshl_add_u64 v[112:113], v[112:113], 2, s[16:17]
	global_load_dword v146, v[112:113], off
	v_or_b32_e32 v44, s34, v62
	v_mad_i64_i32 v[0:1], s[0:1], v44, s50, v[22:23]
	v_add_u32_e32 v21, v54, v55
	global_load_dwordx4 v[46:49], v[0:1], off nt
	v_or_b32_e32 v0, 4, v44
	v_mad_i64_i32 v[0:1], s[0:1], v0, s50, v[22:23]
	global_load_dwordx4 v[88:91], v[0:1], off nt
	v_add_u32_e32 v45, 0x410, v21
	v_or_b32_e32 v0, 8, v44
	v_mad_i64_i32 v[0:1], s[0:1], v0, s50, v[22:23]
	global_load_dwordx4 v[92:95], v[0:1], off nt
	v_or_b32_e32 v0, 12, v44
	v_mad_i64_i32 v[0:1], s[0:1], v0, s50, v[22:23]
	global_load_dwordx4 v[96:99], v[0:1], off nt
	v_or_b32_e32 v0, 16, v44
	v_mad_i64_i32 v[0:1], s[0:1], v0, s50, v[22:23]
	global_load_dwordx4 v[100:103], v[0:1], off nt
	v_or_b32_e32 v0, 20, v44
	v_mad_i64_i32 v[0:1], s[0:1], v0, s50, v[22:23]
	global_load_dwordx4 v[104:107], v[0:1], off nt
	v_or_b32_e32 v0, 24, v44
	v_mad_i64_i32 v[0:1], s[0:1], v0, s50, v[22:23]
	global_load_dwordx4 v[4:7], v[0:1], off nt
	v_or_b32_e32 v0, 28, v44
	v_mad_i64_i32 v[0:1], s[0:1], v0, s50, v[22:23]
	global_load_dwordx4 v[0:3], v[0:1], off nt
	s_ashr_i32 s35, s34, 31
	s_and_b64 vcc, exec, s[14:15]
	s_mov_b64 s[14:15], 0
	s_waitcnt vmcnt(23)
	v_pk_mul_f32 v[110:111], v[24:25], v[116:117] op_sel_hi:[1,0]
	s_waitcnt vmcnt(7)
	v_pk_mul_f32 v[46:47], v[46:47], v[110:111]
	ds_write2_b32 v21, v46, v47 offset1:1
	v_pk_mul_f32 v[46:47], v[26:27], v[116:117] op_sel_hi:[1,0]
	s_nop 0
	v_pk_mul_f32 v[46:47], v[48:49], v[46:47]
	ds_write2_b32 v21, v46, v47 offset0:2 offset1:3
	v_pk_mul_f32 v[48:49], v[24:25], v[118:119] op_sel_hi:[1,0]
	s_nop 0
	s_waitcnt vmcnt(6)
	v_pk_mul_f32 v[48:49], v[88:89], v[48:49]
	v_pk_mul_f32 v[46:47], v[26:27], v[118:119] op_sel_hi:[1,0]
	ds_write2_b32 v45, v48, v49 offset1:1
	v_pk_mul_f32 v[46:47], v[90:91], v[46:47]
	v_add_u32_e32 v45, 0x418, v21
	ds_write2_b32 v45, v46, v47 offset1:1
	v_add_u32_e32 v45, 0x820, v21
	v_pk_mul_f32 v[48:49], v[24:25], v[120:121] op_sel_hi:[1,0]
	s_nop 0
	s_waitcnt vmcnt(5)
	v_pk_mul_f32 v[48:49], v[92:93], v[48:49]
	v_pk_mul_f32 v[46:47], v[26:27], v[120:121] op_sel_hi:[1,0]
	ds_write2_b32 v45, v48, v49 offset1:1
	v_pk_mul_f32 v[46:47], v[94:95], v[46:47]
	v_add_u32_e32 v45, 0x828, v21
	ds_write2_b32 v45, v46, v47 offset1:1
	v_add_u32_e32 v45, 0xc30, v21
	v_pk_mul_f32 v[48:49], v[24:25], v[122:123] op_sel_hi:[1,0]
	s_nop 0
	s_waitcnt vmcnt(4)
	v_pk_mul_f32 v[48:49], v[96:97], v[48:49]
	v_pk_mul_f32 v[46:47], v[26:27], v[122:123] op_sel_hi:[1,0]
	ds_write2_b32 v45, v48, v49 offset1:1
	v_pk_mul_f32 v[46:47], v[98:99], v[46:47]
	v_add_u32_e32 v45, 0xc38, v21
	ds_write2_b32 v45, v46, v47 offset1:1
	v_add_u32_e32 v45, 0x1040, v21
	v_pk_mul_f32 v[48:49], v[24:25], v[124:125] op_sel_hi:[1,0]
	s_nop 0
	s_waitcnt vmcnt(3)
	v_pk_mul_f32 v[48:49], v[100:101], v[48:49]
	v_pk_mul_f32 v[46:47], v[26:27], v[124:125] op_sel_hi:[1,0]
	ds_write2_b32 v45, v48, v49 offset1:1
	v_pk_mul_f32 v[46:47], v[102:103], v[46:47]
	v_add_u32_e32 v45, 0x1048, v21
	ds_write2_b32 v45, v46, v47 offset1:1
	v_add_u32_e32 v21, 0x1450, v21
	v_pk_mul_f32 v[48:49], v[24:25], v[126:127] op_sel_hi:[1,0]
	s_nop 0
	s_waitcnt vmcnt(2)
	v_pk_mul_f32 v[48:49], v[104:105], v[48:49]
	v_pk_mul_f32 v[46:47], v[26:27], v[126:127] op_sel_hi:[1,0]
	ds_write2_b32 v21, v48, v49 offset1:1
	v_pk_mul_f32 v[46:47], v[106:107], v[46:47]
	v_add_u32_e32 v21, v54, v75
	ds_write2_b32 v21, v46, v47 offset0:2 offset1:3
	v_add_u32_e32 v45, 0x410, v21
	v_pk_mul_f32 v[48:49], v[24:25], v[128:129] op_sel_hi:[1,0]
	s_nop 0
	s_waitcnt vmcnt(1)
	v_pk_mul_f32 v[4:5], v[4:5], v[48:49]
	ds_write2_b32 v45, v4, v5 offset1:1
	v_pk_mul_f32 v[4:5], v[26:27], v[128:129] op_sel_hi:[1,0]
	v_or_b32_e32 v45, 40, v44
	v_pk_mul_f32 v[4:5], v[6:7], v[4:5]
	v_add_u32_e32 v6, 0x418, v21
	ds_write2_b32 v6, v4, v5 offset1:1
	v_mad_i64_i32 v[46:47], s[0:1], v45, s50, v[22:23]
	v_or_b32_e32 v45, 44, v44
	v_mad_i64_i32 v[88:89], s[0:1], v45, s50, v[22:23]
	v_or_b32_e32 v45, 48, v44
	v_mad_i64_i32 v[92:93], s[0:1], v45, s50, v[22:23]
	v_or_b32_e32 v45, 52, v44
	v_mad_i64_i32 v[96:97], s[0:1], v45, s50, v[22:23]
	v_or_b32_e32 v45, 56, v44
	v_mad_i64_i32 v[100:101], s[0:1], v45, s50, v[22:23]
	global_load_dwordx4 v[46:49], v[46:47], off nt
	v_pk_mul_f32 v[6:7], v[24:25], v[130:131] op_sel_hi:[1,0]
	s_nop 0
	s_waitcnt vmcnt(1)
	v_pk_mul_f32 v[0:1], v[0:1], v[6:7]
	v_add_u32_e32 v5, 0x820, v21
	ds_write2_b32 v5, v0, v1 offset1:1
	v_pk_mul_f32 v[0:1], v[26:27], v[130:131] op_sel_hi:[1,0]
	v_or_b32_e32 v4, 36, v44
	v_pk_mul_f32 v[0:1], v[2:3], v[0:1]
	v_add_u32_e32 v2, 0x828, v21
	ds_write2_b32 v2, v0, v1 offset1:1
	v_or_b32_e32 v0, 32, v44
	v_or_b32_e32 v44, 60, v44
	v_mad_i64_i32 v[44:45], s[0:1], v44, s50, v[22:23]
	global_load_dwordx4 v[104:107], v[44:45], off nt
	v_mad_i64_i32 v[0:1], s[0:1], v0, s50, v[22:23]
	v_mad_i64_i32 v[4:5], s[0:1], v4, s50, v[22:23]
	global_load_dwordx4 v[0:3], v[0:1], off nt
	s_mov_b32 s0, 64
	global_load_dwordx4 v[4:7], v[4:5], off nt
	v_pk_mul_f32 v[108:109], v[24:25], v[132:133] op_sel_hi:[1,0]
	v_add_u32_e32 v45, 0xc30, v21
	global_load_dwordx4 v[88:91], v[88:89], off nt
	s_waitcnt vmcnt(2)
	v_pk_mul_f32 v[0:1], v[0:1], v[108:109]
	ds_write2_b32 v45, v0, v1 offset1:1
	v_pk_mul_f32 v[0:1], v[26:27], v[132:133] op_sel_hi:[1,0]
	global_load_dwordx4 v[92:95], v[92:93], off nt
	v_pk_mul_f32 v[0:1], v[2:3], v[0:1]
	v_add_u32_e32 v2, 0xc38, v21
	ds_write2_b32 v2, v0, v1 offset1:1
	v_pk_mul_f32 v[2:3], v[24:25], v[134:135] op_sel_hi:[1,0]
	s_nop 0
	s_waitcnt vmcnt(2)
	v_pk_mul_f32 v[2:3], v[4:5], v[2:3]
	v_add_u32_e32 v1, 0x1040, v21
	ds_write2_b32 v1, v2, v3 offset1:1
	v_pk_mul_f32 v[0:1], v[26:27], v[134:135] op_sel_hi:[1,0]
	v_add_u32_e32 v2, 0x1048, v21
	v_pk_mul_f32 v[0:1], v[6:7], v[0:1]
	ds_write2_b32 v2, v0, v1 offset1:1
	v_pk_mul_f32 v[2:3], v[24:25], v[136:137] op_sel_hi:[1,0]
	s_nop 0
	v_pk_mul_f32 v[2:3], v[46:47], v[2:3]
	v_add_u32_e32 v1, 0x1450, v21
	ds_write2_b32 v1, v2, v3 offset1:1
	v_pk_mul_f32 v[0:1], v[26:27], v[136:137] op_sel_hi:[1,0]
	v_add_u32_e32 v2, 0x1458, v21
	v_pk_mul_f32 v[0:1], v[48:49], v[0:1]
	ds_write2_b32 v2, v0, v1 offset1:1
	v_pk_mul_f32 v[2:3], v[24:25], v[138:139] op_sel_hi:[1,0]
	s_nop 0
	s_waitcnt vmcnt(1)
	v_pk_mul_f32 v[2:3], v[88:89], v[2:3]
	v_add_u32_e32 v1, 0x1860, v21
	ds_write2_b32 v1, v2, v3 offset1:1
	v_pk_mul_f32 v[0:1], v[26:27], v[138:139] op_sel_hi:[1,0]
	v_add_u32_e32 v2, 0x1868, v21
	v_pk_mul_f32 v[0:1], v[90:91], v[0:1]
	ds_write2_b32 v2, v0, v1 offset1:1
	v_pk_mul_f32 v[2:3], v[24:25], v[140:141] op_sel_hi:[1,0]
	s_nop 0
	s_waitcnt vmcnt(0)
	v_pk_mul_f32 v[2:3], v[92:93], v[2:3]
	v_add_u32_e32 v1, 0x1c70, v21
	ds_write2_b32 v1, v2, v3 offset1:1
	v_pk_mul_f32 v[0:1], v[26:27], v[140:141] op_sel_hi:[1,0]
	v_add_u32_e32 v2, 0x1c78, v21
	v_pk_mul_f32 v[0:1], v[94:95], v[0:1]
	ds_write2_b32 v2, v0, v1 offset1:1
	v_pk_mul_f32 v[2:3], v[24:25], v[142:143] op_sel_hi:[1,0]
	global_load_dwordx4 v[96:99], v[96:97], off nt
	v_add_u32_e32 v1, 0x2080, v21
	global_load_dwordx4 v[100:103], v[100:101], off nt
	s_waitcnt vmcnt(1)
	v_pk_mul_f32 v[2:3], v[96:97], v[2:3]
	ds_write2_b32 v1, v2, v3 offset1:1
	v_pk_mul_f32 v[0:1], v[26:27], v[142:143] op_sel_hi:[1,0]
	v_add_u32_e32 v2, 0x2088, v21
	v_pk_mul_f32 v[0:1], v[98:99], v[0:1]
	ds_write2_b32 v2, v0, v1 offset1:1
	v_pk_mul_f32 v[2:3], v[24:25], v[144:145] op_sel_hi:[1,0]
	s_nop 0
	s_waitcnt vmcnt(0)
	v_pk_mul_f32 v[2:3], v[100:101], v[2:3]
	v_add_u32_e32 v1, 0x2490, v21
	ds_write2_b32 v1, v2, v3 offset1:1
	v_pk_mul_f32 v[0:1], v[26:27], v[144:145] op_sel_hi:[1,0]
	v_add_u32_e32 v2, 0x2498, v21
	v_pk_mul_f32 v[0:1], v[102:103], v[0:1]
	ds_write2_b32 v2, v0, v1 offset1:1
	v_pk_mul_f32 v[2:3], v[24:25], v[146:147] op_sel_hi:[1,0]
	s_nop 0
	v_pk_mul_f32 v[2:3], v[104:105], v[2:3]
	v_add_u32_e32 v1, 0x28a0, v21
	ds_write2_b32 v1, v2, v3 offset1:1
	v_pk_mul_f32 v[0:1], v[26:27], v[146:147] op_sel_hi:[1,0]
	v_add_u32_e32 v2, 0x28a8, v21
	v_pk_mul_f32 v[0:1], v[106:107], v[0:1]
	ds_write2_b32 v2, v0, v1 offset1:1
	s_waitcnt lgkmcnt(0)
	ds_read2_b32 v[6:7], v9 offset0:130 offset1:138
	ds_read2_b32 v[44:45], v9 offset0:195 offset1:203
	ds_read2_b32 v[2:3], v9 offset1:8
	ds_read2_b32 v[4:5], v9 offset0:65 offset1:73
	v_lshl_add_u64 v[0:1], v[12:13], 0, s[34:35]
	s_waitcnt lgkmcnt(3)
	v_med3_f32 v6, v6, s52, v58
	s_waitcnt lgkmcnt(2)
	v_med3_f32 v21, v44, s52, v58
	v_add_f32_e32 v6, 0x4b400000, v6
	v_add_f32_e32 v21, 0x4b400000, v21
	v_perm_b32 v6, v21, v6, s53
	v_add_u32_e32 v21, 0x400, v9
	ds_read2_b32 v[48:49], v21 offset0:4 offset1:12
	ds_read2_b32 v[88:89], v21 offset0:69 offset1:77
	ds_read2_b32 v[90:91], v21 offset0:134 offset1:142
	ds_read2_b32 v[92:93], v21 offset0:199 offset1:207
	s_waitcnt lgkmcnt(5)
	v_med3_f32 v2, v2, s52, v58
	s_waitcnt lgkmcnt(4)
	v_med3_f32 v4, v4, s52, v58
	v_add_f32_e32 v2, 0x4b400000, v2
	v_add_f32_e32 v4, 0x4b400000, v4
	v_perm_b32 v2, v4, v2, s53
	v_perm_b32 v46, v6, v2, s54
	s_waitcnt lgkmcnt(3)
	v_med3_f32 v2, v48, s52, v58
	s_waitcnt lgkmcnt(2)
	v_med3_f32 v4, v88, s52, v58
	s_waitcnt lgkmcnt(1)
	v_med3_f32 v6, v90, s52, v58
	s_waitcnt lgkmcnt(0)
	v_med3_f32 v44, v92, s52, v58
	v_add_f32_e32 v2, 0x4b400000, v2
	v_add_f32_e32 v4, 0x4b400000, v4
	v_add_f32_e32 v6, 0x4b400000, v6
	v_add_f32_e32 v44, 0x4b400000, v44
	v_perm_b32 v6, v44, v6, s53
	v_perm_b32 v2, v4, v2, s53
	v_perm_b32 v47, v6, v2, s54
	v_med3_f32 v2, v3, s52, v58
	v_med3_f32 v3, v5, s52, v58
	v_med3_f32 v4, v7, s52, v58
	v_med3_f32 v5, v45, s52, v58
	v_add_f32_e32 v2, 0x4b400000, v2
	v_add_f32_e32 v3, 0x4b400000, v3
	v_add_f32_e32 v4, 0x4b400000, v4
	v_add_f32_e32 v5, 0x4b400000, v5
	v_perm_b32 v4, v5, v4, s53
	v_perm_b32 v2, v3, v2, s53
	v_perm_b32 v2, v4, v2, s54
	v_med3_f32 v3, v49, s52, v58
	v_med3_f32 v4, v89, s52, v58
	v_med3_f32 v5, v91, s52, v58
	v_med3_f32 v6, v93, s52, v58
	v_add_f32_e32 v3, 0x4b400000, v3
	v_add_f32_e32 v4, 0x4b400000, v4
	v_add_f32_e32 v5, 0x4b400000, v5
	v_add_f32_e32 v6, 0x4b400000, v6
	v_perm_b32 v5, v6, v5, s53
	v_perm_b32 v3, v4, v3, s53
	v_perm_b32 v3, v5, v3, s54
	v_lshl_add_u64 v[4:5], v[0:1], 0, v[28:29]
	global_store_dwordx2 v[4:5], v[2:3], off
	ds_read2_b32 v[2:3], v9 offset0:16 offset1:24
	ds_read2_b32 v[4:5], v9 offset0:81 offset1:89
	ds_read2_b32 v[6:7], v9 offset0:146 offset1:154
	ds_read2_b32 v[44:45], v9 offset0:211 offset1:219
	ds_read2_b32 v[48:49], v21 offset0:20 offset1:28
	ds_read2_b32 v[88:89], v21 offset0:85 offset1:93
	ds_read2_b32 v[90:91], v21 offset0:150 offset1:158
	ds_read2_b32 v[92:93], v21 offset0:215 offset1:223
	s_waitcnt lgkmcnt(7)
	v_med3_f32 v2, v2, s52, v58
	s_waitcnt lgkmcnt(6)
	v_med3_f32 v4, v4, s52, v58
	s_waitcnt lgkmcnt(5)
	v_med3_f32 v6, v6, s52, v58
	s_waitcnt lgkmcnt(4)
	v_med3_f32 v44, v44, s52, v58
	v_add_f32_e32 v2, 0x4b400000, v2
	v_add_f32_e32 v4, 0x4b400000, v4
	v_add_f32_e32 v6, 0x4b400000, v6
	v_add_f32_e32 v44, 0x4b400000, v44
	v_lshl_add_u64 v[94:95], v[0:1], 0, v[36:37]
	v_perm_b32 v6, v44, v6, s53
	v_perm_b32 v2, v4, v2, s53
	global_store_dwordx2 v[94:95], v[46:47], off
	v_perm_b32 v46, v6, v2, s54
	s_waitcnt lgkmcnt(3)
	v_med3_f32 v2, v48, s52, v58
	s_waitcnt lgkmcnt(2)
	v_med3_f32 v4, v88, s52, v58
	s_waitcnt lgkmcnt(1)
	v_med3_f32 v6, v90, s52, v58
	s_waitcnt lgkmcnt(0)
	v_med3_f32 v44, v92, s52, v58
	v_add_f32_e32 v2, 0x4b400000, v2
	v_add_f32_e32 v4, 0x4b400000, v4
	v_add_f32_e32 v6, 0x4b400000, v6
	v_add_f32_e32 v44, 0x4b400000, v44
	v_perm_b32 v6, v44, v6, s53
	v_perm_b32 v2, v4, v2, s53
	v_perm_b32 v47, v6, v2, s54
	v_med3_f32 v2, v3, s52, v58
	v_med3_f32 v3, v5, s52, v58
	v_med3_f32 v4, v7, s52, v58
	v_med3_f32 v5, v45, s52, v58
	v_add_f32_e32 v2, 0x4b400000, v2
	v_add_f32_e32 v3, 0x4b400000, v3
	v_add_f32_e32 v4, 0x4b400000, v4
	v_add_f32_e32 v5, 0x4b400000, v5
	v_perm_b32 v4, v5, v4, s53
	v_perm_b32 v2, v3, v2, s53
	v_perm_b32 v2, v4, v2, s54
	v_med3_f32 v3, v49, s52, v58
	v_med3_f32 v4, v89, s52, v58
	v_med3_f32 v5, v91, s52, v58
	v_med3_f32 v6, v93, s52, v58
	v_add_f32_e32 v3, 0x4b400000, v3
	v_add_f32_e32 v4, 0x4b400000, v4
	v_add_f32_e32 v5, 0x4b400000, v5
	v_add_f32_e32 v6, 0x4b400000, v6
	v_perm_b32 v5, v6, v5, s53
	v_perm_b32 v3, v4, v3, s53
	v_perm_b32 v3, v5, v3, s54
	v_lshl_add_u64 v[4:5], v[0:1], 0, v[32:33]
	global_store_dwordx2 v[4:5], v[2:3], off
	ds_read2_b32 v[2:3], v9 offset0:32 offset1:40
	ds_read2_b32 v[4:5], v9 offset0:97 offset1:105
	ds_read2_b32 v[6:7], v9 offset0:162 offset1:170
	ds_read2_b32 v[44:45], v9 offset0:227 offset1:235
	ds_read2_b32 v[48:49], v21 offset0:36 offset1:44
	ds_read2_b32 v[88:89], v21 offset0:101 offset1:109
	ds_read2_b32 v[90:91], v21 offset0:166 offset1:174
	ds_read2_b32 v[92:93], v21 offset0:231 offset1:239
	s_waitcnt lgkmcnt(7)
	v_med3_f32 v2, v2, s52, v58
	s_waitcnt lgkmcnt(6)
	v_med3_f32 v4, v4, s52, v58
	s_waitcnt lgkmcnt(5)
	v_med3_f32 v6, v6, s52, v58
	s_waitcnt lgkmcnt(4)
	v_med3_f32 v44, v44, s52, v58
	v_add_f32_e32 v2, 0x4b400000, v2
	v_add_f32_e32 v4, 0x4b400000, v4
	v_add_f32_e32 v6, 0x4b400000, v6
	v_add_f32_e32 v44, 0x4b400000, v44
	v_lshl_add_u64 v[94:95], v[0:1], 0, v[30:31]
	v_perm_b32 v6, v44, v6, s53
	v_perm_b32 v2, v4, v2, s53
	global_store_dwordx2 v[94:95], v[46:47], off
	v_perm_b32 v46, v6, v2, s54
	s_waitcnt lgkmcnt(3)
	v_med3_f32 v2, v48, s52, v58
	s_waitcnt lgkmcnt(2)
	v_med3_f32 v4, v88, s52, v58
	s_waitcnt lgkmcnt(1)
	v_med3_f32 v6, v90, s52, v58
	s_waitcnt lgkmcnt(0)
	v_med3_f32 v44, v92, s52, v58
	v_add_f32_e32 v2, 0x4b400000, v2
	v_add_f32_e32 v4, 0x4b400000, v4
	v_add_f32_e32 v6, 0x4b400000, v6
	v_add_f32_e32 v44, 0x4b400000, v44
	v_perm_b32 v6, v44, v6, s53
	v_perm_b32 v2, v4, v2, s53
	v_perm_b32 v47, v6, v2, s54
	v_med3_f32 v2, v3, s52, v58
	v_med3_f32 v3, v5, s52, v58
	v_med3_f32 v4, v7, s52, v58
	v_med3_f32 v5, v45, s52, v58
	v_add_f32_e32 v2, 0x4b400000, v2
	v_add_f32_e32 v3, 0x4b400000, v3
	v_add_f32_e32 v4, 0x4b400000, v4
	v_add_f32_e32 v5, 0x4b400000, v5
	v_perm_b32 v4, v5, v4, s53
	v_perm_b32 v2, v3, v2, s53
	v_perm_b32 v2, v4, v2, s54
	v_med3_f32 v3, v49, s52, v58
	v_med3_f32 v4, v89, s52, v58
	v_med3_f32 v5, v91, s52, v58
	v_med3_f32 v6, v93, s52, v58
	v_add_f32_e32 v3, 0x4b400000, v3
	v_add_f32_e32 v4, 0x4b400000, v4
	v_add_f32_e32 v5, 0x4b400000, v5
	v_add_f32_e32 v6, 0x4b400000, v6
	v_perm_b32 v5, v6, v5, s53
	v_perm_b32 v3, v4, v3, s53
	v_perm_b32 v3, v5, v3, s54
	v_lshl_add_u64 v[4:5], v[0:1], 0, v[38:39]
	global_store_dwordx2 v[4:5], v[2:3], off
	ds_read2_b32 v[2:3], v9 offset0:48 offset1:56
	ds_read2_b32 v[4:5], v9 offset0:113 offset1:121
	ds_read2_b32 v[6:7], v9 offset0:178 offset1:186
	ds_read2_b32 v[44:45], v9 offset0:243 offset1:251
	ds_read2_b32 v[48:49], v21 offset0:52 offset1:60
	ds_read2_b32 v[88:89], v21 offset0:117 offset1:125
	ds_read2_b32 v[90:91], v21 offset0:182 offset1:190
	ds_read2_b32 v[92:93], v21 offset0:247 offset1:255
	s_waitcnt lgkmcnt(7)
	v_med3_f32 v2, v2, s52, v58
	s_waitcnt lgkmcnt(6)
	v_med3_f32 v4, v4, s52, v58
	s_waitcnt lgkmcnt(5)
	v_med3_f32 v6, v6, s52, v58
	s_waitcnt lgkmcnt(4)
	v_med3_f32 v44, v44, s52, v58
	v_add_f32_e32 v2, 0x4b400000, v2
	v_add_f32_e32 v4, 0x4b400000, v4
	v_add_f32_e32 v6, 0x4b400000, v6
	v_add_f32_e32 v44, 0x4b400000, v44
	v_lshl_add_u64 v[94:95], v[0:1], 0, v[34:35]
	v_perm_b32 v6, v44, v6, s53
	v_perm_b32 v2, v4, v2, s53
	global_store_dwordx2 v[94:95], v[46:47], off
	v_perm_b32 v46, v6, v2, s54
	s_waitcnt lgkmcnt(3)
	v_med3_f32 v2, v48, s52, v58
	s_waitcnt lgkmcnt(2)
	v_med3_f32 v4, v88, s52, v58
	s_waitcnt lgkmcnt(1)
	v_med3_f32 v6, v90, s52, v58
	s_waitcnt lgkmcnt(0)
	v_med3_f32 v21, v92, s52, v58
	v_add_f32_e32 v2, 0x4b400000, v2
	v_add_f32_e32 v4, 0x4b400000, v4
	v_add_f32_e32 v6, 0x4b400000, v6
	v_add_f32_e32 v21, 0x4b400000, v21
	v_perm_b32 v6, v21, v6, s53
	v_perm_b32 v2, v4, v2, s53
	v_perm_b32 v47, v6, v2, s54
	v_med3_f32 v2, v3, s52, v58
	v_med3_f32 v3, v5, s52, v58
	v_med3_f32 v4, v7, s52, v58
	v_med3_f32 v5, v45, s52, v58
	v_add_f32_e32 v2, 0x4b400000, v2
	v_add_f32_e32 v3, 0x4b400000, v3
	v_add_f32_e32 v4, 0x4b400000, v4
	v_add_f32_e32 v5, 0x4b400000, v5
	v_perm_b32 v4, v5, v4, s53
	v_perm_b32 v2, v3, v2, s53
	v_perm_b32 v2, v4, v2, s54
	v_med3_f32 v3, v49, s52, v58
	v_med3_f32 v4, v89, s52, v58
	v_med3_f32 v5, v91, s52, v58
	v_med3_f32 v6, v93, s52, v58
	v_add_f32_e32 v3, 0x4b400000, v3
	v_add_f32_e32 v4, 0x4b400000, v4
	v_add_f32_e32 v5, 0x4b400000, v5
	v_add_f32_e32 v6, 0x4b400000, v6
	v_perm_b32 v5, v6, v5, s53
	v_perm_b32 v3, v4, v3, s53
	v_lshl_add_u64 v[94:95], v[0:1], 0, v[40:41]
	v_perm_b32 v3, v5, v3, s54
	v_lshl_add_u64 v[0:1], v[0:1], 0, v[42:43]
	global_store_dwordx2 v[94:95], v[46:47], off
	global_store_dwordx2 v[0:1], v[2:3], off
	s_waitcnt lgkmcnt(0)
	s_cbranch_vccnz .LBB0_1806
	s_barrier

.LBB0_1810:
	v_or_b32_e32 v110, s0, v86
	v_ashrrev_i32_e32 v111, 31, v110
	v_lshl_add_u64 v[112:113], v[110:111], 2, s[12:13]
	global_load_dword v114, v[112:113], off
	v_or_b32_e32 v110, s0, v86
	v_or_b32_e32 v112, 4, v110
	v_ashrrev_i32_e32 v113, 31, v112
	v_lshl_add_u64 v[110:111], v[112:113], 2, s[12:13]
	global_load_dword v116, v[110:111], off
	v_or_b32_e32 v110, s0, v86
	v_or_b32_e32 v112, 8, v110
	v_ashrrev_i32_e32 v113, 31, v112
	v_lshl_add_u64 v[110:111], v[112:113], 2, s[12:13]
	global_load_dword v118, v[110:111], off
	v_or_b32_e32 v110, s0, v86
	v_or_b32_e32 v112, 12, v110
	v_ashrrev_i32_e32 v113, 31, v112
	v_lshl_add_u64 v[110:111], v[112:113], 2, s[12:13]
	global_load_dword v120, v[110:111], off
	v_or_b32_e32 v110, s0, v86
	v_or_b32_e32 v112, 16, v110
	v_ashrrev_i32_e32 v113, 31, v112
	v_lshl_add_u64 v[110:111], v[112:113], 2, s[12:13]
	global_load_dword v122, v[110:111], off
	v_or_b32_e32 v110, s0, v86
	v_or_b32_e32 v112, 20, v110
	v_ashrrev_i32_e32 v113, 31, v112
	v_lshl_add_u64 v[110:111], v[112:113], 2, s[12:13]
	global_load_dword v124, v[110:111], off
	v_or_b32_e32 v110, s0, v86
	v_or_b32_e32 v112, 24, v110
	v_ashrrev_i32_e32 v113, 31, v112
	v_lshl_add_u64 v[110:111], v[112:113], 2, s[12:13]
	global_load_dword v126, v[110:111], off
	v_or_b32_e32 v110, s0, v86
	v_or_b32_e32 v112, 28, v110
	v_ashrrev_i32_e32 v113, 31, v112
	v_lshl_add_u64 v[110:111], v[112:113], 2, s[12:13]
	global_load_dword v128, v[110:111], off
	v_or_b32_e32 v110, s0, v86
	v_or_b32_e32 v112, 32, v110
	v_ashrrev_i32_e32 v113, 31, v112
	v_lshl_add_u64 v[112:113], v[112:113], 2, s[12:13]
	global_load_dword v130, v[112:113], off
	v_or_b32_e32 v110, s0, v86
	v_or_b32_e32 v112, 36, v110
	v_ashrrev_i32_e32 v113, 31, v112
	v_lshl_add_u64 v[110:111], v[112:113], 2, s[12:13]
	global_load_dword v132, v[110:111], off
	v_or_b32_e32 v110, s0, v86
	v_or_b32_e32 v112, 40, v110
	v_ashrrev_i32_e32 v113, 31, v112
	v_lshl_add_u64 v[110:111], v[112:113], 2, s[12:13]
	global_load_dword v134, v[110:111], off
	v_or_b32_e32 v110, s0, v86
	v_or_b32_e32 v112, 44, v110
	v_ashrrev_i32_e32 v113, 31, v112
	v_lshl_add_u64 v[110:111], v[112:113], 2, s[12:13]
	global_load_dword v136, v[110:111], off
	v_or_b32_e32 v110, s0, v86
	v_or_b32_e32 v112, 48, v110
	v_ashrrev_i32_e32 v113, 31, v112
	v_lshl_add_u64 v[110:111], v[112:113], 2, s[12:13]
	global_load_dword v138, v[110:111], off
	v_or_b32_e32 v110, s0, v86
	v_or_b32_e32 v112, 52, v110
	v_ashrrev_i32_e32 v113, 31, v112
	v_lshl_add_u64 v[110:111], v[112:113], 2, s[12:13]
	global_load_dword v140, v[110:111], off
	v_or_b32_e32 v110, s0, v86
	v_or_b32_e32 v112, 56, v110
	v_ashrrev_i32_e32 v113, 31, v112
	v_lshl_add_u64 v[110:111], v[112:113], 2, s[12:13]
	global_load_dword v142, v[110:111], off
	v_or_b32_e32 v110, s0, v86
	v_or_b32_e32 v110, 60, v110
	v_ashrrev_i32_e32 v111, 31, v110
	v_lshl_add_u64 v[112:113], v[110:111], 2, s[12:13]
	global_load_dword v144, v[112:113], off
	v_or_b32_e32 v92, s0, v86
	v_cndmask_b32_e64 v4, 0, 1, s[14:15]
	v_cmp_ne_u32_e32 vcc, 1, v4
	v_mad_i64_i32 v[4:5], s[0:1], v92, s55, v[22:23]
	global_load_dwordx4 v[4:7], v[4:5], off
	v_or_b32_e32 v94, 4, v92
	v_mad_i64_i32 v[24:25], s[0:1], v94, s55, v[22:23]
	global_load_dwordx4 v[24:27], v[24:25], off
	v_or_b32_e32 v96, 8, v92
	v_mad_i64_i32 v[28:29], s[0:1], v96, s55, v[22:23]
	global_load_dwordx4 v[28:31], v[28:29], off
	v_or_b32_e32 v98, 12, v92
	v_mad_i64_i32 v[32:33], s[0:1], v98, s55, v[22:23]
	global_load_dwordx4 v[32:35], v[32:33], off
	v_or_b32_e32 v100, 16, v92
	v_mad_i64_i32 v[38:39], s[0:1], v100, s55, v[22:23]
	global_load_dwordx4 v[38:41], v[38:39], off
	v_or_b32_e32 v102, 20, v92
	v_mad_i64_i32 v[42:43], s[0:1], v102, s55, v[22:23]
	global_load_dwordx4 v[42:45], v[42:43], off
	v_or_b32_e32 v104, 24, v92
	v_mad_i64_i32 v[46:47], s[0:1], v104, s55, v[22:23]
	global_load_dwordx4 v[46:49], v[46:47], off
	v_or_b32_e32 v106, 28, v92
	v_mad_i64_i32 v[88:89], s[0:1], v106, s55, v[22:23]
	global_load_dwordx4 v[88:91], v[88:89], off
	s_mov_b64 s[14:15], 0
	s_and_b64 vcc, exec, vcc
	s_waitcnt vmcnt(7)
	v_mul_f32_e32 v36, v4, v114
	v_mul_f32_e32 v87, v5, v114
	v_mul_f32_e32 v6, v6, v114
	v_mul_f32_e32 v7, v7, v114
	v_or_b32_e32 v94, 40, v92
	s_waitcnt vmcnt(6)
	v_mul_f32_e32 v5, v24, v116
	v_max3_f32 v3, v3, |v36|, |v5|
	v_mul_f32_e32 v5, v25, v116
	v_max3_f32 v2, v2, |v87|, |v5|
	v_mul_f32_e32 v5, v26, v116
	v_max3_f32 v5, v1, |v6|, |v5|
	v_mul_f32_e32 v1, v27, v116
	v_max3_f32 v4, v0, |v7|, |v1|
	v_or_b32_e32 v96, 44, v92
	s_waitcnt vmcnt(5)
	v_mul_f32_e32 v6, v28, v118
	v_mul_f32_e32 v7, v29, v118
	v_mul_f32_e32 v21, v30, v118
	v_mul_f32_e32 v24, v31, v118
	v_or_b32_e32 v98, 48, v92
	v_mad_i64_i32 v[28:29], s[0:1], v96, s55, v[22:23]
	global_load_dwordx4 v[28:31], v[28:29], off
	s_waitcnt vmcnt(5)
	v_mul_f32_e32 v1, v32, v120
	v_max3_f32 v3, v3, |v6|, |v1|
	v_mul_f32_e32 v1, v33, v120
	v_max3_f32 v2, v2, |v7|, |v1|
	v_mul_f32_e32 v1, v34, v120
	v_mul_f32_e32 v0, v35, v120
	v_max3_f32 v5, v5, |v21|, |v1|
	v_max3_f32 v4, v4, |v24|, |v0|
	v_mad_i64_i32 v[32:33], s[0:1], v98, s55, v[22:23]
	global_load_dwordx4 v[32:35], v[32:33], off
	v_or_b32_e32 v100, 52, v92
	s_waitcnt vmcnt(5)
	v_mul_f32_e32 v6, v38, v122
	v_mul_f32_e32 v7, v39, v122
	v_mul_f32_e32 v21, v40, v122
	v_mul_f32_e32 v24, v41, v122
	v_mad_i64_i32 v[38:39], s[0:1], v100, s55, v[22:23]
	global_load_dwordx4 v[38:41], v[38:39], off
	v_or_b32_e32 v102, 56, v92
	s_waitcnt vmcnt(5)
	v_mul_f32_e32 v1, v42, v124
	v_max3_f32 v3, v3, |v6|, |v1|
	v_mul_f32_e32 v1, v43, v124
	v_max3_f32 v2, v2, |v7|, |v1|
	v_mul_f32_e32 v1, v44, v124
	v_mul_f32_e32 v0, v45, v124
	v_max3_f32 v5, v5, |v21|, |v1|
	v_max3_f32 v4, v4, |v24|, |v0|
	v_mad_i64_i32 v[42:43], s[0:1], v102, s55, v[22:23]
	global_load_dwordx4 v[42:45], v[42:43], off
	s_waitcnt vmcnt(5)
	v_mul_f32_e32 v6, v46, v126
	v_mul_f32_e32 v7, v47, v126
	v_mul_f32_e32 v21, v48, v126
	v_mul_f32_e32 v24, v49, v126
	s_waitcnt vmcnt(4)
	v_mul_f32_e32 v1, v88, v128
	v_max3_f32 v36, v3, |v6|, |v1|
	v_mul_f32_e32 v1, v89, v128
	v_or_b32_e32 v88, 32, v92
	v_max3_f32 v87, v2, |v7|, |v1|
	v_mul_f32_e32 v1, v90, v128
	v_mul_f32_e32 v0, v91, v128
	v_max3_f32 v21, v5, |v21|, |v1|
	v_max3_f32 v104, v4, |v24|, |v0|
	v_mad_i64_i32 v[0:1], s[0:1], v88, s55, v[22:23]
	global_load_dwordx4 v[0:3], v[0:1], off
	v_or_b32_e32 v90, 36, v92
	v_mad_i64_i32 v[4:5], s[0:1], v90, s55, v[22:23]
	global_load_dwordx4 v[4:7], v[4:5], off
	v_mad_i64_i32 v[24:25], s[0:1], v94, s55, v[22:23]
	global_load_dwordx4 v[24:27], v[24:25], off
	v_or_b32_e32 v92, 60, v92
	v_mad_i64_i32 v[46:47], s[0:1], v92, s55, v[22:23]
	global_load_dwordx4 v[46:49], v[46:47], off
	s_mov_b32 s0, 64
	s_waitcnt vmcnt(3)
	v_mul_f32_e32 v89, v0, v130
	v_mul_f32_e32 v105, v1, v130
	v_mul_f32_e32 v2, v2, v130
	v_mul_f32_e32 v3, v3, v130
	s_waitcnt vmcnt(2)
	v_mul_f32_e32 v1, v4, v132
	v_max3_f32 v4, v36, |v89|, |v1|
	v_mul_f32_e32 v1, v5, v132
	v_max3_f32 v5, v87, |v105|, |v1|
	v_mul_f32_e32 v1, v6, v132
	v_mul_f32_e32 v0, v7, v132
	v_max3_f32 v2, v21, |v2|, |v1|
	v_max3_f32 v3, v104, |v3|, |v0|
	s_waitcnt vmcnt(1)
	v_mul_f32_e32 v6, v24, v134
	v_mul_f32_e32 v7, v25, v134
	v_mul_f32_e32 v21, v26, v134
	v_mul_f32_e32 v24, v27, v134
	v_mul_f32_e32 v1, v28, v136
	v_max3_f32 v4, v4, |v6|, |v1|
	v_mul_f32_e32 v1, v29, v136
	v_max3_f32 v5, v5, |v7|, |v1|
	v_mul_f32_e32 v1, v30, v136
	v_mul_f32_e32 v0, v31, v136
	v_max3_f32 v2, v2, |v21|, |v1|
	v_max3_f32 v3, v3, |v24|, |v0|
	v_mul_f32_e32 v6, v32, v138
	v_mul_f32_e32 v7, v33, v138
	v_mul_f32_e32 v21, v34, v138
	v_mul_f32_e32 v24, v35, v138
	v_mul_f32_e32 v1, v38, v140
	v_max3_f32 v4, v4, |v6|, |v1|
	v_mul_f32_e32 v1, v39, v140
	v_max3_f32 v5, v5, |v7|, |v1|
	v_mul_f32_e32 v1, v40, v140
	v_mul_f32_e32 v0, v41, v140
	v_max3_f32 v6, v2, |v21|, |v1|
	v_max3_f32 v7, v3, |v24|, |v0|
	v_mul_f32_e32 v2, v42, v142
	v_mul_f32_e32 v21, v43, v142
	v_mul_f32_e32 v24, v44, v142
	v_mul_f32_e32 v25, v45, v142
	s_waitcnt vmcnt(0)
	v_mul_f32_e32 v1, v46, v144
	v_max3_f32 v3, v4, |v2|, |v1|
	v_mul_f32_e32 v1, v47, v144
	v_max3_f32 v2, v5, |v21|, |v1|
	v_mul_f32_e32 v1, v48, v144
	v_mul_f32_e32 v0, v49, v144
	v_max3_f32 v1, v6, |v24|, |v1|
	v_max3_f32 v0, v7, |v25|, |v0|
	s_cbranch_vccz .LBB0_1810
	v_and_b32_e32 v5, 64, v57
	v_xor_b32_e32 v4, 16, v57
	v_add_u32_e32 v5, 64, v5
	v_cmp_lt_i32_e32 vcc, v4, v5
	s_nop 1
	v_cndmask_b32_e32 v4, v57, v4, vcc
	v_lshlrev_b32_e32 v6, 2, v4
	ds_bpermute_b32 v7, v6, v3
	v_xor_b32_e32 v4, 32, v57
	v_cmp_lt_i32_e32 vcc, v4, v5
	ds_bpermute_b32 v5, v6, v2
	ds_bpermute_b32 v24, v6, v0
	v_cndmask_b32_e32 v4, v57, v4, vcc
	v_lshlrev_b32_e32 v21, 2, v4
	s_waitcnt lgkmcnt(2)
	v_max_f32_e32 v4, v7, v7
	ds_bpermute_b32 v7, v6, v1
	v_max_f32_e32 v3, v3, v3
	s_waitcnt lgkmcnt(2)
	v_max_f32_e32 v5, v5, v5
	v_max_f32_e32 v2, v2, v2
	v_max_f32_e32 v1, v1, v1
	s_waitcnt lgkmcnt(0)
	v_max_f32_e32 v6, v7, v7
	v_max_f32_e32 v7, v24, v24
	v_max_f32_e32 v0, v0, v0
	v_max_f32_e32 v3, v3, v4
	v_max_f32_e32 v2, v2, v5
	v_max_f32_e32 v1, v1, v6
	v_max_f32_e32 v0, v0, v7
	ds_bpermute_b32 v4, v21, v3
	ds_bpermute_b32 v5, v21, v2
	ds_bpermute_b32 v6, v21, v1
	ds_bpermute_b32 v7, v21, v0
	s_and_saveexec_b64 s[14:15], s[4:5]
	s_cbranch_execz .LBB0_1813
	s_waitcnt lgkmcnt(0)
	v_max_f32_e32 v7, v7, v7
	v_max_f32_e32 v0, v0, v0
	v_max_f32_e32 v7, v0, v7
	v_max_f32_e32 v0, v6, v6
	v_max_f32_e32 v1, v1, v1
	v_max_f32_e32 v6, v1, v0
	v_max_f32_e32 v0, v5, v5
	v_max_f32_e32 v1, v2, v2
	v_max_f32_e32 v5, v1, v0
	v_max_f32_e32 v0, v4, v4
	v_max_f32_e32 v1, v3, v3
	v_max_f32_e32 v4, v1, v0
	v_add_u32_e32 v0, s90, v52
	ds_write_b128 v0, v[4:7]

.LBB0_1816:
	s_or_b32 s34, s0, s89
	v_or_b32_e32 v112, s34, v62
	v_ashrrev_i32_e32 v113, 31, v112
	v_lshl_add_u64 v[114:115], v[112:113], 2, s[12:13]
	global_load_dword v116, v[114:115], off
	v_or_b32_e32 v112, s34, v11
	v_ashrrev_i32_e32 v113, 31, v112
	v_lshl_add_u64 v[112:113], v[112:113], 2, s[12:13]
	global_load_dword v118, v[112:113], off
	v_or_b32_e32 v112, s34, v71
	v_ashrrev_i32_e32 v113, 31, v112
	v_lshl_add_u64 v[112:113], v[112:113], 2, s[12:13]
	global_load_dword v120, v[112:113], off
	v_or_b32_e32 v112, s34, v72
	v_ashrrev_i32_e32 v113, 31, v112
	v_lshl_add_u64 v[112:113], v[112:113], 2, s[12:13]
	global_load_dword v122, v[112:113], off
	v_or_b32_e32 v112, s34, v73
	v_ashrrev_i32_e32 v113, 31, v112
	v_lshl_add_u64 v[112:113], v[112:113], 2, s[12:13]
	global_load_dword v124, v[112:113], off
	v_or_b32_e32 v112, s34, v74
	v_ashrrev_i32_e32 v113, 31, v112
	v_lshl_add_u64 v[112:113], v[112:113], 2, s[12:13]
	global_load_dword v126, v[112:113], off
	v_or_b32_e32 v112, s34, v76
	v_ashrrev_i32_e32 v113, 31, v112
	v_lshl_add_u64 v[112:113], v[112:113], 2, s[12:13]
	global_load_dword v128, v[112:113], off
	v_or_b32_e32 v112, s34, v77
	v_ashrrev_i32_e32 v113, 31, v112
	v_lshl_add_u64 v[112:113], v[112:113], 2, s[12:13]
	global_load_dword v130, v[112:113], off
	v_or_b32_e32 v46, s34, v62
	v_mad_i64_i32 v[0:1], s[0:1], v46, s55, v[22:23]
	global_load_dwordx4 v[88:91], v[0:1], off nt
	v_add_u32_e32 v21, v54, v55
	v_or_b32_e32 v0, 4, v46
	v_mad_i64_i32 v[0:1], s[0:1], v0, s55, v[22:23]
	global_load_dwordx4 v[92:95], v[0:1], off nt
	v_add_u32_e32 v47, 0x410, v21
	v_or_b32_e32 v0, 8, v46
	v_mad_i64_i32 v[0:1], s[0:1], v0, s55, v[22:23]
	global_load_dwordx4 v[96:99], v[0:1], off nt
	v_or_b32_e32 v0, 12, v46
	v_mad_i64_i32 v[0:1], s[0:1], v0, s55, v[22:23]
	global_load_dwordx4 v[100:103], v[0:1], off nt
	v_or_b32_e32 v0, 16, v46
	v_mad_i64_i32 v[0:1], s[0:1], v0, s55, v[22:23]
	global_load_dwordx4 v[104:107], v[0:1], off nt
	v_or_b32_e32 v0, 20, v46
	v_mad_i64_i32 v[0:1], s[0:1], v0, s55, v[22:23]
	global_load_dwordx4 v[108:111], v[0:1], off nt
	v_or_b32_e32 v0, 24, v46
	v_mad_i64_i32 v[0:1], s[0:1], v0, s55, v[22:23]
	global_load_dwordx4 v[4:7], v[0:1], off nt
	v_or_b32_e32 v0, 28, v46
	v_mad_i64_i32 v[0:1], s[0:1], v0, s55, v[22:23]
	global_load_dwordx4 v[0:3], v[0:1], off nt
	s_ashr_i32 s35, s34, 31
	s_and_b64 vcc, exec, s[14:15]
	s_mov_b64 s[14:15], 0
	s_waitcnt vmcnt(15)
	v_pk_mul_f32 v[48:49], v[24:25], v[116:117] op_sel_hi:[1,0]
	s_waitcnt vmcnt(7)
	v_pk_mul_f32 v[48:49], v[88:89], v[48:49]
	ds_write2_b32 v21, v48, v49 offset1:1
	v_pk_mul_f32 v[48:49], v[26:27], v[116:117] op_sel_hi:[1,0]
	s_nop 0
	v_pk_mul_f32 v[48:49], v[90:91], v[48:49]
	ds_write2_b32 v21, v48, v49 offset0:2 offset1:3
	v_pk_mul_f32 v[48:49], v[24:25], v[118:119] op_sel_hi:[1,0]
	s_nop 0
	s_waitcnt vmcnt(6)
	v_pk_mul_f32 v[48:49], v[92:93], v[48:49]
	ds_write2_b32 v47, v48, v49 offset1:1
	v_pk_mul_f32 v[48:49], v[26:27], v[118:119] op_sel_hi:[1,0]
	v_add_u32_e32 v36, 0x418, v21
	v_pk_mul_f32 v[48:49], v[94:95], v[48:49]
	ds_write2_b32 v36, v48, v49 offset1:1
	v_add_u32_e32 v47, 0x820, v21
	v_pk_mul_f32 v[48:49], v[24:25], v[120:121] op_sel_hi:[1,0]
	s_nop 0
	s_waitcnt vmcnt(5)
	v_pk_mul_f32 v[48:49], v[96:97], v[48:49]
	ds_write2_b32 v47, v48, v49 offset1:1
	v_pk_mul_f32 v[48:49], v[26:27], v[120:121] op_sel_hi:[1,0]
	v_add_u32_e32 v36, 0x828, v21
	v_pk_mul_f32 v[48:49], v[98:99], v[48:49]
	ds_write2_b32 v36, v48, v49 offset1:1
	v_add_u32_e32 v47, 0xc30, v21
	v_pk_mul_f32 v[48:49], v[24:25], v[122:123] op_sel_hi:[1,0]
	s_nop 0
	s_waitcnt vmcnt(4)
	v_pk_mul_f32 v[48:49], v[100:101], v[48:49]
	ds_write2_b32 v47, v48, v49 offset1:1
	v_pk_mul_f32 v[48:49], v[26:27], v[122:123] op_sel_hi:[1,0]
	v_add_u32_e32 v36, 0xc38, v21
	v_pk_mul_f32 v[48:49], v[102:103], v[48:49]
	ds_write2_b32 v36, v48, v49 offset1:1
	v_add_u32_e32 v47, 0x1040, v21
	v_pk_mul_f32 v[48:49], v[24:25], v[124:125] op_sel_hi:[1,0]
	s_nop 0
	s_waitcnt vmcnt(3)
	v_pk_mul_f32 v[48:49], v[104:105], v[48:49]
	ds_write2_b32 v47, v48, v49 offset1:1
	v_pk_mul_f32 v[48:49], v[26:27], v[124:125] op_sel_hi:[1,0]
	v_add_u32_e32 v36, 0x1048, v21
	v_pk_mul_f32 v[48:49], v[106:107], v[48:49]
	ds_write2_b32 v36, v48, v49 offset1:1
	v_add_u32_e32 v21, 0x1450, v21
	v_pk_mul_f32 v[48:49], v[24:25], v[126:127] op_sel_hi:[1,0]
	s_nop 0
	s_waitcnt vmcnt(2)
	v_pk_mul_f32 v[48:49], v[108:109], v[48:49]
	ds_write2_b32 v21, v48, v49 offset1:1
	v_pk_mul_f32 v[48:49], v[26:27], v[126:127] op_sel_hi:[1,0]
	v_add_u32_e32 v21, v54, v75
	v_pk_mul_f32 v[48:49], v[110:111], v[48:49]
	ds_write2_b32 v21, v48, v49 offset0:2 offset1:3
	v_add_u32_e32 v47, 0x410, v21
	v_or_b32_e32 v108, s34, v78
	v_ashrrev_i32_e32 v109, 31, v108
	v_lshl_add_u64 v[108:109], v[108:109], 2, s[12:13]
	global_load_dword v132, v[108:109], off
	v_or_b32_e32 v112, s34, v79
	v_ashrrev_i32_e32 v113, 31, v112
	v_lshl_add_u64 v[112:113], v[112:113], 2, s[12:13]
	global_load_dword v134, v[112:113], off
	v_or_b32_e32 v112, s34, v80
	v_ashrrev_i32_e32 v113, 31, v112
	v_lshl_add_u64 v[112:113], v[112:113], 2, s[12:13]
	global_load_dword v136, v[112:113], off
	v_or_b32_e32 v112, s34, v81
	v_ashrrev_i32_e32 v113, 31, v112
	v_lshl_add_u64 v[112:113], v[112:113], 2, s[12:13]
	global_load_dword v138, v[112:113], off
	v_or_b32_e32 v112, s34, v82
	v_ashrrev_i32_e32 v113, 31, v112
	v_lshl_add_u64 v[112:113], v[112:113], 2, s[12:13]
	global_load_dword v140, v[112:113], off
	v_or_b32_e32 v112, s34, v83
	v_ashrrev_i32_e32 v113, 31, v112
	v_lshl_add_u64 v[112:113], v[112:113], 2, s[12:13]
	global_load_dword v142, v[112:113], off
	v_or_b32_e32 v112, s34, v84
	v_ashrrev_i32_e32 v113, 31, v112
	v_lshl_add_u64 v[112:113], v[112:113], 2, s[12:13]
	global_load_dword v144, v[112:113], off
	v_or_b32_e32 v112, s34, v85
	v_ashrrev_i32_e32 v113, 31, v112
	v_lshl_add_u64 v[112:113], v[112:113], 2, s[12:13]
	global_load_dword v146, v[112:113], off
	v_add_u32_e32 v87, 0xc30, v21
	v_pk_mul_f32 v[48:49], v[24:25], v[128:129] op_sel_hi:[1,0]
	s_nop 0
	s_waitcnt vmcnt(9)
	v_pk_mul_f32 v[4:5], v[4:5], v[48:49]
	ds_write2_b32 v47, v4, v5 offset1:1
	v_pk_mul_f32 v[4:5], v[26:27], v[128:129] op_sel_hi:[1,0]
	v_or_b32_e32 v36, 40, v46
	v_pk_mul_f32 v[4:5], v[6:7], v[4:5]
	v_add_u32_e32 v6, 0x418, v21
	ds_write2_b32 v6, v4, v5 offset1:1
	v_mad_i64_i32 v[48:49], s[0:1], v36, s55, v[22:23]
	v_or_b32_e32 v36, 44, v46
	global_load_dwordx4 v[88:91], v[48:49], off nt
	v_mad_i64_i32 v[48:49], s[0:1], v36, s55, v[22:23]
	v_or_b32_e32 v36, 48, v46
	global_load_dwordx4 v[92:95], v[48:49], off nt
	v_mad_i64_i32 v[48:49], s[0:1], v36, s55, v[22:23]
	v_or_b32_e32 v36, 52, v46
	global_load_dwordx4 v[96:99], v[48:49], off nt
	v_mad_i64_i32 v[48:49], s[0:1], v36, s55, v[22:23]
	v_or_b32_e32 v36, 56, v46
	global_load_dwordx4 v[100:103], v[48:49], off nt
	v_mad_i64_i32 v[48:49], s[0:1], v36, s55, v[22:23]
	v_or_b32_e32 v36, 60, v46
	global_load_dwordx4 v[104:107], v[48:49], off nt
	v_pk_mul_f32 v[6:7], v[24:25], v[130:131] op_sel_hi:[1,0]
	s_nop 0
	s_waitcnt vmcnt(13)
	v_pk_mul_f32 v[0:1], v[0:1], v[6:7]
	v_add_u32_e32 v5, 0x820, v21
	ds_write2_b32 v5, v0, v1 offset1:1
	v_pk_mul_f32 v[0:1], v[26:27], v[130:131] op_sel_hi:[1,0]
	v_or_b32_e32 v4, 36, v46
	v_pk_mul_f32 v[0:1], v[2:3], v[0:1]
	v_add_u32_e32 v2, 0x828, v21
	ds_write2_b32 v2, v0, v1 offset1:1
	v_or_b32_e32 v0, 32, v46
	v_mad_i64_i32 v[0:1], s[0:1], v0, s55, v[22:23]
	v_mad_i64_i32 v[46:47], s[0:1], v36, s55, v[22:23]
	v_mad_i64_i32 v[4:5], s[0:1], v4, s55, v[22:23]
	global_load_dwordx4 v[0:3], v[0:1], off nt
	s_mov_b32 s0, 64
	global_load_dwordx4 v[4:7], v[4:5], off nt
	s_waitcnt vmcnt(14)
	v_pk_mul_f32 v[108:109], v[24:25], v[132:133] op_sel_hi:[1,0]
	global_load_dwordx4 v[46:49], v[46:47], off nt
	s_waitcnt vmcnt(2)
	v_pk_mul_f32 v[0:1], v[0:1], v[108:109]
	ds_write2_b32 v87, v0, v1 offset1:1
	v_pk_mul_f32 v[0:1], v[26:27], v[132:133] op_sel_hi:[1,0]
	s_nop 0
	v_pk_mul_f32 v[0:1], v[2:3], v[0:1]
	v_add_u32_e32 v2, 0xc38, v21
	ds_write2_b32 v2, v0, v1 offset1:1
	v_pk_mul_f32 v[2:3], v[24:25], v[134:135] op_sel_hi:[1,0]
	s_nop 0
	s_waitcnt vmcnt(1)
	v_pk_mul_f32 v[2:3], v[4:5], v[2:3]
	v_add_u32_e32 v1, 0x1040, v21
	ds_write2_b32 v1, v2, v3 offset1:1
	v_pk_mul_f32 v[0:1], v[26:27], v[134:135] op_sel_hi:[1,0]
	v_add_u32_e32 v2, 0x1048, v21
	v_pk_mul_f32 v[0:1], v[6:7], v[0:1]
	ds_write2_b32 v2, v0, v1 offset1:1
	v_pk_mul_f32 v[2:3], v[24:25], v[136:137] op_sel_hi:[1,0]
	s_nop 0
	v_pk_mul_f32 v[2:3], v[88:89], v[2:3]
	v_add_u32_e32 v1, 0x1450, v21
	ds_write2_b32 v1, v2, v3 offset1:1
	v_pk_mul_f32 v[0:1], v[26:27], v[136:137] op_sel_hi:[1,0]
	v_add_u32_e32 v2, 0x1458, v21
	v_pk_mul_f32 v[0:1], v[90:91], v[0:1]
	ds_write2_b32 v2, v0, v1 offset1:1
	v_pk_mul_f32 v[2:3], v[24:25], v[138:139] op_sel_hi:[1,0]
	s_nop 0
	v_pk_mul_f32 v[2:3], v[92:93], v[2:3]
	v_add_u32_e32 v1, 0x1860, v21
	ds_write2_b32 v1, v2, v3 offset1:1
	v_pk_mul_f32 v[0:1], v[26:27], v[138:139] op_sel_hi:[1,0]
	v_add_u32_e32 v2, 0x1868, v21
	v_pk_mul_f32 v[0:1], v[94:95], v[0:1]
	ds_write2_b32 v2, v0, v1 offset1:1
	v_pk_mul_f32 v[2:3], v[24:25], v[140:141] op_sel_hi:[1,0]
	s_nop 0
	v_pk_mul_f32 v[2:3], v[96:97], v[2:3]
	v_add_u32_e32 v1, 0x1c70, v21
	ds_write2_b32 v1, v2, v3 offset1:1
	v_pk_mul_f32 v[0:1], v[26:27], v[140:141] op_sel_hi:[1,0]
	v_add_u32_e32 v2, 0x1c78, v21
	v_pk_mul_f32 v[0:1], v[98:99], v[0:1]
	ds_write2_b32 v2, v0, v1 offset1:1
	v_pk_mul_f32 v[2:3], v[24:25], v[142:143] op_sel_hi:[1,0]
	s_nop 0
	v_pk_mul_f32 v[2:3], v[100:101], v[2:3]
	v_add_u32_e32 v1, 0x2080, v21
	ds_write2_b32 v1, v2, v3 offset1:1
	v_pk_mul_f32 v[0:1], v[26:27], v[142:143] op_sel_hi:[1,0]
	v_add_u32_e32 v2, 0x2088, v21
	v_pk_mul_f32 v[0:1], v[102:103], v[0:1]
	ds_write2_b32 v2, v0, v1 offset1:1
	v_pk_mul_f32 v[2:3], v[24:25], v[144:145] op_sel_hi:[1,0]
	s_nop 0
	v_pk_mul_f32 v[2:3], v[104:105], v[2:3]
	v_add_u32_e32 v1, 0x2490, v21
	ds_write2_b32 v1, v2, v3 offset1:1
	v_pk_mul_f32 v[0:1], v[26:27], v[144:145] op_sel_hi:[1,0]
	v_add_u32_e32 v2, 0x2498, v21
	v_pk_mul_f32 v[0:1], v[106:107], v[0:1]
	ds_write2_b32 v2, v0, v1 offset1:1
	v_pk_mul_f32 v[2:3], v[24:25], v[146:147] op_sel_hi:[1,0]
	s_nop 0
	s_waitcnt vmcnt(0)
	v_pk_mul_f32 v[2:3], v[46:47], v[2:3]
	v_add_u32_e32 v1, 0x28a0, v21
	ds_write2_b32 v1, v2, v3 offset1:1
	v_pk_mul_f32 v[0:1], v[26:27], v[146:147] op_sel_hi:[1,0]
	v_add_u32_e32 v2, 0x28a8, v21
	v_pk_mul_f32 v[0:1], v[48:49], v[0:1]
	ds_write2_b32 v2, v0, v1 offset1:1
	s_waitcnt lgkmcnt(0)
	ds_read2_b32 v[6:7], v9 offset0:130 offset1:138
	ds_read2_b32 v[46:47], v9 offset0:195 offset1:203
	ds_read2_b32 v[2:3], v9 offset1:8
	ds_read2_b32 v[4:5], v9 offset0:65 offset1:73
	v_lshl_add_u64 v[0:1], v[14:15], 0, s[34:35]
	s_waitcnt lgkmcnt(3)
	v_med3_f32 v6, v6, s52, v58
	s_waitcnt lgkmcnt(2)
	v_med3_f32 v21, v46, s52, v58
	v_add_f32_e32 v6, 0x4b400000, v6
	v_add_f32_e32 v21, 0x4b400000, v21
	v_perm_b32 v6, v21, v6, s53
	v_add_u32_e32 v21, 0x400, v9
	ds_read2_b32 v[88:89], v21 offset0:4 offset1:12
	ds_read2_b32 v[90:91], v21 offset0:69 offset1:77
	ds_read2_b32 v[92:93], v21 offset0:134 offset1:142
	ds_read2_b32 v[94:95], v21 offset0:199 offset1:207
	s_waitcnt lgkmcnt(5)
	v_med3_f32 v2, v2, s52, v58
	s_waitcnt lgkmcnt(4)
	v_med3_f32 v4, v4, s52, v58
	v_add_f32_e32 v2, 0x4b400000, v2
	v_add_f32_e32 v4, 0x4b400000, v4
	v_perm_b32 v2, v4, v2, s53
	v_perm_b32 v48, v6, v2, s54
	s_waitcnt lgkmcnt(3)
	v_med3_f32 v2, v88, s52, v58
	s_waitcnt lgkmcnt(2)
	v_med3_f32 v4, v90, s52, v58
	s_waitcnt lgkmcnt(1)
	v_med3_f32 v6, v92, s52, v58
	s_waitcnt lgkmcnt(0)
	v_med3_f32 v36, v94, s52, v58
	v_add_f32_e32 v2, 0x4b400000, v2
	v_add_f32_e32 v4, 0x4b400000, v4
	v_add_f32_e32 v6, 0x4b400000, v6
	v_add_f32_e32 v36, 0x4b400000, v36
	v_perm_b32 v6, v36, v6, s53
	v_perm_b32 v2, v4, v2, s53
	v_perm_b32 v49, v6, v2, s54
	v_med3_f32 v2, v3, s52, v58
	v_med3_f32 v3, v5, s52, v58
	v_med3_f32 v4, v7, s52, v58
	v_med3_f32 v5, v47, s52, v58
	v_add_f32_e32 v2, 0x4b400000, v2
	v_add_f32_e32 v3, 0x4b400000, v3
	v_add_f32_e32 v4, 0x4b400000, v4
	v_add_f32_e32 v5, 0x4b400000, v5
	v_perm_b32 v4, v5, v4, s53
	v_perm_b32 v2, v3, v2, s53
	v_perm_b32 v2, v4, v2, s54
	v_med3_f32 v3, v89, s52, v58
	v_med3_f32 v4, v91, s52, v58
	v_med3_f32 v5, v93, s52, v58
	v_med3_f32 v6, v95, s52, v58
	v_add_f32_e32 v3, 0x4b400000, v3
	v_add_f32_e32 v4, 0x4b400000, v4
	v_add_f32_e32 v5, 0x4b400000, v5
	v_add_f32_e32 v6, 0x4b400000, v6
	v_perm_b32 v5, v6, v5, s53
	v_perm_b32 v3, v4, v3, s53
	v_perm_b32 v3, v5, v3, s54
	v_lshl_add_u64 v[4:5], v[0:1], 0, v[30:31]
	global_store_dwordx2 v[4:5], v[2:3], off
	ds_read2_b32 v[2:3], v9 offset0:16 offset1:24
	ds_read2_b32 v[4:5], v9 offset0:81 offset1:89
	ds_read2_b32 v[6:7], v9 offset0:146 offset1:154
	ds_read2_b32 v[46:47], v9 offset0:211 offset1:219
	ds_read2_b32 v[88:89], v21 offset0:20 offset1:28
	ds_read2_b32 v[90:91], v21 offset0:85 offset1:93
	ds_read2_b32 v[92:93], v21 offset0:150 offset1:158
	ds_read2_b32 v[94:95], v21 offset0:215 offset1:223
	s_waitcnt lgkmcnt(7)
	v_med3_f32 v2, v2, s52, v58
	s_waitcnt lgkmcnt(6)
	v_med3_f32 v4, v4, s52, v58
	s_waitcnt lgkmcnt(5)
	v_med3_f32 v6, v6, s52, v58
	s_waitcnt lgkmcnt(4)
	v_med3_f32 v36, v46, s52, v58
	v_add_f32_e32 v2, 0x4b400000, v2
	v_add_f32_e32 v4, 0x4b400000, v4
	v_add_f32_e32 v6, 0x4b400000, v6
	v_add_f32_e32 v36, 0x4b400000, v36
	v_lshl_add_u64 v[96:97], v[0:1], 0, v[28:29]
	v_perm_b32 v6, v36, v6, s53
	v_perm_b32 v2, v4, v2, s53
	global_store_dwordx2 v[96:97], v[48:49], off
	v_perm_b32 v48, v6, v2, s54
	s_waitcnt lgkmcnt(3)
	v_med3_f32 v2, v88, s52, v58
	s_waitcnt lgkmcnt(2)
	v_med3_f32 v4, v90, s52, v58
	s_waitcnt lgkmcnt(1)
	v_med3_f32 v6, v92, s52, v58
	s_waitcnt lgkmcnt(0)
	v_med3_f32 v36, v94, s52, v58
	v_add_f32_e32 v2, 0x4b400000, v2
	v_add_f32_e32 v4, 0x4b400000, v4
	v_add_f32_e32 v6, 0x4b400000, v6
	v_add_f32_e32 v36, 0x4b400000, v36
	v_perm_b32 v6, v36, v6, s53
	v_perm_b32 v2, v4, v2, s53
	v_perm_b32 v49, v6, v2, s54
	v_med3_f32 v2, v3, s52, v58
	v_med3_f32 v3, v5, s52, v58
	v_med3_f32 v4, v7, s52, v58
	v_med3_f32 v5, v47, s52, v58
	v_add_f32_e32 v2, 0x4b400000, v2
	v_add_f32_e32 v3, 0x4b400000, v3
	v_add_f32_e32 v4, 0x4b400000, v4
	v_add_f32_e32 v5, 0x4b400000, v5
	v_perm_b32 v4, v5, v4, s53
	v_perm_b32 v2, v3, v2, s53
	v_perm_b32 v2, v4, v2, s54
	v_med3_f32 v3, v89, s52, v58
	v_med3_f32 v4, v91, s52, v58
	v_med3_f32 v5, v93, s52, v58
	v_med3_f32 v6, v95, s52, v58
	v_add_f32_e32 v3, 0x4b400000, v3
	v_add_f32_e32 v4, 0x4b400000, v4
	v_add_f32_e32 v5, 0x4b400000, v5
	v_add_f32_e32 v6, 0x4b400000, v6
	v_perm_b32 v5, v6, v5, s53
	v_perm_b32 v3, v4, v3, s53
	v_perm_b32 v3, v5, v3, s54
	v_lshl_add_u64 v[4:5], v[0:1], 0, v[34:35]
	global_store_dwordx2 v[4:5], v[2:3], off
	ds_read2_b32 v[2:3], v9 offset0:32 offset1:40
	ds_read2_b32 v[4:5], v9 offset0:97 offset1:105
	ds_read2_b32 v[6:7], v9 offset0:162 offset1:170
	ds_read2_b32 v[46:47], v9 offset0:227 offset1:235
	ds_read2_b32 v[88:89], v21 offset0:36 offset1:44
	ds_read2_b32 v[90:91], v21 offset0:101 offset1:109
	ds_read2_b32 v[92:93], v21 offset0:166 offset1:174
	ds_read2_b32 v[94:95], v21 offset0:231 offset1:239
	s_waitcnt lgkmcnt(7)
	v_med3_f32 v2, v2, s52, v58
	s_waitcnt lgkmcnt(6)
	v_med3_f32 v4, v4, s52, v58
	s_waitcnt lgkmcnt(5)
	v_med3_f32 v6, v6, s52, v58
	s_waitcnt lgkmcnt(4)
	v_med3_f32 v36, v46, s52, v58
	v_add_f32_e32 v2, 0x4b400000, v2
	v_add_f32_e32 v4, 0x4b400000, v4
	v_add_f32_e32 v6, 0x4b400000, v6
	v_add_f32_e32 v36, 0x4b400000, v36
	v_lshl_add_u64 v[96:97], v[0:1], 0, v[32:33]
	v_perm_b32 v6, v36, v6, s53
	v_perm_b32 v2, v4, v2, s53
	global_store_dwordx2 v[96:97], v[48:49], off
	v_perm_b32 v48, v6, v2, s54
	s_waitcnt lgkmcnt(3)
	v_med3_f32 v2, v88, s52, v58
	s_waitcnt lgkmcnt(2)
	v_med3_f32 v4, v90, s52, v58
	s_waitcnt lgkmcnt(1)
	v_med3_f32 v6, v92, s52, v58
	s_waitcnt lgkmcnt(0)
	v_med3_f32 v36, v94, s52, v58
	v_add_f32_e32 v2, 0x4b400000, v2
	v_add_f32_e32 v4, 0x4b400000, v4
	v_add_f32_e32 v6, 0x4b400000, v6
	v_add_f32_e32 v36, 0x4b400000, v36
	v_perm_b32 v6, v36, v6, s53
	v_perm_b32 v2, v4, v2, s53
	v_perm_b32 v49, v6, v2, s54
	v_med3_f32 v2, v3, s52, v58
	v_med3_f32 v3, v5, s52, v58
	v_med3_f32 v4, v7, s52, v58
	v_med3_f32 v5, v47, s52, v58
	v_add_f32_e32 v2, 0x4b400000, v2
	v_add_f32_e32 v3, 0x4b400000, v3
	v_add_f32_e32 v4, 0x4b400000, v4
	v_add_f32_e32 v5, 0x4b400000, v5
	v_perm_b32 v4, v5, v4, s53
	v_perm_b32 v2, v3, v2, s53
	v_perm_b32 v2, v4, v2, s54
	v_med3_f32 v3, v89, s52, v58
	v_med3_f32 v4, v91, s52, v58
	v_med3_f32 v5, v93, s52, v58
	v_med3_f32 v6, v95, s52, v58
	v_add_f32_e32 v3, 0x4b400000, v3
	v_add_f32_e32 v4, 0x4b400000, v4
	v_add_f32_e32 v5, 0x4b400000, v5
	v_add_f32_e32 v6, 0x4b400000, v6
	v_perm_b32 v5, v6, v5, s53
	v_perm_b32 v3, v4, v3, s53
	v_perm_b32 v3, v5, v3, s54
	v_lshl_add_u64 v[4:5], v[0:1], 0, v[40:41]
	global_store_dwordx2 v[4:5], v[2:3], off
	ds_read2_b32 v[2:3], v9 offset0:48 offset1:56
	ds_read2_b32 v[4:5], v9 offset0:113 offset1:121
	ds_read2_b32 v[6:7], v9 offset0:178 offset1:186
	ds_read2_b32 v[46:47], v9 offset0:243 offset1:251
	ds_read2_b32 v[88:89], v21 offset0:52 offset1:60
	ds_read2_b32 v[90:91], v21 offset0:117 offset1:125
	ds_read2_b32 v[92:93], v21 offset0:182 offset1:190
	ds_read2_b32 v[94:95], v21 offset0:247 offset1:255
	s_waitcnt lgkmcnt(7)
	v_med3_f32 v2, v2, s52, v58
	s_waitcnt lgkmcnt(6)
	v_med3_f32 v4, v4, s52, v58
	s_waitcnt lgkmcnt(5)
	v_med3_f32 v6, v6, s52, v58
	s_waitcnt lgkmcnt(4)
	v_med3_f32 v36, v46, s52, v58
	v_add_f32_e32 v2, 0x4b400000, v2
	v_add_f32_e32 v4, 0x4b400000, v4
	v_add_f32_e32 v6, 0x4b400000, v6
	v_add_f32_e32 v36, 0x4b400000, v36
	v_lshl_add_u64 v[96:97], v[0:1], 0, v[38:39]
	v_perm_b32 v6, v36, v6, s53
	v_perm_b32 v2, v4, v2, s53
	global_store_dwordx2 v[96:97], v[48:49], off
	v_perm_b32 v48, v6, v2, s54
	s_waitcnt lgkmcnt(3)
	v_med3_f32 v2, v88, s52, v58
	s_waitcnt lgkmcnt(2)
	v_med3_f32 v4, v90, s52, v58
	s_waitcnt lgkmcnt(1)
	v_med3_f32 v6, v92, s52, v58
	s_waitcnt lgkmcnt(0)
	v_med3_f32 v21, v94, s52, v58
	v_add_f32_e32 v2, 0x4b400000, v2
	v_add_f32_e32 v4, 0x4b400000, v4
	v_add_f32_e32 v6, 0x4b400000, v6
	v_add_f32_e32 v21, 0x4b400000, v21
	v_perm_b32 v6, v21, v6, s53
	v_perm_b32 v2, v4, v2, s53
	v_perm_b32 v49, v6, v2, s54
	v_med3_f32 v2, v3, s52, v58
	v_med3_f32 v3, v5, s52, v58
	v_med3_f32 v4, v7, s52, v58
	v_med3_f32 v5, v47, s52, v58
	v_add_f32_e32 v2, 0x4b400000, v2
	v_add_f32_e32 v3, 0x4b400000, v3
	v_add_f32_e32 v4, 0x4b400000, v4
	v_add_f32_e32 v5, 0x4b400000, v5
	v_perm_b32 v4, v5, v4, s53
	v_perm_b32 v2, v3, v2, s53
	v_perm_b32 v2, v4, v2, s54
	v_med3_f32 v3, v89, s52, v58
	v_med3_f32 v4, v91, s52, v58
	v_med3_f32 v5, v93, s52, v58
	v_med3_f32 v6, v95, s52, v58
	v_add_f32_e32 v3, 0x4b400000, v3
	v_add_f32_e32 v4, 0x4b400000, v4
	v_add_f32_e32 v5, 0x4b400000, v5
	v_add_f32_e32 v6, 0x4b400000, v6
	v_perm_b32 v5, v6, v5, s53
	v_perm_b32 v3, v4, v3, s53
	v_lshl_add_u64 v[96:97], v[0:1], 0, v[42:43]
	v_perm_b32 v3, v5, v3, s54
	v_lshl_add_u64 v[0:1], v[0:1], 0, v[44:45]
	global_store_dwordx2 v[96:97], v[48:49], off
	global_store_dwordx2 v[0:1], v[2:3], off
	s_waitcnt lgkmcnt(0)
	s_cbranch_vccnz .LBB0_1816
	s_barrier

.LBB0_1834:
	v_or_b32_e32 v110, s1, v86
	v_ashrrev_i32_e32 v111, 31, v110
	v_lshl_add_u64 v[112:113], v[110:111], 2, s[12:13]
	global_load_dword v114, v[112:113], off
	v_or_b32_e32 v110, s1, v86
	v_or_b32_e32 v112, 4, v110
	v_ashrrev_i32_e32 v113, 31, v112
	v_lshl_add_u64 v[110:111], v[112:113], 2, s[12:13]
	global_load_dword v116, v[110:111], off
	v_or_b32_e32 v110, s1, v86
	v_or_b32_e32 v112, 8, v110
	v_ashrrev_i32_e32 v113, 31, v112
	v_lshl_add_u64 v[110:111], v[112:113], 2, s[12:13]
	global_load_dword v118, v[110:111], off
	v_or_b32_e32 v110, s1, v86
	v_or_b32_e32 v112, 12, v110
	v_ashrrev_i32_e32 v113, 31, v112
	v_lshl_add_u64 v[110:111], v[112:113], 2, s[12:13]
	global_load_dword v120, v[110:111], off
	v_or_b32_e32 v110, s1, v86
	v_or_b32_e32 v112, 16, v110
	v_ashrrev_i32_e32 v113, 31, v112
	v_lshl_add_u64 v[110:111], v[112:113], 2, s[12:13]
	global_load_dword v122, v[110:111], off
	v_or_b32_e32 v110, s1, v86
	v_or_b32_e32 v112, 20, v110
	v_ashrrev_i32_e32 v113, 31, v112
	v_lshl_add_u64 v[110:111], v[112:113], 2, s[12:13]
	global_load_dword v124, v[110:111], off
	v_or_b32_e32 v110, s1, v86
	v_or_b32_e32 v112, 24, v110
	v_ashrrev_i32_e32 v113, 31, v112
	v_lshl_add_u64 v[110:111], v[112:113], 2, s[12:13]
	global_load_dword v126, v[110:111], off
	v_or_b32_e32 v110, s1, v86
	v_or_b32_e32 v112, 28, v110
	v_ashrrev_i32_e32 v113, 31, v112
	v_lshl_add_u64 v[110:111], v[112:113], 2, s[12:13]
	global_load_dword v128, v[110:111], off
	v_or_b32_e32 v110, s1, v86
	v_or_b32_e32 v112, 32, v110
	v_ashrrev_i32_e32 v113, 31, v112
	v_lshl_add_u64 v[112:113], v[112:113], 2, s[12:13]
	global_load_dword v130, v[112:113], off
	v_or_b32_e32 v110, s1, v86
	v_or_b32_e32 v112, 36, v110
	v_ashrrev_i32_e32 v113, 31, v112
	v_lshl_add_u64 v[110:111], v[112:113], 2, s[12:13]
	global_load_dword v132, v[110:111], off
	v_or_b32_e32 v110, s1, v86
	v_or_b32_e32 v112, 40, v110
	v_ashrrev_i32_e32 v113, 31, v112
	v_lshl_add_u64 v[110:111], v[112:113], 2, s[12:13]
	global_load_dword v134, v[110:111], off
	v_or_b32_e32 v110, s1, v86
	v_or_b32_e32 v112, 44, v110
	v_ashrrev_i32_e32 v113, 31, v112
	v_lshl_add_u64 v[110:111], v[112:113], 2, s[12:13]
	global_load_dword v136, v[110:111], off
	v_or_b32_e32 v110, s1, v86
	v_or_b32_e32 v112, 48, v110
	v_ashrrev_i32_e32 v113, 31, v112
	v_lshl_add_u64 v[110:111], v[112:113], 2, s[12:13]
	global_load_dword v138, v[110:111], off
	v_or_b32_e32 v110, s1, v86
	v_or_b32_e32 v112, 52, v110
	v_ashrrev_i32_e32 v113, 31, v112
	v_lshl_add_u64 v[110:111], v[112:113], 2, s[12:13]
	global_load_dword v140, v[110:111], off
	v_or_b32_e32 v110, s1, v86
	v_or_b32_e32 v112, 56, v110
	v_ashrrev_i32_e32 v113, 31, v112
	v_lshl_add_u64 v[110:111], v[112:113], 2, s[12:13]
	global_load_dword v142, v[110:111], off
	v_or_b32_e32 v110, s1, v86
	v_or_b32_e32 v110, 60, v110
	v_ashrrev_i32_e32 v111, 31, v110
	v_lshl_add_u64 v[112:113], v[110:111], 2, s[12:13]
	global_load_dword v144, v[112:113], off
	v_or_b32_e32 v92, s1, v86
	v_cndmask_b32_e64 v4, 0, 1, s[14:15]
	v_cmp_ne_u32_e32 vcc, 1, v4
	v_mad_i64_i32 v[4:5], s[2:3], v92, s55, v[22:23]
	global_load_dwordx4 v[4:7], v[4:5], off
	v_or_b32_e32 v94, 4, v92
	v_mad_i64_i32 v[24:25], s[2:3], v94, s55, v[22:23]
	global_load_dwordx4 v[24:27], v[24:25], off
	v_or_b32_e32 v96, 8, v92
	v_mad_i64_i32 v[28:29], s[2:3], v96, s55, v[22:23]
	global_load_dwordx4 v[28:31], v[28:29], off
	v_or_b32_e32 v98, 12, v92
	v_mad_i64_i32 v[32:33], s[2:3], v98, s55, v[22:23]
	global_load_dwordx4 v[32:35], v[32:33], off
	v_or_b32_e32 v100, 16, v92
	v_mad_i64_i32 v[38:39], s[2:3], v100, s55, v[22:23]
	global_load_dwordx4 v[38:41], v[38:39], off
	v_or_b32_e32 v102, 20, v92
	v_mad_i64_i32 v[42:43], s[2:3], v102, s55, v[22:23]
	global_load_dwordx4 v[42:45], v[42:43], off
	v_or_b32_e32 v104, 24, v92
	v_mad_i64_i32 v[46:47], s[2:3], v104, s55, v[22:23]
	global_load_dwordx4 v[46:49], v[46:47], off
	v_or_b32_e32 v106, 28, v92
	v_mad_i64_i32 v[88:89], s[2:3], v106, s55, v[22:23]
	global_load_dwordx4 v[88:91], v[88:89], off
	s_mov_b32 s1, 64
	s_mov_b64 s[14:15], 0
	s_and_b64 vcc, exec, vcc
	s_waitcnt vmcnt(7)
	v_mul_f32_e32 v36, v4, v114
	v_mul_f32_e32 v87, v5, v114
	v_mul_f32_e32 v6, v6, v114
	v_mul_f32_e32 v7, v7, v114
	v_or_b32_e32 v94, 40, v92
	s_waitcnt vmcnt(6)
	v_mul_f32_e32 v5, v24, v116
	v_max3_f32 v3, v3, |v36|, |v5|
	v_mul_f32_e32 v5, v25, v116
	v_max3_f32 v2, v2, |v87|, |v5|
	v_mul_f32_e32 v5, v26, v116
	v_max3_f32 v5, v1, |v6|, |v5|
	v_mul_f32_e32 v1, v27, v116
	v_max3_f32 v4, v0, |v7|, |v1|
	v_or_b32_e32 v96, 44, v92
	s_waitcnt vmcnt(5)
	v_mul_f32_e32 v6, v28, v118
	v_mul_f32_e32 v7, v29, v118
	v_mul_f32_e32 v21, v30, v118
	v_mul_f32_e32 v24, v31, v118
	v_or_b32_e32 v98, 48, v92
	v_mad_i64_i32 v[28:29], s[2:3], v96, s55, v[22:23]
	global_load_dwordx4 v[28:31], v[28:29], off
	s_waitcnt vmcnt(5)
	v_mul_f32_e32 v1, v32, v120
	v_max3_f32 v3, v3, |v6|, |v1|
	v_mul_f32_e32 v1, v33, v120
	v_max3_f32 v2, v2, |v7|, |v1|
	v_mul_f32_e32 v1, v34, v120
	v_mul_f32_e32 v0, v35, v120
	v_max3_f32 v5, v5, |v21|, |v1|
	v_max3_f32 v4, v4, |v24|, |v0|
	v_mad_i64_i32 v[32:33], s[2:3], v98, s55, v[22:23]
	global_load_dwordx4 v[32:35], v[32:33], off
	v_or_b32_e32 v100, 52, v92
	s_waitcnt vmcnt(5)
	v_mul_f32_e32 v6, v38, v122
	v_mul_f32_e32 v7, v39, v122
	v_mul_f32_e32 v21, v40, v122
	v_mul_f32_e32 v24, v41, v122
	v_mad_i64_i32 v[38:39], s[2:3], v100, s55, v[22:23]
	global_load_dwordx4 v[38:41], v[38:39], off
	v_or_b32_e32 v102, 56, v92
	s_waitcnt vmcnt(5)
	v_mul_f32_e32 v1, v42, v124
	v_max3_f32 v3, v3, |v6|, |v1|
	v_mul_f32_e32 v1, v43, v124
	v_max3_f32 v2, v2, |v7|, |v1|
	v_mul_f32_e32 v1, v44, v124
	v_mul_f32_e32 v0, v45, v124
	v_max3_f32 v5, v5, |v21|, |v1|
	v_max3_f32 v4, v4, |v24|, |v0|
	v_mad_i64_i32 v[42:43], s[2:3], v102, s55, v[22:23]
	global_load_dwordx4 v[42:45], v[42:43], off
	s_waitcnt vmcnt(5)
	v_mul_f32_e32 v6, v46, v126
	v_mul_f32_e32 v7, v47, v126
	v_mul_f32_e32 v21, v48, v126
	v_mul_f32_e32 v24, v49, v126
	s_waitcnt vmcnt(4)
	v_mul_f32_e32 v1, v88, v128
	v_max3_f32 v36, v3, |v6|, |v1|
	v_mul_f32_e32 v1, v89, v128
	v_or_b32_e32 v88, 32, v92
	v_max3_f32 v87, v2, |v7|, |v1|
	v_mul_f32_e32 v1, v90, v128
	v_mul_f32_e32 v0, v91, v128
	v_max3_f32 v21, v5, |v21|, |v1|
	v_max3_f32 v104, v4, |v24|, |v0|
	v_mad_i64_i32 v[0:1], s[2:3], v88, s55, v[22:23]
	global_load_dwordx4 v[0:3], v[0:1], off
	v_or_b32_e32 v90, 36, v92
	v_mad_i64_i32 v[4:5], s[2:3], v90, s55, v[22:23]
	global_load_dwordx4 v[4:7], v[4:5], off
	v_mad_i64_i32 v[24:25], s[2:3], v94, s55, v[22:23]
	global_load_dwordx4 v[24:27], v[24:25], off
	v_or_b32_e32 v92, 60, v92
	v_mad_i64_i32 v[46:47], s[2:3], v92, s55, v[22:23]
	global_load_dwordx4 v[46:49], v[46:47], off
	s_waitcnt vmcnt(3)
	v_mul_f32_e32 v89, v0, v130
	v_mul_f32_e32 v105, v1, v130
	v_mul_f32_e32 v2, v2, v130
	v_mul_f32_e32 v3, v3, v130
	s_waitcnt vmcnt(2)
	v_mul_f32_e32 v1, v4, v132
	v_max3_f32 v4, v36, |v89|, |v1|
	v_mul_f32_e32 v1, v5, v132
	v_max3_f32 v5, v87, |v105|, |v1|
	v_mul_f32_e32 v1, v6, v132
	v_mul_f32_e32 v0, v7, v132
	v_max3_f32 v2, v21, |v2|, |v1|
	v_max3_f32 v3, v104, |v3|, |v0|
	s_waitcnt vmcnt(1)
	v_mul_f32_e32 v6, v24, v134
	v_mul_f32_e32 v7, v25, v134
	v_mul_f32_e32 v21, v26, v134
	v_mul_f32_e32 v24, v27, v134
	v_mul_f32_e32 v1, v28, v136
	v_max3_f32 v4, v4, |v6|, |v1|
	v_mul_f32_e32 v1, v29, v136
	v_max3_f32 v5, v5, |v7|, |v1|
	v_mul_f32_e32 v1, v30, v136
	v_mul_f32_e32 v0, v31, v136
	v_max3_f32 v2, v2, |v21|, |v1|
	v_max3_f32 v3, v3, |v24|, |v0|
	v_mul_f32_e32 v6, v32, v138
	v_mul_f32_e32 v7, v33, v138
	v_mul_f32_e32 v21, v34, v138
	v_mul_f32_e32 v24, v35, v138
	v_mul_f32_e32 v1, v38, v140
	v_max3_f32 v4, v4, |v6|, |v1|
	v_mul_f32_e32 v1, v39, v140
	v_max3_f32 v5, v5, |v7|, |v1|
	v_mul_f32_e32 v1, v40, v140
	v_mul_f32_e32 v0, v41, v140
	v_max3_f32 v6, v2, |v21|, |v1|
	v_max3_f32 v7, v3, |v24|, |v0|
	v_mul_f32_e32 v2, v42, v142
	v_mul_f32_e32 v21, v43, v142
	v_mul_f32_e32 v24, v44, v142
	v_mul_f32_e32 v25, v45, v142
	s_waitcnt vmcnt(0)
	v_mul_f32_e32 v1, v46, v144
	v_max3_f32 v3, v4, |v2|, |v1|
	v_mul_f32_e32 v1, v47, v144
	v_max3_f32 v2, v5, |v21|, |v1|
	v_mul_f32_e32 v1, v48, v144
	v_mul_f32_e32 v0, v49, v144
	v_max3_f32 v1, v6, |v24|, |v1|
	v_max3_f32 v0, v7, |v25|, |v0|
	s_cbranch_vccz .LBB0_1834
	v_and_b32_e32 v5, 64, v57
	v_xor_b32_e32 v4, 16, v57
	v_add_u32_e32 v5, 64, v5
	v_cmp_lt_i32_e32 vcc, v4, v5
	s_nop 1
	v_cndmask_b32_e32 v4, v57, v4, vcc
	v_lshlrev_b32_e32 v6, 2, v4
	ds_bpermute_b32 v7, v6, v3
	v_xor_b32_e32 v4, 32, v57
	v_cmp_lt_i32_e32 vcc, v4, v5
	ds_bpermute_b32 v5, v6, v2
	ds_bpermute_b32 v24, v6, v0
	v_cndmask_b32_e32 v4, v57, v4, vcc
	v_lshlrev_b32_e32 v21, 2, v4
	s_waitcnt lgkmcnt(2)
	v_max_f32_e32 v4, v7, v7
	ds_bpermute_b32 v7, v6, v1
	v_max_f32_e32 v3, v3, v3
	s_waitcnt lgkmcnt(2)
	v_max_f32_e32 v5, v5, v5
	v_max_f32_e32 v2, v2, v2
	v_max_f32_e32 v1, v1, v1
	s_waitcnt lgkmcnt(0)
	v_max_f32_e32 v6, v7, v7
	v_max_f32_e32 v7, v24, v24
	v_max_f32_e32 v0, v0, v0
	v_max_f32_e32 v3, v3, v4
	v_max_f32_e32 v2, v2, v5
	v_max_f32_e32 v1, v1, v6
	v_max_f32_e32 v0, v0, v7
	ds_bpermute_b32 v4, v21, v3
	ds_bpermute_b32 v5, v21, v2
	ds_bpermute_b32 v6, v21, v1
	ds_bpermute_b32 v7, v21, v0
	s_and_saveexec_b64 s[14:15], s[4:5]
	s_cbranch_execz .LBB0_1837
	s_waitcnt lgkmcnt(0)
	v_max_f32_e32 v7, v7, v7
	v_max_f32_e32 v0, v0, v0
	v_max_f32_e32 v7, v0, v7
	v_max_f32_e32 v0, v6, v6
	v_max_f32_e32 v1, v1, v1
	v_max_f32_e32 v6, v1, v0
	v_max_f32_e32 v0, v5, v5
	v_max_f32_e32 v1, v2, v2
	v_max_f32_e32 v5, v1, v0
	v_max_f32_e32 v0, v4, v4
	v_max_f32_e32 v1, v3, v3
	v_max_f32_e32 v4, v1, v0
	v_add_u32_e32 v0, s90, v52
	ds_write_b128 v0, v[4:7]

.LBB0_1840:
	s_or_b32 s34, s0, s89
	v_or_b32_e32 v112, s34, v62
	v_ashrrev_i32_e32 v113, 31, v112
	v_lshl_add_u64 v[114:115], v[112:113], 2, s[12:13]
	global_load_dword v116, v[114:115], off
	v_or_b32_e32 v112, s34, v11
	v_ashrrev_i32_e32 v113, 31, v112
	v_lshl_add_u64 v[112:113], v[112:113], 2, s[12:13]
	global_load_dword v118, v[112:113], off
	v_or_b32_e32 v112, s34, v71
	v_ashrrev_i32_e32 v113, 31, v112
	v_lshl_add_u64 v[112:113], v[112:113], 2, s[12:13]
	global_load_dword v120, v[112:113], off
	v_or_b32_e32 v112, s34, v72
	v_ashrrev_i32_e32 v113, 31, v112
	v_lshl_add_u64 v[112:113], v[112:113], 2, s[12:13]
	global_load_dword v122, v[112:113], off
	v_or_b32_e32 v112, s34, v73
	v_ashrrev_i32_e32 v113, 31, v112
	v_lshl_add_u64 v[112:113], v[112:113], 2, s[12:13]
	global_load_dword v124, v[112:113], off
	v_or_b32_e32 v112, s34, v74
	v_ashrrev_i32_e32 v113, 31, v112
	v_lshl_add_u64 v[112:113], v[112:113], 2, s[12:13]
	global_load_dword v126, v[112:113], off
	v_or_b32_e32 v112, s34, v76
	v_ashrrev_i32_e32 v113, 31, v112
	v_lshl_add_u64 v[112:113], v[112:113], 2, s[12:13]
	global_load_dword v128, v[112:113], off
	v_or_b32_e32 v112, s34, v77
	v_ashrrev_i32_e32 v113, 31, v112
	v_lshl_add_u64 v[112:113], v[112:113], 2, s[12:13]
	global_load_dword v130, v[112:113], off
	v_or_b32_e32 v46, s34, v62
	v_mad_i64_i32 v[0:1], s[0:1], v46, s55, v[22:23]
	global_load_dwordx4 v[88:91], v[0:1], off nt
	v_add_u32_e32 v21, v54, v55
	v_or_b32_e32 v0, 4, v46
	v_mad_i64_i32 v[0:1], s[0:1], v0, s55, v[22:23]
	global_load_dwordx4 v[92:95], v[0:1], off nt
	v_add_u32_e32 v47, 0x410, v21
	v_or_b32_e32 v0, 8, v46
	v_mad_i64_i32 v[0:1], s[0:1], v0, s55, v[22:23]
	global_load_dwordx4 v[96:99], v[0:1], off nt
	v_or_b32_e32 v0, 12, v46
	v_mad_i64_i32 v[0:1], s[0:1], v0, s55, v[22:23]
	global_load_dwordx4 v[100:103], v[0:1], off nt
	v_or_b32_e32 v0, 16, v46
	v_mad_i64_i32 v[0:1], s[0:1], v0, s55, v[22:23]
	global_load_dwordx4 v[104:107], v[0:1], off nt
	v_or_b32_e32 v0, 20, v46
	v_mad_i64_i32 v[0:1], s[0:1], v0, s55, v[22:23]
	global_load_dwordx4 v[108:111], v[0:1], off nt
	v_or_b32_e32 v0, 24, v46
	v_mad_i64_i32 v[0:1], s[0:1], v0, s55, v[22:23]
	global_load_dwordx4 v[4:7], v[0:1], off nt
	v_or_b32_e32 v0, 28, v46
	v_mad_i64_i32 v[0:1], s[0:1], v0, s55, v[22:23]
	global_load_dwordx4 v[0:3], v[0:1], off nt
	s_ashr_i32 s35, s34, 31
	s_and_b64 vcc, exec, s[14:15]
	s_mov_b64 s[14:15], 0
	s_waitcnt vmcnt(15)
	v_pk_mul_f32 v[48:49], v[24:25], v[116:117] op_sel_hi:[1,0]
	s_waitcnt vmcnt(7)
	v_pk_mul_f32 v[48:49], v[88:89], v[48:49]
	ds_write2_b32 v21, v48, v49 offset1:1
	v_pk_mul_f32 v[48:49], v[26:27], v[116:117] op_sel_hi:[1,0]
	s_nop 0
	v_pk_mul_f32 v[48:49], v[90:91], v[48:49]
	ds_write2_b32 v21, v48, v49 offset0:2 offset1:3
	v_pk_mul_f32 v[48:49], v[24:25], v[118:119] op_sel_hi:[1,0]
	s_nop 0
	s_waitcnt vmcnt(6)
	v_pk_mul_f32 v[48:49], v[92:93], v[48:49]
	ds_write2_b32 v47, v48, v49 offset1:1
	v_pk_mul_f32 v[48:49], v[26:27], v[118:119] op_sel_hi:[1,0]
	v_add_u32_e32 v36, 0x418, v21
	v_pk_mul_f32 v[48:49], v[94:95], v[48:49]
	ds_write2_b32 v36, v48, v49 offset1:1
	v_add_u32_e32 v47, 0x820, v21
	v_pk_mul_f32 v[48:49], v[24:25], v[120:121] op_sel_hi:[1,0]
	s_nop 0
	s_waitcnt vmcnt(5)
	v_pk_mul_f32 v[48:49], v[96:97], v[48:49]
	ds_write2_b32 v47, v48, v49 offset1:1
	v_pk_mul_f32 v[48:49], v[26:27], v[120:121] op_sel_hi:[1,0]
	v_add_u32_e32 v36, 0x828, v21
	v_pk_mul_f32 v[48:49], v[98:99], v[48:49]
	ds_write2_b32 v36, v48, v49 offset1:1
	v_add_u32_e32 v47, 0xc30, v21
	v_pk_mul_f32 v[48:49], v[24:25], v[122:123] op_sel_hi:[1,0]
	s_nop 0
	s_waitcnt vmcnt(4)
	v_pk_mul_f32 v[48:49], v[100:101], v[48:49]
	ds_write2_b32 v47, v48, v49 offset1:1
	v_pk_mul_f32 v[48:49], v[26:27], v[122:123] op_sel_hi:[1,0]
	v_add_u32_e32 v36, 0xc38, v21
	v_pk_mul_f32 v[48:49], v[102:103], v[48:49]
	ds_write2_b32 v36, v48, v49 offset1:1
	v_add_u32_e32 v47, 0x1040, v21
	v_pk_mul_f32 v[48:49], v[24:25], v[124:125] op_sel_hi:[1,0]
	s_nop 0
	s_waitcnt vmcnt(3)
	v_pk_mul_f32 v[48:49], v[104:105], v[48:49]
	ds_write2_b32 v47, v48, v49 offset1:1
	v_pk_mul_f32 v[48:49], v[26:27], v[124:125] op_sel_hi:[1,0]
	v_add_u32_e32 v36, 0x1048, v21
	v_pk_mul_f32 v[48:49], v[106:107], v[48:49]
	ds_write2_b32 v36, v48, v49 offset1:1
	v_add_u32_e32 v21, 0x1450, v21
	v_pk_mul_f32 v[48:49], v[24:25], v[126:127] op_sel_hi:[1,0]
	s_nop 0
	s_waitcnt vmcnt(2)
	v_pk_mul_f32 v[48:49], v[108:109], v[48:49]
	ds_write2_b32 v21, v48, v49 offset1:1
	v_pk_mul_f32 v[48:49], v[26:27], v[126:127] op_sel_hi:[1,0]
	v_add_u32_e32 v21, v54, v75
	v_pk_mul_f32 v[48:49], v[110:111], v[48:49]
	ds_write2_b32 v21, v48, v49 offset0:2 offset1:3
	v_add_u32_e32 v47, 0x410, v21
	v_or_b32_e32 v108, s34, v78
	v_ashrrev_i32_e32 v109, 31, v108
	v_lshl_add_u64 v[108:109], v[108:109], 2, s[12:13]
	global_load_dword v132, v[108:109], off
	v_or_b32_e32 v112, s34, v79
	v_ashrrev_i32_e32 v113, 31, v112
	v_lshl_add_u64 v[112:113], v[112:113], 2, s[12:13]
	global_load_dword v134, v[112:113], off
	v_or_b32_e32 v112, s34, v80
	v_ashrrev_i32_e32 v113, 31, v112
	v_lshl_add_u64 v[112:113], v[112:113], 2, s[12:13]
	global_load_dword v136, v[112:113], off
	v_or_b32_e32 v112, s34, v81
	v_ashrrev_i32_e32 v113, 31, v112
	v_lshl_add_u64 v[112:113], v[112:113], 2, s[12:13]
	global_load_dword v138, v[112:113], off
	v_or_b32_e32 v112, s34, v82
	v_ashrrev_i32_e32 v113, 31, v112
	v_lshl_add_u64 v[112:113], v[112:113], 2, s[12:13]
	global_load_dword v140, v[112:113], off
	v_or_b32_e32 v112, s34, v83
	v_ashrrev_i32_e32 v113, 31, v112
	v_lshl_add_u64 v[112:113], v[112:113], 2, s[12:13]
	global_load_dword v142, v[112:113], off
	v_or_b32_e32 v112, s34, v84
	v_ashrrev_i32_e32 v113, 31, v112
	v_lshl_add_u64 v[112:113], v[112:113], 2, s[12:13]
	global_load_dword v144, v[112:113], off
	v_or_b32_e32 v112, s34, v85
	v_ashrrev_i32_e32 v113, 31, v112
	v_lshl_add_u64 v[112:113], v[112:113], 2, s[12:13]
	global_load_dword v146, v[112:113], off
	v_add_u32_e32 v87, 0xc30, v21
	v_pk_mul_f32 v[48:49], v[24:25], v[128:129] op_sel_hi:[1,0]
	s_nop 0
	s_waitcnt vmcnt(9)
	v_pk_mul_f32 v[4:5], v[4:5], v[48:49]
	ds_write2_b32 v47, v4, v5 offset1:1
	v_pk_mul_f32 v[4:5], v[26:27], v[128:129] op_sel_hi:[1,0]
	v_or_b32_e32 v36, 40, v46
	v_pk_mul_f32 v[4:5], v[6:7], v[4:5]
	v_add_u32_e32 v6, 0x418, v21
	ds_write2_b32 v6, v4, v5 offset1:1
	v_mad_i64_i32 v[48:49], s[0:1], v36, s55, v[22:23]
	v_or_b32_e32 v36, 44, v46
	global_load_dwordx4 v[88:91], v[48:49], off nt
	v_mad_i64_i32 v[48:49], s[0:1], v36, s55, v[22:23]
	v_or_b32_e32 v36, 48, v46
	global_load_dwordx4 v[92:95], v[48:49], off nt
	v_mad_i64_i32 v[48:49], s[0:1], v36, s55, v[22:23]
	v_or_b32_e32 v36, 52, v46
	global_load_dwordx4 v[96:99], v[48:49], off nt
	v_mad_i64_i32 v[48:49], s[0:1], v36, s55, v[22:23]
	v_or_b32_e32 v36, 56, v46
	global_load_dwordx4 v[100:103], v[48:49], off nt
	v_mad_i64_i32 v[48:49], s[0:1], v36, s55, v[22:23]
	v_or_b32_e32 v36, 60, v46
	global_load_dwordx4 v[104:107], v[48:49], off nt
	v_pk_mul_f32 v[6:7], v[24:25], v[130:131] op_sel_hi:[1,0]
	s_nop 0
	s_waitcnt vmcnt(13)
	v_pk_mul_f32 v[0:1], v[0:1], v[6:7]
	v_add_u32_e32 v5, 0x820, v21
	ds_write2_b32 v5, v0, v1 offset1:1
	v_pk_mul_f32 v[0:1], v[26:27], v[130:131] op_sel_hi:[1,0]
	v_or_b32_e32 v4, 36, v46
	v_pk_mul_f32 v[0:1], v[2:3], v[0:1]
	v_add_u32_e32 v2, 0x828, v21
	ds_write2_b32 v2, v0, v1 offset1:1
	v_or_b32_e32 v0, 32, v46
	v_mad_i64_i32 v[0:1], s[0:1], v0, s55, v[22:23]
	v_mad_i64_i32 v[46:47], s[0:1], v36, s55, v[22:23]
	v_mad_i64_i32 v[4:5], s[0:1], v4, s55, v[22:23]
	global_load_dwordx4 v[0:3], v[0:1], off nt
	s_mov_b32 s0, 64
	global_load_dwordx4 v[4:7], v[4:5], off nt
	s_waitcnt vmcnt(14)
	v_pk_mul_f32 v[108:109], v[24:25], v[132:133] op_sel_hi:[1,0]
	global_load_dwordx4 v[46:49], v[46:47], off nt
	s_waitcnt vmcnt(2)
	v_pk_mul_f32 v[0:1], v[0:1], v[108:109]
	ds_write2_b32 v87, v0, v1 offset1:1
	v_pk_mul_f32 v[0:1], v[26:27], v[132:133] op_sel_hi:[1,0]
	s_nop 0
	v_pk_mul_f32 v[0:1], v[2:3], v[0:1]
	v_add_u32_e32 v2, 0xc38, v21
	ds_write2_b32 v2, v0, v1 offset1:1
	v_pk_mul_f32 v[2:3], v[24:25], v[134:135] op_sel_hi:[1,0]
	s_nop 0
	s_waitcnt vmcnt(1)
	v_pk_mul_f32 v[2:3], v[4:5], v[2:3]
	v_add_u32_e32 v1, 0x1040, v21
	ds_write2_b32 v1, v2, v3 offset1:1
	v_pk_mul_f32 v[0:1], v[26:27], v[134:135] op_sel_hi:[1,0]
	v_add_u32_e32 v2, 0x1048, v21
	v_pk_mul_f32 v[0:1], v[6:7], v[0:1]
	ds_write2_b32 v2, v0, v1 offset1:1
	v_pk_mul_f32 v[2:3], v[24:25], v[136:137] op_sel_hi:[1,0]
	s_nop 0
	v_pk_mul_f32 v[2:3], v[88:89], v[2:3]
	v_add_u32_e32 v1, 0x1450, v21
	ds_write2_b32 v1, v2, v3 offset1:1
	v_pk_mul_f32 v[0:1], v[26:27], v[136:137] op_sel_hi:[1,0]
	v_add_u32_e32 v2, 0x1458, v21
	v_pk_mul_f32 v[0:1], v[90:91], v[0:1]
	ds_write2_b32 v2, v0, v1 offset1:1
	v_pk_mul_f32 v[2:3], v[24:25], v[138:139] op_sel_hi:[1,0]
	s_nop 0
	v_pk_mul_f32 v[2:3], v[92:93], v[2:3]
	v_add_u32_e32 v1, 0x1860, v21
	ds_write2_b32 v1, v2, v3 offset1:1
	v_pk_mul_f32 v[0:1], v[26:27], v[138:139] op_sel_hi:[1,0]
	v_add_u32_e32 v2, 0x1868, v21
	v_pk_mul_f32 v[0:1], v[94:95], v[0:1]
	ds_write2_b32 v2, v0, v1 offset1:1
	v_pk_mul_f32 v[2:3], v[24:25], v[140:141] op_sel_hi:[1,0]
	s_nop 0
	v_pk_mul_f32 v[2:3], v[96:97], v[2:3]
	v_add_u32_e32 v1, 0x1c70, v21
	ds_write2_b32 v1, v2, v3 offset1:1
	v_pk_mul_f32 v[0:1], v[26:27], v[140:141] op_sel_hi:[1,0]
	v_add_u32_e32 v2, 0x1c78, v21
	v_pk_mul_f32 v[0:1], v[98:99], v[0:1]
	ds_write2_b32 v2, v0, v1 offset1:1
	v_pk_mul_f32 v[2:3], v[24:25], v[142:143] op_sel_hi:[1,0]
	s_nop 0
	v_pk_mul_f32 v[2:3], v[100:101], v[2:3]
	v_add_u32_e32 v1, 0x2080, v21
	ds_write2_b32 v1, v2, v3 offset1:1
	v_pk_mul_f32 v[0:1], v[26:27], v[142:143] op_sel_hi:[1,0]
	v_add_u32_e32 v2, 0x2088, v21
	v_pk_mul_f32 v[0:1], v[102:103], v[0:1]
	ds_write2_b32 v2, v0, v1 offset1:1
	v_pk_mul_f32 v[2:3], v[24:25], v[144:145] op_sel_hi:[1,0]
	s_nop 0
	v_pk_mul_f32 v[2:3], v[104:105], v[2:3]
	v_add_u32_e32 v1, 0x2490, v21
	ds_write2_b32 v1, v2, v3 offset1:1
	v_pk_mul_f32 v[0:1], v[26:27], v[144:145] op_sel_hi:[1,0]
	v_add_u32_e32 v2, 0x2498, v21
	v_pk_mul_f32 v[0:1], v[106:107], v[0:1]
	ds_write2_b32 v2, v0, v1 offset1:1
	v_pk_mul_f32 v[2:3], v[24:25], v[146:147] op_sel_hi:[1,0]
	s_nop 0
	s_waitcnt vmcnt(0)
	v_pk_mul_f32 v[2:3], v[46:47], v[2:3]
	v_add_u32_e32 v1, 0x28a0, v21
	ds_write2_b32 v1, v2, v3 offset1:1
	v_pk_mul_f32 v[0:1], v[26:27], v[146:147] op_sel_hi:[1,0]
	v_add_u32_e32 v2, 0x28a8, v21
	v_pk_mul_f32 v[0:1], v[48:49], v[0:1]
	ds_write2_b32 v2, v0, v1 offset1:1
	s_waitcnt lgkmcnt(0)
	ds_read2_b32 v[6:7], v9 offset0:130 offset1:138
	ds_read2_b32 v[46:47], v9 offset0:195 offset1:203
	ds_read2_b32 v[2:3], v9 offset1:8
	ds_read2_b32 v[4:5], v9 offset0:65 offset1:73
	v_lshl_add_u64 v[0:1], v[18:19], 0, s[34:35]
	s_waitcnt lgkmcnt(3)
	v_med3_f32 v6, v6, s52, v58
	s_waitcnt lgkmcnt(2)
	v_med3_f32 v21, v46, s52, v58
	v_add_f32_e32 v6, 0x4b400000, v6
	v_add_f32_e32 v21, 0x4b400000, v21
	v_perm_b32 v6, v21, v6, s53
	v_add_u32_e32 v21, 0x400, v9
	ds_read2_b32 v[88:89], v21 offset0:4 offset1:12
	ds_read2_b32 v[90:91], v21 offset0:69 offset1:77
	ds_read2_b32 v[92:93], v21 offset0:134 offset1:142
	ds_read2_b32 v[94:95], v21 offset0:199 offset1:207
	s_waitcnt lgkmcnt(5)
	v_med3_f32 v2, v2, s52, v58
	s_waitcnt lgkmcnt(4)
	v_med3_f32 v4, v4, s52, v58
	v_add_f32_e32 v2, 0x4b400000, v2
	v_add_f32_e32 v4, 0x4b400000, v4
	v_perm_b32 v2, v4, v2, s53
	v_perm_b32 v48, v6, v2, s54
	s_waitcnt lgkmcnt(3)
	v_med3_f32 v2, v88, s52, v58
	s_waitcnt lgkmcnt(2)
	v_med3_f32 v4, v90, s52, v58
	s_waitcnt lgkmcnt(1)
	v_med3_f32 v6, v92, s52, v58
	s_waitcnt lgkmcnt(0)
	v_med3_f32 v36, v94, s52, v58
	v_add_f32_e32 v2, 0x4b400000, v2
	v_add_f32_e32 v4, 0x4b400000, v4
	v_add_f32_e32 v6, 0x4b400000, v6
	v_add_f32_e32 v36, 0x4b400000, v36
	v_perm_b32 v6, v36, v6, s53
	v_perm_b32 v2, v4, v2, s53
	v_perm_b32 v49, v6, v2, s54
	v_med3_f32 v2, v3, s52, v58
	v_med3_f32 v3, v5, s52, v58
	v_med3_f32 v4, v7, s52, v58
	v_med3_f32 v5, v47, s52, v58
	v_add_f32_e32 v2, 0x4b400000, v2
	v_add_f32_e32 v3, 0x4b400000, v3
	v_add_f32_e32 v4, 0x4b400000, v4
	v_add_f32_e32 v5, 0x4b400000, v5
	v_perm_b32 v4, v5, v4, s53
	v_perm_b32 v2, v3, v2, s53
	v_perm_b32 v2, v4, v2, s54
	v_med3_f32 v3, v89, s52, v58
	v_med3_f32 v4, v91, s52, v58
	v_med3_f32 v5, v93, s52, v58
	v_med3_f32 v6, v95, s52, v58
	v_add_f32_e32 v3, 0x4b400000, v3
	v_add_f32_e32 v4, 0x4b400000, v4
	v_add_f32_e32 v5, 0x4b400000, v5
	v_add_f32_e32 v6, 0x4b400000, v6
	v_perm_b32 v5, v6, v5, s53
	v_perm_b32 v3, v4, v3, s53
	v_perm_b32 v3, v5, v3, s54
	v_lshl_add_u64 v[4:5], v[0:1], 0, v[30:31]
	global_store_dwordx2 v[4:5], v[2:3], off
	ds_read2_b32 v[2:3], v9 offset0:16 offset1:24
	ds_read2_b32 v[4:5], v9 offset0:81 offset1:89
	ds_read2_b32 v[6:7], v9 offset0:146 offset1:154
	ds_read2_b32 v[46:47], v9 offset0:211 offset1:219
	ds_read2_b32 v[88:89], v21 offset0:20 offset1:28
	ds_read2_b32 v[90:91], v21 offset0:85 offset1:93
	ds_read2_b32 v[92:93], v21 offset0:150 offset1:158
	ds_read2_b32 v[94:95], v21 offset0:215 offset1:223
	s_waitcnt lgkmcnt(7)
	v_med3_f32 v2, v2, s52, v58
	s_waitcnt lgkmcnt(6)
	v_med3_f32 v4, v4, s52, v58
	s_waitcnt lgkmcnt(5)
	v_med3_f32 v6, v6, s52, v58
	s_waitcnt lgkmcnt(4)
	v_med3_f32 v36, v46, s52, v58
	v_add_f32_e32 v2, 0x4b400000, v2
	v_add_f32_e32 v4, 0x4b400000, v4
	v_add_f32_e32 v6, 0x4b400000, v6
	v_add_f32_e32 v36, 0x4b400000, v36
	v_lshl_add_u64 v[96:97], v[0:1], 0, v[28:29]
	v_perm_b32 v6, v36, v6, s53
	v_perm_b32 v2, v4, v2, s53
	global_store_dwordx2 v[96:97], v[48:49], off
	v_perm_b32 v48, v6, v2, s54
	s_waitcnt lgkmcnt(3)
	v_med3_f32 v2, v88, s52, v58
	s_waitcnt lgkmcnt(2)
	v_med3_f32 v4, v90, s52, v58
	s_waitcnt lgkmcnt(1)
	v_med3_f32 v6, v92, s52, v58
	s_waitcnt lgkmcnt(0)
	v_med3_f32 v36, v94, s52, v58
	v_add_f32_e32 v2, 0x4b400000, v2
	v_add_f32_e32 v4, 0x4b400000, v4
	v_add_f32_e32 v6, 0x4b400000, v6
	v_add_f32_e32 v36, 0x4b400000, v36
	v_perm_b32 v6, v36, v6, s53
	v_perm_b32 v2, v4, v2, s53
	v_perm_b32 v49, v6, v2, s54
	v_med3_f32 v2, v3, s52, v58
	v_med3_f32 v3, v5, s52, v58
	v_med3_f32 v4, v7, s52, v58
	v_med3_f32 v5, v47, s52, v58
	v_add_f32_e32 v2, 0x4b400000, v2
	v_add_f32_e32 v3, 0x4b400000, v3
	v_add_f32_e32 v4, 0x4b400000, v4
	v_add_f32_e32 v5, 0x4b400000, v5
	v_perm_b32 v4, v5, v4, s53
	v_perm_b32 v2, v3, v2, s53
	v_perm_b32 v2, v4, v2, s54
	v_med3_f32 v3, v89, s52, v58
	v_med3_f32 v4, v91, s52, v58
	v_med3_f32 v5, v93, s52, v58
	v_med3_f32 v6, v95, s52, v58
	v_add_f32_e32 v3, 0x4b400000, v3
	v_add_f32_e32 v4, 0x4b400000, v4
	v_add_f32_e32 v5, 0x4b400000, v5
	v_add_f32_e32 v6, 0x4b400000, v6
	v_perm_b32 v5, v6, v5, s53
	v_perm_b32 v3, v4, v3, s53
	v_perm_b32 v3, v5, v3, s54
	v_lshl_add_u64 v[4:5], v[0:1], 0, v[34:35]
	global_store_dwordx2 v[4:5], v[2:3], off
	ds_read2_b32 v[2:3], v9 offset0:32 offset1:40
	ds_read2_b32 v[4:5], v9 offset0:97 offset1:105
	ds_read2_b32 v[6:7], v9 offset0:162 offset1:170
	ds_read2_b32 v[46:47], v9 offset0:227 offset1:235
	ds_read2_b32 v[88:89], v21 offset0:36 offset1:44
	ds_read2_b32 v[90:91], v21 offset0:101 offset1:109
	ds_read2_b32 v[92:93], v21 offset0:166 offset1:174
	ds_read2_b32 v[94:95], v21 offset0:231 offset1:239
	s_waitcnt lgkmcnt(7)
	v_med3_f32 v2, v2, s52, v58
	s_waitcnt lgkmcnt(6)
	v_med3_f32 v4, v4, s52, v58
	s_waitcnt lgkmcnt(5)
	v_med3_f32 v6, v6, s52, v58
	s_waitcnt lgkmcnt(4)
	v_med3_f32 v36, v46, s52, v58
	v_add_f32_e32 v2, 0x4b400000, v2
	v_add_f32_e32 v4, 0x4b400000, v4
	v_add_f32_e32 v6, 0x4b400000, v6
	v_add_f32_e32 v36, 0x4b400000, v36
	v_lshl_add_u64 v[96:97], v[0:1], 0, v[32:33]
	v_perm_b32 v6, v36, v6, s53
	v_perm_b32 v2, v4, v2, s53
	global_store_dwordx2 v[96:97], v[48:49], off
	v_perm_b32 v48, v6, v2, s54
	s_waitcnt lgkmcnt(3)
	v_med3_f32 v2, v88, s52, v58
	s_waitcnt lgkmcnt(2)
	v_med3_f32 v4, v90, s52, v58
	s_waitcnt lgkmcnt(1)
	v_med3_f32 v6, v92, s52, v58
	s_waitcnt lgkmcnt(0)
	v_med3_f32 v36, v94, s52, v58
	v_add_f32_e32 v2, 0x4b400000, v2
	v_add_f32_e32 v4, 0x4b400000, v4
	v_add_f32_e32 v6, 0x4b400000, v6
	v_add_f32_e32 v36, 0x4b400000, v36
	v_perm_b32 v6, v36, v6, s53
	v_perm_b32 v2, v4, v2, s53
	v_perm_b32 v49, v6, v2, s54
	v_med3_f32 v2, v3, s52, v58
	v_med3_f32 v3, v5, s52, v58
	v_med3_f32 v4, v7, s52, v58
	v_med3_f32 v5, v47, s52, v58
	v_add_f32_e32 v2, 0x4b400000, v2
	v_add_f32_e32 v3, 0x4b400000, v3
	v_add_f32_e32 v4, 0x4b400000, v4
	v_add_f32_e32 v5, 0x4b400000, v5
	v_perm_b32 v4, v5, v4, s53
	v_perm_b32 v2, v3, v2, s53
	v_perm_b32 v2, v4, v2, s54
	v_med3_f32 v3, v89, s52, v58
	v_med3_f32 v4, v91, s52, v58
	v_med3_f32 v5, v93, s52, v58
	v_med3_f32 v6, v95, s52, v58
	v_add_f32_e32 v3, 0x4b400000, v3
	v_add_f32_e32 v4, 0x4b400000, v4
	v_add_f32_e32 v5, 0x4b400000, v5
	v_add_f32_e32 v6, 0x4b400000, v6
	v_perm_b32 v5, v6, v5, s53
	v_perm_b32 v3, v4, v3, s53
	v_perm_b32 v3, v5, v3, s54
	v_lshl_add_u64 v[4:5], v[0:1], 0, v[40:41]
	global_store_dwordx2 v[4:5], v[2:3], off
	ds_read2_b32 v[2:3], v9 offset0:48 offset1:56
	ds_read2_b32 v[4:5], v9 offset0:113 offset1:121
	ds_read2_b32 v[6:7], v9 offset0:178 offset1:186
	ds_read2_b32 v[46:47], v9 offset0:243 offset1:251
	ds_read2_b32 v[88:89], v21 offset0:52 offset1:60
	ds_read2_b32 v[90:91], v21 offset0:117 offset1:125
	ds_read2_b32 v[92:93], v21 offset0:182 offset1:190
	ds_read2_b32 v[94:95], v21 offset0:247 offset1:255
	s_waitcnt lgkmcnt(7)
	v_med3_f32 v2, v2, s52, v58
	s_waitcnt lgkmcnt(6)
	v_med3_f32 v4, v4, s52, v58
	s_waitcnt lgkmcnt(5)
	v_med3_f32 v6, v6, s52, v58
	s_waitcnt lgkmcnt(4)
	v_med3_f32 v36, v46, s52, v58
	v_add_f32_e32 v2, 0x4b400000, v2
	v_add_f32_e32 v4, 0x4b400000, v4
	v_add_f32_e32 v6, 0x4b400000, v6
	v_add_f32_e32 v36, 0x4b400000, v36
	v_lshl_add_u64 v[96:97], v[0:1], 0, v[38:39]
	v_perm_b32 v6, v36, v6, s53
	v_perm_b32 v2, v4, v2, s53
	global_store_dwordx2 v[96:97], v[48:49], off
	v_perm_b32 v48, v6, v2, s54
	s_waitcnt lgkmcnt(3)
	v_med3_f32 v2, v88, s52, v58
	s_waitcnt lgkmcnt(2)
	v_med3_f32 v4, v90, s52, v58
	s_waitcnt lgkmcnt(1)
	v_med3_f32 v6, v92, s52, v58
	s_waitcnt lgkmcnt(0)
	v_med3_f32 v21, v94, s52, v58
	v_add_f32_e32 v2, 0x4b400000, v2
	v_add_f32_e32 v4, 0x4b400000, v4
	v_add_f32_e32 v6, 0x4b400000, v6
	v_add_f32_e32 v21, 0x4b400000, v21
	v_perm_b32 v6, v21, v6, s53
	v_perm_b32 v2, v4, v2, s53
	v_perm_b32 v49, v6, v2, s54
	v_med3_f32 v2, v3, s52, v58
	v_med3_f32 v3, v5, s52, v58
	v_med3_f32 v4, v7, s52, v58
	v_med3_f32 v5, v47, s52, v58
	v_add_f32_e32 v2, 0x4b400000, v2
	v_add_f32_e32 v3, 0x4b400000, v3
	v_add_f32_e32 v4, 0x4b400000, v4
	v_add_f32_e32 v5, 0x4b400000, v5
	v_perm_b32 v4, v5, v4, s53
	v_perm_b32 v2, v3, v2, s53
	v_perm_b32 v2, v4, v2, s54
	v_med3_f32 v3, v89, s52, v58
	v_med3_f32 v4, v91, s52, v58
	v_med3_f32 v5, v93, s52, v58
	v_med3_f32 v6, v95, s52, v58
	v_add_f32_e32 v3, 0x4b400000, v3
	v_add_f32_e32 v4, 0x4b400000, v4
	v_add_f32_e32 v5, 0x4b400000, v5
	v_add_f32_e32 v6, 0x4b400000, v6
	v_perm_b32 v5, v6, v5, s53
	v_perm_b32 v3, v4, v3, s53
	v_lshl_add_u64 v[96:97], v[0:1], 0, v[42:43]
	v_perm_b32 v3, v5, v3, s54
	v_lshl_add_u64 v[0:1], v[0:1], 0, v[44:45]
	global_store_dwordx2 v[96:97], v[48:49], off
	global_store_dwordx2 v[0:1], v[2:3], off
	s_waitcnt lgkmcnt(0)
	s_cbranch_vccnz .LBB0_1840
	s_barrier
	s_branch .LBB0_1796

.LBB0_1911:
	v_or_b32_e32 v108, s2, v85
	v_ashrrev_i32_e32 v109, 31, v108
	v_lshl_add_u64 v[110:111], v[108:109], 2, s[16:17]
	global_load_dword v112, v[110:111], off
	v_or_b32_e32 v108, s2, v85
	v_or_b32_e32 v110, 4, v108
	v_ashrrev_i32_e32 v111, 31, v110
	v_lshl_add_u64 v[108:109], v[110:111], 2, s[16:17]
	global_load_dword v114, v[108:109], off
	v_or_b32_e32 v108, s2, v85
	v_or_b32_e32 v110, 8, v108
	v_ashrrev_i32_e32 v111, 31, v110
	v_lshl_add_u64 v[108:109], v[110:111], 2, s[16:17]
	global_load_dword v116, v[108:109], off
	v_or_b32_e32 v108, s2, v85
	v_or_b32_e32 v110, 12, v108
	v_ashrrev_i32_e32 v111, 31, v110
	v_lshl_add_u64 v[108:109], v[110:111], 2, s[16:17]
	global_load_dword v118, v[108:109], off
	v_or_b32_e32 v108, s2, v85
	v_or_b32_e32 v110, 16, v108
	v_ashrrev_i32_e32 v111, 31, v110
	v_lshl_add_u64 v[108:109], v[110:111], 2, s[16:17]
	global_load_dword v120, v[108:109], off
	v_or_b32_e32 v108, s2, v85
	v_or_b32_e32 v110, 20, v108
	v_ashrrev_i32_e32 v111, 31, v110
	v_lshl_add_u64 v[108:109], v[110:111], 2, s[16:17]
	global_load_dword v122, v[108:109], off
	v_or_b32_e32 v108, s2, v85
	v_or_b32_e32 v110, 24, v108
	v_ashrrev_i32_e32 v111, 31, v110
	v_lshl_add_u64 v[108:109], v[110:111], 2, s[16:17]
	global_load_dword v124, v[108:109], off
	v_or_b32_e32 v108, s2, v85
	v_or_b32_e32 v110, 28, v108
	v_ashrrev_i32_e32 v111, 31, v110
	v_lshl_add_u64 v[108:109], v[110:111], 2, s[16:17]
	global_load_dword v126, v[108:109], off
	v_or_b32_e32 v108, s2, v85
	v_or_b32_e32 v110, 32, v108
	v_ashrrev_i32_e32 v111, 31, v110
	v_lshl_add_u64 v[110:111], v[110:111], 2, s[16:17]
	global_load_dword v128, v[110:111], off
	v_or_b32_e32 v108, s2, v85
	v_or_b32_e32 v110, 36, v108
	v_ashrrev_i32_e32 v111, 31, v110
	v_lshl_add_u64 v[108:109], v[110:111], 2, s[16:17]
	global_load_dword v130, v[108:109], off
	v_or_b32_e32 v108, s2, v85
	v_or_b32_e32 v110, 40, v108
	v_ashrrev_i32_e32 v111, 31, v110
	v_lshl_add_u64 v[108:109], v[110:111], 2, s[16:17]
	global_load_dword v132, v[108:109], off
	v_or_b32_e32 v108, s2, v85
	v_or_b32_e32 v110, 44, v108
	v_ashrrev_i32_e32 v111, 31, v110
	v_lshl_add_u64 v[108:109], v[110:111], 2, s[16:17]
	global_load_dword v134, v[108:109], off
	v_or_b32_e32 v108, s2, v85
	v_or_b32_e32 v110, 48, v108
	v_ashrrev_i32_e32 v111, 31, v110
	v_lshl_add_u64 v[108:109], v[110:111], 2, s[16:17]
	global_load_dword v136, v[108:109], off
	v_or_b32_e32 v108, s2, v85
	v_or_b32_e32 v110, 52, v108
	v_ashrrev_i32_e32 v111, 31, v110
	v_lshl_add_u64 v[108:109], v[110:111], 2, s[16:17]
	global_load_dword v138, v[108:109], off
	v_or_b32_e32 v108, s2, v85
	v_or_b32_e32 v110, 56, v108
	v_ashrrev_i32_e32 v111, 31, v110
	v_lshl_add_u64 v[108:109], v[110:111], 2, s[16:17]
	global_load_dword v140, v[108:109], off
	v_or_b32_e32 v108, s2, v85
	v_or_b32_e32 v108, 60, v108
	v_ashrrev_i32_e32 v109, 31, v108
	v_lshl_add_u64 v[110:111], v[108:109], 2, s[16:17]
	global_load_dword v142, v[110:111], off
	v_or_b32_e32 v90, s2, v85
	v_cndmask_b32_e64 v4, 0, 1, s[14:15]
	v_cmp_ne_u32_e32 vcc, 1, v4
	v_mad_i64_i32 v[4:5], s[2:3], v90, s48, v[22:23]
	global_load_dwordx4 v[4:7], v[4:5], off
	v_or_b32_e32 v92, 4, v90
	v_mad_i64_i32 v[24:25], s[2:3], v92, s48, v[22:23]
	global_load_dwordx4 v[24:27], v[24:25], off
	v_or_b32_e32 v94, 8, v90
	v_mad_i64_i32 v[28:29], s[2:3], v94, s48, v[22:23]
	global_load_dwordx4 v[28:31], v[28:29], off
	v_or_b32_e32 v96, 12, v90
	v_mad_i64_i32 v[32:33], s[2:3], v96, s48, v[22:23]
	global_load_dwordx4 v[32:35], v[32:33], off
	v_or_b32_e32 v98, 16, v90
	v_mad_i64_i32 v[38:39], s[2:3], v98, s48, v[22:23]
	global_load_dwordx4 v[38:41], v[38:39], off
	v_or_b32_e32 v100, 20, v90
	v_mad_i64_i32 v[42:43], s[2:3], v100, s48, v[22:23]
	global_load_dwordx4 v[42:45], v[42:43], off
	v_or_b32_e32 v102, 24, v90
	v_mad_i64_i32 v[46:47], s[2:3], v102, s48, v[22:23]
	global_load_dwordx4 v[46:49], v[46:47], off
	v_or_b32_e32 v104, 28, v90
	v_mad_i64_i32 v[86:87], s[2:3], v104, s48, v[22:23]
	global_load_dwordx4 v[86:89], v[86:87], off
	s_mov_b64 s[14:15], 0
	s_and_b64 vcc, exec, vcc
	s_waitcnt vmcnt(7)
	v_mul_f32_e32 v36, v4, v112
	v_mul_f32_e32 v91, v5, v112
	v_mul_f32_e32 v6, v6, v112
	v_mul_f32_e32 v7, v7, v112
	v_or_b32_e32 v92, 40, v90
	s_waitcnt vmcnt(6)
	v_mul_f32_e32 v5, v24, v114
	v_max3_f32 v3, v3, |v36|, |v5|
	v_mul_f32_e32 v5, v25, v114
	v_max3_f32 v2, v2, |v91|, |v5|
	v_mul_f32_e32 v5, v26, v114
	v_max3_f32 v5, v1, |v6|, |v5|
	v_mul_f32_e32 v1, v27, v114
	v_max3_f32 v4, v0, |v7|, |v1|
	v_or_b32_e32 v94, 44, v90
	s_waitcnt vmcnt(5)
	v_mul_f32_e32 v6, v28, v116
	v_mul_f32_e32 v7, v29, v116
	v_mul_f32_e32 v21, v30, v116
	v_mul_f32_e32 v24, v31, v116
	v_or_b32_e32 v96, 48, v90
	v_mad_i64_i32 v[28:29], s[2:3], v94, s48, v[22:23]
	global_load_dwordx4 v[28:31], v[28:29], off
	s_waitcnt vmcnt(5)
	v_mul_f32_e32 v1, v32, v118
	v_max3_f32 v3, v3, |v6|, |v1|
	v_mul_f32_e32 v1, v33, v118
	v_max3_f32 v2, v2, |v7|, |v1|
	v_mul_f32_e32 v1, v34, v118
	v_mul_f32_e32 v0, v35, v118
	v_max3_f32 v5, v5, |v21|, |v1|
	v_max3_f32 v4, v4, |v24|, |v0|
	v_mad_i64_i32 v[32:33], s[2:3], v96, s48, v[22:23]
	global_load_dwordx4 v[32:35], v[32:33], off
	v_or_b32_e32 v98, 52, v90
	s_waitcnt vmcnt(5)
	v_mul_f32_e32 v6, v38, v120
	v_mul_f32_e32 v7, v39, v120
	v_mul_f32_e32 v21, v40, v120
	v_mul_f32_e32 v24, v41, v120
	v_mad_i64_i32 v[38:39], s[2:3], v98, s48, v[22:23]
	global_load_dwordx4 v[38:41], v[38:39], off
	v_or_b32_e32 v100, 56, v90
	s_waitcnt vmcnt(5)
	v_mul_f32_e32 v1, v42, v122
	v_max3_f32 v3, v3, |v6|, |v1|
	v_mul_f32_e32 v1, v43, v122
	v_max3_f32 v2, v2, |v7|, |v1|
	v_mul_f32_e32 v1, v44, v122
	v_mul_f32_e32 v0, v45, v122
	v_max3_f32 v5, v5, |v21|, |v1|
	v_max3_f32 v4, v4, |v24|, |v0|
	v_mad_i64_i32 v[42:43], s[2:3], v100, s48, v[22:23]
	global_load_dwordx4 v[42:45], v[42:43], off
	s_waitcnt vmcnt(5)
	v_mul_f32_e32 v6, v46, v124
	v_mul_f32_e32 v7, v47, v124
	v_mul_f32_e32 v21, v48, v124
	v_mul_f32_e32 v24, v49, v124
	s_waitcnt vmcnt(4)
	v_mul_f32_e32 v1, v86, v126
	v_max3_f32 v36, v3, |v6|, |v1|
	v_mul_f32_e32 v1, v87, v126
	v_or_b32_e32 v86, 32, v90
	v_max3_f32 v102, v2, |v7|, |v1|
	v_mul_f32_e32 v1, v88, v126
	v_mul_f32_e32 v0, v89, v126
	v_max3_f32 v21, v5, |v21|, |v1|
	v_max3_f32 v103, v4, |v24|, |v0|
	v_mad_i64_i32 v[0:1], s[2:3], v86, s48, v[22:23]
	global_load_dwordx4 v[0:3], v[0:1], off
	v_or_b32_e32 v88, 36, v90
	v_mad_i64_i32 v[4:5], s[2:3], v88, s48, v[22:23]
	global_load_dwordx4 v[4:7], v[4:5], off
	v_mad_i64_i32 v[24:25], s[2:3], v92, s48, v[22:23]
	global_load_dwordx4 v[24:27], v[24:25], off
	v_or_b32_e32 v90, 60, v90
	v_mad_i64_i32 v[46:47], s[2:3], v90, s48, v[22:23]
	global_load_dwordx4 v[46:49], v[46:47], off
	s_mov_b32 s2, 64
	s_waitcnt vmcnt(3)
	v_mul_f32_e32 v87, v0, v128
	v_mul_f32_e32 v104, v1, v128
	v_mul_f32_e32 v2, v2, v128
	v_mul_f32_e32 v3, v3, v128
	s_waitcnt vmcnt(2)
	v_mul_f32_e32 v1, v4, v130
	v_max3_f32 v4, v36, |v87|, |v1|
	v_mul_f32_e32 v1, v5, v130
	v_max3_f32 v5, v102, |v104|, |v1|
	v_mul_f32_e32 v1, v6, v130
	v_mul_f32_e32 v0, v7, v130
	v_max3_f32 v2, v21, |v2|, |v1|
	v_max3_f32 v3, v103, |v3|, |v0|
	s_waitcnt vmcnt(1)
	v_mul_f32_e32 v6, v24, v132
	v_mul_f32_e32 v7, v25, v132
	v_mul_f32_e32 v21, v26, v132
	v_mul_f32_e32 v24, v27, v132
	v_mul_f32_e32 v1, v28, v134
	v_max3_f32 v4, v4, |v6|, |v1|
	v_mul_f32_e32 v1, v29, v134
	v_max3_f32 v5, v5, |v7|, |v1|
	v_mul_f32_e32 v1, v30, v134
	v_mul_f32_e32 v0, v31, v134
	v_max3_f32 v2, v2, |v21|, |v1|
	v_max3_f32 v3, v3, |v24|, |v0|
	v_mul_f32_e32 v6, v32, v136
	v_mul_f32_e32 v7, v33, v136
	v_mul_f32_e32 v21, v34, v136
	v_mul_f32_e32 v24, v35, v136
	v_mul_f32_e32 v1, v38, v138
	v_max3_f32 v4, v4, |v6|, |v1|
	v_mul_f32_e32 v1, v39, v138
	v_max3_f32 v5, v5, |v7|, |v1|
	v_mul_f32_e32 v1, v40, v138
	v_mul_f32_e32 v0, v41, v138
	v_max3_f32 v6, v2, |v21|, |v1|
	v_max3_f32 v7, v3, |v24|, |v0|
	v_mul_f32_e32 v2, v42, v140
	v_mul_f32_e32 v21, v43, v140
	v_mul_f32_e32 v24, v44, v140
	v_mul_f32_e32 v25, v45, v140
	s_waitcnt vmcnt(0)
	v_mul_f32_e32 v1, v46, v142
	v_max3_f32 v3, v4, |v2|, |v1|
	v_mul_f32_e32 v1, v47, v142
	v_max3_f32 v2, v5, |v21|, |v1|
	v_mul_f32_e32 v1, v48, v142
	v_mul_f32_e32 v0, v49, v142
	v_max3_f32 v1, v6, |v24|, |v1|
	v_max3_f32 v0, v7, |v25|, |v0|
	s_cbranch_vccz .LBB0_1911
	v_and_b32_e32 v5, 64, v159
	v_xor_b32_e32 v4, 16, v159
	v_add_u32_e32 v5, 64, v5
	v_cmp_lt_i32_e32 vcc, v4, v5
	s_nop 1
	v_cndmask_b32_e32 v4, v159, v4, vcc
	v_lshlrev_b32_e32 v6, 2, v4
	ds_bpermute_b32 v7, v6, v3
	v_xor_b32_e32 v4, 32, v159
	v_cmp_lt_i32_e32 vcc, v4, v5
	ds_bpermute_b32 v5, v6, v2
	ds_bpermute_b32 v24, v6, v0
	v_cndmask_b32_e32 v4, v159, v4, vcc
	v_lshlrev_b32_e32 v21, 2, v4
	s_waitcnt lgkmcnt(2)
	v_max_f32_e32 v4, v7, v7
	ds_bpermute_b32 v7, v6, v1
	v_max_f32_e32 v3, v3, v3
	s_waitcnt lgkmcnt(2)
	v_max_f32_e32 v5, v5, v5
	v_max_f32_e32 v2, v2, v2
	v_max_f32_e32 v1, v1, v1
	s_waitcnt lgkmcnt(0)
	v_max_f32_e32 v6, v7, v7
	v_max_f32_e32 v7, v24, v24
	v_max_f32_e32 v0, v0, v0
	v_max_f32_e32 v3, v3, v4
	v_max_f32_e32 v2, v2, v5
	v_max_f32_e32 v1, v1, v6
	v_max_f32_e32 v0, v0, v7
	ds_bpermute_b32 v4, v21, v3
	ds_bpermute_b32 v5, v21, v2
	ds_bpermute_b32 v6, v21, v1
	ds_bpermute_b32 v7, v21, v0
	s_and_saveexec_b64 s[14:15], s[4:5]
	s_cbranch_execz .LBB0_1914
	s_waitcnt lgkmcnt(0)
	v_max_f32_e32 v7, v7, v7
	v_max_f32_e32 v0, v0, v0
	v_max_f32_e32 v7, v0, v7
	v_max_f32_e32 v0, v6, v6
	v_max_f32_e32 v1, v1, v1
	v_max_f32_e32 v6, v1, v0
	v_max_f32_e32 v0, v5, v5
	v_max_f32_e32 v1, v2, v2
	v_max_f32_e32 v5, v1, v0
	v_max_f32_e32 v0, v4, v4
	v_max_f32_e32 v1, v3, v3
	v_max_f32_e32 v4, v1, v0
	v_add_u32_e32 v0, s90, v67
	ds_write_b128 v0, v[4:7]

.LBB0_1917:
	s_or_b32 s34, s0, s89
	v_or_b32_e32 v110, s34, v57
	v_ashrrev_i32_e32 v111, 31, v110
	v_lshl_add_u64 v[112:113], v[110:111], 2, s[16:17]
	global_load_dword v114, v[112:113], off
	v_or_b32_e32 v110, s34, v11
	v_ashrrev_i32_e32 v111, 31, v110
	v_lshl_add_u64 v[110:111], v[110:111], 2, s[16:17]
	global_load_dword v116, v[110:111], off
	v_or_b32_e32 v110, s34, v70
	v_ashrrev_i32_e32 v111, 31, v110
	v_lshl_add_u64 v[110:111], v[110:111], 2, s[16:17]
	global_load_dword v118, v[110:111], off
	v_or_b32_e32 v110, s34, v71
	v_ashrrev_i32_e32 v111, 31, v110
	v_lshl_add_u64 v[110:111], v[110:111], 2, s[16:17]
	global_load_dword v120, v[110:111], off
	v_or_b32_e32 v110, s34, v72
	v_ashrrev_i32_e32 v111, 31, v110
	v_lshl_add_u64 v[110:111], v[110:111], 2, s[16:17]
	global_load_dword v122, v[110:111], off
	v_or_b32_e32 v110, s34, v73
	v_ashrrev_i32_e32 v111, 31, v110
	v_lshl_add_u64 v[110:111], v[110:111], 2, s[16:17]
	global_load_dword v124, v[110:111], off
	v_or_b32_e32 v110, s34, v75
	v_ashrrev_i32_e32 v111, 31, v110
	v_lshl_add_u64 v[110:111], v[110:111], 2, s[16:17]
	global_load_dword v126, v[110:111], off
	v_or_b32_e32 v110, s34, v76
	v_ashrrev_i32_e32 v111, 31, v110
	v_lshl_add_u64 v[110:111], v[110:111], 2, s[16:17]
	global_load_dword v128, v[110:111], off
	v_or_b32_e32 v110, s34, v77
	v_ashrrev_i32_e32 v111, 31, v110
	v_lshl_add_u64 v[110:111], v[110:111], 2, s[16:17]
	global_load_dword v130, v[110:111], off
	v_or_b32_e32 v110, s34, v78
	v_ashrrev_i32_e32 v111, 31, v110
	v_lshl_add_u64 v[110:111], v[110:111], 2, s[16:17]
	global_load_dword v132, v[110:111], off
	v_or_b32_e32 v110, s34, v79
	v_ashrrev_i32_e32 v111, 31, v110
	v_lshl_add_u64 v[110:111], v[110:111], 2, s[16:17]
	global_load_dword v134, v[110:111], off
	v_or_b32_e32 v110, s34, v80
	v_ashrrev_i32_e32 v111, 31, v110
	v_lshl_add_u64 v[110:111], v[110:111], 2, s[16:17]
	global_load_dword v136, v[110:111], off
	v_or_b32_e32 v110, s34, v81
	v_ashrrev_i32_e32 v111, 31, v110
	v_lshl_add_u64 v[110:111], v[110:111], 2, s[16:17]
	global_load_dword v138, v[110:111], off
	v_or_b32_e32 v110, s34, v82
	v_ashrrev_i32_e32 v111, 31, v110
	v_lshl_add_u64 v[110:111], v[110:111], 2, s[16:17]
	global_load_dword v140, v[110:111], off
	v_or_b32_e32 v110, s34, v83
	v_ashrrev_i32_e32 v111, 31, v110
	v_lshl_add_u64 v[110:111], v[110:111], 2, s[16:17]
	global_load_dword v142, v[110:111], off
	v_or_b32_e32 v110, s34, v84
	v_ashrrev_i32_e32 v111, 31, v110
	v_lshl_add_u64 v[110:111], v[110:111], 2, s[16:17]
	global_load_dword v144, v[110:111], off
	v_or_b32_e32 v44, s34, v57
	v_mad_i64_i32 v[0:1], s[0:1], v44, s48, v[22:23]
	v_add_u32_e32 v21, v69, v59
	global_load_dwordx4 v[46:49], v[0:1], off nt
	v_or_b32_e32 v0, 4, v44
	v_mad_i64_i32 v[0:1], s[0:1], v0, s48, v[22:23]
	global_load_dwordx4 v[86:89], v[0:1], off nt
	v_add_u32_e32 v45, 0x410, v21
	v_or_b32_e32 v0, 8, v44
	v_mad_i64_i32 v[0:1], s[0:1], v0, s48, v[22:23]
	global_load_dwordx4 v[90:93], v[0:1], off nt
	v_or_b32_e32 v0, 12, v44
	v_mad_i64_i32 v[0:1], s[0:1], v0, s48, v[22:23]
	global_load_dwordx4 v[94:97], v[0:1], off nt
	v_or_b32_e32 v0, 16, v44
	v_mad_i64_i32 v[0:1], s[0:1], v0, s48, v[22:23]
	global_load_dwordx4 v[98:101], v[0:1], off nt
	v_or_b32_e32 v0, 20, v44
	v_mad_i64_i32 v[0:1], s[0:1], v0, s48, v[22:23]
	global_load_dwordx4 v[102:105], v[0:1], off nt
	v_or_b32_e32 v0, 24, v44
	v_mad_i64_i32 v[0:1], s[0:1], v0, s48, v[22:23]
	global_load_dwordx4 v[4:7], v[0:1], off nt
	v_or_b32_e32 v0, 28, v44
	v_mad_i64_i32 v[0:1], s[0:1], v0, s48, v[22:23]
	global_load_dwordx4 v[0:3], v[0:1], off nt
	s_ashr_i32 s35, s34, 31
	s_and_b64 vcc, exec, s[14:15]
	s_mov_b64 s[14:15], 0
	s_waitcnt vmcnt(23)
	v_pk_mul_f32 v[108:109], v[24:25], v[114:115] op_sel_hi:[1,0]
	s_waitcnt vmcnt(7)
	v_pk_mul_f32 v[46:47], v[46:47], v[108:109]
	ds_write2_b32 v21, v46, v47 offset1:1
	v_pk_mul_f32 v[46:47], v[26:27], v[114:115] op_sel_hi:[1,0]
	s_nop 0
	v_pk_mul_f32 v[46:47], v[48:49], v[46:47]
	ds_write2_b32 v21, v46, v47 offset0:2 offset1:3
	v_pk_mul_f32 v[48:49], v[24:25], v[116:117] op_sel_hi:[1,0]
	s_nop 0
	s_waitcnt vmcnt(6)
	v_pk_mul_f32 v[48:49], v[86:87], v[48:49]
	v_pk_mul_f32 v[46:47], v[26:27], v[116:117] op_sel_hi:[1,0]
	ds_write2_b32 v45, v48, v49 offset1:1
	v_pk_mul_f32 v[46:47], v[88:89], v[46:47]
	v_add_u32_e32 v45, 0x418, v21
	ds_write2_b32 v45, v46, v47 offset1:1
	v_add_u32_e32 v45, 0x820, v21
	v_pk_mul_f32 v[48:49], v[24:25], v[118:119] op_sel_hi:[1,0]
	s_nop 0
	s_waitcnt vmcnt(5)
	v_pk_mul_f32 v[48:49], v[90:91], v[48:49]
	v_pk_mul_f32 v[46:47], v[26:27], v[118:119] op_sel_hi:[1,0]
	ds_write2_b32 v45, v48, v49 offset1:1
	v_pk_mul_f32 v[46:47], v[92:93], v[46:47]
	v_add_u32_e32 v45, 0x828, v21
	ds_write2_b32 v45, v46, v47 offset1:1
	v_add_u32_e32 v45, 0xc30, v21
	v_pk_mul_f32 v[48:49], v[24:25], v[120:121] op_sel_hi:[1,0]
	s_nop 0
	s_waitcnt vmcnt(4)
	v_pk_mul_f32 v[48:49], v[94:95], v[48:49]
	v_pk_mul_f32 v[46:47], v[26:27], v[120:121] op_sel_hi:[1,0]
	ds_write2_b32 v45, v48, v49 offset1:1
	v_pk_mul_f32 v[46:47], v[96:97], v[46:47]
	v_add_u32_e32 v45, 0xc38, v21
	ds_write2_b32 v45, v46, v47 offset1:1
	v_add_u32_e32 v45, 0x1040, v21
	v_pk_mul_f32 v[48:49], v[24:25], v[122:123] op_sel_hi:[1,0]
	s_nop 0
	s_waitcnt vmcnt(3)
	v_pk_mul_f32 v[48:49], v[98:99], v[48:49]
	v_pk_mul_f32 v[46:47], v[26:27], v[122:123] op_sel_hi:[1,0]
	ds_write2_b32 v45, v48, v49 offset1:1
	v_pk_mul_f32 v[46:47], v[100:101], v[46:47]
	v_add_u32_e32 v45, 0x1048, v21
	ds_write2_b32 v45, v46, v47 offset1:1
	v_add_u32_e32 v21, 0x1450, v21
	v_pk_mul_f32 v[48:49], v[24:25], v[124:125] op_sel_hi:[1,0]
	s_nop 0
	s_waitcnt vmcnt(2)
	v_pk_mul_f32 v[48:49], v[102:103], v[48:49]
	v_pk_mul_f32 v[46:47], v[26:27], v[124:125] op_sel_hi:[1,0]
	ds_write2_b32 v21, v48, v49 offset1:1
	v_pk_mul_f32 v[46:47], v[104:105], v[46:47]
	v_add_u32_e32 v21, v69, v74
	ds_write2_b32 v21, v46, v47 offset0:2 offset1:3
	v_add_u32_e32 v45, 0x410, v21
	v_pk_mul_f32 v[48:49], v[24:25], v[126:127] op_sel_hi:[1,0]
	s_nop 0
	s_waitcnt vmcnt(1)
	v_pk_mul_f32 v[4:5], v[4:5], v[48:49]
	ds_write2_b32 v45, v4, v5 offset1:1
	v_pk_mul_f32 v[4:5], v[26:27], v[126:127] op_sel_hi:[1,0]
	v_or_b32_e32 v45, 40, v44
	v_pk_mul_f32 v[4:5], v[6:7], v[4:5]
	v_add_u32_e32 v6, 0x418, v21
	ds_write2_b32 v6, v4, v5 offset1:1
	v_mad_i64_i32 v[46:47], s[0:1], v45, s48, v[22:23]
	v_or_b32_e32 v45, 44, v44
	v_mad_i64_i32 v[86:87], s[0:1], v45, s48, v[22:23]
	v_or_b32_e32 v45, 48, v44
	v_mad_i64_i32 v[90:91], s[0:1], v45, s48, v[22:23]
	v_or_b32_e32 v45, 52, v44
	v_mad_i64_i32 v[94:95], s[0:1], v45, s48, v[22:23]
	v_or_b32_e32 v45, 56, v44
	v_mad_i64_i32 v[98:99], s[0:1], v45, s48, v[22:23]
	global_load_dwordx4 v[46:49], v[46:47], off nt
	v_pk_mul_f32 v[6:7], v[24:25], v[128:129] op_sel_hi:[1,0]
	s_nop 0
	s_waitcnt vmcnt(1)
	v_pk_mul_f32 v[0:1], v[0:1], v[6:7]
	v_add_u32_e32 v5, 0x820, v21
	ds_write2_b32 v5, v0, v1 offset1:1
	v_pk_mul_f32 v[0:1], v[26:27], v[128:129] op_sel_hi:[1,0]
	v_or_b32_e32 v4, 36, v44
	v_pk_mul_f32 v[0:1], v[2:3], v[0:1]
	v_add_u32_e32 v2, 0x828, v21
	ds_write2_b32 v2, v0, v1 offset1:1
	v_or_b32_e32 v0, 32, v44
	v_or_b32_e32 v44, 60, v44
	v_mad_i64_i32 v[44:45], s[0:1], v44, s48, v[22:23]
	global_load_dwordx4 v[102:105], v[44:45], off nt
	v_mad_i64_i32 v[0:1], s[0:1], v0, s48, v[22:23]
	v_mad_i64_i32 v[4:5], s[0:1], v4, s48, v[22:23]
	global_load_dwordx4 v[0:3], v[0:1], off nt
	s_mov_b32 s0, 64
	global_load_dwordx4 v[4:7], v[4:5], off nt
	v_pk_mul_f32 v[106:107], v[24:25], v[130:131] op_sel_hi:[1,0]
	v_add_u32_e32 v45, 0xc30, v21
	global_load_dwordx4 v[86:89], v[86:87], off nt
	s_waitcnt vmcnt(2)
	v_pk_mul_f32 v[0:1], v[0:1], v[106:107]
	ds_write2_b32 v45, v0, v1 offset1:1
	v_pk_mul_f32 v[0:1], v[26:27], v[130:131] op_sel_hi:[1,0]
	global_load_dwordx4 v[90:93], v[90:91], off nt
	v_pk_mul_f32 v[0:1], v[2:3], v[0:1]
	v_add_u32_e32 v2, 0xc38, v21
	ds_write2_b32 v2, v0, v1 offset1:1
	v_pk_mul_f32 v[2:3], v[24:25], v[132:133] op_sel_hi:[1,0]
	s_nop 0
	s_waitcnt vmcnt(2)
	v_pk_mul_f32 v[2:3], v[4:5], v[2:3]
	v_add_u32_e32 v1, 0x1040, v21
	ds_write2_b32 v1, v2, v3 offset1:1
	v_pk_mul_f32 v[0:1], v[26:27], v[132:133] op_sel_hi:[1,0]
	v_add_u32_e32 v2, 0x1048, v21
	v_pk_mul_f32 v[0:1], v[6:7], v[0:1]
	ds_write2_b32 v2, v0, v1 offset1:1
	v_pk_mul_f32 v[2:3], v[24:25], v[134:135] op_sel_hi:[1,0]
	s_nop 0
	v_pk_mul_f32 v[2:3], v[46:47], v[2:3]
	v_add_u32_e32 v1, 0x1450, v21
	ds_write2_b32 v1, v2, v3 offset1:1
	v_pk_mul_f32 v[0:1], v[26:27], v[134:135] op_sel_hi:[1,0]
	v_add_u32_e32 v2, 0x1458, v21
	v_pk_mul_f32 v[0:1], v[48:49], v[0:1]
	ds_write2_b32 v2, v0, v1 offset1:1
	v_pk_mul_f32 v[2:3], v[24:25], v[136:137] op_sel_hi:[1,0]
	s_nop 0
	s_waitcnt vmcnt(1)
	v_pk_mul_f32 v[2:3], v[86:87], v[2:3]
	v_add_u32_e32 v1, 0x1860, v21
	ds_write2_b32 v1, v2, v3 offset1:1
	v_pk_mul_f32 v[0:1], v[26:27], v[136:137] op_sel_hi:[1,0]
	v_add_u32_e32 v2, 0x1868, v21
	v_pk_mul_f32 v[0:1], v[88:89], v[0:1]
	ds_write2_b32 v2, v0, v1 offset1:1
	v_pk_mul_f32 v[2:3], v[24:25], v[138:139] op_sel_hi:[1,0]
	s_nop 0
	s_waitcnt vmcnt(0)
	v_pk_mul_f32 v[2:3], v[90:91], v[2:3]
	v_add_u32_e32 v1, 0x1c70, v21
	ds_write2_b32 v1, v2, v3 offset1:1
	v_pk_mul_f32 v[0:1], v[26:27], v[138:139] op_sel_hi:[1,0]
	v_add_u32_e32 v2, 0x1c78, v21
	v_pk_mul_f32 v[0:1], v[92:93], v[0:1]
	ds_write2_b32 v2, v0, v1 offset1:1
	v_pk_mul_f32 v[2:3], v[24:25], v[140:141] op_sel_hi:[1,0]
	global_load_dwordx4 v[94:97], v[94:95], off nt
	v_add_u32_e32 v1, 0x2080, v21
	global_load_dwordx4 v[98:101], v[98:99], off nt
	s_waitcnt vmcnt(1)
	v_pk_mul_f32 v[2:3], v[94:95], v[2:3]
	ds_write2_b32 v1, v2, v3 offset1:1
	v_pk_mul_f32 v[0:1], v[26:27], v[140:141] op_sel_hi:[1,0]
	v_add_u32_e32 v2, 0x2088, v21
	v_pk_mul_f32 v[0:1], v[96:97], v[0:1]
	ds_write2_b32 v2, v0, v1 offset1:1
	v_pk_mul_f32 v[2:3], v[24:25], v[142:143] op_sel_hi:[1,0]
	s_nop 0
	s_waitcnt vmcnt(0)
	v_pk_mul_f32 v[2:3], v[98:99], v[2:3]
	v_add_u32_e32 v1, 0x2490, v21
	ds_write2_b32 v1, v2, v3 offset1:1
	v_pk_mul_f32 v[0:1], v[26:27], v[142:143] op_sel_hi:[1,0]
	v_add_u32_e32 v2, 0x2498, v21
	v_pk_mul_f32 v[0:1], v[100:101], v[0:1]
	ds_write2_b32 v2, v0, v1 offset1:1
	v_pk_mul_f32 v[2:3], v[24:25], v[144:145] op_sel_hi:[1,0]
	s_nop 0
	v_pk_mul_f32 v[2:3], v[102:103], v[2:3]
	v_add_u32_e32 v1, 0x28a0, v21
	ds_write2_b32 v1, v2, v3 offset1:1
	v_pk_mul_f32 v[0:1], v[26:27], v[144:145] op_sel_hi:[1,0]
	v_add_u32_e32 v2, 0x28a8, v21
	v_pk_mul_f32 v[0:1], v[104:105], v[0:1]
	ds_write2_b32 v2, v0, v1 offset1:1
	s_waitcnt lgkmcnt(0)
	ds_read2_b32 v[6:7], v9 offset0:130 offset1:138
	ds_read2_b32 v[44:45], v9 offset0:195 offset1:203
	ds_read2_b32 v[2:3], v9 offset1:8
	ds_read2_b32 v[4:5], v9 offset0:65 offset1:73
	v_lshl_add_u64 v[0:1], v[12:13], 0, s[34:35]
	s_waitcnt lgkmcnt(3)
	v_med3_f32 v6, v6, s52, v53
	s_waitcnt lgkmcnt(2)
	v_med3_f32 v21, v44, s52, v53
	v_add_f32_e32 v6, 0x4b400000, v6
	v_add_f32_e32 v21, 0x4b400000, v21
	v_perm_b32 v6, v21, v6, s53
	v_add_u32_e32 v21, 0x400, v9
	ds_read2_b32 v[48:49], v21 offset0:4 offset1:12
	ds_read2_b32 v[86:87], v21 offset0:69 offset1:77
	ds_read2_b32 v[88:89], v21 offset0:134 offset1:142
	ds_read2_b32 v[90:91], v21 offset0:199 offset1:207
	s_waitcnt lgkmcnt(5)
	v_med3_f32 v2, v2, s52, v53
	s_waitcnt lgkmcnt(4)
	v_med3_f32 v4, v4, s52, v53
	v_add_f32_e32 v2, 0x4b400000, v2
	v_add_f32_e32 v4, 0x4b400000, v4
	v_perm_b32 v2, v4, v2, s53
	v_perm_b32 v46, v6, v2, s54
	s_waitcnt lgkmcnt(3)
	v_med3_f32 v2, v48, s52, v53
	s_waitcnt lgkmcnt(2)
	v_med3_f32 v4, v86, s52, v53
	s_waitcnt lgkmcnt(1)
	v_med3_f32 v6, v88, s52, v53
	s_waitcnt lgkmcnt(0)
	v_med3_f32 v44, v90, s52, v53
	v_add_f32_e32 v2, 0x4b400000, v2
	v_add_f32_e32 v4, 0x4b400000, v4
	v_add_f32_e32 v6, 0x4b400000, v6
	v_add_f32_e32 v44, 0x4b400000, v44
	v_perm_b32 v6, v44, v6, s53
	v_perm_b32 v2, v4, v2, s53
	v_perm_b32 v47, v6, v2, s54
	v_med3_f32 v2, v3, s52, v53
	v_med3_f32 v3, v5, s52, v53
	v_med3_f32 v4, v7, s52, v53
	v_med3_f32 v5, v45, s52, v53
	v_add_f32_e32 v2, 0x4b400000, v2
	v_add_f32_e32 v3, 0x4b400000, v3
	v_add_f32_e32 v4, 0x4b400000, v4
	v_add_f32_e32 v5, 0x4b400000, v5
	v_perm_b32 v4, v5, v4, s53
	v_perm_b32 v2, v3, v2, s53
	v_perm_b32 v2, v4, v2, s54
	v_med3_f32 v3, v49, s52, v53
	v_med3_f32 v4, v87, s52, v53
	v_med3_f32 v5, v89, s52, v53
	v_med3_f32 v6, v91, s52, v53
	v_add_f32_e32 v3, 0x4b400000, v3
	v_add_f32_e32 v4, 0x4b400000, v4
	v_add_f32_e32 v5, 0x4b400000, v5
	v_add_f32_e32 v6, 0x4b400000, v6
	v_perm_b32 v5, v6, v5, s53
	v_perm_b32 v3, v4, v3, s53
	v_perm_b32 v3, v5, v3, s54
	v_lshl_add_u64 v[4:5], v[0:1], 0, v[28:29]
	global_store_dwordx2 v[4:5], v[2:3], off
	ds_read2_b32 v[2:3], v9 offset0:16 offset1:24
	ds_read2_b32 v[4:5], v9 offset0:81 offset1:89
	ds_read2_b32 v[6:7], v9 offset0:146 offset1:154
	ds_read2_b32 v[44:45], v9 offset0:211 offset1:219
	ds_read2_b32 v[48:49], v21 offset0:20 offset1:28
	ds_read2_b32 v[86:87], v21 offset0:85 offset1:93
	ds_read2_b32 v[88:89], v21 offset0:150 offset1:158
	ds_read2_b32 v[90:91], v21 offset0:215 offset1:223
	s_waitcnt lgkmcnt(7)
	v_med3_f32 v2, v2, s52, v53
	s_waitcnt lgkmcnt(6)
	v_med3_f32 v4, v4, s52, v53
	s_waitcnt lgkmcnt(5)
	v_med3_f32 v6, v6, s52, v53
	s_waitcnt lgkmcnt(4)
	v_med3_f32 v44, v44, s52, v53
	v_add_f32_e32 v2, 0x4b400000, v2
	v_add_f32_e32 v4, 0x4b400000, v4
	v_add_f32_e32 v6, 0x4b400000, v6
	v_add_f32_e32 v44, 0x4b400000, v44
	v_lshl_add_u64 v[92:93], v[0:1], 0, v[36:37]
	v_perm_b32 v6, v44, v6, s53
	v_perm_b32 v2, v4, v2, s53
	global_store_dwordx2 v[92:93], v[46:47], off
	v_perm_b32 v46, v6, v2, s54
	s_waitcnt lgkmcnt(3)
	v_med3_f32 v2, v48, s52, v53
	s_waitcnt lgkmcnt(2)
	v_med3_f32 v4, v86, s52, v53
	s_waitcnt lgkmcnt(1)
	v_med3_f32 v6, v88, s52, v53
	s_waitcnt lgkmcnt(0)
	v_med3_f32 v44, v90, s52, v53
	v_add_f32_e32 v2, 0x4b400000, v2
	v_add_f32_e32 v4, 0x4b400000, v4
	v_add_f32_e32 v6, 0x4b400000, v6
	v_add_f32_e32 v44, 0x4b400000, v44
	v_perm_b32 v6, v44, v6, s53
	v_perm_b32 v2, v4, v2, s53
	v_perm_b32 v47, v6, v2, s54
	v_med3_f32 v2, v3, s52, v53
	v_med3_f32 v3, v5, s52, v53
	v_med3_f32 v4, v7, s52, v53
	v_med3_f32 v5, v45, s52, v53
	v_add_f32_e32 v2, 0x4b400000, v2
	v_add_f32_e32 v3, 0x4b400000, v3
	v_add_f32_e32 v4, 0x4b400000, v4
	v_add_f32_e32 v5, 0x4b400000, v5
	v_perm_b32 v4, v5, v4, s53
	v_perm_b32 v2, v3, v2, s53
	v_perm_b32 v2, v4, v2, s54
	v_med3_f32 v3, v49, s52, v53
	v_med3_f32 v4, v87, s52, v53
	v_med3_f32 v5, v89, s52, v53
	v_med3_f32 v6, v91, s52, v53
	v_add_f32_e32 v3, 0x4b400000, v3
	v_add_f32_e32 v4, 0x4b400000, v4
	v_add_f32_e32 v5, 0x4b400000, v5
	v_add_f32_e32 v6, 0x4b400000, v6
	v_perm_b32 v5, v6, v5, s53
	v_perm_b32 v3, v4, v3, s53
	v_perm_b32 v3, v5, v3, s54
	v_lshl_add_u64 v[4:5], v[0:1], 0, v[32:33]
	global_store_dwordx2 v[4:5], v[2:3], off
	ds_read2_b32 v[2:3], v9 offset0:32 offset1:40
	ds_read2_b32 v[4:5], v9 offset0:97 offset1:105
	ds_read2_b32 v[6:7], v9 offset0:162 offset1:170
	ds_read2_b32 v[44:45], v9 offset0:227 offset1:235
	ds_read2_b32 v[48:49], v21 offset0:36 offset1:44
	ds_read2_b32 v[86:87], v21 offset0:101 offset1:109
	ds_read2_b32 v[88:89], v21 offset0:166 offset1:174
	ds_read2_b32 v[90:91], v21 offset0:231 offset1:239
	s_waitcnt lgkmcnt(7)
	v_med3_f32 v2, v2, s52, v53
	s_waitcnt lgkmcnt(6)
	v_med3_f32 v4, v4, s52, v53
	s_waitcnt lgkmcnt(5)
	v_med3_f32 v6, v6, s52, v53
	s_waitcnt lgkmcnt(4)
	v_med3_f32 v44, v44, s52, v53
	v_add_f32_e32 v2, 0x4b400000, v2
	v_add_f32_e32 v4, 0x4b400000, v4
	v_add_f32_e32 v6, 0x4b400000, v6
	v_add_f32_e32 v44, 0x4b400000, v44
	v_lshl_add_u64 v[92:93], v[0:1], 0, v[30:31]
	v_perm_b32 v6, v44, v6, s53
	v_perm_b32 v2, v4, v2, s53
	global_store_dwordx2 v[92:93], v[46:47], off
	v_perm_b32 v46, v6, v2, s54
	s_waitcnt lgkmcnt(3)
	v_med3_f32 v2, v48, s52, v53
	s_waitcnt lgkmcnt(2)
	v_med3_f32 v4, v86, s52, v53
	s_waitcnt lgkmcnt(1)
	v_med3_f32 v6, v88, s52, v53
	s_waitcnt lgkmcnt(0)
	v_med3_f32 v44, v90, s52, v53
	v_add_f32_e32 v2, 0x4b400000, v2
	v_add_f32_e32 v4, 0x4b400000, v4
	v_add_f32_e32 v6, 0x4b400000, v6
	v_add_f32_e32 v44, 0x4b400000, v44
	v_perm_b32 v6, v44, v6, s53
	v_perm_b32 v2, v4, v2, s53
	v_perm_b32 v47, v6, v2, s54
	v_med3_f32 v2, v3, s52, v53
	v_med3_f32 v3, v5, s52, v53
	v_med3_f32 v4, v7, s52, v53
	v_med3_f32 v5, v45, s52, v53
	v_add_f32_e32 v2, 0x4b400000, v2
	v_add_f32_e32 v3, 0x4b400000, v3
	v_add_f32_e32 v4, 0x4b400000, v4
	v_add_f32_e32 v5, 0x4b400000, v5
	v_perm_b32 v4, v5, v4, s53
	v_perm_b32 v2, v3, v2, s53
	v_perm_b32 v2, v4, v2, s54
	v_med3_f32 v3, v49, s52, v53
	v_med3_f32 v4, v87, s52, v53
	v_med3_f32 v5, v89, s52, v53
	v_med3_f32 v6, v91, s52, v53
	v_add_f32_e32 v3, 0x4b400000, v3
	v_add_f32_e32 v4, 0x4b400000, v4
	v_add_f32_e32 v5, 0x4b400000, v5
	v_add_f32_e32 v6, 0x4b400000, v6
	v_perm_b32 v5, v6, v5, s53
	v_perm_b32 v3, v4, v3, s53
	v_perm_b32 v3, v5, v3, s54
	v_lshl_add_u64 v[4:5], v[0:1], 0, v[38:39]
	global_store_dwordx2 v[4:5], v[2:3], off
	ds_read2_b32 v[2:3], v9 offset0:48 offset1:56
	ds_read2_b32 v[4:5], v9 offset0:113 offset1:121
	ds_read2_b32 v[6:7], v9 offset0:178 offset1:186
	ds_read2_b32 v[44:45], v9 offset0:243 offset1:251
	ds_read2_b32 v[48:49], v21 offset0:52 offset1:60
	ds_read2_b32 v[86:87], v21 offset0:117 offset1:125
	ds_read2_b32 v[88:89], v21 offset0:182 offset1:190
	ds_read2_b32 v[90:91], v21 offset0:247 offset1:255
	s_waitcnt lgkmcnt(7)
	v_med3_f32 v2, v2, s52, v53
	s_waitcnt lgkmcnt(6)
	v_med3_f32 v4, v4, s52, v53
	s_waitcnt lgkmcnt(5)
	v_med3_f32 v6, v6, s52, v53
	s_waitcnt lgkmcnt(4)
	v_med3_f32 v44, v44, s52, v53
	v_add_f32_e32 v2, 0x4b400000, v2
	v_add_f32_e32 v4, 0x4b400000, v4
	v_add_f32_e32 v6, 0x4b400000, v6
	v_add_f32_e32 v44, 0x4b400000, v44
	v_lshl_add_u64 v[92:93], v[0:1], 0, v[34:35]
	v_perm_b32 v6, v44, v6, s53
	v_perm_b32 v2, v4, v2, s53
	global_store_dwordx2 v[92:93], v[46:47], off
	v_perm_b32 v46, v6, v2, s54
	s_waitcnt lgkmcnt(3)
	v_med3_f32 v2, v48, s52, v53
	s_waitcnt lgkmcnt(2)
	v_med3_f32 v4, v86, s52, v53
	s_waitcnt lgkmcnt(1)
	v_med3_f32 v6, v88, s52, v53
	s_waitcnt lgkmcnt(0)
	v_med3_f32 v21, v90, s52, v53
	v_add_f32_e32 v2, 0x4b400000, v2
	v_add_f32_e32 v4, 0x4b400000, v4
	v_add_f32_e32 v6, 0x4b400000, v6
	v_add_f32_e32 v21, 0x4b400000, v21
	v_perm_b32 v6, v21, v6, s53
	v_perm_b32 v2, v4, v2, s53
	v_perm_b32 v47, v6, v2, s54
	v_med3_f32 v2, v3, s52, v53
	v_med3_f32 v3, v5, s52, v53
	v_med3_f32 v4, v7, s52, v53
	v_med3_f32 v5, v45, s52, v53
	v_add_f32_e32 v2, 0x4b400000, v2
	v_add_f32_e32 v3, 0x4b400000, v3
	v_add_f32_e32 v4, 0x4b400000, v4
	v_add_f32_e32 v5, 0x4b400000, v5
	v_perm_b32 v4, v5, v4, s53
	v_perm_b32 v2, v3, v2, s53
	v_perm_b32 v2, v4, v2, s54
	v_med3_f32 v3, v49, s52, v53
	v_med3_f32 v4, v87, s52, v53
	v_med3_f32 v5, v89, s52, v53
	v_med3_f32 v6, v91, s52, v53
	v_add_f32_e32 v3, 0x4b400000, v3
	v_add_f32_e32 v4, 0x4b400000, v4
	v_add_f32_e32 v5, 0x4b400000, v5
	v_add_f32_e32 v6, 0x4b400000, v6
	v_perm_b32 v5, v6, v5, s53
	v_perm_b32 v3, v4, v3, s53
	v_lshl_add_u64 v[92:93], v[0:1], 0, v[40:41]
	v_perm_b32 v3, v5, v3, s54
	v_lshl_add_u64 v[0:1], v[0:1], 0, v[42:43]
	global_store_dwordx2 v[92:93], v[46:47], off
	global_store_dwordx2 v[0:1], v[2:3], off
	s_waitcnt lgkmcnt(0)
	s_cbranch_vccnz .LBB0_1917
	s_barrier

.LBB0_1921:
	v_or_b32_e32 v108, s0, v85
	v_ashrrev_i32_e32 v109, 31, v108
	v_lshl_add_u64 v[110:111], v[108:109], 2, s[12:13]
	global_load_dword v112, v[110:111], off
	v_or_b32_e32 v108, s0, v85
	v_or_b32_e32 v110, 4, v108
	v_ashrrev_i32_e32 v111, 31, v110
	v_lshl_add_u64 v[108:109], v[110:111], 2, s[12:13]
	global_load_dword v114, v[108:109], off
	v_or_b32_e32 v108, s0, v85
	v_or_b32_e32 v110, 8, v108
	v_ashrrev_i32_e32 v111, 31, v110
	v_lshl_add_u64 v[108:109], v[110:111], 2, s[12:13]
	global_load_dword v116, v[108:109], off
	v_or_b32_e32 v108, s0, v85
	v_or_b32_e32 v110, 12, v108
	v_ashrrev_i32_e32 v111, 31, v110
	v_lshl_add_u64 v[108:109], v[110:111], 2, s[12:13]
	global_load_dword v118, v[108:109], off
	v_or_b32_e32 v108, s0, v85
	v_or_b32_e32 v110, 16, v108
	v_ashrrev_i32_e32 v111, 31, v110
	v_lshl_add_u64 v[108:109], v[110:111], 2, s[12:13]
	global_load_dword v120, v[108:109], off
	v_or_b32_e32 v108, s0, v85
	v_or_b32_e32 v110, 20, v108
	v_ashrrev_i32_e32 v111, 31, v110
	v_lshl_add_u64 v[108:109], v[110:111], 2, s[12:13]
	global_load_dword v122, v[108:109], off
	v_or_b32_e32 v108, s0, v85
	v_or_b32_e32 v110, 24, v108
	v_ashrrev_i32_e32 v111, 31, v110
	v_lshl_add_u64 v[108:109], v[110:111], 2, s[12:13]
	global_load_dword v124, v[108:109], off
	v_or_b32_e32 v108, s0, v85
	v_or_b32_e32 v110, 28, v108
	v_ashrrev_i32_e32 v111, 31, v110
	v_lshl_add_u64 v[108:109], v[110:111], 2, s[12:13]
	global_load_dword v126, v[108:109], off
	v_or_b32_e32 v108, s0, v85
	v_or_b32_e32 v110, 32, v108
	v_ashrrev_i32_e32 v111, 31, v110
	v_lshl_add_u64 v[110:111], v[110:111], 2, s[12:13]
	global_load_dword v128, v[110:111], off
	v_or_b32_e32 v108, s0, v85
	v_or_b32_e32 v110, 36, v108
	v_ashrrev_i32_e32 v111, 31, v110
	v_lshl_add_u64 v[108:109], v[110:111], 2, s[12:13]
	global_load_dword v130, v[108:109], off
	v_or_b32_e32 v108, s0, v85
	v_or_b32_e32 v110, 40, v108
	v_ashrrev_i32_e32 v111, 31, v110
	v_lshl_add_u64 v[108:109], v[110:111], 2, s[12:13]
	global_load_dword v132, v[108:109], off
	v_or_b32_e32 v108, s0, v85
	v_or_b32_e32 v110, 44, v108
	v_ashrrev_i32_e32 v111, 31, v110
	v_lshl_add_u64 v[108:109], v[110:111], 2, s[12:13]
	global_load_dword v134, v[108:109], off
	v_or_b32_e32 v108, s0, v85
	v_or_b32_e32 v110, 48, v108
	v_ashrrev_i32_e32 v111, 31, v110
	v_lshl_add_u64 v[108:109], v[110:111], 2, s[12:13]
	global_load_dword v136, v[108:109], off
	v_or_b32_e32 v108, s0, v85
	v_or_b32_e32 v110, 52, v108
	v_ashrrev_i32_e32 v111, 31, v110
	v_lshl_add_u64 v[108:109], v[110:111], 2, s[12:13]
	global_load_dword v138, v[108:109], off
	v_or_b32_e32 v108, s0, v85
	v_or_b32_e32 v110, 56, v108
	v_ashrrev_i32_e32 v111, 31, v110
	v_lshl_add_u64 v[108:109], v[110:111], 2, s[12:13]
	global_load_dword v140, v[108:109], off
	v_or_b32_e32 v108, s0, v85
	v_or_b32_e32 v108, 60, v108
	v_ashrrev_i32_e32 v109, 31, v108
	v_lshl_add_u64 v[110:111], v[108:109], 2, s[12:13]
	global_load_dword v142, v[110:111], off
	v_or_b32_e32 v90, s0, v85
	v_cndmask_b32_e64 v4, 0, 1, s[14:15]
	v_cmp_ne_u32_e32 vcc, 1, v4
	v_mad_i64_i32 v[4:5], s[0:1], v90, s55, v[22:23]
	global_load_dwordx4 v[4:7], v[4:5], off
	v_or_b32_e32 v92, 4, v90
	v_mad_i64_i32 v[24:25], s[0:1], v92, s55, v[22:23]
	global_load_dwordx4 v[24:27], v[24:25], off
	v_or_b32_e32 v94, 8, v90
	v_mad_i64_i32 v[28:29], s[0:1], v94, s55, v[22:23]
	global_load_dwordx4 v[28:31], v[28:29], off
	v_or_b32_e32 v96, 12, v90
	v_mad_i64_i32 v[32:33], s[0:1], v96, s55, v[22:23]
	global_load_dwordx4 v[32:35], v[32:33], off
	v_or_b32_e32 v98, 16, v90
	v_mad_i64_i32 v[38:39], s[0:1], v98, s55, v[22:23]
	global_load_dwordx4 v[38:41], v[38:39], off
	v_or_b32_e32 v100, 20, v90
	v_mad_i64_i32 v[42:43], s[0:1], v100, s55, v[22:23]
	global_load_dwordx4 v[42:45], v[42:43], off
	v_or_b32_e32 v102, 24, v90
	v_mad_i64_i32 v[46:47], s[0:1], v102, s55, v[22:23]
	global_load_dwordx4 v[46:49], v[46:47], off
	v_or_b32_e32 v104, 28, v90
	v_mad_i64_i32 v[86:87], s[0:1], v104, s55, v[22:23]
	global_load_dwordx4 v[86:89], v[86:87], off
	s_mov_b64 s[14:15], 0
	s_and_b64 vcc, exec, vcc
	s_waitcnt vmcnt(7)
	v_mul_f32_e32 v36, v4, v112
	v_mul_f32_e32 v91, v5, v112
	v_mul_f32_e32 v6, v6, v112
	v_mul_f32_e32 v7, v7, v112
	v_or_b32_e32 v92, 40, v90
	s_waitcnt vmcnt(6)
	v_mul_f32_e32 v5, v24, v114
	v_max3_f32 v3, v3, |v36|, |v5|
	v_mul_f32_e32 v5, v25, v114
	v_max3_f32 v2, v2, |v91|, |v5|
	v_mul_f32_e32 v5, v26, v114
	v_max3_f32 v5, v1, |v6|, |v5|
	v_mul_f32_e32 v1, v27, v114
	v_max3_f32 v4, v0, |v7|, |v1|
	v_or_b32_e32 v94, 44, v90
	s_waitcnt vmcnt(5)
	v_mul_f32_e32 v6, v28, v116
	v_mul_f32_e32 v7, v29, v116
	v_mul_f32_e32 v21, v30, v116
	v_mul_f32_e32 v24, v31, v116
	v_or_b32_e32 v96, 48, v90
	v_mad_i64_i32 v[28:29], s[0:1], v94, s55, v[22:23]
	global_load_dwordx4 v[28:31], v[28:29], off
	s_waitcnt vmcnt(5)
	v_mul_f32_e32 v1, v32, v118
	v_max3_f32 v3, v3, |v6|, |v1|
	v_mul_f32_e32 v1, v33, v118
	v_max3_f32 v2, v2, |v7|, |v1|
	v_mul_f32_e32 v1, v34, v118
	v_mul_f32_e32 v0, v35, v118
	v_max3_f32 v5, v5, |v21|, |v1|
	v_max3_f32 v4, v4, |v24|, |v0|
	v_mad_i64_i32 v[32:33], s[0:1], v96, s55, v[22:23]
	global_load_dwordx4 v[32:35], v[32:33], off
	v_or_b32_e32 v98, 52, v90
	s_waitcnt vmcnt(5)
	v_mul_f32_e32 v6, v38, v120
	v_mul_f32_e32 v7, v39, v120
	v_mul_f32_e32 v21, v40, v120
	v_mul_f32_e32 v24, v41, v120
	v_mad_i64_i32 v[38:39], s[0:1], v98, s55, v[22:23]
	global_load_dwordx4 v[38:41], v[38:39], off
	v_or_b32_e32 v100, 56, v90
	s_waitcnt vmcnt(5)
	v_mul_f32_e32 v1, v42, v122
	v_max3_f32 v3, v3, |v6|, |v1|
	v_mul_f32_e32 v1, v43, v122
	v_max3_f32 v2, v2, |v7|, |v1|
	v_mul_f32_e32 v1, v44, v122
	v_mul_f32_e32 v0, v45, v122
	v_max3_f32 v5, v5, |v21|, |v1|
	v_max3_f32 v4, v4, |v24|, |v0|
	v_mad_i64_i32 v[42:43], s[0:1], v100, s55, v[22:23]
	global_load_dwordx4 v[42:45], v[42:43], off
	s_waitcnt vmcnt(5)
	v_mul_f32_e32 v6, v46, v124
	v_mul_f32_e32 v7, v47, v124
	v_mul_f32_e32 v21, v48, v124
	v_mul_f32_e32 v24, v49, v124
	s_waitcnt vmcnt(4)
	v_mul_f32_e32 v1, v86, v126
	v_max3_f32 v36, v3, |v6|, |v1|
	v_mul_f32_e32 v1, v87, v126
	v_or_b32_e32 v86, 32, v90
	v_max3_f32 v102, v2, |v7|, |v1|
	v_mul_f32_e32 v1, v88, v126
	v_mul_f32_e32 v0, v89, v126
	v_max3_f32 v21, v5, |v21|, |v1|
	v_max3_f32 v103, v4, |v24|, |v0|
	v_mad_i64_i32 v[0:1], s[0:1], v86, s55, v[22:23]
	global_load_dwordx4 v[0:3], v[0:1], off
	v_or_b32_e32 v88, 36, v90
	v_mad_i64_i32 v[4:5], s[0:1], v88, s55, v[22:23]
	global_load_dwordx4 v[4:7], v[4:5], off
	v_mad_i64_i32 v[24:25], s[0:1], v92, s55, v[22:23]
	global_load_dwordx4 v[24:27], v[24:25], off
	v_or_b32_e32 v90, 60, v90
	v_mad_i64_i32 v[46:47], s[0:1], v90, s55, v[22:23]
	global_load_dwordx4 v[46:49], v[46:47], off
	s_mov_b32 s0, 64
	s_waitcnt vmcnt(3)
	v_mul_f32_e32 v87, v0, v128
	v_mul_f32_e32 v104, v1, v128
	v_mul_f32_e32 v2, v2, v128
	v_mul_f32_e32 v3, v3, v128
	s_waitcnt vmcnt(2)
	v_mul_f32_e32 v1, v4, v130
	v_max3_f32 v4, v36, |v87|, |v1|
	v_mul_f32_e32 v1, v5, v130
	v_max3_f32 v5, v102, |v104|, |v1|
	v_mul_f32_e32 v1, v6, v130
	v_mul_f32_e32 v0, v7, v130
	v_max3_f32 v2, v21, |v2|, |v1|
	v_max3_f32 v3, v103, |v3|, |v0|
	s_waitcnt vmcnt(1)
	v_mul_f32_e32 v6, v24, v132
	v_mul_f32_e32 v7, v25, v132
	v_mul_f32_e32 v21, v26, v132
	v_mul_f32_e32 v24, v27, v132
	v_mul_f32_e32 v1, v28, v134
	v_max3_f32 v4, v4, |v6|, |v1|
	v_mul_f32_e32 v1, v29, v134
	v_max3_f32 v5, v5, |v7|, |v1|
	v_mul_f32_e32 v1, v30, v134
	v_mul_f32_e32 v0, v31, v134
	v_max3_f32 v2, v2, |v21|, |v1|
	v_max3_f32 v3, v3, |v24|, |v0|
	v_mul_f32_e32 v6, v32, v136
	v_mul_f32_e32 v7, v33, v136
	v_mul_f32_e32 v21, v34, v136
	v_mul_f32_e32 v24, v35, v136
	v_mul_f32_e32 v1, v38, v138
	v_max3_f32 v4, v4, |v6|, |v1|
	v_mul_f32_e32 v1, v39, v138
	v_max3_f32 v5, v5, |v7|, |v1|
	v_mul_f32_e32 v1, v40, v138
	v_mul_f32_e32 v0, v41, v138
	v_max3_f32 v6, v2, |v21|, |v1|
	v_max3_f32 v7, v3, |v24|, |v0|
	v_mul_f32_e32 v2, v42, v140
	v_mul_f32_e32 v21, v43, v140
	v_mul_f32_e32 v24, v44, v140
	v_mul_f32_e32 v25, v45, v140
	s_waitcnt vmcnt(0)
	v_mul_f32_e32 v1, v46, v142
	v_max3_f32 v3, v4, |v2|, |v1|
	v_mul_f32_e32 v1, v47, v142
	v_max3_f32 v2, v5, |v21|, |v1|
	v_mul_f32_e32 v1, v48, v142
	v_mul_f32_e32 v0, v49, v142
	v_max3_f32 v1, v6, |v24|, |v1|
	v_max3_f32 v0, v7, |v25|, |v0|
	s_cbranch_vccz .LBB0_1921
	v_and_b32_e32 v5, 64, v159
	v_xor_b32_e32 v4, 16, v159
	v_add_u32_e32 v5, 64, v5
	v_cmp_lt_i32_e32 vcc, v4, v5
	s_nop 1
	v_cndmask_b32_e32 v4, v159, v4, vcc
	v_lshlrev_b32_e32 v6, 2, v4
	ds_bpermute_b32 v7, v6, v3
	v_xor_b32_e32 v4, 32, v159
	v_cmp_lt_i32_e32 vcc, v4, v5
	ds_bpermute_b32 v5, v6, v2
	ds_bpermute_b32 v24, v6, v0
	v_cndmask_b32_e32 v4, v159, v4, vcc
	v_lshlrev_b32_e32 v21, 2, v4
	s_waitcnt lgkmcnt(2)
	v_max_f32_e32 v4, v7, v7
	ds_bpermute_b32 v7, v6, v1
	v_max_f32_e32 v3, v3, v3
	s_waitcnt lgkmcnt(2)
	v_max_f32_e32 v5, v5, v5
	v_max_f32_e32 v2, v2, v2
	v_max_f32_e32 v1, v1, v1
	s_waitcnt lgkmcnt(0)
	v_max_f32_e32 v6, v7, v7
	v_max_f32_e32 v7, v24, v24
	v_max_f32_e32 v0, v0, v0
	v_max_f32_e32 v3, v3, v4
	v_max_f32_e32 v2, v2, v5
	v_max_f32_e32 v1, v1, v6
	v_max_f32_e32 v0, v0, v7
	ds_bpermute_b32 v4, v21, v3
	ds_bpermute_b32 v5, v21, v2
	ds_bpermute_b32 v6, v21, v1
	ds_bpermute_b32 v7, v21, v0
	s_and_saveexec_b64 s[14:15], s[4:5]
	s_cbranch_execz .LBB0_1924
	s_waitcnt lgkmcnt(0)
	v_max_f32_e32 v7, v7, v7
	v_max_f32_e32 v0, v0, v0
	v_max_f32_e32 v7, v0, v7
	v_max_f32_e32 v0, v6, v6
	v_max_f32_e32 v1, v1, v1
	v_max_f32_e32 v6, v1, v0
	v_max_f32_e32 v0, v5, v5
	v_max_f32_e32 v1, v2, v2
	v_max_f32_e32 v5, v1, v0
	v_max_f32_e32 v0, v4, v4
	v_max_f32_e32 v1, v3, v3
	v_max_f32_e32 v4, v1, v0
	v_add_u32_e32 v0, s90, v67
	ds_write_b128 v0, v[4:7]

.LBB0_1927:
	s_or_b32 s34, s0, s89
	v_or_b32_e32 v110, s34, v57
	v_ashrrev_i32_e32 v111, 31, v110
	v_lshl_add_u64 v[112:113], v[110:111], 2, s[12:13]
	global_load_dword v114, v[112:113], off
	v_or_b32_e32 v110, s34, v11
	v_ashrrev_i32_e32 v111, 31, v110
	v_lshl_add_u64 v[110:111], v[110:111], 2, s[12:13]
	global_load_dword v116, v[110:111], off
	v_or_b32_e32 v110, s34, v70
	v_ashrrev_i32_e32 v111, 31, v110
	v_lshl_add_u64 v[110:111], v[110:111], 2, s[12:13]
	global_load_dword v118, v[110:111], off
	v_or_b32_e32 v110, s34, v71
	v_ashrrev_i32_e32 v111, 31, v110
	v_lshl_add_u64 v[110:111], v[110:111], 2, s[12:13]
	global_load_dword v120, v[110:111], off
	v_or_b32_e32 v110, s34, v72
	v_ashrrev_i32_e32 v111, 31, v110
	v_lshl_add_u64 v[110:111], v[110:111], 2, s[12:13]
	global_load_dword v122, v[110:111], off
	v_or_b32_e32 v110, s34, v73
	v_ashrrev_i32_e32 v111, 31, v110
	v_lshl_add_u64 v[110:111], v[110:111], 2, s[12:13]
	global_load_dword v124, v[110:111], off
	v_or_b32_e32 v110, s34, v75
	v_ashrrev_i32_e32 v111, 31, v110
	v_lshl_add_u64 v[110:111], v[110:111], 2, s[12:13]
	global_load_dword v126, v[110:111], off
	v_or_b32_e32 v110, s34, v76
	v_ashrrev_i32_e32 v111, 31, v110
	v_lshl_add_u64 v[110:111], v[110:111], 2, s[12:13]
	global_load_dword v128, v[110:111], off
	v_or_b32_e32 v46, s34, v57
	v_mad_i64_i32 v[0:1], s[0:1], v46, s55, v[22:23]
	global_load_dwordx4 v[86:89], v[0:1], off nt
	v_add_u32_e32 v21, v69, v59
	v_or_b32_e32 v0, 4, v46
	v_mad_i64_i32 v[0:1], s[0:1], v0, s55, v[22:23]
	global_load_dwordx4 v[90:93], v[0:1], off nt
	v_add_u32_e32 v47, 0x410, v21
	v_or_b32_e32 v0, 8, v46
	v_mad_i64_i32 v[0:1], s[0:1], v0, s55, v[22:23]
	global_load_dwordx4 v[94:97], v[0:1], off nt
	v_or_b32_e32 v0, 12, v46
	v_mad_i64_i32 v[0:1], s[0:1], v0, s55, v[22:23]
	global_load_dwordx4 v[98:101], v[0:1], off nt
	v_or_b32_e32 v0, 16, v46
	v_mad_i64_i32 v[0:1], s[0:1], v0, s55, v[22:23]
	global_load_dwordx4 v[102:105], v[0:1], off nt
	v_or_b32_e32 v0, 20, v46
	v_mad_i64_i32 v[0:1], s[0:1], v0, s55, v[22:23]
	global_load_dwordx4 v[106:109], v[0:1], off nt
	v_or_b32_e32 v0, 24, v46
	v_mad_i64_i32 v[0:1], s[0:1], v0, s55, v[22:23]
	global_load_dwordx4 v[4:7], v[0:1], off nt
	v_or_b32_e32 v0, 28, v46
	v_mad_i64_i32 v[0:1], s[0:1], v0, s55, v[22:23]
	global_load_dwordx4 v[0:3], v[0:1], off nt
	s_ashr_i32 s35, s34, 31
	s_and_b64 vcc, exec, s[14:15]
	s_mov_b64 s[14:15], 0
	s_waitcnt vmcnt(15)
	v_pk_mul_f32 v[48:49], v[24:25], v[114:115] op_sel_hi:[1,0]
	s_waitcnt vmcnt(7)
	v_pk_mul_f32 v[48:49], v[86:87], v[48:49]
	ds_write2_b32 v21, v48, v49 offset1:1
	v_pk_mul_f32 v[48:49], v[26:27], v[114:115] op_sel_hi:[1,0]
	s_nop 0
	v_pk_mul_f32 v[48:49], v[88:89], v[48:49]
	ds_write2_b32 v21, v48, v49 offset0:2 offset1:3
	v_pk_mul_f32 v[48:49], v[24:25], v[116:117] op_sel_hi:[1,0]
	s_nop 0
	s_waitcnt vmcnt(6)
	v_pk_mul_f32 v[48:49], v[90:91], v[48:49]
	ds_write2_b32 v47, v48, v49 offset1:1
	v_pk_mul_f32 v[48:49], v[26:27], v[116:117] op_sel_hi:[1,0]
	v_add_u32_e32 v36, 0x418, v21
	v_pk_mul_f32 v[48:49], v[92:93], v[48:49]
	ds_write2_b32 v36, v48, v49 offset1:1
	v_add_u32_e32 v47, 0x820, v21
	v_pk_mul_f32 v[48:49], v[24:25], v[118:119] op_sel_hi:[1,0]
	s_nop 0
	s_waitcnt vmcnt(5)
	v_pk_mul_f32 v[48:49], v[94:95], v[48:49]
	ds_write2_b32 v47, v48, v49 offset1:1
	v_pk_mul_f32 v[48:49], v[26:27], v[118:119] op_sel_hi:[1,0]
	v_add_u32_e32 v36, 0x828, v21
	v_pk_mul_f32 v[48:49], v[96:97], v[48:49]
	ds_write2_b32 v36, v48, v49 offset1:1
	v_add_u32_e32 v47, 0xc30, v21
	v_pk_mul_f32 v[48:49], v[24:25], v[120:121] op_sel_hi:[1,0]
	s_nop 0
	s_waitcnt vmcnt(4)
	v_pk_mul_f32 v[48:49], v[98:99], v[48:49]
	ds_write2_b32 v47, v48, v49 offset1:1
	v_pk_mul_f32 v[48:49], v[26:27], v[120:121] op_sel_hi:[1,0]
	v_add_u32_e32 v36, 0xc38, v21
	v_pk_mul_f32 v[48:49], v[100:101], v[48:49]
	ds_write2_b32 v36, v48, v49 offset1:1
	v_add_u32_e32 v47, 0x1040, v21
	v_pk_mul_f32 v[48:49], v[24:25], v[122:123] op_sel_hi:[1,0]
	s_nop 0
	s_waitcnt vmcnt(3)
	v_pk_mul_f32 v[48:49], v[102:103], v[48:49]
	ds_write2_b32 v47, v48, v49 offset1:1
	v_pk_mul_f32 v[48:49], v[26:27], v[122:123] op_sel_hi:[1,0]
	v_add_u32_e32 v36, 0x1048, v21
	v_pk_mul_f32 v[48:49], v[104:105], v[48:49]
	ds_write2_b32 v36, v48, v49 offset1:1
	v_add_u32_e32 v21, 0x1450, v21
	v_pk_mul_f32 v[48:49], v[24:25], v[124:125] op_sel_hi:[1,0]
	s_nop 0
	s_waitcnt vmcnt(2)
	v_pk_mul_f32 v[48:49], v[106:107], v[48:49]
	ds_write2_b32 v21, v48, v49 offset1:1
	v_pk_mul_f32 v[48:49], v[26:27], v[124:125] op_sel_hi:[1,0]
	v_add_u32_e32 v21, v69, v74
	v_pk_mul_f32 v[48:49], v[108:109], v[48:49]
	ds_write2_b32 v21, v48, v49 offset0:2 offset1:3
	v_add_u32_e32 v47, 0x410, v21
	v_or_b32_e32 v106, s34, v77
	v_ashrrev_i32_e32 v107, 31, v106
	v_lshl_add_u64 v[106:107], v[106:107], 2, s[12:13]
	global_load_dword v130, v[106:107], off
	v_or_b32_e32 v110, s34, v78
	v_ashrrev_i32_e32 v111, 31, v110
	v_lshl_add_u64 v[110:111], v[110:111], 2, s[12:13]
	global_load_dword v132, v[110:111], off
	v_or_b32_e32 v110, s34, v79
	v_ashrrev_i32_e32 v111, 31, v110
	v_lshl_add_u64 v[110:111], v[110:111], 2, s[12:13]
	global_load_dword v134, v[110:111], off
	v_or_b32_e32 v110, s34, v80
	v_ashrrev_i32_e32 v111, 31, v110
	v_lshl_add_u64 v[110:111], v[110:111], 2, s[12:13]
	global_load_dword v136, v[110:111], off
	v_or_b32_e32 v110, s34, v81
	v_ashrrev_i32_e32 v111, 31, v110
	v_lshl_add_u64 v[110:111], v[110:111], 2, s[12:13]
	global_load_dword v138, v[110:111], off
	v_or_b32_e32 v110, s34, v82
	v_ashrrev_i32_e32 v111, 31, v110
	v_lshl_add_u64 v[110:111], v[110:111], 2, s[12:13]
	global_load_dword v140, v[110:111], off
	v_or_b32_e32 v110, s34, v83
	v_ashrrev_i32_e32 v111, 31, v110
	v_lshl_add_u64 v[110:111], v[110:111], 2, s[12:13]
	global_load_dword v142, v[110:111], off
	v_or_b32_e32 v110, s34, v84
	v_ashrrev_i32_e32 v111, 31, v110
	v_lshl_add_u64 v[110:111], v[110:111], 2, s[12:13]
	global_load_dword v144, v[110:111], off
	v_pk_mul_f32 v[48:49], v[24:25], v[126:127] op_sel_hi:[1,0]
	s_nop 0
	s_waitcnt vmcnt(9)
	v_pk_mul_f32 v[4:5], v[4:5], v[48:49]
	ds_write2_b32 v47, v4, v5 offset1:1
	v_pk_mul_f32 v[4:5], v[26:27], v[126:127] op_sel_hi:[1,0]
	v_or_b32_e32 v36, 40, v46
	v_pk_mul_f32 v[4:5], v[6:7], v[4:5]
	v_add_u32_e32 v6, 0x418, v21
	ds_write2_b32 v6, v4, v5 offset1:1
	v_mad_i64_i32 v[48:49], s[0:1], v36, s55, v[22:23]
	v_or_b32_e32 v36, 44, v46
	global_load_dwordx4 v[86:89], v[48:49], off nt
	v_mad_i64_i32 v[48:49], s[0:1], v36, s55, v[22:23]
	v_or_b32_e32 v36, 48, v46
	global_load_dwordx4 v[90:93], v[48:49], off nt
	v_mad_i64_i32 v[48:49], s[0:1], v36, s55, v[22:23]
	v_or_b32_e32 v36, 52, v46
	global_load_dwordx4 v[94:97], v[48:49], off nt
	v_mad_i64_i32 v[48:49], s[0:1], v36, s55, v[22:23]
	v_or_b32_e32 v36, 56, v46
	global_load_dwordx4 v[98:101], v[48:49], off nt
	v_mad_i64_i32 v[48:49], s[0:1], v36, s55, v[22:23]
	v_or_b32_e32 v36, 60, v46
	global_load_dwordx4 v[102:105], v[48:49], off nt
	v_pk_mul_f32 v[6:7], v[24:25], v[128:129] op_sel_hi:[1,0]
	s_nop 0
	s_waitcnt vmcnt(13)
	v_pk_mul_f32 v[0:1], v[0:1], v[6:7]
	v_add_u32_e32 v5, 0x820, v21
	ds_write2_b32 v5, v0, v1 offset1:1
	v_pk_mul_f32 v[0:1], v[26:27], v[128:129] op_sel_hi:[1,0]
	v_or_b32_e32 v4, 36, v46
	v_pk_mul_f32 v[0:1], v[2:3], v[0:1]
	v_add_u32_e32 v2, 0x828, v21
	ds_write2_b32 v2, v0, v1 offset1:1
	v_or_b32_e32 v0, 32, v46
	v_mad_i64_i32 v[0:1], s[0:1], v0, s55, v[22:23]
	v_mad_i64_i32 v[46:47], s[0:1], v36, s55, v[22:23]
	v_mad_i64_i32 v[4:5], s[0:1], v4, s55, v[22:23]
	global_load_dwordx4 v[0:3], v[0:1], off nt
	s_mov_b32 s0, 64
	global_load_dwordx4 v[4:7], v[4:5], off nt
	s_waitcnt vmcnt(14)
	v_pk_mul_f32 v[106:107], v[24:25], v[130:131] op_sel_hi:[1,0]
	global_load_dwordx4 v[46:49], v[46:47], off nt
	s_waitcnt vmcnt(2)
	v_pk_mul_f32 v[0:1], v[0:1], v[106:107]
	v_add_u32_e32 v106, 0xc30, v21
	ds_write2_b32 v106, v0, v1 offset1:1
	v_pk_mul_f32 v[0:1], v[26:27], v[130:131] op_sel_hi:[1,0]
	s_nop 0
	v_pk_mul_f32 v[0:1], v[2:3], v[0:1]
	v_add_u32_e32 v2, 0xc38, v21
	ds_write2_b32 v2, v0, v1 offset1:1
	v_pk_mul_f32 v[2:3], v[24:25], v[132:133] op_sel_hi:[1,0]
	s_nop 0
	s_waitcnt vmcnt(1)
	v_pk_mul_f32 v[2:3], v[4:5], v[2:3]
	v_add_u32_e32 v1, 0x1040, v21
	ds_write2_b32 v1, v2, v3 offset1:1
	v_pk_mul_f32 v[0:1], v[26:27], v[132:133] op_sel_hi:[1,0]
	v_add_u32_e32 v2, 0x1048, v21
	v_pk_mul_f32 v[0:1], v[6:7], v[0:1]
	ds_write2_b32 v2, v0, v1 offset1:1
	v_pk_mul_f32 v[2:3], v[24:25], v[134:135] op_sel_hi:[1,0]
	s_nop 0
	v_pk_mul_f32 v[2:3], v[86:87], v[2:3]
	v_add_u32_e32 v1, 0x1450, v21
	ds_write2_b32 v1, v2, v3 offset1:1
	v_pk_mul_f32 v[0:1], v[26:27], v[134:135] op_sel_hi:[1,0]
	v_add_u32_e32 v2, 0x1458, v21
	v_pk_mul_f32 v[0:1], v[88:89], v[0:1]
	ds_write2_b32 v2, v0, v1 offset1:1
	v_pk_mul_f32 v[2:3], v[24:25], v[136:137] op_sel_hi:[1,0]
	s_nop 0
	v_pk_mul_f32 v[2:3], v[90:91], v[2:3]
	v_add_u32_e32 v1, 0x1860, v21
	ds_write2_b32 v1, v2, v3 offset1:1
	v_pk_mul_f32 v[0:1], v[26:27], v[136:137] op_sel_hi:[1,0]
	v_add_u32_e32 v2, 0x1868, v21
	v_pk_mul_f32 v[0:1], v[92:93], v[0:1]
	ds_write2_b32 v2, v0, v1 offset1:1
	v_pk_mul_f32 v[2:3], v[24:25], v[138:139] op_sel_hi:[1,0]
	s_nop 0
	v_pk_mul_f32 v[2:3], v[94:95], v[2:3]
	v_add_u32_e32 v1, 0x1c70, v21
	ds_write2_b32 v1, v2, v3 offset1:1
	v_pk_mul_f32 v[0:1], v[26:27], v[138:139] op_sel_hi:[1,0]
	v_add_u32_e32 v2, 0x1c78, v21
	v_pk_mul_f32 v[0:1], v[96:97], v[0:1]
	ds_write2_b32 v2, v0, v1 offset1:1
	v_pk_mul_f32 v[2:3], v[24:25], v[140:141] op_sel_hi:[1,0]
	s_nop 0
	v_pk_mul_f32 v[2:3], v[98:99], v[2:3]
	v_add_u32_e32 v1, 0x2080, v21
	ds_write2_b32 v1, v2, v3 offset1:1
	v_pk_mul_f32 v[0:1], v[26:27], v[140:141] op_sel_hi:[1,0]
	v_add_u32_e32 v2, 0x2088, v21
	v_pk_mul_f32 v[0:1], v[100:101], v[0:1]
	ds_write2_b32 v2, v0, v1 offset1:1
	v_pk_mul_f32 v[2:3], v[24:25], v[142:143] op_sel_hi:[1,0]
	s_nop 0
	v_pk_mul_f32 v[2:3], v[102:103], v[2:3]
	v_add_u32_e32 v1, 0x2490, v21
	ds_write2_b32 v1, v2, v3 offset1:1
	v_pk_mul_f32 v[0:1], v[26:27], v[142:143] op_sel_hi:[1,0]
	v_add_u32_e32 v2, 0x2498, v21
	v_pk_mul_f32 v[0:1], v[104:105], v[0:1]
	ds_write2_b32 v2, v0, v1 offset1:1
	v_pk_mul_f32 v[2:3], v[24:25], v[144:145] op_sel_hi:[1,0]
	s_nop 0
	s_waitcnt vmcnt(0)
	v_pk_mul_f32 v[2:3], v[46:47], v[2:3]
	v_add_u32_e32 v1, 0x28a0, v21
	ds_write2_b32 v1, v2, v3 offset1:1
	v_pk_mul_f32 v[0:1], v[26:27], v[144:145] op_sel_hi:[1,0]
	v_add_u32_e32 v2, 0x28a8, v21
	v_pk_mul_f32 v[0:1], v[48:49], v[0:1]
	ds_write2_b32 v2, v0, v1 offset1:1
	s_waitcnt lgkmcnt(0)
	ds_read2_b32 v[6:7], v9 offset0:130 offset1:138
	ds_read2_b32 v[46:47], v9 offset0:195 offset1:203
	ds_read2_b32 v[2:3], v9 offset1:8
	ds_read2_b32 v[4:5], v9 offset0:65 offset1:73
	v_lshl_add_u64 v[0:1], v[14:15], 0, s[34:35]
	s_waitcnt lgkmcnt(3)
	v_med3_f32 v6, v6, s52, v53
	s_waitcnt lgkmcnt(2)
	v_med3_f32 v21, v46, s52, v53
	v_add_f32_e32 v6, 0x4b400000, v6
	v_add_f32_e32 v21, 0x4b400000, v21
	v_perm_b32 v6, v21, v6, s53
	v_add_u32_e32 v21, 0x400, v9
	ds_read2_b32 v[86:87], v21 offset0:4 offset1:12
	ds_read2_b32 v[88:89], v21 offset0:69 offset1:77
	ds_read2_b32 v[90:91], v21 offset0:134 offset1:142
	ds_read2_b32 v[92:93], v21 offset0:199 offset1:207
	s_waitcnt lgkmcnt(5)
	v_med3_f32 v2, v2, s52, v53
	s_waitcnt lgkmcnt(4)
	v_med3_f32 v4, v4, s52, v53
	v_add_f32_e32 v2, 0x4b400000, v2
	v_add_f32_e32 v4, 0x4b400000, v4
	v_perm_b32 v2, v4, v2, s53
	v_perm_b32 v48, v6, v2, s54
	s_waitcnt lgkmcnt(3)
	v_med3_f32 v2, v86, s52, v53
	s_waitcnt lgkmcnt(2)
	v_med3_f32 v4, v88, s52, v53
	s_waitcnt lgkmcnt(1)
	v_med3_f32 v6, v90, s52, v53
	s_waitcnt lgkmcnt(0)
	v_med3_f32 v36, v92, s52, v53
	v_add_f32_e32 v2, 0x4b400000, v2
	v_add_f32_e32 v4, 0x4b400000, v4
	v_add_f32_e32 v6, 0x4b400000, v6
	v_add_f32_e32 v36, 0x4b400000, v36
	v_perm_b32 v6, v36, v6, s53
	v_perm_b32 v2, v4, v2, s53
	v_perm_b32 v49, v6, v2, s54
	v_med3_f32 v2, v3, s52, v53
	v_med3_f32 v3, v5, s52, v53
	v_med3_f32 v4, v7, s52, v53
	v_med3_f32 v5, v47, s52, v53
	v_add_f32_e32 v2, 0x4b400000, v2
	v_add_f32_e32 v3, 0x4b400000, v3
	v_add_f32_e32 v4, 0x4b400000, v4
	v_add_f32_e32 v5, 0x4b400000, v5
	v_perm_b32 v4, v5, v4, s53
	v_perm_b32 v2, v3, v2, s53
	v_perm_b32 v2, v4, v2, s54
	v_med3_f32 v3, v87, s52, v53
	v_med3_f32 v4, v89, s52, v53
	v_med3_f32 v5, v91, s52, v53
	v_med3_f32 v6, v93, s52, v53
	v_add_f32_e32 v3, 0x4b400000, v3
	v_add_f32_e32 v4, 0x4b400000, v4
	v_add_f32_e32 v5, 0x4b400000, v5
	v_add_f32_e32 v6, 0x4b400000, v6
	v_perm_b32 v5, v6, v5, s53
	v_perm_b32 v3, v4, v3, s53
	v_perm_b32 v3, v5, v3, s54
	v_lshl_add_u64 v[4:5], v[0:1], 0, v[30:31]
	global_store_dwordx2 v[4:5], v[2:3], off
	ds_read2_b32 v[2:3], v9 offset0:16 offset1:24
	ds_read2_b32 v[4:5], v9 offset0:81 offset1:89
	ds_read2_b32 v[6:7], v9 offset0:146 offset1:154
	ds_read2_b32 v[46:47], v9 offset0:211 offset1:219
	ds_read2_b32 v[86:87], v21 offset0:20 offset1:28
	ds_read2_b32 v[88:89], v21 offset0:85 offset1:93
	ds_read2_b32 v[90:91], v21 offset0:150 offset1:158
	ds_read2_b32 v[92:93], v21 offset0:215 offset1:223
	s_waitcnt lgkmcnt(7)
	v_med3_f32 v2, v2, s52, v53
	s_waitcnt lgkmcnt(6)
	v_med3_f32 v4, v4, s52, v53
	s_waitcnt lgkmcnt(5)
	v_med3_f32 v6, v6, s52, v53
	s_waitcnt lgkmcnt(4)
	v_med3_f32 v36, v46, s52, v53
	v_add_f32_e32 v2, 0x4b400000, v2
	v_add_f32_e32 v4, 0x4b400000, v4
	v_add_f32_e32 v6, 0x4b400000, v6
	v_add_f32_e32 v36, 0x4b400000, v36
	v_lshl_add_u64 v[94:95], v[0:1], 0, v[28:29]
	v_perm_b32 v6, v36, v6, s53
	v_perm_b32 v2, v4, v2, s53
	global_store_dwordx2 v[94:95], v[48:49], off
	v_perm_b32 v48, v6, v2, s54
	s_waitcnt lgkmcnt(3)
	v_med3_f32 v2, v86, s52, v53
	s_waitcnt lgkmcnt(2)
	v_med3_f32 v4, v88, s52, v53
	s_waitcnt lgkmcnt(1)
	v_med3_f32 v6, v90, s52, v53
	s_waitcnt lgkmcnt(0)
	v_med3_f32 v36, v92, s52, v53
	v_add_f32_e32 v2, 0x4b400000, v2
	v_add_f32_e32 v4, 0x4b400000, v4
	v_add_f32_e32 v6, 0x4b400000, v6
	v_add_f32_e32 v36, 0x4b400000, v36
	v_perm_b32 v6, v36, v6, s53
	v_perm_b32 v2, v4, v2, s53
	v_perm_b32 v49, v6, v2, s54
	v_med3_f32 v2, v3, s52, v53
	v_med3_f32 v3, v5, s52, v53
	v_med3_f32 v4, v7, s52, v53
	v_med3_f32 v5, v47, s52, v53
	v_add_f32_e32 v2, 0x4b400000, v2
	v_add_f32_e32 v3, 0x4b400000, v3
	v_add_f32_e32 v4, 0x4b400000, v4
	v_add_f32_e32 v5, 0x4b400000, v5
	v_perm_b32 v4, v5, v4, s53
	v_perm_b32 v2, v3, v2, s53
	v_perm_b32 v2, v4, v2, s54
	v_med3_f32 v3, v87, s52, v53
	v_med3_f32 v4, v89, s52, v53
	v_med3_f32 v5, v91, s52, v53
	v_med3_f32 v6, v93, s52, v53
	v_add_f32_e32 v3, 0x4b400000, v3
	v_add_f32_e32 v4, 0x4b400000, v4
	v_add_f32_e32 v5, 0x4b400000, v5
	v_add_f32_e32 v6, 0x4b400000, v6
	v_perm_b32 v5, v6, v5, s53
	v_perm_b32 v3, v4, v3, s53
	v_perm_b32 v3, v5, v3, s54
	v_lshl_add_u64 v[4:5], v[0:1], 0, v[34:35]
	global_store_dwordx2 v[4:5], v[2:3], off
	ds_read2_b32 v[2:3], v9 offset0:32 offset1:40
	ds_read2_b32 v[4:5], v9 offset0:97 offset1:105
	ds_read2_b32 v[6:7], v9 offset0:162 offset1:170
	ds_read2_b32 v[46:47], v9 offset0:227 offset1:235
	ds_read2_b32 v[86:87], v21 offset0:36 offset1:44
	ds_read2_b32 v[88:89], v21 offset0:101 offset1:109
	ds_read2_b32 v[90:91], v21 offset0:166 offset1:174
	ds_read2_b32 v[92:93], v21 offset0:231 offset1:239
	s_waitcnt lgkmcnt(7)
	v_med3_f32 v2, v2, s52, v53
	s_waitcnt lgkmcnt(6)
	v_med3_f32 v4, v4, s52, v53
	s_waitcnt lgkmcnt(5)
	v_med3_f32 v6, v6, s52, v53
	s_waitcnt lgkmcnt(4)
	v_med3_f32 v36, v46, s52, v53
	v_add_f32_e32 v2, 0x4b400000, v2
	v_add_f32_e32 v4, 0x4b400000, v4
	v_add_f32_e32 v6, 0x4b400000, v6
	v_add_f32_e32 v36, 0x4b400000, v36
	v_lshl_add_u64 v[94:95], v[0:1], 0, v[32:33]
	v_perm_b32 v6, v36, v6, s53
	v_perm_b32 v2, v4, v2, s53
	global_store_dwordx2 v[94:95], v[48:49], off
	v_perm_b32 v48, v6, v2, s54
	s_waitcnt lgkmcnt(3)
	v_med3_f32 v2, v86, s52, v53
	s_waitcnt lgkmcnt(2)
	v_med3_f32 v4, v88, s52, v53
	s_waitcnt lgkmcnt(1)
	v_med3_f32 v6, v90, s52, v53
	s_waitcnt lgkmcnt(0)
	v_med3_f32 v36, v92, s52, v53
	v_add_f32_e32 v2, 0x4b400000, v2
	v_add_f32_e32 v4, 0x4b400000, v4
	v_add_f32_e32 v6, 0x4b400000, v6
	v_add_f32_e32 v36, 0x4b400000, v36
	v_perm_b32 v6, v36, v6, s53
	v_perm_b32 v2, v4, v2, s53
	v_perm_b32 v49, v6, v2, s54
	v_med3_f32 v2, v3, s52, v53
	v_med3_f32 v3, v5, s52, v53
	v_med3_f32 v4, v7, s52, v53
	v_med3_f32 v5, v47, s52, v53
	v_add_f32_e32 v2, 0x4b400000, v2
	v_add_f32_e32 v3, 0x4b400000, v3
	v_add_f32_e32 v4, 0x4b400000, v4
	v_add_f32_e32 v5, 0x4b400000, v5
	v_perm_b32 v4, v5, v4, s53
	v_perm_b32 v2, v3, v2, s53
	v_perm_b32 v2, v4, v2, s54
	v_med3_f32 v3, v87, s52, v53
	v_med3_f32 v4, v89, s52, v53
	v_med3_f32 v5, v91, s52, v53
	v_med3_f32 v6, v93, s52, v53
	v_add_f32_e32 v3, 0x4b400000, v3
	v_add_f32_e32 v4, 0x4b400000, v4
	v_add_f32_e32 v5, 0x4b400000, v5
	v_add_f32_e32 v6, 0x4b400000, v6
	v_perm_b32 v5, v6, v5, s53
	v_perm_b32 v3, v4, v3, s53
	v_perm_b32 v3, v5, v3, s54
	v_lshl_add_u64 v[4:5], v[0:1], 0, v[40:41]
	global_store_dwordx2 v[4:5], v[2:3], off
	ds_read2_b32 v[2:3], v9 offset0:48 offset1:56
	ds_read2_b32 v[4:5], v9 offset0:113 offset1:121
	ds_read2_b32 v[6:7], v9 offset0:178 offset1:186
	ds_read2_b32 v[46:47], v9 offset0:243 offset1:251
	ds_read2_b32 v[86:87], v21 offset0:52 offset1:60
	ds_read2_b32 v[88:89], v21 offset0:117 offset1:125
	ds_read2_b32 v[90:91], v21 offset0:182 offset1:190
	ds_read2_b32 v[92:93], v21 offset0:247 offset1:255
	s_waitcnt lgkmcnt(7)
	v_med3_f32 v2, v2, s52, v53
	s_waitcnt lgkmcnt(6)
	v_med3_f32 v4, v4, s52, v53
	s_waitcnt lgkmcnt(5)
	v_med3_f32 v6, v6, s52, v53
	s_waitcnt lgkmcnt(4)
	v_med3_f32 v36, v46, s52, v53
	v_add_f32_e32 v2, 0x4b400000, v2
	v_add_f32_e32 v4, 0x4b400000, v4
	v_add_f32_e32 v6, 0x4b400000, v6
	v_add_f32_e32 v36, 0x4b400000, v36
	v_lshl_add_u64 v[94:95], v[0:1], 0, v[38:39]
	v_perm_b32 v6, v36, v6, s53
	v_perm_b32 v2, v4, v2, s53
	global_store_dwordx2 v[94:95], v[48:49], off
	v_perm_b32 v48, v6, v2, s54
	s_waitcnt lgkmcnt(3)
	v_med3_f32 v2, v86, s52, v53
	s_waitcnt lgkmcnt(2)
	v_med3_f32 v4, v88, s52, v53
	s_waitcnt lgkmcnt(1)
	v_med3_f32 v6, v90, s52, v53
	s_waitcnt lgkmcnt(0)
	v_med3_f32 v21, v92, s52, v53
	v_add_f32_e32 v2, 0x4b400000, v2
	v_add_f32_e32 v4, 0x4b400000, v4
	v_add_f32_e32 v6, 0x4b400000, v6
	v_add_f32_e32 v21, 0x4b400000, v21
	v_perm_b32 v6, v21, v6, s53
	v_perm_b32 v2, v4, v2, s53
	v_perm_b32 v49, v6, v2, s54
	v_med3_f32 v2, v3, s52, v53
	v_med3_f32 v3, v5, s52, v53
	v_med3_f32 v4, v7, s52, v53
	v_med3_f32 v5, v47, s52, v53
	v_add_f32_e32 v2, 0x4b400000, v2
	v_add_f32_e32 v3, 0x4b400000, v3
	v_add_f32_e32 v4, 0x4b400000, v4
	v_add_f32_e32 v5, 0x4b400000, v5
	v_perm_b32 v4, v5, v4, s53
	v_perm_b32 v2, v3, v2, s53
	v_perm_b32 v2, v4, v2, s54
	v_med3_f32 v3, v87, s52, v53
	v_med3_f32 v4, v89, s52, v53
	v_med3_f32 v5, v91, s52, v53
	v_med3_f32 v6, v93, s52, v53
	v_add_f32_e32 v3, 0x4b400000, v3
	v_add_f32_e32 v4, 0x4b400000, v4
	v_add_f32_e32 v5, 0x4b400000, v5
	v_add_f32_e32 v6, 0x4b400000, v6
	v_perm_b32 v5, v6, v5, s53
	v_perm_b32 v3, v4, v3, s53
	v_lshl_add_u64 v[94:95], v[0:1], 0, v[42:43]
	v_perm_b32 v3, v5, v3, s54
	v_lshl_add_u64 v[0:1], v[0:1], 0, v[44:45]
	global_store_dwordx2 v[94:95], v[48:49], off
	global_store_dwordx2 v[0:1], v[2:3], off
	s_waitcnt lgkmcnt(0)
	s_cbranch_vccnz .LBB0_1927
	s_barrier

.LBB0_1945:
	v_or_b32_e32 v108, s1, v85
	v_ashrrev_i32_e32 v109, 31, v108
	v_lshl_add_u64 v[110:111], v[108:109], 2, s[12:13]
	global_load_dword v112, v[110:111], off
	v_or_b32_e32 v108, s1, v85
	v_or_b32_e32 v110, 4, v108
	v_ashrrev_i32_e32 v111, 31, v110
	v_lshl_add_u64 v[108:109], v[110:111], 2, s[12:13]
	global_load_dword v114, v[108:109], off
	v_or_b32_e32 v108, s1, v85
	v_or_b32_e32 v110, 8, v108
	v_ashrrev_i32_e32 v111, 31, v110
	v_lshl_add_u64 v[108:109], v[110:111], 2, s[12:13]
	global_load_dword v116, v[108:109], off
	v_or_b32_e32 v108, s1, v85
	v_or_b32_e32 v110, 12, v108
	v_ashrrev_i32_e32 v111, 31, v110
	v_lshl_add_u64 v[108:109], v[110:111], 2, s[12:13]
	global_load_dword v118, v[108:109], off
	v_or_b32_e32 v108, s1, v85
	v_or_b32_e32 v110, 16, v108
	v_ashrrev_i32_e32 v111, 31, v110
	v_lshl_add_u64 v[108:109], v[110:111], 2, s[12:13]
	global_load_dword v120, v[108:109], off
	v_or_b32_e32 v108, s1, v85
	v_or_b32_e32 v110, 20, v108
	v_ashrrev_i32_e32 v111, 31, v110
	v_lshl_add_u64 v[108:109], v[110:111], 2, s[12:13]
	global_load_dword v122, v[108:109], off
	v_or_b32_e32 v108, s1, v85
	v_or_b32_e32 v110, 24, v108
	v_ashrrev_i32_e32 v111, 31, v110
	v_lshl_add_u64 v[108:109], v[110:111], 2, s[12:13]
	global_load_dword v124, v[108:109], off
	v_or_b32_e32 v108, s1, v85
	v_or_b32_e32 v110, 28, v108
	v_ashrrev_i32_e32 v111, 31, v110
	v_lshl_add_u64 v[108:109], v[110:111], 2, s[12:13]
	global_load_dword v126, v[108:109], off
	v_or_b32_e32 v108, s1, v85
	v_or_b32_e32 v110, 32, v108
	v_ashrrev_i32_e32 v111, 31, v110
	v_lshl_add_u64 v[110:111], v[110:111], 2, s[12:13]
	global_load_dword v128, v[110:111], off
	v_or_b32_e32 v108, s1, v85
	v_or_b32_e32 v110, 36, v108
	v_ashrrev_i32_e32 v111, 31, v110
	v_lshl_add_u64 v[108:109], v[110:111], 2, s[12:13]
	global_load_dword v130, v[108:109], off
	v_or_b32_e32 v108, s1, v85
	v_or_b32_e32 v110, 40, v108
	v_ashrrev_i32_e32 v111, 31, v110
	v_lshl_add_u64 v[108:109], v[110:111], 2, s[12:13]
	global_load_dword v132, v[108:109], off
	v_or_b32_e32 v108, s1, v85
	v_or_b32_e32 v110, 44, v108
	v_ashrrev_i32_e32 v111, 31, v110
	v_lshl_add_u64 v[108:109], v[110:111], 2, s[12:13]
	global_load_dword v134, v[108:109], off
	v_or_b32_e32 v108, s1, v85
	v_or_b32_e32 v110, 48, v108
	v_ashrrev_i32_e32 v111, 31, v110
	v_lshl_add_u64 v[108:109], v[110:111], 2, s[12:13]
	global_load_dword v136, v[108:109], off
	v_or_b32_e32 v108, s1, v85
	v_or_b32_e32 v110, 52, v108
	v_ashrrev_i32_e32 v111, 31, v110
	v_lshl_add_u64 v[108:109], v[110:111], 2, s[12:13]
	global_load_dword v138, v[108:109], off
	v_or_b32_e32 v108, s1, v85
	v_or_b32_e32 v110, 56, v108
	v_ashrrev_i32_e32 v111, 31, v110
	v_lshl_add_u64 v[108:109], v[110:111], 2, s[12:13]
	global_load_dword v140, v[108:109], off
	v_or_b32_e32 v108, s1, v85
	v_or_b32_e32 v108, 60, v108
	v_ashrrev_i32_e32 v109, 31, v108
	v_lshl_add_u64 v[110:111], v[108:109], 2, s[12:13]
	global_load_dword v142, v[110:111], off
	v_or_b32_e32 v90, s1, v85
	v_cndmask_b32_e64 v4, 0, 1, s[14:15]
	v_cmp_ne_u32_e32 vcc, 1, v4
	v_mad_i64_i32 v[4:5], s[2:3], v90, s55, v[22:23]
	global_load_dwordx4 v[4:7], v[4:5], off
	v_or_b32_e32 v92, 4, v90
	v_mad_i64_i32 v[24:25], s[2:3], v92, s55, v[22:23]
	global_load_dwordx4 v[24:27], v[24:25], off
	v_or_b32_e32 v94, 8, v90
	v_mad_i64_i32 v[28:29], s[2:3], v94, s55, v[22:23]
	global_load_dwordx4 v[28:31], v[28:29], off
	v_or_b32_e32 v96, 12, v90
	v_mad_i64_i32 v[32:33], s[2:3], v96, s55, v[22:23]
	global_load_dwordx4 v[32:35], v[32:33], off
	v_or_b32_e32 v98, 16, v90
	v_mad_i64_i32 v[38:39], s[2:3], v98, s55, v[22:23]
	global_load_dwordx4 v[38:41], v[38:39], off
	v_or_b32_e32 v100, 20, v90
	v_mad_i64_i32 v[42:43], s[2:3], v100, s55, v[22:23]
	global_load_dwordx4 v[42:45], v[42:43], off
	v_or_b32_e32 v102, 24, v90
	v_mad_i64_i32 v[46:47], s[2:3], v102, s55, v[22:23]
	global_load_dwordx4 v[46:49], v[46:47], off
	v_or_b32_e32 v104, 28, v90
	v_mad_i64_i32 v[86:87], s[2:3], v104, s55, v[22:23]
	global_load_dwordx4 v[86:89], v[86:87], off
	s_mov_b32 s1, 64
	s_mov_b64 s[14:15], 0
	s_and_b64 vcc, exec, vcc
	s_waitcnt vmcnt(7)
	v_mul_f32_e32 v36, v4, v112
	v_mul_f32_e32 v91, v5, v112
	v_mul_f32_e32 v6, v6, v112
	v_mul_f32_e32 v7, v7, v112
	v_or_b32_e32 v92, 40, v90
	s_waitcnt vmcnt(6)
	v_mul_f32_e32 v5, v24, v114
	v_max3_f32 v3, v3, |v36|, |v5|
	v_mul_f32_e32 v5, v25, v114
	v_max3_f32 v2, v2, |v91|, |v5|
	v_mul_f32_e32 v5, v26, v114
	v_max3_f32 v5, v1, |v6|, |v5|
	v_mul_f32_e32 v1, v27, v114
	v_max3_f32 v4, v0, |v7|, |v1|
	v_or_b32_e32 v94, 44, v90
	s_waitcnt vmcnt(5)
	v_mul_f32_e32 v6, v28, v116
	v_mul_f32_e32 v7, v29, v116
	v_mul_f32_e32 v21, v30, v116
	v_mul_f32_e32 v24, v31, v116
	v_or_b32_e32 v96, 48, v90
	v_mad_i64_i32 v[28:29], s[2:3], v94, s55, v[22:23]
	global_load_dwordx4 v[28:31], v[28:29], off
	s_waitcnt vmcnt(5)
	v_mul_f32_e32 v1, v32, v118
	v_max3_f32 v3, v3, |v6|, |v1|
	v_mul_f32_e32 v1, v33, v118
	v_max3_f32 v2, v2, |v7|, |v1|
	v_mul_f32_e32 v1, v34, v118
	v_mul_f32_e32 v0, v35, v118
	v_max3_f32 v5, v5, |v21|, |v1|
	v_max3_f32 v4, v4, |v24|, |v0|
	v_mad_i64_i32 v[32:33], s[2:3], v96, s55, v[22:23]
	global_load_dwordx4 v[32:35], v[32:33], off
	v_or_b32_e32 v98, 52, v90
	s_waitcnt vmcnt(5)
	v_mul_f32_e32 v6, v38, v120
	v_mul_f32_e32 v7, v39, v120
	v_mul_f32_e32 v21, v40, v120
	v_mul_f32_e32 v24, v41, v120
	v_mad_i64_i32 v[38:39], s[2:3], v98, s55, v[22:23]
	global_load_dwordx4 v[38:41], v[38:39], off
	v_or_b32_e32 v100, 56, v90
	s_waitcnt vmcnt(5)
	v_mul_f32_e32 v1, v42, v122
	v_max3_f32 v3, v3, |v6|, |v1|
	v_mul_f32_e32 v1, v43, v122
	v_max3_f32 v2, v2, |v7|, |v1|
	v_mul_f32_e32 v1, v44, v122
	v_mul_f32_e32 v0, v45, v122
	v_max3_f32 v5, v5, |v21|, |v1|
	v_max3_f32 v4, v4, |v24|, |v0|
	v_mad_i64_i32 v[42:43], s[2:3], v100, s55, v[22:23]
	global_load_dwordx4 v[42:45], v[42:43], off
	s_waitcnt vmcnt(5)
	v_mul_f32_e32 v6, v46, v124
	v_mul_f32_e32 v7, v47, v124
	v_mul_f32_e32 v21, v48, v124
	v_mul_f32_e32 v24, v49, v124
	s_waitcnt vmcnt(4)
	v_mul_f32_e32 v1, v86, v126
	v_max3_f32 v36, v3, |v6|, |v1|
	v_mul_f32_e32 v1, v87, v126
	v_or_b32_e32 v86, 32, v90
	v_max3_f32 v102, v2, |v7|, |v1|
	v_mul_f32_e32 v1, v88, v126
	v_mul_f32_e32 v0, v89, v126
	v_max3_f32 v21, v5, |v21|, |v1|
	v_max3_f32 v103, v4, |v24|, |v0|
	v_mad_i64_i32 v[0:1], s[2:3], v86, s55, v[22:23]
	global_load_dwordx4 v[0:3], v[0:1], off
	v_or_b32_e32 v88, 36, v90
	v_mad_i64_i32 v[4:5], s[2:3], v88, s55, v[22:23]
	global_load_dwordx4 v[4:7], v[4:5], off
	v_mad_i64_i32 v[24:25], s[2:3], v92, s55, v[22:23]
	global_load_dwordx4 v[24:27], v[24:25], off
	v_or_b32_e32 v90, 60, v90
	v_mad_i64_i32 v[46:47], s[2:3], v90, s55, v[22:23]
	global_load_dwordx4 v[46:49], v[46:47], off
	s_waitcnt vmcnt(3)
	v_mul_f32_e32 v87, v0, v128
	v_mul_f32_e32 v104, v1, v128
	v_mul_f32_e32 v2, v2, v128
	v_mul_f32_e32 v3, v3, v128
	s_waitcnt vmcnt(2)
	v_mul_f32_e32 v1, v4, v130
	v_max3_f32 v4, v36, |v87|, |v1|
	v_mul_f32_e32 v1, v5, v130
	v_max3_f32 v5, v102, |v104|, |v1|
	v_mul_f32_e32 v1, v6, v130
	v_mul_f32_e32 v0, v7, v130
	v_max3_f32 v2, v21, |v2|, |v1|
	v_max3_f32 v3, v103, |v3|, |v0|
	s_waitcnt vmcnt(1)
	v_mul_f32_e32 v6, v24, v132
	v_mul_f32_e32 v7, v25, v132
	v_mul_f32_e32 v21, v26, v132
	v_mul_f32_e32 v24, v27, v132
	v_mul_f32_e32 v1, v28, v134
	v_max3_f32 v4, v4, |v6|, |v1|
	v_mul_f32_e32 v1, v29, v134
	v_max3_f32 v5, v5, |v7|, |v1|
	v_mul_f32_e32 v1, v30, v134
	v_mul_f32_e32 v0, v31, v134
	v_max3_f32 v2, v2, |v21|, |v1|
	v_max3_f32 v3, v3, |v24|, |v0|
	v_mul_f32_e32 v6, v32, v136
	v_mul_f32_e32 v7, v33, v136
	v_mul_f32_e32 v21, v34, v136
	v_mul_f32_e32 v24, v35, v136
	v_mul_f32_e32 v1, v38, v138
	v_max3_f32 v4, v4, |v6|, |v1|
	v_mul_f32_e32 v1, v39, v138
	v_max3_f32 v5, v5, |v7|, |v1|
	v_mul_f32_e32 v1, v40, v138
	v_mul_f32_e32 v0, v41, v138
	v_max3_f32 v6, v2, |v21|, |v1|
	v_max3_f32 v7, v3, |v24|, |v0|
	v_mul_f32_e32 v2, v42, v140
	v_mul_f32_e32 v21, v43, v140
	v_mul_f32_e32 v24, v44, v140
	v_mul_f32_e32 v25, v45, v140
	s_waitcnt vmcnt(0)
	v_mul_f32_e32 v1, v46, v142
	v_max3_f32 v3, v4, |v2|, |v1|
	v_mul_f32_e32 v1, v47, v142
	v_max3_f32 v2, v5, |v21|, |v1|
	v_mul_f32_e32 v1, v48, v142
	v_mul_f32_e32 v0, v49, v142
	v_max3_f32 v1, v6, |v24|, |v1|
	v_max3_f32 v0, v7, |v25|, |v0|
	s_cbranch_vccz .LBB0_1945
	v_and_b32_e32 v5, 64, v159
	v_xor_b32_e32 v4, 16, v159
	v_add_u32_e32 v5, 64, v5
	v_cmp_lt_i32_e32 vcc, v4, v5
	s_nop 1
	v_cndmask_b32_e32 v4, v159, v4, vcc
	v_lshlrev_b32_e32 v6, 2, v4
	ds_bpermute_b32 v7, v6, v3
	v_xor_b32_e32 v4, 32, v159
	v_cmp_lt_i32_e32 vcc, v4, v5
	ds_bpermute_b32 v5, v6, v2
	ds_bpermute_b32 v24, v6, v0
	v_cndmask_b32_e32 v4, v159, v4, vcc
	v_lshlrev_b32_e32 v21, 2, v4
	s_waitcnt lgkmcnt(2)
	v_max_f32_e32 v4, v7, v7
	ds_bpermute_b32 v7, v6, v1
	v_max_f32_e32 v3, v3, v3
	s_waitcnt lgkmcnt(2)
	v_max_f32_e32 v5, v5, v5
	v_max_f32_e32 v2, v2, v2
	v_max_f32_e32 v1, v1, v1
	s_waitcnt lgkmcnt(0)
	v_max_f32_e32 v6, v7, v7
	v_max_f32_e32 v7, v24, v24
	v_max_f32_e32 v0, v0, v0
	v_max_f32_e32 v3, v3, v4
	v_max_f32_e32 v2, v2, v5
	v_max_f32_e32 v1, v1, v6
	v_max_f32_e32 v0, v0, v7
	ds_bpermute_b32 v4, v21, v3
	ds_bpermute_b32 v5, v21, v2
	ds_bpermute_b32 v6, v21, v1
	ds_bpermute_b32 v7, v21, v0
	s_and_saveexec_b64 s[14:15], s[4:5]
	s_cbranch_execz .LBB0_1948
	s_waitcnt lgkmcnt(0)
	v_max_f32_e32 v7, v7, v7
	v_max_f32_e32 v0, v0, v0
	v_max_f32_e32 v7, v0, v7
	v_max_f32_e32 v0, v6, v6
	v_max_f32_e32 v1, v1, v1
	v_max_f32_e32 v6, v1, v0
	v_max_f32_e32 v0, v5, v5
	v_max_f32_e32 v1, v2, v2
	v_max_f32_e32 v5, v1, v0
	v_max_f32_e32 v0, v4, v4
	v_max_f32_e32 v1, v3, v3
	v_max_f32_e32 v4, v1, v0
	v_add_u32_e32 v0, s90, v67
	ds_write_b128 v0, v[4:7]

.LBB0_1951:
	s_or_b32 s34, s0, s89
	v_or_b32_e32 v110, s34, v57
	v_ashrrev_i32_e32 v111, 31, v110
	v_lshl_add_u64 v[112:113], v[110:111], 2, s[12:13]
	global_load_dword v114, v[112:113], off
	v_or_b32_e32 v110, s34, v11
	v_ashrrev_i32_e32 v111, 31, v110
	v_lshl_add_u64 v[110:111], v[110:111], 2, s[12:13]
	global_load_dword v116, v[110:111], off
	v_or_b32_e32 v110, s34, v70
	v_ashrrev_i32_e32 v111, 31, v110
	v_lshl_add_u64 v[110:111], v[110:111], 2, s[12:13]
	global_load_dword v118, v[110:111], off
	v_or_b32_e32 v110, s34, v71
	v_ashrrev_i32_e32 v111, 31, v110
	v_lshl_add_u64 v[110:111], v[110:111], 2, s[12:13]
	global_load_dword v120, v[110:111], off
	v_or_b32_e32 v110, s34, v72
	v_ashrrev_i32_e32 v111, 31, v110
	v_lshl_add_u64 v[110:111], v[110:111], 2, s[12:13]
	global_load_dword v122, v[110:111], off
	v_or_b32_e32 v110, s34, v73
	v_ashrrev_i32_e32 v111, 31, v110
	v_lshl_add_u64 v[110:111], v[110:111], 2, s[12:13]
	global_load_dword v124, v[110:111], off
	v_or_b32_e32 v110, s34, v75
	v_ashrrev_i32_e32 v111, 31, v110
	v_lshl_add_u64 v[110:111], v[110:111], 2, s[12:13]
	global_load_dword v126, v[110:111], off
	v_or_b32_e32 v110, s34, v76
	v_ashrrev_i32_e32 v111, 31, v110
	v_lshl_add_u64 v[110:111], v[110:111], 2, s[12:13]
	global_load_dword v128, v[110:111], off
	v_or_b32_e32 v46, s34, v57
	v_mad_i64_i32 v[0:1], s[0:1], v46, s55, v[22:23]
	global_load_dwordx4 v[86:89], v[0:1], off nt
	v_add_u32_e32 v21, v69, v59
	v_or_b32_e32 v0, 4, v46
	v_mad_i64_i32 v[0:1], s[0:1], v0, s55, v[22:23]
	global_load_dwordx4 v[90:93], v[0:1], off nt
	v_add_u32_e32 v47, 0x410, v21
	v_or_b32_e32 v0, 8, v46
	v_mad_i64_i32 v[0:1], s[0:1], v0, s55, v[22:23]
	global_load_dwordx4 v[94:97], v[0:1], off nt
	v_or_b32_e32 v0, 12, v46
	v_mad_i64_i32 v[0:1], s[0:1], v0, s55, v[22:23]
	global_load_dwordx4 v[98:101], v[0:1], off nt
	v_or_b32_e32 v0, 16, v46
	v_mad_i64_i32 v[0:1], s[0:1], v0, s55, v[22:23]
	global_load_dwordx4 v[102:105], v[0:1], off nt
	v_or_b32_e32 v0, 20, v46
	v_mad_i64_i32 v[0:1], s[0:1], v0, s55, v[22:23]
	global_load_dwordx4 v[106:109], v[0:1], off nt
	v_or_b32_e32 v0, 24, v46
	v_mad_i64_i32 v[0:1], s[0:1], v0, s55, v[22:23]
	global_load_dwordx4 v[4:7], v[0:1], off nt
	v_or_b32_e32 v0, 28, v46
	v_mad_i64_i32 v[0:1], s[0:1], v0, s55, v[22:23]
	global_load_dwordx4 v[0:3], v[0:1], off nt
	s_ashr_i32 s35, s34, 31
	s_and_b64 vcc, exec, s[14:15]
	s_mov_b64 s[14:15], 0
	s_waitcnt vmcnt(15)
	v_pk_mul_f32 v[48:49], v[24:25], v[114:115] op_sel_hi:[1,0]
	s_waitcnt vmcnt(7)
	v_pk_mul_f32 v[48:49], v[86:87], v[48:49]
	ds_write2_b32 v21, v48, v49 offset1:1
	v_pk_mul_f32 v[48:49], v[26:27], v[114:115] op_sel_hi:[1,0]
	s_nop 0
	v_pk_mul_f32 v[48:49], v[88:89], v[48:49]
	ds_write2_b32 v21, v48, v49 offset0:2 offset1:3
	v_pk_mul_f32 v[48:49], v[24:25], v[116:117] op_sel_hi:[1,0]
	s_nop 0
	s_waitcnt vmcnt(6)
	v_pk_mul_f32 v[48:49], v[90:91], v[48:49]
	ds_write2_b32 v47, v48, v49 offset1:1
	v_pk_mul_f32 v[48:49], v[26:27], v[116:117] op_sel_hi:[1,0]
	v_add_u32_e32 v36, 0x418, v21
	v_pk_mul_f32 v[48:49], v[92:93], v[48:49]
	ds_write2_b32 v36, v48, v49 offset1:1
	v_add_u32_e32 v47, 0x820, v21
	v_pk_mul_f32 v[48:49], v[24:25], v[118:119] op_sel_hi:[1,0]
	s_nop 0
	s_waitcnt vmcnt(5)
	v_pk_mul_f32 v[48:49], v[94:95], v[48:49]
	ds_write2_b32 v47, v48, v49 offset1:1
	v_pk_mul_f32 v[48:49], v[26:27], v[118:119] op_sel_hi:[1,0]
	v_add_u32_e32 v36, 0x828, v21
	v_pk_mul_f32 v[48:49], v[96:97], v[48:49]
	ds_write2_b32 v36, v48, v49 offset1:1
	v_add_u32_e32 v47, 0xc30, v21
	v_pk_mul_f32 v[48:49], v[24:25], v[120:121] op_sel_hi:[1,0]
	s_nop 0
	s_waitcnt vmcnt(4)
	v_pk_mul_f32 v[48:49], v[98:99], v[48:49]
	ds_write2_b32 v47, v48, v49 offset1:1
	v_pk_mul_f32 v[48:49], v[26:27], v[120:121] op_sel_hi:[1,0]
	v_add_u32_e32 v36, 0xc38, v21
	v_pk_mul_f32 v[48:49], v[100:101], v[48:49]
	ds_write2_b32 v36, v48, v49 offset1:1
	v_add_u32_e32 v47, 0x1040, v21
	v_pk_mul_f32 v[48:49], v[24:25], v[122:123] op_sel_hi:[1,0]
	s_nop 0
	s_waitcnt vmcnt(3)
	v_pk_mul_f32 v[48:49], v[102:103], v[48:49]
	ds_write2_b32 v47, v48, v49 offset1:1
	v_pk_mul_f32 v[48:49], v[26:27], v[122:123] op_sel_hi:[1,0]
	v_add_u32_e32 v36, 0x1048, v21
	v_pk_mul_f32 v[48:49], v[104:105], v[48:49]
	ds_write2_b32 v36, v48, v49 offset1:1
	v_add_u32_e32 v21, 0x1450, v21
	v_pk_mul_f32 v[48:49], v[24:25], v[124:125] op_sel_hi:[1,0]
	s_nop 0
	s_waitcnt vmcnt(2)
	v_pk_mul_f32 v[48:49], v[106:107], v[48:49]
	ds_write2_b32 v21, v48, v49 offset1:1
	v_pk_mul_f32 v[48:49], v[26:27], v[124:125] op_sel_hi:[1,0]
	v_add_u32_e32 v21, v69, v74
	v_pk_mul_f32 v[48:49], v[108:109], v[48:49]
	ds_write2_b32 v21, v48, v49 offset0:2 offset1:3
	v_add_u32_e32 v47, 0x410, v21
	v_or_b32_e32 v106, s34, v77
	v_ashrrev_i32_e32 v107, 31, v106
	v_lshl_add_u64 v[106:107], v[106:107], 2, s[12:13]
	global_load_dword v130, v[106:107], off
	v_or_b32_e32 v110, s34, v78
	v_ashrrev_i32_e32 v111, 31, v110
	v_lshl_add_u64 v[110:111], v[110:111], 2, s[12:13]
	global_load_dword v132, v[110:111], off
	v_or_b32_e32 v110, s34, v79
	v_ashrrev_i32_e32 v111, 31, v110
	v_lshl_add_u64 v[110:111], v[110:111], 2, s[12:13]
	global_load_dword v134, v[110:111], off
	v_or_b32_e32 v110, s34, v80
	v_ashrrev_i32_e32 v111, 31, v110
	v_lshl_add_u64 v[110:111], v[110:111], 2, s[12:13]
	global_load_dword v136, v[110:111], off
	v_or_b32_e32 v110, s34, v81
	v_ashrrev_i32_e32 v111, 31, v110
	v_lshl_add_u64 v[110:111], v[110:111], 2, s[12:13]
	global_load_dword v138, v[110:111], off
	v_or_b32_e32 v110, s34, v82
	v_ashrrev_i32_e32 v111, 31, v110
	v_lshl_add_u64 v[110:111], v[110:111], 2, s[12:13]
	global_load_dword v140, v[110:111], off
	v_or_b32_e32 v110, s34, v83
	v_ashrrev_i32_e32 v111, 31, v110
	v_lshl_add_u64 v[110:111], v[110:111], 2, s[12:13]
	global_load_dword v142, v[110:111], off
	v_or_b32_e32 v110, s34, v84
	v_ashrrev_i32_e32 v111, 31, v110
	v_lshl_add_u64 v[110:111], v[110:111], 2, s[12:13]
	global_load_dword v144, v[110:111], off
	v_pk_mul_f32 v[48:49], v[24:25], v[126:127] op_sel_hi:[1,0]
	s_nop 0
	s_waitcnt vmcnt(9)
	v_pk_mul_f32 v[4:5], v[4:5], v[48:49]
	ds_write2_b32 v47, v4, v5 offset1:1
	v_pk_mul_f32 v[4:5], v[26:27], v[126:127] op_sel_hi:[1,0]
	v_or_b32_e32 v36, 40, v46
	v_pk_mul_f32 v[4:5], v[6:7], v[4:5]
	v_add_u32_e32 v6, 0x418, v21
	ds_write2_b32 v6, v4, v5 offset1:1
	v_mad_i64_i32 v[48:49], s[0:1], v36, s55, v[22:23]
	v_or_b32_e32 v36, 44, v46
	global_load_dwordx4 v[86:89], v[48:49], off nt
	v_mad_i64_i32 v[48:49], s[0:1], v36, s55, v[22:23]
	v_or_b32_e32 v36, 48, v46
	global_load_dwordx4 v[90:93], v[48:49], off nt
	v_mad_i64_i32 v[48:49], s[0:1], v36, s55, v[22:23]
	v_or_b32_e32 v36, 52, v46
	global_load_dwordx4 v[94:97], v[48:49], off nt
	v_mad_i64_i32 v[48:49], s[0:1], v36, s55, v[22:23]
	v_or_b32_e32 v36, 56, v46
	global_load_dwordx4 v[98:101], v[48:49], off nt
	v_mad_i64_i32 v[48:49], s[0:1], v36, s55, v[22:23]
	v_or_b32_e32 v36, 60, v46
	global_load_dwordx4 v[102:105], v[48:49], off nt
	v_pk_mul_f32 v[6:7], v[24:25], v[128:129] op_sel_hi:[1,0]
	s_nop 0
	s_waitcnt vmcnt(13)
	v_pk_mul_f32 v[0:1], v[0:1], v[6:7]
	v_add_u32_e32 v5, 0x820, v21
	ds_write2_b32 v5, v0, v1 offset1:1
	v_pk_mul_f32 v[0:1], v[26:27], v[128:129] op_sel_hi:[1,0]
	v_or_b32_e32 v4, 36, v46
	v_pk_mul_f32 v[0:1], v[2:3], v[0:1]
	v_add_u32_e32 v2, 0x828, v21
	ds_write2_b32 v2, v0, v1 offset1:1
	v_or_b32_e32 v0, 32, v46
	v_mad_i64_i32 v[0:1], s[0:1], v0, s55, v[22:23]
	v_mad_i64_i32 v[46:47], s[0:1], v36, s55, v[22:23]
	v_mad_i64_i32 v[4:5], s[0:1], v4, s55, v[22:23]
	global_load_dwordx4 v[0:3], v[0:1], off nt
	s_mov_b32 s0, 64
	global_load_dwordx4 v[4:7], v[4:5], off nt
	s_waitcnt vmcnt(14)
	v_pk_mul_f32 v[106:107], v[24:25], v[130:131] op_sel_hi:[1,0]
	global_load_dwordx4 v[46:49], v[46:47], off nt
	s_waitcnt vmcnt(2)
	v_pk_mul_f32 v[0:1], v[0:1], v[106:107]
	v_add_u32_e32 v106, 0xc30, v21
	ds_write2_b32 v106, v0, v1 offset1:1
	v_pk_mul_f32 v[0:1], v[26:27], v[130:131] op_sel_hi:[1,0]
	s_nop 0
	v_pk_mul_f32 v[0:1], v[2:3], v[0:1]
	v_add_u32_e32 v2, 0xc38, v21
	ds_write2_b32 v2, v0, v1 offset1:1
	v_pk_mul_f32 v[2:3], v[24:25], v[132:133] op_sel_hi:[1,0]
	s_nop 0
	s_waitcnt vmcnt(1)
	v_pk_mul_f32 v[2:3], v[4:5], v[2:3]
	v_add_u32_e32 v1, 0x1040, v21
	ds_write2_b32 v1, v2, v3 offset1:1
	v_pk_mul_f32 v[0:1], v[26:27], v[132:133] op_sel_hi:[1,0]
	v_add_u32_e32 v2, 0x1048, v21
	v_pk_mul_f32 v[0:1], v[6:7], v[0:1]
	ds_write2_b32 v2, v0, v1 offset1:1
	v_pk_mul_f32 v[2:3], v[24:25], v[134:135] op_sel_hi:[1,0]
	s_nop 0
	v_pk_mul_f32 v[2:3], v[86:87], v[2:3]
	v_add_u32_e32 v1, 0x1450, v21
	ds_write2_b32 v1, v2, v3 offset1:1
	v_pk_mul_f32 v[0:1], v[26:27], v[134:135] op_sel_hi:[1,0]
	v_add_u32_e32 v2, 0x1458, v21
	v_pk_mul_f32 v[0:1], v[88:89], v[0:1]
	ds_write2_b32 v2, v0, v1 offset1:1
	v_pk_mul_f32 v[2:3], v[24:25], v[136:137] op_sel_hi:[1,0]
	s_nop 0
	v_pk_mul_f32 v[2:3], v[90:91], v[2:3]
	v_add_u32_e32 v1, 0x1860, v21
	ds_write2_b32 v1, v2, v3 offset1:1
	v_pk_mul_f32 v[0:1], v[26:27], v[136:137] op_sel_hi:[1,0]
	v_add_u32_e32 v2, 0x1868, v21
	v_pk_mul_f32 v[0:1], v[92:93], v[0:1]
	ds_write2_b32 v2, v0, v1 offset1:1
	v_pk_mul_f32 v[2:3], v[24:25], v[138:139] op_sel_hi:[1,0]
	s_nop 0
	v_pk_mul_f32 v[2:3], v[94:95], v[2:3]
	v_add_u32_e32 v1, 0x1c70, v21
	ds_write2_b32 v1, v2, v3 offset1:1
	v_pk_mul_f32 v[0:1], v[26:27], v[138:139] op_sel_hi:[1,0]
	v_add_u32_e32 v2, 0x1c78, v21
	v_pk_mul_f32 v[0:1], v[96:97], v[0:1]
	ds_write2_b32 v2, v0, v1 offset1:1
	v_pk_mul_f32 v[2:3], v[24:25], v[140:141] op_sel_hi:[1,0]
	s_nop 0
	v_pk_mul_f32 v[2:3], v[98:99], v[2:3]
	v_add_u32_e32 v1, 0x2080, v21
	ds_write2_b32 v1, v2, v3 offset1:1
	v_pk_mul_f32 v[0:1], v[26:27], v[140:141] op_sel_hi:[1,0]
	v_add_u32_e32 v2, 0x2088, v21
	v_pk_mul_f32 v[0:1], v[100:101], v[0:1]
	ds_write2_b32 v2, v0, v1 offset1:1
	v_pk_mul_f32 v[2:3], v[24:25], v[142:143] op_sel_hi:[1,0]
	s_nop 0
	v_pk_mul_f32 v[2:3], v[102:103], v[2:3]
	v_add_u32_e32 v1, 0x2490, v21
	ds_write2_b32 v1, v2, v3 offset1:1
	v_pk_mul_f32 v[0:1], v[26:27], v[142:143] op_sel_hi:[1,0]
	v_add_u32_e32 v2, 0x2498, v21
	v_pk_mul_f32 v[0:1], v[104:105], v[0:1]
	ds_write2_b32 v2, v0, v1 offset1:1
	v_pk_mul_f32 v[2:3], v[24:25], v[144:145] op_sel_hi:[1,0]
	s_nop 0
	s_waitcnt vmcnt(0)
	v_pk_mul_f32 v[2:3], v[46:47], v[2:3]
	v_add_u32_e32 v1, 0x28a0, v21
	ds_write2_b32 v1, v2, v3 offset1:1
	v_pk_mul_f32 v[0:1], v[26:27], v[144:145] op_sel_hi:[1,0]
	v_add_u32_e32 v2, 0x28a8, v21
	v_pk_mul_f32 v[0:1], v[48:49], v[0:1]
	ds_write2_b32 v2, v0, v1 offset1:1
	s_waitcnt lgkmcnt(0)
	ds_read2_b32 v[6:7], v9 offset0:130 offset1:138
	ds_read2_b32 v[46:47], v9 offset0:195 offset1:203
	ds_read2_b32 v[2:3], v9 offset1:8
	ds_read2_b32 v[4:5], v9 offset0:65 offset1:73
	v_lshl_add_u64 v[0:1], v[18:19], 0, s[34:35]
	s_waitcnt lgkmcnt(3)
	v_med3_f32 v6, v6, s52, v53
	s_waitcnt lgkmcnt(2)
	v_med3_f32 v21, v46, s52, v53
	v_add_f32_e32 v6, 0x4b400000, v6
	v_add_f32_e32 v21, 0x4b400000, v21
	v_perm_b32 v6, v21, v6, s53
	v_add_u32_e32 v21, 0x400, v9
	ds_read2_b32 v[86:87], v21 offset0:4 offset1:12
	ds_read2_b32 v[88:89], v21 offset0:69 offset1:77
	ds_read2_b32 v[90:91], v21 offset0:134 offset1:142
	ds_read2_b32 v[92:93], v21 offset0:199 offset1:207
	s_waitcnt lgkmcnt(5)
	v_med3_f32 v2, v2, s52, v53
	s_waitcnt lgkmcnt(4)
	v_med3_f32 v4, v4, s52, v53
	v_add_f32_e32 v2, 0x4b400000, v2
	v_add_f32_e32 v4, 0x4b400000, v4
	v_perm_b32 v2, v4, v2, s53
	v_perm_b32 v48, v6, v2, s54
	s_waitcnt lgkmcnt(3)
	v_med3_f32 v2, v86, s52, v53
	s_waitcnt lgkmcnt(2)
	v_med3_f32 v4, v88, s52, v53
	s_waitcnt lgkmcnt(1)
	v_med3_f32 v6, v90, s52, v53
	s_waitcnt lgkmcnt(0)
	v_med3_f32 v36, v92, s52, v53
	v_add_f32_e32 v2, 0x4b400000, v2
	v_add_f32_e32 v4, 0x4b400000, v4
	v_add_f32_e32 v6, 0x4b400000, v6
	v_add_f32_e32 v36, 0x4b400000, v36
	v_perm_b32 v6, v36, v6, s53
	v_perm_b32 v2, v4, v2, s53
	v_perm_b32 v49, v6, v2, s54
	v_med3_f32 v2, v3, s52, v53
	v_med3_f32 v3, v5, s52, v53
	v_med3_f32 v4, v7, s52, v53
	v_med3_f32 v5, v47, s52, v53
	v_add_f32_e32 v2, 0x4b400000, v2
	v_add_f32_e32 v3, 0x4b400000, v3
	v_add_f32_e32 v4, 0x4b400000, v4
	v_add_f32_e32 v5, 0x4b400000, v5
	v_perm_b32 v4, v5, v4, s53
	v_perm_b32 v2, v3, v2, s53
	v_perm_b32 v2, v4, v2, s54
	v_med3_f32 v3, v87, s52, v53
	v_med3_f32 v4, v89, s52, v53
	v_med3_f32 v5, v91, s52, v53
	v_med3_f32 v6, v93, s52, v53
	v_add_f32_e32 v3, 0x4b400000, v3
	v_add_f32_e32 v4, 0x4b400000, v4
	v_add_f32_e32 v5, 0x4b400000, v5
	v_add_f32_e32 v6, 0x4b400000, v6
	v_perm_b32 v5, v6, v5, s53
	v_perm_b32 v3, v4, v3, s53
	v_perm_b32 v3, v5, v3, s54
	v_lshl_add_u64 v[4:5], v[0:1], 0, v[30:31]
	global_store_dwordx2 v[4:5], v[2:3], off
	ds_read2_b32 v[2:3], v9 offset0:16 offset1:24
	ds_read2_b32 v[4:5], v9 offset0:81 offset1:89
	ds_read2_b32 v[6:7], v9 offset0:146 offset1:154
	ds_read2_b32 v[46:47], v9 offset0:211 offset1:219
	ds_read2_b32 v[86:87], v21 offset0:20 offset1:28
	ds_read2_b32 v[88:89], v21 offset0:85 offset1:93
	ds_read2_b32 v[90:91], v21 offset0:150 offset1:158
	ds_read2_b32 v[92:93], v21 offset0:215 offset1:223
	s_waitcnt lgkmcnt(7)
	v_med3_f32 v2, v2, s52, v53
	s_waitcnt lgkmcnt(6)
	v_med3_f32 v4, v4, s52, v53
	s_waitcnt lgkmcnt(5)
	v_med3_f32 v6, v6, s52, v53
	s_waitcnt lgkmcnt(4)
	v_med3_f32 v36, v46, s52, v53
	v_add_f32_e32 v2, 0x4b400000, v2
	v_add_f32_e32 v4, 0x4b400000, v4
	v_add_f32_e32 v6, 0x4b400000, v6
	v_add_f32_e32 v36, 0x4b400000, v36
	v_lshl_add_u64 v[94:95], v[0:1], 0, v[28:29]
	v_perm_b32 v6, v36, v6, s53
	v_perm_b32 v2, v4, v2, s53
	global_store_dwordx2 v[94:95], v[48:49], off
	v_perm_b32 v48, v6, v2, s54
	s_waitcnt lgkmcnt(3)
	v_med3_f32 v2, v86, s52, v53
	s_waitcnt lgkmcnt(2)
	v_med3_f32 v4, v88, s52, v53
	s_waitcnt lgkmcnt(1)
	v_med3_f32 v6, v90, s52, v53
	s_waitcnt lgkmcnt(0)
	v_med3_f32 v36, v92, s52, v53
	v_add_f32_e32 v2, 0x4b400000, v2
	v_add_f32_e32 v4, 0x4b400000, v4
	v_add_f32_e32 v6, 0x4b400000, v6
	v_add_f32_e32 v36, 0x4b400000, v36
	v_perm_b32 v6, v36, v6, s53
	v_perm_b32 v2, v4, v2, s53
	v_perm_b32 v49, v6, v2, s54
	v_med3_f32 v2, v3, s52, v53
	v_med3_f32 v3, v5, s52, v53
	v_med3_f32 v4, v7, s52, v53
	v_med3_f32 v5, v47, s52, v53
	v_add_f32_e32 v2, 0x4b400000, v2
	v_add_f32_e32 v3, 0x4b400000, v3
	v_add_f32_e32 v4, 0x4b400000, v4
	v_add_f32_e32 v5, 0x4b400000, v5
	v_perm_b32 v4, v5, v4, s53
	v_perm_b32 v2, v3, v2, s53
	v_perm_b32 v2, v4, v2, s54
	v_med3_f32 v3, v87, s52, v53
	v_med3_f32 v4, v89, s52, v53
	v_med3_f32 v5, v91, s52, v53
	v_med3_f32 v6, v93, s52, v53
	v_add_f32_e32 v3, 0x4b400000, v3
	v_add_f32_e32 v4, 0x4b400000, v4
	v_add_f32_e32 v5, 0x4b400000, v5
	v_add_f32_e32 v6, 0x4b400000, v6
	v_perm_b32 v5, v6, v5, s53
	v_perm_b32 v3, v4, v3, s53
	v_perm_b32 v3, v5, v3, s54
	v_lshl_add_u64 v[4:5], v[0:1], 0, v[34:35]
	global_store_dwordx2 v[4:5], v[2:3], off
	ds_read2_b32 v[2:3], v9 offset0:32 offset1:40
	ds_read2_b32 v[4:5], v9 offset0:97 offset1:105
	ds_read2_b32 v[6:7], v9 offset0:162 offset1:170
	ds_read2_b32 v[46:47], v9 offset0:227 offset1:235
	ds_read2_b32 v[86:87], v21 offset0:36 offset1:44
	ds_read2_b32 v[88:89], v21 offset0:101 offset1:109
	ds_read2_b32 v[90:91], v21 offset0:166 offset1:174
	ds_read2_b32 v[92:93], v21 offset0:231 offset1:239
	s_waitcnt lgkmcnt(7)
	v_med3_f32 v2, v2, s52, v53
	s_waitcnt lgkmcnt(6)
	v_med3_f32 v4, v4, s52, v53
	s_waitcnt lgkmcnt(5)
	v_med3_f32 v6, v6, s52, v53
	s_waitcnt lgkmcnt(4)
	v_med3_f32 v36, v46, s52, v53
	v_add_f32_e32 v2, 0x4b400000, v2
	v_add_f32_e32 v4, 0x4b400000, v4
	v_add_f32_e32 v6, 0x4b400000, v6
	v_add_f32_e32 v36, 0x4b400000, v36
	v_lshl_add_u64 v[94:95], v[0:1], 0, v[32:33]
	v_perm_b32 v6, v36, v6, s53
	v_perm_b32 v2, v4, v2, s53
	global_store_dwordx2 v[94:95], v[48:49], off
	v_perm_b32 v48, v6, v2, s54
	s_waitcnt lgkmcnt(3)
	v_med3_f32 v2, v86, s52, v53
	s_waitcnt lgkmcnt(2)
	v_med3_f32 v4, v88, s52, v53
	s_waitcnt lgkmcnt(1)
	v_med3_f32 v6, v90, s52, v53
	s_waitcnt lgkmcnt(0)
	v_med3_f32 v36, v92, s52, v53
	v_add_f32_e32 v2, 0x4b400000, v2
	v_add_f32_e32 v4, 0x4b400000, v4
	v_add_f32_e32 v6, 0x4b400000, v6
	v_add_f32_e32 v36, 0x4b400000, v36
	v_perm_b32 v6, v36, v6, s53
	v_perm_b32 v2, v4, v2, s53
	v_perm_b32 v49, v6, v2, s54
	v_med3_f32 v2, v3, s52, v53
	v_med3_f32 v3, v5, s52, v53
	v_med3_f32 v4, v7, s52, v53
	v_med3_f32 v5, v47, s52, v53
	v_add_f32_e32 v2, 0x4b400000, v2
	v_add_f32_e32 v3, 0x4b400000, v3
	v_add_f32_e32 v4, 0x4b400000, v4
	v_add_f32_e32 v5, 0x4b400000, v5
	v_perm_b32 v4, v5, v4, s53
	v_perm_b32 v2, v3, v2, s53
	v_perm_b32 v2, v4, v2, s54
	v_med3_f32 v3, v87, s52, v53
	v_med3_f32 v4, v89, s52, v53
	v_med3_f32 v5, v91, s52, v53
	v_med3_f32 v6, v93, s52, v53
	v_add_f32_e32 v3, 0x4b400000, v3
	v_add_f32_e32 v4, 0x4b400000, v4
	v_add_f32_e32 v5, 0x4b400000, v5
	v_add_f32_e32 v6, 0x4b400000, v6
	v_perm_b32 v5, v6, v5, s53
	v_perm_b32 v3, v4, v3, s53
	v_perm_b32 v3, v5, v3, s54
	v_lshl_add_u64 v[4:5], v[0:1], 0, v[40:41]
	global_store_dwordx2 v[4:5], v[2:3], off
	ds_read2_b32 v[2:3], v9 offset0:48 offset1:56
	ds_read2_b32 v[4:5], v9 offset0:113 offset1:121
	ds_read2_b32 v[6:7], v9 offset0:178 offset1:186
	ds_read2_b32 v[46:47], v9 offset0:243 offset1:251
	ds_read2_b32 v[86:87], v21 offset0:52 offset1:60
	ds_read2_b32 v[88:89], v21 offset0:117 offset1:125
	ds_read2_b32 v[90:91], v21 offset0:182 offset1:190
	ds_read2_b32 v[92:93], v21 offset0:247 offset1:255
	s_waitcnt lgkmcnt(7)
	v_med3_f32 v2, v2, s52, v53
	s_waitcnt lgkmcnt(6)
	v_med3_f32 v4, v4, s52, v53
	s_waitcnt lgkmcnt(5)
	v_med3_f32 v6, v6, s52, v53
	s_waitcnt lgkmcnt(4)
	v_med3_f32 v36, v46, s52, v53
	v_add_f32_e32 v2, 0x4b400000, v2
	v_add_f32_e32 v4, 0x4b400000, v4
	v_add_f32_e32 v6, 0x4b400000, v6
	v_add_f32_e32 v36, 0x4b400000, v36
	v_lshl_add_u64 v[94:95], v[0:1], 0, v[38:39]
	v_perm_b32 v6, v36, v6, s53
	v_perm_b32 v2, v4, v2, s53
	global_store_dwordx2 v[94:95], v[48:49], off
	v_perm_b32 v48, v6, v2, s54
	s_waitcnt lgkmcnt(3)
	v_med3_f32 v2, v86, s52, v53
	s_waitcnt lgkmcnt(2)
	v_med3_f32 v4, v88, s52, v53
	s_waitcnt lgkmcnt(1)
	v_med3_f32 v6, v90, s52, v53
	s_waitcnt lgkmcnt(0)
	v_med3_f32 v21, v92, s52, v53
	v_add_f32_e32 v2, 0x4b400000, v2
	v_add_f32_e32 v4, 0x4b400000, v4
	v_add_f32_e32 v6, 0x4b400000, v6
	v_add_f32_e32 v21, 0x4b400000, v21
	v_perm_b32 v6, v21, v6, s53
	v_perm_b32 v2, v4, v2, s53
	v_perm_b32 v49, v6, v2, s54
	v_med3_f32 v2, v3, s52, v53
	v_med3_f32 v3, v5, s52, v53
	v_med3_f32 v4, v7, s52, v53
	v_med3_f32 v5, v47, s52, v53
	v_add_f32_e32 v2, 0x4b400000, v2
	v_add_f32_e32 v3, 0x4b400000, v3
	v_add_f32_e32 v4, 0x4b400000, v4
	v_add_f32_e32 v5, 0x4b400000, v5
	v_perm_b32 v4, v5, v4, s53
	v_perm_b32 v2, v3, v2, s53
	v_perm_b32 v2, v4, v2, s54
	v_med3_f32 v3, v87, s52, v53
	v_med3_f32 v4, v89, s52, v53
	v_med3_f32 v5, v91, s52, v53
	v_med3_f32 v6, v93, s52, v53
	v_add_f32_e32 v3, 0x4b400000, v3
	v_add_f32_e32 v4, 0x4b400000, v4
	v_add_f32_e32 v5, 0x4b400000, v5
	v_add_f32_e32 v6, 0x4b400000, v6
	v_perm_b32 v5, v6, v5, s53
	v_perm_b32 v3, v4, v3, s53
	v_lshl_add_u64 v[94:95], v[0:1], 0, v[42:43]
	v_perm_b32 v3, v5, v3, s54
	v_lshl_add_u64 v[0:1], v[0:1], 0, v[44:45]
	global_store_dwordx2 v[94:95], v[48:49], off
	global_store_dwordx2 v[0:1], v[2:3], off
	s_waitcnt lgkmcnt(0)
	s_cbranch_vccnz .LBB0_1951
	s_barrier
	s_branch .LBB0_1907
